# attention latent loop: softmax exp/sum/cvt interleaved with PV MFMAs per 8-key group; g1 V fragments preloaded into spare VGPRs; flat->global
# speedup vs baseline: 1.0049x; 1.0049x over previous
.LBB0_34:
	s_mov_b32 s11, 0xed780000
	v_add_co_u32_e32 v6, vcc, s11, v4
	s_mov_b32 s12, 0xed858000
	s_nop 0
	v_addc_co_u32_e32 v7, vcc, -1, v5, vcc
	v_add_co_u32_e32 v8, vcc, s12, v4
	s_mov_b32 s13, 0xed930000
	s_nop 0
	v_addc_co_u32_e32 v9, vcc, -1, v5, vcc
	v_add_co_u32_e32 v10, vcc, s13, v4
	s_mov_b32 s14, 0xeda08000
	s_nop 0
	v_addc_co_u32_e32 v11, vcc, -1, v5, vcc
	v_add_co_u32_e32 v12, vcc, s14, v4
	s_mov_b32 s15, 0xedae0000
	s_nop 0
	v_addc_co_u32_e32 v13, vcc, -1, v5, vcc
	v_add_co_u32_e32 v14, vcc, s15, v4
	s_mov_b32 s16, 0xedbb8000
	s_nop 0
	v_addc_co_u32_e32 v15, vcc, -1, v5, vcc
	v_add_co_u32_e32 v16, vcc, s16, v4
	s_mov_b32 s17, 0xedc90000
	s_nop 0
	v_addc_co_u32_e32 v17, vcc, -1, v5, vcc
	v_add_co_u32_e32 v18, vcc, s17, v4
	s_mov_b32 s18, 0xedd68000
	s_nop 0
	v_addc_co_u32_e32 v19, vcc, -1, v5, vcc
	v_add_co_u32_e32 v20, vcc, s18, v4
	s_mov_b32 s19, 0xede40000
	s_nop 0
	v_addc_co_u32_e32 v21, vcc, -1, v5, vcc
	v_add_co_u32_e32 v22, vcc, s19, v4
	s_mov_b32 s10, 0x2aaaaaab
	s_mov_b32 s20, 0xedf18000
	v_addc_co_u32_e32 v23, vcc, -1, v5, vcc
	v_mul_hi_i32 v3, v2, s10
	v_add_co_u32_e32 v24, vcc, s20, v4
	s_mov_b32 s5, 0x4bda12f7
	s_mov_b32 s21, 0xedff0000
	v_addc_co_u32_e32 v25, vcc, -1, v5, vcc
	v_lshrrev_b32_e32 v33, 31, v3
	v_ashrrev_i32_e32 v3, 10, v3
	v_mul_hi_i32 v0, v2, s5
	v_add_co_u32_e32 v26, vcc, s21, v4
	v_add_u32_e32 v3, v3, v33
	s_mov_b32 s22, 0xee0c8000
	v_addc_co_u32_e32 v27, vcc, -1, v5, vcc
	v_lshrrev_b32_e32 v32, 31, v0
	v_ashrrev_i32_e32 v0, 14, v0
	v_mul_i32_i24_e32 v3, 0x1800, v3
	s_movk_i32 s25, 0x1800
	v_add_co_u32_e32 v28, vcc, s22, v4
	v_add_u32_e32 v0, v0, v32
	v_sub_u32_e32 v3, v2, v3
	v_addc_co_u32_e32 v29, vcc, -1, v5, vcc
	global_load_dword v34, v[6:7], off
	global_load_dword v35, v[8:9], off
	s_nop 0
	global_load_dword v10, v[10:11], off
	s_nop 0
	global_load_dword v11, v[12:13], off
	s_nop 0
	global_load_dword v12, v[14:15], off
	global_load_dword v13, v[16:17], off
	s_nop 0
	global_load_dword v14, v[18:19], off
	global_load_dword v15, v[20:21], off
	global_load_dword v16, v[22:23], off
	global_load_dword v17, v[24:25], off
	s_nop 0
	global_load_dword v18, v[26:27], off
	global_load_dword v19, v[28:29], off
	v_mad_i32_i24 v8, v0, s25, v3
	v_ashrrev_i32_e32 v9, 31, v8
	v_lshl_add_u64 v[8:9], v[8:9], 2, s[44:45]
	global_load_dword v0, v[8:9], off
	s_mov_b32 s23, 0xee1a0000
	v_add_co_u32_e32 v30, vcc, s23, v4
	s_mov_b32 s24, 0xee278000
	s_nop 0
	v_addc_co_u32_e32 v31, vcc, -1, v5, vcc
	v_add_co_u32_e32 v6, vcc, s24, v4
	s_mov_b32 s26, 0xee350000
	s_nop 0
	v_addc_co_u32_e32 v7, vcc, -1, v5, vcc
	v_add_co_u32_e32 v8, vcc, s26, v4
	global_load_dword v3, v[30:31], off
	global_load_dword v20, v[6:7], off
	v_addc_co_u32_e32 v9, vcc, -1, v5, vcc
	v_add_co_u32_e32 v6, vcc, 0xee428000, v4
	s_mov_b32 s5, 0x35fff
	s_nop 0
	v_addc_co_u32_e32 v7, vcc, -1, v5, vcc
	global_load_dword v8, v[8:9], off
	s_nop 0
	global_load_dword v6, v[6:7], off
	v_add_u32_e32 v2, s4, v2
	v_cmp_lt_i32_e32 vcc, s5, v2
	s_or_b64 s[8:9], vcc, s[8:9]
	s_waitcnt vmcnt(0) lgkmcnt(0)
	v_add_f32_e32 v0, v0, v34
	v_add_f32_e32 v0, v0, v35
	v_add_f32_e32 v0, v0, v10
	v_add_f32_e32 v0, v0, v11
	v_add_f32_e32 v0, v0, v12
	v_add_f32_e32 v0, v0, v13
	v_add_f32_e32 v0, v0, v14
	v_add_f32_e32 v0, v0, v15
	v_add_f32_e32 v0, v0, v16
	v_add_f32_e32 v0, v0, v17
	v_add_f32_e32 v0, v0, v18
	v_add_f32_e32 v0, v0, v19
	v_add_f32_e32 v0, v0, v3
	v_add_f32_e32 v0, v0, v20
	v_add_f32_e32 v0, v0, v8
	v_add_f32_e32 v0, v0, v6
	global_store_dword v[4:5], v0, off
	v_lshl_add_u64 v[4:5], v[4:5], 0, s[6:7]
	s_andn2_b64 exec, exec, s[8:9]
	s_cbranch_execnz .LBB0_34

.LBB0_47:
	s_add_i32 s4, s16, 0xfffff000
	s_lshr_b32 s4, s4, 12
	s_add_i32 s4, s4, 1
	s_cmp_gt_i32 s17, 15
	s_cselect_b32 s4, s4, 0
	v_readlane_b32 s18, v254, 23
	s_add_u32 s4, s2, s4
	s_mul_hi_i32 s5, s18, 9
	s_addc_u32 s5, s5, 0
	s_waitcnt vmcnt(5)
	v_ashrrev_i32_e32 v66, 1, v134
	s_mulk_i32 s5, 0x6000
	s_mul_hi_u32 s17, s4, 0x6000
	v_and_b32_e32 v66, 0xffffffc0, v66
	s_add_i32 s17, s17, s5
	s_mulk_i32 s4, 0x6000
	v_add_u32_e32 v66, s16, v66
	s_add_u32 s4, s78, s4
	v_and_or_b32 v68, v134, 31, v66
	v_lshrrev_b32_e32 v66, 3, v134
	v_and_b32_e32 v0, 64, v134
	s_addc_u32 s5, s79, s17
	v_and_b32_e32 v66, 4, v66
	v_ashrrev_i32_e32 v69, 31, v68
	v_readlane_b32 s16, v254, 21
	v_or3_b32 v0, v0, v66, s15
	v_lshlrev_b64 v[66:67], 12, v[68:69]
	v_readlane_b32 s17, v254, 22
	s_add_u32 s4, s4, 0x1d485000
	v_lshlrev_b32_e32 v0, 2, v0
	v_lshl_add_u64 v[66:67], s[16:17], 0, v[66:67]
	s_addc_u32 s5, s5, 0
	s_waitcnt vmcnt(4)
	v_lshl_add_u64 v[70:71], v[66:67], 0, v[0:1]
	v_lshl_add_u64 v[66:67], s[4:5], 0, v[0:1]
	s_waitcnt vmcnt(3)
	global_load_dwordx4 v[72:75], v[70:71], off
	s_waitcnt vmcnt(0)
	global_load_dwordx4 v[76:79], v[66:67], off
	v_readlane_b32 s19, v254, 24
	s_waitcnt vmcnt(0) lgkmcnt(0)
	v_pk_fma_f32 v[50:51], v[50:51], v[76:77], v[72:73]
	v_pk_fma_f32 v[52:53], v[52:53], v[78:79], v[74:75]
	global_store_dwordx4 v[70:71], v[50:53], off
	s_nop 1
	v_or_b32_e32 v50, 32, v0
	v_mov_b32_e32 v51, v1
	v_lshl_add_u64 v[50:51], s[4:5], 0, v[50:51]
	global_load_dwordx4 v[72:75], v[70:71], off offset:32
	global_load_dwordx4 v[76:79], v[50:51], off
	s_waitcnt vmcnt(0) lgkmcnt(0)
	v_pk_fma_f32 v[52:53], v[54:55], v[76:77], v[72:73]
	v_pk_fma_f32 v[54:55], v[56:57], v[78:79], v[74:75]
	global_store_dwordx4 v[70:71], v[52:55], off offset:32
	s_nop 1
	v_or_b32_e32 v52, 64, v0
	v_mov_b32_e32 v53, v1
	v_lshl_add_u64 v[52:53], s[4:5], 0, v[52:53]
	global_load_dwordx4 v[54:57], v[70:71], off offset:64
	global_load_dwordx4 v[72:75], v[52:53], off
	s_waitcnt vmcnt(0) lgkmcnt(0)
	v_pk_fma_f32 v[54:55], v[58:59], v[72:73], v[54:55]
	v_pk_fma_f32 v[56:57], v[60:61], v[74:75], v[56:57]
	global_store_dwordx4 v[70:71], v[54:57], off offset:64
	s_nop 1
	v_or_b32_e32 v54, 0x60, v0
	v_mov_b32_e32 v55, v1
	v_lshl_add_u64 v[54:55], s[4:5], 0, v[54:55]
	global_load_dwordx4 v[56:59], v[70:71], off offset:96
	global_load_dwordx4 v[72:75], v[54:55], off
	s_waitcnt vmcnt(0) lgkmcnt(0)
	v_pk_fma_f32 v[56:57], v[62:63], v[72:73], v[56:57]
	v_pk_fma_f32 v[58:59], v[64:65], v[74:75], v[58:59]
	global_store_dwordx4 v[70:71], v[56:59], off offset:96
	s_nop 1
	v_or_b32_e32 v56, 0x80, v0
	v_mov_b32_e32 v57, v1
	v_lshl_add_u64 v[56:57], s[4:5], 0, v[56:57]
	global_load_dwordx4 v[58:61], v[70:71], off offset:128
	global_load_dwordx4 v[62:65], v[56:57], off
	s_waitcnt vmcnt(0) lgkmcnt(0)
	v_pk_fma_f32 v[34:35], v[34:35], v[62:63], v[58:59]
	v_pk_fma_f32 v[36:37], v[36:37], v[64:65], v[60:61]
	global_store_dwordx4 v[70:71], v[34:37], off offset:128
	s_nop 1
	v_or_b32_e32 v34, 0xa0, v0
	v_mov_b32_e32 v35, v1
	v_lshl_add_u64 v[34:35], s[4:5], 0, v[34:35]
	global_load_dwordx4 v[58:61], v[70:71], off offset:160
	global_load_dwordx4 v[62:65], v[34:35], off
	s_waitcnt vmcnt(0) lgkmcnt(0)
	v_pk_fma_f32 v[36:37], v[38:39], v[62:63], v[58:59]
	v_pk_fma_f32 v[38:39], v[40:41], v[64:65], v[60:61]
	global_store_dwordx4 v[70:71], v[36:39], off offset:160
	s_nop 1
	v_or_b32_e32 v36, 0xc0, v0
	v_mov_b32_e32 v37, v1
	v_lshl_add_u64 v[36:37], s[4:5], 0, v[36:37]
	global_load_dwordx4 v[38:41], v[70:71], off offset:192
	global_load_dwordx4 v[58:61], v[36:37], off
	s_waitcnt vmcnt(0) lgkmcnt(0)
	v_pk_fma_f32 v[38:39], v[42:43], v[58:59], v[38:39]
	v_pk_fma_f32 v[40:41], v[44:45], v[60:61], v[40:41]
	global_store_dwordx4 v[70:71], v[38:41], off offset:192
	s_nop 1
	v_or_b32_e32 v38, 0xe0, v0
	v_mov_b32_e32 v39, v1
	v_lshl_add_u64 v[38:39], s[4:5], 0, v[38:39]
	global_load_dwordx4 v[40:43], v[70:71], off offset:224
	global_load_dwordx4 v[58:61], v[38:39], off
	s_mov_b64 s[4:5], 0
	s_waitcnt vmcnt(0) lgkmcnt(0)
	v_pk_fma_f32 v[40:41], v[46:47], v[58:59], v[40:41]
	v_pk_fma_f32 v[42:43], v[48:49], v[60:61], v[42:43]
	global_store_dwordx4 v[70:71], v[40:43], off offset:224
	s_nop 1
	v_or_b32_e32 v40, 32, v68
	v_ashrrev_i32_e32 v41, 31, v40
	v_lshlrev_b64 v[40:41], 12, v[40:41]
	v_lshl_add_u64 v[40:41], s[16:17], 0, v[40:41]
	v_lshl_add_u64 v[40:41], v[40:41], 0, v[0:1]
	global_load_dwordx4 v[42:45], v[40:41], off
	global_load_dwordx4 v[46:49], v[66:67], off
	s_waitcnt vmcnt(0) lgkmcnt(0)
	v_pk_fma_f32 v[18:19], v[18:19], v[46:47], v[42:43]
	v_pk_fma_f32 v[20:21], v[20:21], v[48:49], v[44:45]
	global_store_dwordx4 v[40:41], v[18:21], off
	global_load_dwordx4 v[18:21], v[40:41], off offset:32
	s_nop 0
	global_load_dwordx4 v[42:45], v[50:51], off
	s_waitcnt vmcnt(0) lgkmcnt(0)
	v_pk_fma_f32 v[18:19], v[22:23], v[42:43], v[18:19]
	v_pk_fma_f32 v[20:21], v[24:25], v[44:45], v[20:21]
	global_store_dwordx4 v[40:41], v[18:21], off offset:32
	global_load_dwordx4 v[18:21], v[40:41], off offset:64
	s_nop 0
	global_load_dwordx4 v[22:25], v[52:53], off
	s_waitcnt vmcnt(0) lgkmcnt(0)
	v_pk_fma_f32 v[18:19], v[26:27], v[22:23], v[18:19]
	v_pk_fma_f32 v[20:21], v[28:29], v[24:25], v[20:21]
	global_store_dwordx4 v[40:41], v[18:21], off offset:64
	global_load_dwordx4 v[18:21], v[40:41], off offset:96
	s_nop 0
	global_load_dwordx4 v[22:25], v[54:55], off
	s_waitcnt vmcnt(0) lgkmcnt(0)
	v_pk_fma_f32 v[18:19], v[30:31], v[22:23], v[18:19]
	v_pk_fma_f32 v[20:21], v[32:33], v[24:25], v[20:21]
	global_store_dwordx4 v[40:41], v[18:21], off offset:96
	global_load_dwordx4 v[18:21], v[40:41], off offset:128
	s_nop 0
	global_load_dwordx4 v[22:25], v[56:57], off
	s_waitcnt vmcnt(0) lgkmcnt(0)
	v_pk_fma_f32 v[2:3], v[2:3], v[22:23], v[18:19]
	v_pk_fma_f32 v[4:5], v[4:5], v[24:25], v[20:21]
	global_store_dwordx4 v[40:41], v[2:5], off offset:128
	global_load_dwordx4 v[2:5], v[40:41], off offset:160
	s_nop 0
	global_load_dwordx4 v[18:21], v[34:35], off
	s_waitcnt vmcnt(0) lgkmcnt(0)
	v_pk_fma_f32 v[2:3], v[6:7], v[18:19], v[2:3]
	v_pk_fma_f32 v[4:5], v[8:9], v[20:21], v[4:5]
	global_store_dwordx4 v[40:41], v[2:5], off offset:160
	global_load_dwordx4 v[2:5], v[40:41], off offset:192
	s_nop 0
	global_load_dwordx4 v[6:9], v[36:37], off
	s_waitcnt vmcnt(0) lgkmcnt(0)
	v_pk_fma_f32 v[2:3], v[10:11], v[6:7], v[2:3]
	v_pk_fma_f32 v[4:5], v[12:13], v[8:9], v[4:5]
	global_store_dwordx4 v[40:41], v[2:5], off offset:192
	global_load_dwordx4 v[2:5], v[40:41], off offset:224
	s_nop 0
	global_load_dwordx4 v[6:9], v[38:39], off
	s_waitcnt vmcnt(0) lgkmcnt(0)
	v_pk_fma_f32 v[2:3], v[14:15], v[6:7], v[2:3]
	v_pk_fma_f32 v[4:5], v[16:17], v[8:9], v[4:5]
	global_store_dwordx4 v[40:41], v[2:5], off offset:224

.LBB0_49:
	v_mov_b32_e32 v0, v228
	s_waitcnt lgkmcnt(0)
	s_barrier
	s_nop 0
	v_cmp_eq_u32_e32 vcc, 0, v0
	s_and_saveexec_b64 s[4:5], vcc
	s_cbranch_execz .LBB0_51
	v_mov_b64_e32 v[2:3], s[0:1]
	global_atomic_add v0, v[2:3], v229, off sc0
	v_mov_b32_e32 v2, s33
	s_waitcnt vmcnt(0) lgkmcnt(0)
	ds_write_b32 v2, v0

.LBB0_78:
	s_sext_i32_i16 s6, s6
	v_ashrrev_i32_e32 v0, 1, v211
	v_and_b32_e32 v0, 0xffffffc0, v0
	s_lshl_b32 s6, s6, 7
	v_add_u32_e32 v0, s8, v0
	s_waitcnt vmcnt(7)
	v_and_or_b32 v130, v211, 64, s6
	s_waitcnt vmcnt(6)
	v_and_or_b32 v134, v211, 31, v0
	v_ashrrev_i32_e32 v131, 31, v130
	v_lshrrev_b32_e32 v0, 1, v211
	v_lshl_add_u64 v[130:131], v[130:131], 1, s[0:1]
	v_and_b32_e32 v0, 16, v0
	v_lshl_add_u64 v[130:131], v[130:131], 0, v[0:1]
	v_mul_f32_e32 v0, 0xbfb8aa3b, v114
	v_exp_f32_e32 v136, v0
	v_mul_f32_e32 v0, 0xbfb8aa3b, v115
	v_exp_f32_e32 v137, v0
	s_movk_i32 s8, 0x1600
	v_mad_i64_i32 v[132:133], s[6:7], v134, s8, v[130:131]
	v_pk_add_f32 v[136:137], v[136:137], 1.0 op_sel_hi:[1,0]
	s_nop 0
	v_div_scale_f32 v0, s[6:7], v137, v137, v115
	v_rcp_f32_e32 v135, v0
	s_waitcnt vmcnt(5)
	v_fma_f32 v138, -v0, v135, 1.0
	v_fmac_f32_e32 v135, v138, v135
	v_div_scale_f32 v138, vcc, v115, v137, v115
	v_mul_f32_e32 v139, v138, v135
	v_fma_f32 v140, -v0, v139, v138
	v_fmac_f32_e32 v139, v140, v135
	v_fma_f32 v0, -v0, v139, v138
	v_div_fmas_f32 v0, v0, v135, v139
	v_div_fixup_f32 v115, v0, v137, v115
	v_div_scale_f32 v0, s[6:7], v136, v136, v114
	v_rcp_f32_e32 v135, v0
	s_nop 0
	v_fma_f32 v137, -v0, v135, 1.0
	v_fmac_f32_e32 v135, v137, v135
	v_div_scale_f32 v137, vcc, v114, v136, v114
	v_mul_f32_e32 v138, v137, v135
	v_fma_f32 v139, -v0, v138, v137
	v_fmac_f32_e32 v138, v139, v135
	v_fma_f32 v0, -v0, v138, v137
	v_div_fmas_f32 v0, v0, v135, v138
	v_div_fixup_f32 v114, v0, v136, v114
	v_mul_f32_e32 v0, 0xbfb8aa3b, v116
	v_pk_mul_f32 v[98:99], v[98:99], v[114:115]
	v_exp_f32_e32 v114, v0
	v_mul_f32_e32 v0, 0xbfb8aa3b, v117
	v_exp_f32_e32 v115, v0
	v_cvt_pk_bf16_f32 v98, v98, v99
	v_pk_add_f32 v[114:115], v[114:115], 1.0 op_sel_hi:[1,0]
	s_nop 0
	v_div_scale_f32 v0, s[6:7], v115, v115, v117
	v_rcp_f32_e32 v135, v0
	s_nop 0
	v_fma_f32 v136, -v0, v135, 1.0
	v_fmac_f32_e32 v135, v136, v135
	v_div_scale_f32 v136, vcc, v117, v115, v117
	v_mul_f32_e32 v137, v136, v135
	v_fma_f32 v138, -v0, v137, v136
	v_fmac_f32_e32 v137, v138, v135
	v_fma_f32 v0, -v0, v137, v136
	v_div_fmas_f32 v0, v0, v135, v137
	v_div_fixup_f32 v115, v0, v115, v117
	v_div_scale_f32 v0, s[6:7], v114, v114, v116
	v_rcp_f32_e32 v117, v0
	s_nop 0
	v_fma_f32 v135, -v0, v117, 1.0
	v_fmac_f32_e32 v117, v135, v117
	v_div_scale_f32 v135, vcc, v116, v114, v116
	v_mul_f32_e32 v136, v135, v117
	v_fma_f32 v137, -v0, v136, v135
	v_fmac_f32_e32 v136, v137, v117
	v_fma_f32 v0, -v0, v136, v135
	v_div_fmas_f32 v0, v0, v117, v136
	v_div_fixup_f32 v114, v0, v114, v116
	v_pk_mul_f32 v[100:101], v[100:101], v[114:115]
	v_mul_f32_e32 v0, 0xbfb8aa3b, v118
	v_cvt_pk_bf16_f32 v99, v100, v101
	v_exp_f32_e32 v100, v0
	v_mul_f32_e32 v0, 0xbfb8aa3b, v119
	v_exp_f32_e32 v101, v0
	s_nop 0
	v_pk_add_f32 v[100:101], v[100:101], 1.0 op_sel_hi:[1,0]
	s_nop 0
	v_div_scale_f32 v0, s[6:7], v101, v101, v119
	v_rcp_f32_e32 v114, v0
	s_nop 0
	v_fma_f32 v115, -v0, v114, 1.0
	v_fmac_f32_e32 v114, v115, v114
	v_div_scale_f32 v115, vcc, v119, v101, v119
	v_mul_f32_e32 v116, v115, v114
	v_fma_f32 v117, -v0, v116, v115
	v_fmac_f32_e32 v116, v117, v114
	v_fma_f32 v0, -v0, v116, v115
	v_div_fmas_f32 v0, v0, v114, v116
	v_div_fixup_f32 v101, v0, v101, v119
	v_div_scale_f32 v0, s[6:7], v100, v100, v118
	v_rcp_f32_e32 v114, v0
	s_nop 0
	v_fma_f32 v115, -v0, v114, 1.0
	v_fmac_f32_e32 v114, v115, v114
	v_div_scale_f32 v115, vcc, v118, v100, v118
	v_mul_f32_e32 v116, v115, v114
	v_fma_f32 v117, -v0, v116, v115
	v_fmac_f32_e32 v116, v117, v114
	v_fma_f32 v0, -v0, v116, v115
	v_div_fmas_f32 v0, v0, v114, v116
	v_div_fixup_f32 v100, v0, v100, v118
	v_mul_f32_e32 v0, 0xbfb8aa3b, v120
	v_pk_mul_f32 v[100:101], v[102:103], v[100:101]
	v_exp_f32_e32 v102, v0
	v_mul_f32_e32 v0, 0xbfb8aa3b, v121
	v_exp_f32_e32 v103, v0
	v_cvt_pk_bf16_f32 v100, v100, v101
	s_nop 1
	v_permlane32_swap_b32_e32 v98, v100
	v_pk_add_f32 v[102:103], v[102:103], 1.0 op_sel_hi:[1,0]
	s_nop 0
	v_div_scale_f32 v0, s[6:7], v103, v103, v121
	v_rcp_f32_e32 v114, v0
	s_nop 0
	v_fma_f32 v115, -v0, v114, 1.0
	v_fmac_f32_e32 v114, v115, v114
	v_div_scale_f32 v115, vcc, v121, v103, v121
	v_mul_f32_e32 v116, v115, v114
	v_fma_f32 v117, -v0, v116, v115
	v_fmac_f32_e32 v116, v117, v114
	v_fma_f32 v0, -v0, v116, v115
	v_div_fmas_f32 v0, v0, v114, v116
	v_div_fixup_f32 v103, v0, v103, v121
	v_div_scale_f32 v0, s[6:7], v102, v102, v120
	v_rcp_f32_e32 v114, v0
	s_nop 0
	v_fma_f32 v115, -v0, v114, 1.0
	v_fmac_f32_e32 v114, v115, v114
	v_div_scale_f32 v115, vcc, v120, v102, v120
	v_mul_f32_e32 v116, v115, v114
	v_fma_f32 v117, -v0, v116, v115
	v_fmac_f32_e32 v116, v117, v114
	v_fma_f32 v0, -v0, v116, v115
	v_div_fmas_f32 v0, v0, v114, v116
	v_div_fixup_f32 v102, v0, v102, v120
	v_pk_mul_f32 v[102:103], v[104:105], v[102:103]
	v_mul_f32_e32 v0, 0xbfb8aa3b, v122
	v_cvt_pk_bf16_f32 v101, v102, v103
	s_nop 1
	v_permlane32_swap_b32_e32 v99, v101
	global_store_dwordx4 v[132:133], v[98:101], off
	s_nop 1
	v_exp_f32_e32 v98, v0
	v_mul_f32_e32 v0, 0xbfb8aa3b, v123
	v_exp_f32_e32 v99, v0
	s_nop 0
	v_pk_add_f32 v[98:99], v[98:99], 1.0 op_sel_hi:[1,0]
	s_nop 0
	v_div_scale_f32 v0, s[6:7], v99, v99, v123
	v_rcp_f32_e32 v100, v0
	s_nop 0
	v_fma_f32 v101, -v0, v100, 1.0
	v_fmac_f32_e32 v100, v101, v100
	v_div_scale_f32 v101, vcc, v123, v99, v123
	v_mul_f32_e32 v102, v101, v100
	v_fma_f32 v103, -v0, v102, v101
	v_fmac_f32_e32 v102, v103, v100
	v_fma_f32 v0, -v0, v102, v101
	v_div_fmas_f32 v0, v0, v100, v102
	v_div_fixup_f32 v99, v0, v99, v123
	v_div_scale_f32 v0, s[6:7], v98, v98, v122
	v_rcp_f32_e32 v100, v0
	s_nop 0
	v_fma_f32 v101, -v0, v100, 1.0
	v_fmac_f32_e32 v100, v101, v100
	v_div_scale_f32 v101, vcc, v122, v98, v122
	v_mul_f32_e32 v102, v101, v100
	v_fma_f32 v103, -v0, v102, v101
	v_fmac_f32_e32 v102, v103, v100
	v_fma_f32 v0, -v0, v102, v101
	v_div_fmas_f32 v0, v0, v100, v102
	v_div_fixup_f32 v98, v0, v98, v122
	v_mul_f32_e32 v0, 0xbfb8aa3b, v124
	v_exp_f32_e32 v100, v0
	v_mul_f32_e32 v0, 0xbfb8aa3b, v125
	v_exp_f32_e32 v101, v0
	v_pk_mul_f32 v[98:99], v[106:107], v[98:99]
	v_pk_add_f32 v[100:101], v[100:101], 1.0 op_sel_hi:[1,0]
	s_nop 0
	v_div_scale_f32 v0, s[6:7], v101, v101, v125
	v_rcp_f32_e32 v102, v0
	v_cvt_pk_bf16_f32 v98, v98, v99
	v_fma_f32 v103, -v0, v102, 1.0
	v_fmac_f32_e32 v102, v103, v102
	v_div_scale_f32 v103, vcc, v125, v101, v125
	v_mul_f32_e32 v104, v103, v102
	v_fma_f32 v105, -v0, v104, v103
	v_fmac_f32_e32 v104, v105, v102
	v_fma_f32 v0, -v0, v104, v103
	v_div_fmas_f32 v0, v0, v102, v104
	v_div_fixup_f32 v101, v0, v101, v125
	v_div_scale_f32 v0, s[6:7], v100, v100, v124
	v_rcp_f32_e32 v102, v0
	s_nop 0
	v_fma_f32 v103, -v0, v102, 1.0
	v_fmac_f32_e32 v102, v103, v102
	v_div_scale_f32 v103, vcc, v124, v100, v124
	v_mul_f32_e32 v104, v103, v102
	v_fma_f32 v105, -v0, v104, v103
	v_fmac_f32_e32 v104, v105, v102
	v_fma_f32 v0, -v0, v104, v103
	v_div_fmas_f32 v0, v0, v102, v104
	v_div_fixup_f32 v100, v0, v100, v124
	v_pk_mul_f32 v[100:101], v[108:109], v[100:101]
	v_mul_f32_e32 v0, 0xbfb8aa3b, v126
	v_cvt_pk_bf16_f32 v99, v100, v101
	v_exp_f32_e32 v100, v0
	v_mul_f32_e32 v0, 0xbfb8aa3b, v127
	v_exp_f32_e32 v101, v0
	s_nop 0
	v_pk_add_f32 v[100:101], v[100:101], 1.0 op_sel_hi:[1,0]
	s_nop 0
	v_div_scale_f32 v0, s[6:7], v101, v101, v127
	v_rcp_f32_e32 v102, v0
	s_nop 0
	v_fma_f32 v103, -v0, v102, 1.0
	v_fmac_f32_e32 v102, v103, v102
	v_div_scale_f32 v103, vcc, v127, v101, v127
	v_mul_f32_e32 v104, v103, v102
	v_fma_f32 v105, -v0, v104, v103
	v_fmac_f32_e32 v104, v105, v102
	v_fma_f32 v0, -v0, v104, v103
	v_div_fmas_f32 v0, v0, v102, v104
	v_div_fixup_f32 v101, v0, v101, v127
	v_div_scale_f32 v0, s[6:7], v100, v100, v126
	v_rcp_f32_e32 v102, v0
	s_nop 0
	v_fma_f32 v103, -v0, v102, 1.0
	v_fmac_f32_e32 v102, v103, v102
	v_div_scale_f32 v103, vcc, v126, v100, v126
	v_mul_f32_e32 v104, v103, v102
	v_fma_f32 v105, -v0, v104, v103
	v_fmac_f32_e32 v104, v105, v102
	v_fma_f32 v0, -v0, v104, v103
	v_div_fmas_f32 v0, v0, v102, v104
	v_div_fixup_f32 v100, v0, v100, v126
	v_mul_f32_e32 v0, 0xbfb8aa3b, v128
	v_exp_f32_e32 v102, v0
	v_mul_f32_e32 v0, 0xbfb8aa3b, v129
	v_exp_f32_e32 v103, v0
	v_pk_mul_f32 v[100:101], v[110:111], v[100:101]
	v_pk_add_f32 v[102:103], v[102:103], 1.0 op_sel_hi:[1,0]
	s_nop 0
	v_div_scale_f32 v0, s[6:7], v103, v103, v129
	v_rcp_f32_e32 v104, v0
	v_cvt_pk_bf16_f32 v100, v100, v101
	s_nop 1
	v_permlane32_swap_b32_e32 v98, v100
	v_fma_f32 v105, -v0, v104, 1.0
	v_fmac_f32_e32 v104, v105, v104
	v_div_scale_f32 v105, vcc, v129, v103, v129
	v_mul_f32_e32 v106, v105, v104
	v_fma_f32 v107, -v0, v106, v105
	v_fmac_f32_e32 v106, v107, v104
	v_fma_f32 v0, -v0, v106, v105
	v_div_fmas_f32 v0, v0, v104, v106
	v_div_fixup_f32 v103, v0, v103, v129
	v_div_scale_f32 v0, s[6:7], v102, v102, v128
	v_rcp_f32_e32 v104, v0
	s_nop 0
	v_fma_f32 v105, -v0, v104, 1.0
	v_fmac_f32_e32 v104, v105, v104
	v_div_scale_f32 v105, vcc, v128, v102, v128
	v_mul_f32_e32 v106, v105, v104
	v_fma_f32 v107, -v0, v106, v105
	v_fmac_f32_e32 v106, v107, v104
	v_fma_f32 v0, -v0, v106, v105
	v_div_fmas_f32 v0, v0, v104, v106
	v_div_fixup_f32 v102, v0, v102, v128
	v_pk_mul_f32 v[102:103], v[112:113], v[102:103]
	v_mul_f32_e32 v0, 0xbfb8aa3b, v82
	v_cvt_pk_bf16_f32 v101, v102, v103
	s_nop 1
	v_permlane32_swap_b32_e32 v99, v101
	global_store_dwordx4 v[132:133], v[98:101], off offset:32
	s_nop 1
	v_exp_f32_e32 v98, v0
	v_mul_f32_e32 v0, 0xbfb8aa3b, v83
	v_exp_f32_e32 v99, v0
	s_nop 0
	v_pk_add_f32 v[98:99], v[98:99], 1.0 op_sel_hi:[1,0]
	s_nop 0
	v_div_scale_f32 v0, s[6:7], v99, v99, v83
	v_rcp_f32_e32 v100, v0
	s_nop 0
	v_fma_f32 v101, -v0, v100, 1.0
	v_fmac_f32_e32 v100, v101, v100
	v_div_scale_f32 v101, vcc, v83, v99, v83
	v_mul_f32_e32 v102, v101, v100
	v_fma_f32 v103, -v0, v102, v101
	v_fmac_f32_e32 v102, v103, v100
	v_fma_f32 v0, -v0, v102, v101
	v_div_fmas_f32 v0, v0, v100, v102
	v_div_fixup_f32 v83, v0, v99, v83
	v_div_scale_f32 v0, s[6:7], v98, v98, v82
	v_rcp_f32_e32 v99, v0
	s_nop 0
	v_fma_f32 v100, -v0, v99, 1.0
	v_fmac_f32_e32 v99, v100, v99
	v_div_scale_f32 v100, vcc, v82, v98, v82
	v_mul_f32_e32 v101, v100, v99
	v_fma_f32 v102, -v0, v101, v100
	v_fmac_f32_e32 v101, v102, v99
	v_fma_f32 v0, -v0, v101, v100
	v_div_fmas_f32 v0, v0, v99, v101
	v_div_fixup_f32 v82, v0, v98, v82
	v_mul_f32_e32 v0, 0xbfb8aa3b, v84
	v_pk_mul_f32 v[66:67], v[66:67], v[82:83]
	v_exp_f32_e32 v82, v0
	v_mul_f32_e32 v0, 0xbfb8aa3b, v85
	v_exp_f32_e32 v83, v0
	v_cvt_pk_bf16_f32 v66, v66, v67
	v_pk_add_f32 v[82:83], v[82:83], 1.0 op_sel_hi:[1,0]
	s_nop 0
	v_div_scale_f32 v0, s[6:7], v83, v83, v85
	v_rcp_f32_e32 v98, v0
	s_nop 0
	v_fma_f32 v99, -v0, v98, 1.0
	v_fmac_f32_e32 v98, v99, v98
	v_div_scale_f32 v99, vcc, v85, v83, v85
	v_mul_f32_e32 v100, v99, v98
	v_fma_f32 v101, -v0, v100, v99
	v_fmac_f32_e32 v100, v101, v98
	v_fma_f32 v0, -v0, v100, v99
	v_div_fmas_f32 v0, v0, v98, v100
	v_div_fixup_f32 v83, v0, v83, v85
	v_div_scale_f32 v0, s[6:7], v82, v82, v84
	v_rcp_f32_e32 v85, v0
	s_nop 0
	v_fma_f32 v98, -v0, v85, 1.0
	v_fmac_f32_e32 v85, v98, v85
	v_div_scale_f32 v98, vcc, v84, v82, v84
	v_mul_f32_e32 v99, v98, v85
	v_fma_f32 v100, -v0, v99, v98
	v_fmac_f32_e32 v99, v100, v85
	v_fma_f32 v0, -v0, v99, v98
	v_div_fmas_f32 v0, v0, v85, v99
	v_div_fixup_f32 v82, v0, v82, v84
	v_pk_mul_f32 v[68:69], v[68:69], v[82:83]
	v_mul_f32_e32 v0, 0xbfb8aa3b, v86
	v_cvt_pk_bf16_f32 v67, v68, v69
	v_exp_f32_e32 v68, v0
	v_mul_f32_e32 v0, 0xbfb8aa3b, v87
	v_exp_f32_e32 v69, v0
	s_nop 0
	v_pk_add_f32 v[68:69], v[68:69], 1.0 op_sel_hi:[1,0]
	s_nop 0
	v_div_scale_f32 v0, s[6:7], v69, v69, v87
	v_rcp_f32_e32 v82, v0
	s_nop 0
	v_fma_f32 v83, -v0, v82, 1.0
	v_fmac_f32_e32 v82, v83, v82
	v_div_scale_f32 v83, vcc, v87, v69, v87
	v_mul_f32_e32 v84, v83, v82
	v_fma_f32 v85, -v0, v84, v83
	v_fmac_f32_e32 v84, v85, v82
	v_fma_f32 v0, -v0, v84, v83
	v_div_fmas_f32 v0, v0, v82, v84
	v_div_fixup_f32 v69, v0, v69, v87
	v_div_scale_f32 v0, s[6:7], v68, v68, v86
	v_rcp_f32_e32 v82, v0
	s_nop 0
	v_fma_f32 v83, -v0, v82, 1.0
	v_fmac_f32_e32 v82, v83, v82
	v_div_scale_f32 v83, vcc, v86, v68, v86
	v_mul_f32_e32 v84, v83, v82
	v_fma_f32 v85, -v0, v84, v83
	v_fmac_f32_e32 v84, v85, v82
	v_fma_f32 v0, -v0, v84, v83
	v_div_fmas_f32 v0, v0, v82, v84
	v_div_fixup_f32 v68, v0, v68, v86
	v_mul_f32_e32 v0, 0xbfb8aa3b, v88
	v_pk_mul_f32 v[68:69], v[70:71], v[68:69]
	v_exp_f32_e32 v70, v0
	v_mul_f32_e32 v0, 0xbfb8aa3b, v89
	v_exp_f32_e32 v71, v0
	v_cvt_pk_bf16_f32 v68, v68, v69
	s_nop 1
	v_permlane32_swap_b32_e32 v66, v68
	v_pk_add_f32 v[70:71], v[70:71], 1.0 op_sel_hi:[1,0]
	s_nop 0
	v_div_scale_f32 v0, s[6:7], v71, v71, v89
	v_rcp_f32_e32 v82, v0
	s_nop 0
	v_fma_f32 v83, -v0, v82, 1.0
	v_fmac_f32_e32 v82, v83, v82
	v_div_scale_f32 v83, vcc, v89, v71, v89
	v_mul_f32_e32 v84, v83, v82
	v_fma_f32 v85, -v0, v84, v83
	v_fmac_f32_e32 v84, v85, v82
	v_fma_f32 v0, -v0, v84, v83
	v_div_fmas_f32 v0, v0, v82, v84
	v_div_fixup_f32 v71, v0, v71, v89
	v_div_scale_f32 v0, s[6:7], v70, v70, v88
	v_rcp_f32_e32 v82, v0
	s_nop 0
	v_fma_f32 v83, -v0, v82, 1.0
	v_fmac_f32_e32 v82, v83, v82
	v_div_scale_f32 v83, vcc, v88, v70, v88
	v_mul_f32_e32 v84, v83, v82
	v_fma_f32 v85, -v0, v84, v83
	v_fmac_f32_e32 v84, v85, v82
	v_fma_f32 v0, -v0, v84, v83
	v_div_fmas_f32 v0, v0, v82, v84
	v_div_fixup_f32 v70, v0, v70, v88
	v_pk_mul_f32 v[70:71], v[72:73], v[70:71]
	v_mul_f32_e32 v0, 0xbfb8aa3b, v90
	v_cvt_pk_bf16_f32 v69, v70, v71
	s_nop 1
	v_permlane32_swap_b32_e32 v67, v69
	global_store_dwordx4 v[132:133], v[66:69], off offset:64
	s_nop 1
	v_exp_f32_e32 v66, v0
	v_mul_f32_e32 v0, 0xbfb8aa3b, v91
	v_exp_f32_e32 v67, v0
	s_nop 0
	v_pk_add_f32 v[66:67], v[66:67], 1.0 op_sel_hi:[1,0]
	s_nop 0
	v_div_scale_f32 v0, s[6:7], v67, v67, v91
	v_rcp_f32_e32 v68, v0
	s_nop 0
	v_fma_f32 v69, -v0, v68, 1.0
	v_fmac_f32_e32 v68, v69, v68
	v_div_scale_f32 v69, vcc, v91, v67, v91
	v_mul_f32_e32 v70, v69, v68
	v_fma_f32 v71, -v0, v70, v69
	v_fmac_f32_e32 v70, v71, v68
	v_fma_f32 v0, -v0, v70, v69
	v_div_fmas_f32 v0, v0, v68, v70
	v_div_fixup_f32 v67, v0, v67, v91
	v_div_scale_f32 v0, s[6:7], v66, v66, v90
	v_rcp_f32_e32 v68, v0
	s_nop 0
	v_fma_f32 v69, -v0, v68, 1.0
	v_fmac_f32_e32 v68, v69, v68
	v_div_scale_f32 v69, vcc, v90, v66, v90
	v_mul_f32_e32 v70, v69, v68
	v_fma_f32 v71, -v0, v70, v69
	v_fmac_f32_e32 v70, v71, v68
	v_fma_f32 v0, -v0, v70, v69
	v_div_fmas_f32 v0, v0, v68, v70
	v_div_fixup_f32 v66, v0, v66, v90
	v_mul_f32_e32 v0, 0xbfb8aa3b, v92
	v_exp_f32_e32 v68, v0
	v_mul_f32_e32 v0, 0xbfb8aa3b, v93
	v_exp_f32_e32 v69, v0
	v_pk_mul_f32 v[66:67], v[74:75], v[66:67]
	v_pk_add_f32 v[68:69], v[68:69], 1.0 op_sel_hi:[1,0]
	s_nop 0
	v_div_scale_f32 v0, s[6:7], v69, v69, v93
	v_rcp_f32_e32 v70, v0
	v_cvt_pk_bf16_f32 v66, v66, v67
	v_fma_f32 v71, -v0, v70, 1.0
	v_fmac_f32_e32 v70, v71, v70
	v_div_scale_f32 v71, vcc, v93, v69, v93
	v_mul_f32_e32 v72, v71, v70
	v_fma_f32 v73, -v0, v72, v71
	v_fmac_f32_e32 v72, v73, v70
	v_fma_f32 v0, -v0, v72, v71
	v_div_fmas_f32 v0, v0, v70, v72
	v_div_fixup_f32 v69, v0, v69, v93
	v_div_scale_f32 v0, s[6:7], v68, v68, v92
	v_rcp_f32_e32 v70, v0
	s_nop 0
	v_fma_f32 v71, -v0, v70, 1.0
	v_fmac_f32_e32 v70, v71, v70
	v_div_scale_f32 v71, vcc, v92, v68, v92
	v_mul_f32_e32 v72, v71, v70
	v_fma_f32 v73, -v0, v72, v71
	v_fmac_f32_e32 v72, v73, v70
	v_fma_f32 v0, -v0, v72, v71
	v_div_fmas_f32 v0, v0, v70, v72
	v_div_fixup_f32 v68, v0, v68, v92
	v_pk_mul_f32 v[68:69], v[76:77], v[68:69]
	v_mul_f32_e32 v0, 0xbfb8aa3b, v94
	v_cvt_pk_bf16_f32 v67, v68, v69
	v_exp_f32_e32 v68, v0
	v_mul_f32_e32 v0, 0xbfb8aa3b, v95
	v_exp_f32_e32 v69, v0
	s_nop 0
	v_pk_add_f32 v[68:69], v[68:69], 1.0 op_sel_hi:[1,0]
	s_nop 0
	v_div_scale_f32 v0, s[6:7], v69, v69, v95
	v_rcp_f32_e32 v70, v0
	s_nop 0
	v_fma_f32 v71, -v0, v70, 1.0
	v_fmac_f32_e32 v70, v71, v70
	v_div_scale_f32 v71, vcc, v95, v69, v95
	v_mul_f32_e32 v72, v71, v70
	v_fma_f32 v73, -v0, v72, v71
	v_fmac_f32_e32 v72, v73, v70
	v_fma_f32 v0, -v0, v72, v71
	v_div_fmas_f32 v0, v0, v70, v72
	v_div_fixup_f32 v69, v0, v69, v95
	v_div_scale_f32 v0, s[6:7], v68, v68, v94
	v_rcp_f32_e32 v70, v0
	s_nop 0
	v_fma_f32 v71, -v0, v70, 1.0
	v_fmac_f32_e32 v70, v71, v70
	v_div_scale_f32 v71, vcc, v94, v68, v94
	v_mul_f32_e32 v72, v71, v70
	v_fma_f32 v73, -v0, v72, v71
	v_fmac_f32_e32 v72, v73, v70
	v_fma_f32 v0, -v0, v72, v71
	v_div_fmas_f32 v0, v0, v70, v72
	v_div_fixup_f32 v68, v0, v68, v94
	v_mul_f32_e32 v0, 0xbfb8aa3b, v96
	v_exp_f32_e32 v70, v0
	v_mul_f32_e32 v0, 0xbfb8aa3b, v97
	v_exp_f32_e32 v71, v0
	v_pk_mul_f32 v[68:69], v[78:79], v[68:69]
	v_pk_add_f32 v[70:71], v[70:71], 1.0 op_sel_hi:[1,0]
	s_nop 0
	v_div_scale_f32 v0, s[6:7], v71, v71, v97
	v_rcp_f32_e32 v72, v0
	v_cvt_pk_bf16_f32 v68, v68, v69
	s_nop 1
	v_permlane32_swap_b32_e32 v66, v68
	v_fma_f32 v73, -v0, v72, 1.0
	v_fmac_f32_e32 v72, v73, v72
	v_div_scale_f32 v73, vcc, v97, v71, v97
	v_mul_f32_e32 v74, v73, v72
	v_fma_f32 v75, -v0, v74, v73
	v_fmac_f32_e32 v74, v75, v72
	v_fma_f32 v0, -v0, v74, v73
	v_div_fmas_f32 v0, v0, v72, v74
	v_div_fixup_f32 v71, v0, v71, v97
	v_div_scale_f32 v0, s[6:7], v70, v70, v96
	v_rcp_f32_e32 v72, v0
	s_nop 0
	v_fma_f32 v73, -v0, v72, 1.0
	v_fmac_f32_e32 v72, v73, v72
	v_div_scale_f32 v73, vcc, v96, v70, v96
	v_mul_f32_e32 v74, v73, v72
	v_fma_f32 v75, -v0, v74, v73
	v_fmac_f32_e32 v74, v75, v72
	v_fma_f32 v0, -v0, v74, v73
	v_div_fmas_f32 v0, v0, v72, v74
	v_div_fixup_f32 v70, v0, v70, v96
	v_pk_mul_f32 v[70:71], v[80:81], v[70:71]
	v_or_b32_e32 v0, 32, v134
	v_cvt_pk_bf16_f32 v69, v70, v71
	s_nop 1
	v_permlane32_swap_b32_e32 v67, v69
	global_store_dwordx4 v[132:133], v[66:69], off offset:96
	s_nop 1
	v_mad_i64_i32 v[66:67], s[6:7], v0, s8, v[130:131]
	v_mul_f32_e32 v0, 0xbfb8aa3b, v50
	v_exp_f32_e32 v68, v0
	v_mul_f32_e32 v0, 0xbfb8aa3b, v51
	v_exp_f32_e32 v69, v0
	s_nop 0
	v_pk_add_f32 v[68:69], v[68:69], 1.0 op_sel_hi:[1,0]
	s_nop 0
	v_div_scale_f32 v0, s[6:7], v69, v69, v51
	v_rcp_f32_e32 v70, v0
	s_nop 0
	v_fma_f32 v71, -v0, v70, 1.0
	v_fmac_f32_e32 v70, v71, v70
	v_div_scale_f32 v71, vcc, v51, v69, v51
	v_mul_f32_e32 v72, v71, v70
	v_fma_f32 v73, -v0, v72, v71
	v_fmac_f32_e32 v72, v73, v70
	v_fma_f32 v0, -v0, v72, v71
	v_div_fmas_f32 v0, v0, v70, v72
	v_div_fixup_f32 v51, v0, v69, v51
	v_div_scale_f32 v0, s[6:7], v68, v68, v50
	v_rcp_f32_e32 v69, v0
	s_nop 0
	v_fma_f32 v70, -v0, v69, 1.0
	v_fmac_f32_e32 v69, v70, v69
	v_div_scale_f32 v70, vcc, v50, v68, v50
	v_mul_f32_e32 v71, v70, v69
	v_fma_f32 v72, -v0, v71, v70
	v_fmac_f32_e32 v71, v72, v69
	v_fma_f32 v0, -v0, v71, v70
	v_div_fmas_f32 v0, v0, v69, v71
	v_div_fixup_f32 v50, v0, v68, v50
	v_mul_f32_e32 v0, 0xbfb8aa3b, v52
	v_pk_mul_f32 v[34:35], v[34:35], v[50:51]
	v_exp_f32_e32 v50, v0
	v_mul_f32_e32 v0, 0xbfb8aa3b, v53
	v_exp_f32_e32 v51, v0
	v_cvt_pk_bf16_f32 v34, v34, v35
	v_pk_add_f32 v[50:51], v[50:51], 1.0 op_sel_hi:[1,0]
	s_nop 0
	v_div_scale_f32 v0, s[6:7], v51, v51, v53
	v_rcp_f32_e32 v68, v0
	s_nop 0
	v_fma_f32 v69, -v0, v68, 1.0
	v_fmac_f32_e32 v68, v69, v68
	v_div_scale_f32 v69, vcc, v53, v51, v53
	v_mul_f32_e32 v70, v69, v68
	v_fma_f32 v71, -v0, v70, v69
	v_fmac_f32_e32 v70, v71, v68
	v_fma_f32 v0, -v0, v70, v69
	v_div_fmas_f32 v0, v0, v68, v70
	v_div_fixup_f32 v51, v0, v51, v53
	v_div_scale_f32 v0, s[6:7], v50, v50, v52
	v_rcp_f32_e32 v53, v0
	s_nop 0
	v_fma_f32 v68, -v0, v53, 1.0
	v_fmac_f32_e32 v53, v68, v53
	v_div_scale_f32 v68, vcc, v52, v50, v52
	v_mul_f32_e32 v69, v68, v53
	v_fma_f32 v70, -v0, v69, v68
	v_fmac_f32_e32 v69, v70, v53
	v_fma_f32 v0, -v0, v69, v68
	v_div_fmas_f32 v0, v0, v53, v69
	v_div_fixup_f32 v50, v0, v50, v52
	v_pk_mul_f32 v[36:37], v[36:37], v[50:51]
	v_mul_f32_e32 v0, 0xbfb8aa3b, v54
	v_cvt_pk_bf16_f32 v35, v36, v37
	v_exp_f32_e32 v36, v0
	v_mul_f32_e32 v0, 0xbfb8aa3b, v55
	v_exp_f32_e32 v37, v0
	s_nop 0
	v_pk_add_f32 v[36:37], v[36:37], 1.0 op_sel_hi:[1,0]
	s_nop 0
	v_div_scale_f32 v0, s[6:7], v37, v37, v55
	v_rcp_f32_e32 v50, v0
	s_nop 0
	v_fma_f32 v51, -v0, v50, 1.0
	v_fmac_f32_e32 v50, v51, v50
	v_div_scale_f32 v51, vcc, v55, v37, v55
	v_mul_f32_e32 v52, v51, v50
	v_fma_f32 v53, -v0, v52, v51
	v_fmac_f32_e32 v52, v53, v50
	v_fma_f32 v0, -v0, v52, v51
	v_div_fmas_f32 v0, v0, v50, v52
	v_div_fixup_f32 v37, v0, v37, v55
	v_div_scale_f32 v0, s[6:7], v36, v36, v54
	v_rcp_f32_e32 v50, v0
	s_nop 0
	v_fma_f32 v51, -v0, v50, 1.0
	v_fmac_f32_e32 v50, v51, v50
	v_div_scale_f32 v51, vcc, v54, v36, v54
	v_mul_f32_e32 v52, v51, v50
	v_fma_f32 v53, -v0, v52, v51
	v_fmac_f32_e32 v52, v53, v50
	v_fma_f32 v0, -v0, v52, v51
	v_div_fmas_f32 v0, v0, v50, v52
	v_div_fixup_f32 v36, v0, v36, v54
	v_mul_f32_e32 v0, 0xbfb8aa3b, v56
	v_pk_mul_f32 v[36:37], v[38:39], v[36:37]
	v_exp_f32_e32 v38, v0
	v_mul_f32_e32 v0, 0xbfb8aa3b, v57
	v_exp_f32_e32 v39, v0
	v_cvt_pk_bf16_f32 v36, v36, v37
	s_nop 1
	v_permlane32_swap_b32_e32 v34, v36
	v_pk_add_f32 v[38:39], v[38:39], 1.0 op_sel_hi:[1,0]
	s_nop 0
	v_div_scale_f32 v0, s[6:7], v39, v39, v57
	v_rcp_f32_e32 v50, v0
	s_nop 0
	v_fma_f32 v51, -v0, v50, 1.0
	v_fmac_f32_e32 v50, v51, v50
	v_div_scale_f32 v51, vcc, v57, v39, v57
	v_mul_f32_e32 v52, v51, v50
	v_fma_f32 v53, -v0, v52, v51
	v_fmac_f32_e32 v52, v53, v50
	v_fma_f32 v0, -v0, v52, v51
	v_div_fmas_f32 v0, v0, v50, v52
	v_div_fixup_f32 v39, v0, v39, v57
	v_div_scale_f32 v0, s[6:7], v38, v38, v56
	v_rcp_f32_e32 v50, v0
	s_nop 0
	v_fma_f32 v51, -v0, v50, 1.0
	v_fmac_f32_e32 v50, v51, v50
	v_div_scale_f32 v51, vcc, v56, v38, v56
	v_mul_f32_e32 v52, v51, v50
	v_fma_f32 v53, -v0, v52, v51
	v_fmac_f32_e32 v52, v53, v50
	v_fma_f32 v0, -v0, v52, v51
	v_div_fmas_f32 v0, v0, v50, v52
	v_div_fixup_f32 v38, v0, v38, v56
	v_pk_mul_f32 v[38:39], v[40:41], v[38:39]
	v_mul_f32_e32 v0, 0xbfb8aa3b, v58
	v_cvt_pk_bf16_f32 v37, v38, v39
	s_nop 1
	v_permlane32_swap_b32_e32 v35, v37
	global_store_dwordx4 v[66:67], v[34:37], off
	s_nop 1
	v_exp_f32_e32 v34, v0
	v_mul_f32_e32 v0, 0xbfb8aa3b, v59
	v_exp_f32_e32 v35, v0
	s_nop 0
	v_pk_add_f32 v[34:35], v[34:35], 1.0 op_sel_hi:[1,0]
	s_nop 0
	v_div_scale_f32 v0, s[6:7], v35, v35, v59
	v_rcp_f32_e32 v36, v0
	s_nop 0
	v_fma_f32 v37, -v0, v36, 1.0
	v_fmac_f32_e32 v36, v37, v36
	v_div_scale_f32 v37, vcc, v59, v35, v59
	v_mul_f32_e32 v38, v37, v36
	v_fma_f32 v39, -v0, v38, v37
	v_fmac_f32_e32 v38, v39, v36
	v_fma_f32 v0, -v0, v38, v37
	v_div_fmas_f32 v0, v0, v36, v38
	v_div_fixup_f32 v35, v0, v35, v59
	v_div_scale_f32 v0, s[6:7], v34, v34, v58
	v_rcp_f32_e32 v36, v0
	s_nop 0
	v_fma_f32 v37, -v0, v36, 1.0
	v_fmac_f32_e32 v36, v37, v36
	v_div_scale_f32 v37, vcc, v58, v34, v58
	v_mul_f32_e32 v38, v37, v36
	v_fma_f32 v39, -v0, v38, v37
	v_fmac_f32_e32 v38, v39, v36
	v_fma_f32 v0, -v0, v38, v37
	v_div_fmas_f32 v0, v0, v36, v38
	v_div_fixup_f32 v34, v0, v34, v58
	v_mul_f32_e32 v0, 0xbfb8aa3b, v60
	v_exp_f32_e32 v36, v0
	v_mul_f32_e32 v0, 0xbfb8aa3b, v61
	v_exp_f32_e32 v37, v0
	v_pk_mul_f32 v[34:35], v[42:43], v[34:35]
	v_pk_add_f32 v[36:37], v[36:37], 1.0 op_sel_hi:[1,0]
	s_nop 0
	v_div_scale_f32 v0, s[6:7], v37, v37, v61
	v_rcp_f32_e32 v38, v0
	v_cvt_pk_bf16_f32 v34, v34, v35
	v_fma_f32 v39, -v0, v38, 1.0
	v_fmac_f32_e32 v38, v39, v38
	v_div_scale_f32 v39, vcc, v61, v37, v61
	v_mul_f32_e32 v40, v39, v38
	v_fma_f32 v41, -v0, v40, v39
	v_fmac_f32_e32 v40, v41, v38
	v_fma_f32 v0, -v0, v40, v39
	v_div_fmas_f32 v0, v0, v38, v40
	v_div_fixup_f32 v37, v0, v37, v61
	v_div_scale_f32 v0, s[6:7], v36, v36, v60
	v_rcp_f32_e32 v38, v0
	s_nop 0
	v_fma_f32 v39, -v0, v38, 1.0
	v_fmac_f32_e32 v38, v39, v38
	v_div_scale_f32 v39, vcc, v60, v36, v60
	v_mul_f32_e32 v40, v39, v38
	v_fma_f32 v41, -v0, v40, v39
	v_fmac_f32_e32 v40, v41, v38
	v_fma_f32 v0, -v0, v40, v39
	v_div_fmas_f32 v0, v0, v38, v40
	v_div_fixup_f32 v36, v0, v36, v60
	v_pk_mul_f32 v[36:37], v[44:45], v[36:37]
	v_mul_f32_e32 v0, 0xbfb8aa3b, v62
	v_cvt_pk_bf16_f32 v35, v36, v37
	v_exp_f32_e32 v36, v0
	v_mul_f32_e32 v0, 0xbfb8aa3b, v63
	v_exp_f32_e32 v37, v0
	s_nop 0
	v_pk_add_f32 v[36:37], v[36:37], 1.0 op_sel_hi:[1,0]
	s_nop 0
	v_div_scale_f32 v0, s[6:7], v37, v37, v63
	v_rcp_f32_e32 v38, v0
	s_nop 0
	v_fma_f32 v39, -v0, v38, 1.0
	v_fmac_f32_e32 v38, v39, v38
	v_div_scale_f32 v39, vcc, v63, v37, v63
	v_mul_f32_e32 v40, v39, v38
	v_fma_f32 v41, -v0, v40, v39
	v_fmac_f32_e32 v40, v41, v38
	v_fma_f32 v0, -v0, v40, v39
	v_div_fmas_f32 v0, v0, v38, v40
	v_div_fixup_f32 v37, v0, v37, v63
	v_div_scale_f32 v0, s[6:7], v36, v36, v62
	v_rcp_f32_e32 v38, v0
	s_nop 0
	v_fma_f32 v39, -v0, v38, 1.0
	v_fmac_f32_e32 v38, v39, v38
	v_div_scale_f32 v39, vcc, v62, v36, v62
	v_mul_f32_e32 v40, v39, v38
	v_fma_f32 v41, -v0, v40, v39
	v_fmac_f32_e32 v40, v41, v38
	v_fma_f32 v0, -v0, v40, v39
	v_div_fmas_f32 v0, v0, v38, v40
	v_div_fixup_f32 v36, v0, v36, v62
	v_mul_f32_e32 v0, 0xbfb8aa3b, v64
	v_exp_f32_e32 v38, v0
	v_mul_f32_e32 v0, 0xbfb8aa3b, v65
	v_exp_f32_e32 v39, v0
	v_pk_mul_f32 v[36:37], v[46:47], v[36:37]
	v_pk_add_f32 v[38:39], v[38:39], 1.0 op_sel_hi:[1,0]
	s_nop 0
	v_div_scale_f32 v0, s[6:7], v39, v39, v65
	v_rcp_f32_e32 v40, v0
	v_cvt_pk_bf16_f32 v36, v36, v37
	s_nop 1
	v_permlane32_swap_b32_e32 v34, v36
	v_fma_f32 v41, -v0, v40, 1.0
	v_fmac_f32_e32 v40, v41, v40
	v_div_scale_f32 v41, vcc, v65, v39, v65
	v_mul_f32_e32 v42, v41, v40
	v_fma_f32 v43, -v0, v42, v41
	v_fmac_f32_e32 v42, v43, v40
	v_fma_f32 v0, -v0, v42, v41
	v_div_fmas_f32 v0, v0, v40, v42
	v_div_fixup_f32 v39, v0, v39, v65
	v_div_scale_f32 v0, s[6:7], v38, v38, v64
	v_rcp_f32_e32 v40, v0
	s_nop 0
	v_fma_f32 v41, -v0, v40, 1.0
	v_fmac_f32_e32 v40, v41, v40
	v_div_scale_f32 v41, vcc, v64, v38, v64
	v_mul_f32_e32 v42, v41, v40
	v_fma_f32 v43, -v0, v42, v41
	v_fmac_f32_e32 v42, v43, v40
	v_fma_f32 v0, -v0, v42, v41
	v_div_fmas_f32 v0, v0, v40, v42
	v_div_fixup_f32 v38, v0, v38, v64
	v_pk_mul_f32 v[38:39], v[48:49], v[38:39]
	v_mul_f32_e32 v0, 0xbfb8aa3b, v18
	v_cvt_pk_bf16_f32 v37, v38, v39
	s_nop 1
	v_permlane32_swap_b32_e32 v35, v37
	global_store_dwordx4 v[66:67], v[34:37], off offset:32
	s_nop 1
	v_exp_f32_e32 v34, v0
	v_mul_f32_e32 v0, 0xbfb8aa3b, v19
	v_exp_f32_e32 v35, v0
	s_nop 0
	v_pk_add_f32 v[34:35], v[34:35], 1.0 op_sel_hi:[1,0]
	s_nop 0
	v_div_scale_f32 v0, s[6:7], v35, v35, v19
	v_rcp_f32_e32 v36, v0
	s_nop 0
	v_fma_f32 v37, -v0, v36, 1.0
	v_fmac_f32_e32 v36, v37, v36
	v_div_scale_f32 v37, vcc, v19, v35, v19
	v_mul_f32_e32 v38, v37, v36
	v_fma_f32 v39, -v0, v38, v37
	v_fmac_f32_e32 v38, v39, v36
	v_fma_f32 v0, -v0, v38, v37
	v_div_fmas_f32 v0, v0, v36, v38
	v_div_fixup_f32 v19, v0, v35, v19
	v_div_scale_f32 v0, s[6:7], v34, v34, v18
	v_rcp_f32_e32 v35, v0
	s_nop 0
	v_fma_f32 v36, -v0, v35, 1.0
	v_fmac_f32_e32 v35, v36, v35
	v_div_scale_f32 v36, vcc, v18, v34, v18
	v_mul_f32_e32 v37, v36, v35
	v_fma_f32 v38, -v0, v37, v36
	v_fmac_f32_e32 v37, v38, v35
	v_fma_f32 v0, -v0, v37, v36
	v_div_fmas_f32 v0, v0, v35, v37
	v_div_fixup_f32 v18, v0, v34, v18
	v_mul_f32_e32 v0, 0xbfb8aa3b, v20
	v_pk_mul_f32 v[2:3], v[2:3], v[18:19]
	v_exp_f32_e32 v18, v0
	v_mul_f32_e32 v0, 0xbfb8aa3b, v21
	v_exp_f32_e32 v19, v0
	v_cvt_pk_bf16_f32 v2, v2, v3
	v_pk_add_f32 v[18:19], v[18:19], 1.0 op_sel_hi:[1,0]
	s_nop 0
	v_div_scale_f32 v0, s[6:7], v19, v19, v21
	v_rcp_f32_e32 v34, v0
	s_nop 0
	v_fma_f32 v35, -v0, v34, 1.0
	v_fmac_f32_e32 v34, v35, v34
	v_div_scale_f32 v35, vcc, v21, v19, v21
	v_mul_f32_e32 v36, v35, v34
	v_fma_f32 v37, -v0, v36, v35
	v_fmac_f32_e32 v36, v37, v34
	v_fma_f32 v0, -v0, v36, v35
	v_div_fmas_f32 v0, v0, v34, v36
	v_div_fixup_f32 v19, v0, v19, v21
	v_div_scale_f32 v0, s[6:7], v18, v18, v20
	v_rcp_f32_e32 v21, v0
	s_nop 0
	v_fma_f32 v34, -v0, v21, 1.0
	v_fmac_f32_e32 v21, v34, v21
	v_div_scale_f32 v34, vcc, v20, v18, v20
	v_mul_f32_e32 v35, v34, v21
	v_fma_f32 v36, -v0, v35, v34
	v_fmac_f32_e32 v35, v36, v21
	v_fma_f32 v0, -v0, v35, v34
	v_div_fmas_f32 v0, v0, v21, v35
	v_div_fixup_f32 v18, v0, v18, v20
	v_pk_mul_f32 v[4:5], v[4:5], v[18:19]
	v_mul_f32_e32 v0, 0xbfb8aa3b, v22
	v_cvt_pk_bf16_f32 v3, v4, v5
	v_exp_f32_e32 v4, v0
	v_mul_f32_e32 v0, 0xbfb8aa3b, v23
	v_exp_f32_e32 v5, v0
	s_nop 0
	v_pk_add_f32 v[4:5], v[4:5], 1.0 op_sel_hi:[1,0]
	s_nop 0
	v_div_scale_f32 v0, s[6:7], v5, v5, v23
	v_rcp_f32_e32 v18, v0
	s_nop 0
	v_fma_f32 v19, -v0, v18, 1.0
	v_fmac_f32_e32 v18, v19, v18
	v_div_scale_f32 v19, vcc, v23, v5, v23
	v_mul_f32_e32 v20, v19, v18
	v_fma_f32 v21, -v0, v20, v19
	v_fmac_f32_e32 v20, v21, v18
	v_fma_f32 v0, -v0, v20, v19
	v_div_fmas_f32 v0, v0, v18, v20
	v_div_fixup_f32 v5, v0, v5, v23
	v_div_scale_f32 v0, s[6:7], v4, v4, v22
	v_rcp_f32_e32 v18, v0
	s_nop 0
	v_fma_f32 v19, -v0, v18, 1.0
	v_fmac_f32_e32 v18, v19, v18
	v_div_scale_f32 v19, vcc, v22, v4, v22
	v_mul_f32_e32 v20, v19, v18
	v_fma_f32 v21, -v0, v20, v19
	v_fmac_f32_e32 v20, v21, v18
	v_fma_f32 v0, -v0, v20, v19
	v_div_fmas_f32 v0, v0, v18, v20
	v_div_fixup_f32 v4, v0, v4, v22
	v_mul_f32_e32 v0, 0xbfb8aa3b, v24
	v_pk_mul_f32 v[4:5], v[6:7], v[4:5]
	v_exp_f32_e32 v6, v0
	v_mul_f32_e32 v0, 0xbfb8aa3b, v25
	v_exp_f32_e32 v7, v0
	v_cvt_pk_bf16_f32 v4, v4, v5
	s_nop 1
	v_permlane32_swap_b32_e32 v2, v4
	v_pk_add_f32 v[6:7], v[6:7], 1.0 op_sel_hi:[1,0]
	s_nop 0
	v_div_scale_f32 v0, s[6:7], v7, v7, v25
	v_rcp_f32_e32 v18, v0
	s_nop 0
	v_fma_f32 v19, -v0, v18, 1.0
	v_fmac_f32_e32 v18, v19, v18
	v_div_scale_f32 v19, vcc, v25, v7, v25
	v_mul_f32_e32 v20, v19, v18
	v_fma_f32 v21, -v0, v20, v19
	v_fmac_f32_e32 v20, v21, v18
	v_fma_f32 v0, -v0, v20, v19
	v_div_fmas_f32 v0, v0, v18, v20
	v_div_fixup_f32 v7, v0, v7, v25
	v_div_scale_f32 v0, s[6:7], v6, v6, v24
	v_rcp_f32_e32 v18, v0
	s_nop 0
	v_fma_f32 v19, -v0, v18, 1.0
	v_fmac_f32_e32 v18, v19, v18
	v_div_scale_f32 v19, vcc, v24, v6, v24
	v_mul_f32_e32 v20, v19, v18
	v_fma_f32 v21, -v0, v20, v19
	v_fmac_f32_e32 v20, v21, v18
	v_fma_f32 v0, -v0, v20, v19
	v_div_fmas_f32 v0, v0, v18, v20
	v_div_fixup_f32 v6, v0, v6, v24
	v_pk_mul_f32 v[6:7], v[8:9], v[6:7]
	v_mul_f32_e32 v0, 0xbfb8aa3b, v26
	v_cvt_pk_bf16_f32 v5, v6, v7
	s_nop 1
	v_permlane32_swap_b32_e32 v3, v5
	global_store_dwordx4 v[66:67], v[2:5], off offset:64
	s_nop 1
	v_exp_f32_e32 v2, v0
	v_mul_f32_e32 v0, 0xbfb8aa3b, v27
	v_exp_f32_e32 v3, v0
	s_nop 0
	v_pk_add_f32 v[2:3], v[2:3], 1.0 op_sel_hi:[1,0]
	s_nop 0
	v_div_scale_f32 v0, s[6:7], v3, v3, v27
	v_rcp_f32_e32 v4, v0
	s_nop 0
	v_fma_f32 v5, -v0, v4, 1.0
	v_fmac_f32_e32 v4, v5, v4
	v_div_scale_f32 v5, vcc, v27, v3, v27
	v_mul_f32_e32 v6, v5, v4
	v_fma_f32 v7, -v0, v6, v5
	v_fmac_f32_e32 v6, v7, v4
	v_fma_f32 v0, -v0, v6, v5
	v_div_fmas_f32 v0, v0, v4, v6
	v_div_fixup_f32 v3, v0, v3, v27
	v_div_scale_f32 v0, s[6:7], v2, v2, v26
	v_rcp_f32_e32 v4, v0
	s_nop 0
	v_fma_f32 v5, -v0, v4, 1.0
	v_fmac_f32_e32 v4, v5, v4
	v_div_scale_f32 v5, vcc, v26, v2, v26
	v_mul_f32_e32 v6, v5, v4
	v_fma_f32 v7, -v0, v6, v5
	v_fmac_f32_e32 v6, v7, v4
	v_fma_f32 v0, -v0, v6, v5
	v_div_fmas_f32 v0, v0, v4, v6
	v_div_fixup_f32 v2, v0, v2, v26
	v_mul_f32_e32 v0, 0xbfb8aa3b, v28
	v_exp_f32_e32 v4, v0
	v_mul_f32_e32 v0, 0xbfb8aa3b, v29
	v_exp_f32_e32 v5, v0
	v_pk_mul_f32 v[2:3], v[10:11], v[2:3]
	v_pk_add_f32 v[4:5], v[4:5], 1.0 op_sel_hi:[1,0]
	s_nop 0
	v_div_scale_f32 v0, s[6:7], v5, v5, v29
	v_rcp_f32_e32 v6, v0
	v_cvt_pk_bf16_f32 v2, v2, v3
	v_fma_f32 v7, -v0, v6, 1.0
	v_fmac_f32_e32 v6, v7, v6
	v_div_scale_f32 v7, vcc, v29, v5, v29
	v_mul_f32_e32 v8, v7, v6
	v_fma_f32 v9, -v0, v8, v7
	v_fmac_f32_e32 v8, v9, v6
	v_fma_f32 v0, -v0, v8, v7
	v_div_fmas_f32 v0, v0, v6, v8
	v_div_fixup_f32 v5, v0, v5, v29
	v_div_scale_f32 v0, s[6:7], v4, v4, v28
	v_rcp_f32_e32 v6, v0
	s_nop 0
	v_fma_f32 v7, -v0, v6, 1.0
	v_fmac_f32_e32 v6, v7, v6
	v_div_scale_f32 v7, vcc, v28, v4, v28
	v_mul_f32_e32 v8, v7, v6
	v_fma_f32 v9, -v0, v8, v7
	v_fmac_f32_e32 v8, v9, v6
	v_fma_f32 v0, -v0, v8, v7
	v_div_fmas_f32 v0, v0, v6, v8
	v_div_fixup_f32 v4, v0, v4, v28
	v_pk_mul_f32 v[4:5], v[12:13], v[4:5]
	v_mul_f32_e32 v0, 0xbfb8aa3b, v30
	v_cvt_pk_bf16_f32 v3, v4, v5
	v_exp_f32_e32 v4, v0
	v_mul_f32_e32 v0, 0xbfb8aa3b, v31
	v_exp_f32_e32 v5, v0
	s_nop 0
	v_pk_add_f32 v[4:5], v[4:5], 1.0 op_sel_hi:[1,0]
	s_nop 0
	v_div_scale_f32 v0, s[6:7], v5, v5, v31
	v_rcp_f32_e32 v6, v0
	s_nop 0
	v_fma_f32 v7, -v0, v6, 1.0
	v_fmac_f32_e32 v6, v7, v6
	v_div_scale_f32 v7, vcc, v31, v5, v31
	v_mul_f32_e32 v8, v7, v6
	v_fma_f32 v9, -v0, v8, v7
	v_fmac_f32_e32 v8, v9, v6
	v_fma_f32 v0, -v0, v8, v7
	v_div_fmas_f32 v0, v0, v6, v8
	v_div_fixup_f32 v5, v0, v5, v31
	v_div_scale_f32 v0, s[6:7], v4, v4, v30
	v_rcp_f32_e32 v6, v0
	s_nop 0
	v_fma_f32 v7, -v0, v6, 1.0
	v_fmac_f32_e32 v6, v7, v6
	v_div_scale_f32 v7, vcc, v30, v4, v30
	v_mul_f32_e32 v8, v7, v6
	v_fma_f32 v9, -v0, v8, v7
	v_fmac_f32_e32 v8, v9, v6
	v_fma_f32 v0, -v0, v8, v7
	v_div_fmas_f32 v0, v0, v6, v8
	v_div_fixup_f32 v4, v0, v4, v30
	v_mul_f32_e32 v0, 0xbfb8aa3b, v32
	v_exp_f32_e32 v6, v0
	v_mul_f32_e32 v0, 0xbfb8aa3b, v33
	v_exp_f32_e32 v7, v0
	v_pk_mul_f32 v[4:5], v[14:15], v[4:5]
	v_pk_add_f32 v[6:7], v[6:7], 1.0 op_sel_hi:[1,0]
	s_nop 0
	v_div_scale_f32 v0, s[6:7], v7, v7, v33
	v_rcp_f32_e32 v8, v0
	v_cvt_pk_bf16_f32 v4, v4, v5
	s_nop 1
	v_permlane32_swap_b32_e32 v2, v4
	v_fma_f32 v9, -v0, v8, 1.0
	v_fmac_f32_e32 v8, v9, v8
	v_div_scale_f32 v9, vcc, v33, v7, v33
	v_mul_f32_e32 v10, v9, v8
	v_fma_f32 v11, -v0, v10, v9
	v_fmac_f32_e32 v10, v11, v8
	v_fma_f32 v0, -v0, v10, v9
	v_div_fmas_f32 v0, v0, v8, v10
	v_div_fixup_f32 v7, v0, v7, v33
	v_div_scale_f32 v0, s[6:7], v6, v6, v32
	v_rcp_f32_e32 v8, v0
	s_mov_b64 s[6:7], 0
	v_fma_f32 v9, -v0, v8, 1.0
	v_fmac_f32_e32 v8, v9, v8
	v_div_scale_f32 v9, vcc, v32, v6, v32
	v_mul_f32_e32 v10, v9, v8
	v_fma_f32 v11, -v0, v10, v9
	v_fmac_f32_e32 v10, v11, v8
	v_fma_f32 v0, -v0, v10, v9
	v_div_fmas_f32 v0, v0, v8, v10
	v_div_fixup_f32 v6, v0, v6, v32
	v_pk_mul_f32 v[6:7], v[16:17], v[6:7]
	s_nop 0
	v_cvt_pk_bf16_f32 v5, v6, v7
	s_nop 1
	v_permlane32_swap_b32_e32 v3, v5
	global_store_dwordx4 v[66:67], v[2:5], off offset:96

.LBB0_80:
	v_mov_b32_e32 v0, v228
	s_waitcnt lgkmcnt(0)
	s_barrier
	s_nop 0
	v_cmp_eq_u32_e32 vcc, 0, v0
	s_and_saveexec_b64 s[6:7], vcc
	s_cbranch_execz .LBB0_82
	v_mov_b64_e32 v[2:3], s[4:5]
	global_atomic_add v0, v[2:3], v229, off sc0
	v_mov_b32_e32 v2, s33
	s_waitcnt vmcnt(0) lgkmcnt(0)
	ds_write_b32 v2, v0

.LBB0_97:
	s_or_b64 exec, exec, s[16:17]
	v_pk_mul_f32 v[66:67], v[30:31], v[30:31]
	v_pk_mul_f32 v[68:69], v[26:27], v[26:27]
	v_pk_mul_f32 v[62:63], v[32:33], v[32:33]
	v_pk_mul_f32 v[64:65], v[28:29], v[28:29]
	v_mov_b32_e32 v70, v66
	v_mov_b32_e32 v71, v68
	v_mov_b32_e32 v68, v67
	v_pk_add_f32 v[66:67], v[70:71], v[68:69]
	v_mov_b32_e32 v68, v62
	v_mov_b32_e32 v69, v64
	v_pk_mul_f32 v[58:59], v[2:3], v[2:3]
	v_pk_mul_f32 v[60:61], v[10:11], v[10:11]
	v_pk_add_f32 v[66:67], v[68:69], v[66:67]
	v_mov_b32_e32 v64, v63
	v_pk_mul_f32 v[48:49], v[4:5], v[4:5]
	v_pk_mul_f32 v[50:51], v[12:13], v[12:13]
	v_pk_add_f32 v[62:63], v[64:65], v[66:67]
	v_mov_b32_e32 v64, v58
	v_mov_b32_e32 v65, v60
	v_mov_b32_e32 v60, v59
	v_pk_add_f32 v[58:59], v[64:65], v[60:61]
	v_mov_b32_e32 v60, v48
	v_mov_b32_e32 v61, v50
	s_and_b64 s[0:1], exec, vcc
	v_add_u32_e32 v41, 0xfffff000, v46
	v_pk_add_f32 v[58:59], v[60:61], v[58:59]
	v_mov_b32_e32 v50, v49
	s_or_b64 s[14:15], s[0:1], s[14:15]
	v_lshrrev_b32_e32 v41, 12, v41
	s_movk_i32 s0, 0xfff
	v_pk_add_f32 v[48:49], v[50:51], v[58:59]
	v_add_f32_e32 v43, v62, v63
	v_add_u32_e32 v41, 1, v41
	v_cmp_lt_i32_e32 vcc, s0, v46
	v_add_f32_e32 v43, v49, v43
	v_add_f32_e32 v43, v48, v43
	v_cndmask_b32_e32 v41, 0, v41, vcc
	v_mov_b64_e32 v[48:49], s[8:9]
	v_mad_u64_u32 v[48:49], s[0:1], v41, s89, v[48:49]
	s_mov_b64 s[0:1], 0x1000
	s_nop 0
	v_lshl_add_u64 v[50:51], v[48:49], 0, s[0:1]
	v_lshl_add_u64 v[66:67], v[50:51], 0, v[0:1]
	v_lshl_add_u64 v[48:49], v[48:49], 0, v[0:1]
	global_load_dwordx4 v[58:61], v[34:35], off
	global_load_dwordx4 v[62:65], v[48:49], off
	s_nop 0
	global_load_dwordx4 v[66:69], v[66:67], off
	ds_bpermute_b32 v41, v52, v43
	v_mov_b32_e32 v45, v1
	v_lshl_add_u64 v[38:39], v[38:39], 0, s[12:13]
	s_waitcnt lgkmcnt(0)
	v_add_f32_e32 v41, v43, v41
	ds_bpermute_b32 v43, v53, v41
	s_waitcnt lgkmcnt(0)
	v_add_f32_e32 v41, v41, v43
	ds_bpermute_b32 v43, v54, v41
	s_waitcnt lgkmcnt(0)
	v_add_f32_e32 v41, v41, v43
	ds_bpermute_b32 v43, v55, v41
	s_waitcnt lgkmcnt(0)
	v_add_f32_e32 v41, v41, v43
	ds_bpermute_b32 v43, v56, v41
	s_waitcnt lgkmcnt(0)
	v_add_f32_e32 v41, v41, v43
	ds_bpermute_b32 v43, v57, v41
	s_waitcnt lgkmcnt(0)
	v_add_f32_e32 v41, v41, v43
	v_fmamk_f32 v41, v41, 0x3a800000, v230
	v_cmp_gt_f32_e32 vcc, s95, v41
	v_mul_f32_e32 v43, 0x4b800000, v41
	s_nop 0
	v_cndmask_b32_e32 v41, v41, v43, vcc
	v_rsq_f32_e32 v41, v41
	s_nop 0
	v_mul_f32_e32 v43, 0x45800000, v41
	v_cndmask_b32_e32 v46, v41, v43, vcc
	v_pk_mul_f32 v[30:31], v[30:31], v[46:47] op_sel_hi:[1,0]
	v_pk_mul_f32 v[32:33], v[32:33], v[46:47] op_sel_hi:[1,0]
	v_mov_b32_e32 v41, v1
	v_pk_mul_f32 v[26:27], v[26:27], v[46:47] op_sel_hi:[1,0]
	v_pk_mul_f32 v[28:29], v[28:29], v[46:47] op_sel_hi:[1,0]
	v_mov_b32_e32 v43, v1
	v_pk_mul_f32 v[10:11], v[10:11], v[46:47] op_sel_hi:[1,0]
	v_pk_mul_f32 v[12:13], v[12:13], v[46:47] op_sel_hi:[1,0]
	v_pk_mul_f32 v[2:3], v[2:3], v[46:47] op_sel_hi:[1,0]
	v_pk_mul_f32 v[4:5], v[4:5], v[46:47] op_sel_hi:[1,0]
	v_mov_b32_e32 v46, v47
	s_waitcnt vmcnt(0)
	v_pk_mul_f32 v[30:31], v[58:59], v[30:31]
	v_pk_mul_f32 v[32:33], v[60:61], v[32:33]
	v_pk_add_f32 v[58:59], v[66:67], 1.0 op_sel_hi:[1,0]
	s_nop 0
	v_pk_fma_f32 v[30:31], v[58:59], v[30:31], v[62:63]
	v_pk_add_f32 v[58:59], v[68:69], 1.0 op_sel_hi:[1,0]
	v_cvt_pk_bf16_f32 v30, v30, v31
	v_pk_fma_f32 v[32:33], v[32:33], v[58:59], v[64:65]
	v_lshl_add_u64 v[62:63], v[50:51], 0, v[40:41]
	v_cvt_pk_bf16_f32 v31, v32, v33
	global_store_dwordx2 v[36:37], v[30:31], off
	global_load_dwordx4 v[30:33], v[34:35], off offset:1024
	s_nop 0
	global_load_dwordx4 v[58:61], v[48:49], off offset:1024
	s_nop 0
	global_load_dwordx4 v[62:65], v[62:63], off
	s_waitcnt vmcnt(0)
	v_pk_mul_f32 v[26:27], v[26:27], v[30:31]
	v_pk_mul_f32 v[28:29], v[28:29], v[32:33]
	s_waitcnt lgkmcnt(0)
	v_pk_add_f32 v[30:31], v[62:63], 1.0 op_sel_hi:[1,0]
	s_nop 0
	v_pk_fma_f32 v[26:27], v[26:27], v[30:31], v[58:59]
	v_pk_add_f32 v[30:31], v[64:65], 1.0 op_sel_hi:[1,0]
	v_cvt_pk_bf16_f32 v26, v26, v27
	v_pk_fma_f32 v[28:29], v[28:29], v[30:31], v[60:61]
	v_lshl_add_u64 v[58:59], v[50:51], 0, v[42:43]
	v_cvt_pk_bf16_f32 v27, v28, v29
	global_store_dwordx2 v[36:37], v[26:27], off offset:512
	global_load_dwordx4 v[26:29], v[34:35], off offset:2048
	s_nop 0
	global_load_dwordx4 v[30:33], v[48:49], off offset:2048
	s_nop 0
	global_load_dwordx4 v[58:61], v[58:59], off
	s_waitcnt vmcnt(0)
	v_pk_mul_f32 v[10:11], v[10:11], v[26:27]
	v_pk_mul_f32 v[12:13], v[12:13], v[28:29]
	s_waitcnt lgkmcnt(0)
	v_pk_add_f32 v[26:27], v[58:59], 1.0 op_sel_hi:[1,0]
	s_nop 0
	v_pk_fma_f32 v[10:11], v[10:11], v[26:27], v[30:31]
	v_pk_add_f32 v[26:27], v[60:61], 1.0 op_sel_hi:[1,0]
	v_cvt_pk_bf16_f32 v10, v10, v11
	v_pk_fma_f32 v[12:13], v[12:13], v[26:27], v[32:33]
	v_lshl_add_u64 v[30:31], v[50:51], 0, v[44:45]
	v_cvt_pk_bf16_f32 v11, v12, v13
	global_store_dwordx2 v[36:37], v[10:11], off offset:1024
	global_load_dwordx4 v[10:13], v[34:35], off offset:3072
	s_nop 0
	global_load_dwordx4 v[26:29], v[48:49], off offset:3072
	s_nop 0
	global_load_dwordx4 v[30:33], v[30:31], off
	s_waitcnt vmcnt(0)
	v_pk_mul_f32 v[2:3], v[2:3], v[10:11]
	v_pk_mul_f32 v[4:5], v[4:5], v[12:13]
	s_waitcnt lgkmcnt(0)
	v_pk_add_f32 v[10:11], v[30:31], 1.0 op_sel_hi:[1,0]
	v_mov_b32_e32 v30, v14
	v_pk_fma_f32 v[2:3], v[2:3], v[10:11], v[26:27]
	v_pk_add_f32 v[10:11], v[32:33], 1.0 op_sel_hi:[1,0]
	v_cvt_pk_bf16_f32 v2, v2, v3
	v_pk_fma_f32 v[4:5], v[4:5], v[10:11], v[28:29]
	v_mov_b32_e32 v31, v15
	v_cvt_pk_bf16_f32 v3, v4, v5
	global_store_dwordx2 v[36:37], v[2:3], off offset:1536
	v_lshl_add_u64 v[36:37], v[36:37], 0, s[10:11]
	v_mov_b32_e32 v32, v16
	v_mov_b32_e32 v33, v17
	v_mov_b32_e32 v26, v18
	v_mov_b32_e32 v27, v19
	v_mov_b32_e32 v28, v20
	v_mov_b32_e32 v29, v21
	v_mov_b32_e32 v10, v22
	v_mov_b32_e32 v11, v23
	v_mov_b32_e32 v12, v24
	v_mov_b32_e32 v13, v25
	v_mov_b32_e32 v2, v6
	v_mov_b32_e32 v3, v7
	v_mov_b32_e32 v4, v8
	v_mov_b32_e32 v5, v9
	s_andn2_b64 exec, exec, s[14:15]
	s_cbranch_execz .LBB0_100

.LBB0_108:
	s_add_i32 s7, s6, 0xfffff000
	s_waitcnt vmcnt(5)
	v_ashrrev_i32_e32 v66, 1, v134
	s_lshr_b32 s7, s7, 12
	v_and_b32_e32 v66, 0xffffffc0, v66
	s_add_i32 s7, s7, 1
	v_add_u32_e32 v66, s6, v66
	v_readlane_b32 s44, v253, 35
	s_cmp_gt_i32 s20, 15
	v_and_or_b32 v66, v134, 31, v66
	v_lshrrev_b32_e32 v67, 3, v134
	s_movk_i32 s6, 0x1000
	v_readlane_b32 s45, v253, 36
	v_readlane_b32 s46, v253, 37
	v_readlane_b32 s47, v253, 38
	v_readlane_b32 s20, v254, 21
	v_and_b32_e32 v0, 64, v134
	s_cselect_b32 s7, s7, 0
	v_readlane_b32 s8, v254, 23
	v_and_b32_e32 v67, 4, v67
	v_cmp_gt_i32_e32 vcc, s6, v66
	s_waitcnt vmcnt(1)
	v_mov_b32_e32 v82, s46
	v_mov_b32_e32 v83, s44
	v_mov_b32_e32 v84, s47
	v_mov_b32_e32 v85, s45
	v_readlane_b32 s21, v254, 22
	s_add_u32 s7, s2, s7
	s_mul_hi_i32 s8, s8, 9
	v_or3_b32 v0, v0, v67, s19
	v_cndmask_b32_e32 v67, v82, v83, vcc
	v_cndmask_b32_e32 v68, v84, v85, vcc
	s_waitcnt vmcnt(0)
	v_mov_b32_e32 v86, s21
	v_mov_b32_e32 v87, s20
	v_readlane_b32 s9, v254, 24
	s_addc_u32 s8, s8, 0
	v_cndmask_b32_e64 v69, v86, v68, s[0:1]
	v_cndmask_b32_e64 v68, v87, v67, s[0:1]
	v_add_u32_e32 v67, 0xfffff000, v66
	s_mulk_i32 s8, 0x6000
	s_mul_hi_u32 s9, s7, 0x6000
	v_cndmask_b32_e32 v67, v67, v66, vcc
	s_add_i32 s9, s9, s8
	s_mulk_i32 s7, 0x6000
	v_cndmask_b32_e64 v70, v66, v67, s[0:1]
	s_add_u32 s7, s78, s7
	v_ashrrev_i32_e32 v71, 31, v70
	s_addc_u32 s9, s79, s9
	v_lshlrev_b64 v[70:71], 12, v[70:71]
	s_add_u32 s8, s7, 0x1d482000
	v_lshl_add_u64 v[68:69], v[68:69], 0, v[70:71]
	v_lshlrev_b32_e32 v0, 2, v0
	s_addc_u32 s9, s9, 0
	v_lshl_add_u64 v[72:73], v[68:69], 0, v[0:1]
	v_lshl_add_u64 v[68:69], s[8:9], 0, v[0:1]
	global_load_dwordx4 v[74:77], v[72:73], off
	global_load_dwordx4 v[78:81], v[68:69], off
	v_ashrrev_i32_e32 v67, 31, v66
	v_lshlrev_b64 v[70:71], 12, v[66:67]
	v_lshl_add_u64 v[70:71], s[20:21], 0, v[70:71]
	v_lshl_add_u64 v[70:71], v[70:71], 0, v[0:1]
	v_readlane_b32 s48, v253, 39
	v_readlane_b32 s49, v253, 40
	v_readlane_b32 s50, v253, 41
	v_readlane_b32 s51, v253, 42
	v_readlane_b32 s52, v253, 43
	v_readlane_b32 s53, v253, 44
	v_readlane_b32 s54, v253, 45
	v_readlane_b32 s55, v253, 46
	v_readlane_b32 s56, v253, 47
	v_readlane_b32 s57, v253, 48
	v_readlane_b32 s58, v253, 49
	v_readlane_b32 s59, v253, 50
	s_waitcnt vmcnt(0) lgkmcnt(0)
	v_pk_fma_f32 v[50:51], v[50:51], v[78:79], v[74:75]
	v_pk_fma_f32 v[52:53], v[52:53], v[80:81], v[76:77]
	global_store_dwordx4 v[70:71], v[50:53], off
	s_nop 1
	v_or_b32_e32 v50, 32, v0
	v_mov_b32_e32 v51, v1
	v_lshl_add_u64 v[50:51], s[8:9], 0, v[50:51]
	global_load_dwordx4 v[74:77], v[72:73], off offset:32
	global_load_dwordx4 v[78:81], v[50:51], off
	s_waitcnt vmcnt(0) lgkmcnt(0)
	v_pk_fma_f32 v[52:53], v[54:55], v[78:79], v[74:75]
	v_pk_fma_f32 v[54:55], v[56:57], v[80:81], v[76:77]
	global_store_dwordx4 v[70:71], v[52:55], off offset:32
	s_nop 1
	v_or_b32_e32 v52, 64, v0
	v_mov_b32_e32 v53, v1
	v_lshl_add_u64 v[52:53], s[8:9], 0, v[52:53]
	global_load_dwordx4 v[54:57], v[72:73], off offset:64
	global_load_dwordx4 v[74:77], v[52:53], off
	s_waitcnt vmcnt(0) lgkmcnt(0)
	v_pk_fma_f32 v[54:55], v[58:59], v[74:75], v[54:55]
	v_pk_fma_f32 v[56:57], v[60:61], v[76:77], v[56:57]
	global_store_dwordx4 v[70:71], v[54:57], off offset:64
	s_nop 1
	v_or_b32_e32 v54, 0x60, v0
	v_mov_b32_e32 v55, v1
	v_lshl_add_u64 v[54:55], s[8:9], 0, v[54:55]
	global_load_dwordx4 v[56:59], v[72:73], off offset:96
	global_load_dwordx4 v[74:77], v[54:55], off
	s_waitcnt vmcnt(0) lgkmcnt(0)
	v_pk_fma_f32 v[56:57], v[62:63], v[74:75], v[56:57]
	v_pk_fma_f32 v[58:59], v[64:65], v[76:77], v[58:59]
	global_store_dwordx4 v[70:71], v[56:59], off offset:96
	s_nop 1
	v_or_b32_e32 v56, 0x80, v0
	v_mov_b32_e32 v57, v1
	v_lshl_add_u64 v[56:57], s[8:9], 0, v[56:57]
	global_load_dwordx4 v[58:61], v[72:73], off offset:128
	global_load_dwordx4 v[62:65], v[56:57], off
	s_waitcnt vmcnt(0) lgkmcnt(0)
	v_pk_fma_f32 v[34:35], v[34:35], v[62:63], v[58:59]
	v_pk_fma_f32 v[36:37], v[36:37], v[64:65], v[60:61]
	global_store_dwordx4 v[70:71], v[34:37], off offset:128
	s_nop 1
	v_or_b32_e32 v34, 0xa0, v0
	v_mov_b32_e32 v35, v1
	v_lshl_add_u64 v[34:35], s[8:9], 0, v[34:35]
	global_load_dwordx4 v[58:61], v[72:73], off offset:160
	global_load_dwordx4 v[62:65], v[34:35], off
	s_waitcnt vmcnt(0) lgkmcnt(0)
	v_pk_fma_f32 v[36:37], v[38:39], v[62:63], v[58:59]
	v_pk_fma_f32 v[38:39], v[40:41], v[64:65], v[60:61]
	global_store_dwordx4 v[70:71], v[36:39], off offset:160
	s_nop 1
	v_or_b32_e32 v36, 0xc0, v0
	v_mov_b32_e32 v37, v1
	v_lshl_add_u64 v[36:37], s[8:9], 0, v[36:37]
	global_load_dwordx4 v[38:41], v[72:73], off offset:192
	global_load_dwordx4 v[58:61], v[36:37], off
	s_waitcnt vmcnt(0) lgkmcnt(0)
	v_pk_fma_f32 v[38:39], v[42:43], v[58:59], v[38:39]
	v_pk_fma_f32 v[40:41], v[44:45], v[60:61], v[40:41]
	global_store_dwordx4 v[70:71], v[38:41], off offset:192
	s_nop 1
	v_or_b32_e32 v38, 0xe0, v0
	v_mov_b32_e32 v39, v1
	v_lshl_add_u64 v[38:39], s[8:9], 0, v[38:39]
	global_load_dwordx4 v[40:43], v[72:73], off offset:224
	global_load_dwordx4 v[58:61], v[38:39], off
	s_waitcnt vmcnt(0) lgkmcnt(0)
	v_pk_fma_f32 v[40:41], v[46:47], v[58:59], v[40:41]
	v_pk_fma_f32 v[42:43], v[48:49], v[60:61], v[42:43]
	global_store_dwordx4 v[70:71], v[40:43], off offset:224
	s_nop 1
	v_or_b32_e32 v40, 32, v66
	v_cmp_gt_i32_e32 vcc, s6, v40
	s_mov_b64 s[6:7], 0
	s_nop 0
	v_cndmask_b32_e32 v41, v82, v83, vcc
	v_cndmask_b32_e32 v42, v84, v85, vcc
	v_cndmask_b32_e64 v43, v86, v42, s[0:1]
	v_cndmask_b32_e64 v42, v87, v41, s[0:1]
	v_add_u32_e32 v41, 0xfffff020, v66
	v_cndmask_b32_e32 v41, v41, v40, vcc
	v_cndmask_b32_e64 v44, v40, v41, s[0:1]
	v_ashrrev_i32_e32 v45, 31, v44
	v_lshlrev_b64 v[44:45], 12, v[44:45]
	v_ashrrev_i32_e32 v41, 31, v40
	v_lshl_add_u64 v[42:43], v[42:43], 0, v[44:45]
	v_lshlrev_b64 v[40:41], 12, v[40:41]
	v_lshl_add_u64 v[40:41], s[20:21], 0, v[40:41]
	v_lshl_add_u64 v[48:49], v[42:43], 0, v[0:1]
	v_lshl_add_u64 v[58:59], v[40:41], 0, v[0:1]
	global_load_dwordx4 v[40:43], v[48:49], off
	global_load_dwordx4 v[44:47], v[68:69], off
	s_waitcnt vmcnt(0) lgkmcnt(0)
	v_pk_fma_f32 v[18:19], v[18:19], v[44:45], v[40:41]
	v_pk_fma_f32 v[20:21], v[20:21], v[46:47], v[42:43]
	global_store_dwordx4 v[58:59], v[18:21], off
	global_load_dwordx4 v[18:21], v[48:49], off offset:32
	s_nop 0
	global_load_dwordx4 v[40:43], v[50:51], off
	s_waitcnt vmcnt(0) lgkmcnt(0)
	v_pk_fma_f32 v[18:19], v[22:23], v[40:41], v[18:19]
	v_pk_fma_f32 v[20:21], v[24:25], v[42:43], v[20:21]
	global_store_dwordx4 v[58:59], v[18:21], off offset:32
	global_load_dwordx4 v[18:21], v[48:49], off offset:64
	s_nop 0
	global_load_dwordx4 v[22:25], v[52:53], off
	s_waitcnt vmcnt(0) lgkmcnt(0)
	v_pk_fma_f32 v[18:19], v[26:27], v[22:23], v[18:19]
	v_pk_fma_f32 v[20:21], v[28:29], v[24:25], v[20:21]
	global_store_dwordx4 v[58:59], v[18:21], off offset:64
	global_load_dwordx4 v[18:21], v[48:49], off offset:96
	s_nop 0
	global_load_dwordx4 v[22:25], v[54:55], off
	s_waitcnt vmcnt(0) lgkmcnt(0)
	v_pk_fma_f32 v[18:19], v[30:31], v[22:23], v[18:19]
	v_pk_fma_f32 v[20:21], v[32:33], v[24:25], v[20:21]
	global_store_dwordx4 v[58:59], v[18:21], off offset:96
	global_load_dwordx4 v[18:21], v[48:49], off offset:128
	s_nop 0
	global_load_dwordx4 v[22:25], v[56:57], off
	s_waitcnt vmcnt(0) lgkmcnt(0)
	v_pk_fma_f32 v[2:3], v[2:3], v[22:23], v[18:19]
	v_pk_fma_f32 v[4:5], v[4:5], v[24:25], v[20:21]
	global_store_dwordx4 v[58:59], v[2:5], off offset:128
	global_load_dwordx4 v[2:5], v[48:49], off offset:160
	s_nop 0
	global_load_dwordx4 v[18:21], v[34:35], off
	s_waitcnt vmcnt(0) lgkmcnt(0)
	v_pk_fma_f32 v[2:3], v[6:7], v[18:19], v[2:3]
	v_pk_fma_f32 v[4:5], v[8:9], v[20:21], v[4:5]
	global_store_dwordx4 v[58:59], v[2:5], off offset:160
	global_load_dwordx4 v[2:5], v[48:49], off offset:192
	s_nop 0
	global_load_dwordx4 v[6:9], v[36:37], off
	s_waitcnt vmcnt(0) lgkmcnt(0)
	v_pk_fma_f32 v[2:3], v[10:11], v[6:7], v[2:3]
	v_pk_fma_f32 v[4:5], v[12:13], v[8:9], v[4:5]
	global_store_dwordx4 v[58:59], v[2:5], off offset:192
	global_load_dwordx4 v[2:5], v[48:49], off offset:224
	s_nop 0
	global_load_dwordx4 v[6:9], v[38:39], off
	s_waitcnt vmcnt(0) lgkmcnt(0)
	v_pk_fma_f32 v[2:3], v[14:15], v[6:7], v[2:3]
	v_pk_fma_f32 v[4:5], v[16:17], v[8:9], v[4:5]
	global_store_dwordx4 v[58:59], v[2:5], off offset:224

.LBB0_128:
	v_ashrrev_i32_e32 v2, 1, v227
	s_lshl_b32 s0, s22, 8
	v_and_b32_e32 v0, 64, v227
	v_and_b32_e32 v2, 0xffffffc0, v2
	s_add_u32 s0, s15, s0
	v_add_u32_e32 v2, s6, v2
	s_addc_u32 s1, s16, 0
	v_lshlrev_b32_e32 v0, 1, v0
	v_and_or_b32 v2, v227, 31, v2
	v_lshl_add_u64 v[4:5], s[0:1], 0, v[0:1]
	v_lshrrev_b32_e32 v0, 1, v227
	v_and_b32_e32 v0, 16, v0
	v_ashrrev_i32_e32 v3, 31, v2
	v_lshl_add_u64 v[4:5], v[4:5], 0, v[0:1]
	v_lshlrev_b64 v[6:7], 11, v[2:3]
	v_permlane32_swap_b32_e32 v144, v247
	v_permlane32_swap_b32_e32 v145, v248
	v_lshl_add_u64 v[6:7], v[4:5], 0, v[6:7]
	v_mov_b32_e32 v146, v247
	v_mov_b32_e32 v147, v248
	v_permlane32_swap_b32_e32 v142, v245
	v_permlane32_swap_b32_e32 v143, v246
	global_store_dwordx4 v[6:7], v[144:147], off
	v_permlane32_swap_b32_e32 v140, v225
	s_nop 0
	v_mov_b32_e32 v144, v245
	v_mov_b32_e32 v145, v246
	v_permlane32_swap_b32_e32 v141, v226
	v_or_b32_e32 v2, 32, v2
	global_store_dwordx4 v[6:7], v[142:145], off offset:32
	v_permlane32_swap_b32_e32 v138, v223
	s_nop 0
	v_mov_b32_e32 v142, v225
	v_mov_b32_e32 v143, v226
	v_permlane32_swap_b32_e32 v139, v224
	v_ashrrev_i32_e32 v3, 31, v2
	global_store_dwordx4 v[6:7], v[140:143], off offset:64
	v_lshlrev_b64 v[2:3], 11, v[2:3]
	v_permlane32_swap_b32_e32 v136, v221
	v_mov_b32_e32 v140, v223
	v_mov_b32_e32 v141, v224
	v_permlane32_swap_b32_e32 v137, v222
	global_store_dwordx4 v[6:7], v[138:141], off offset:96
	v_lshl_add_u64 v[2:3], v[4:5], 0, v[2:3]
	v_permlane32_swap_b32_e32 v134, v219
	v_mov_b32_e32 v138, v221
	v_mov_b32_e32 v139, v222
	v_permlane32_swap_b32_e32 v135, v220
	global_store_dwordx4 v[2:3], v[136:139], off
	v_permlane32_swap_b32_e32 v132, v217
	s_nop 0
	v_mov_b32_e32 v136, v219
	v_mov_b32_e32 v137, v220
	v_permlane32_swap_b32_e32 v133, v218
	global_store_dwordx4 v[2:3], v[134:137], off offset:32
	v_permlane32_swap_b32_e32 v130, v211
	s_nop 0
	v_mov_b32_e32 v134, v217
	v_mov_b32_e32 v135, v218
	v_permlane32_swap_b32_e32 v131, v216
	global_store_dwordx4 v[2:3], v[132:135], off offset:64
	s_mov_b64 s[0:1], 0
	s_nop 0
	v_mov_b32_e32 v132, v211
	v_mov_b32_e32 v133, v216
	global_store_dwordx4 v[2:3], v[130:133], off offset:96

.LBB0_130:
	v_mov_b32_e32 v0, v228
	s_waitcnt lgkmcnt(0)
	s_barrier
	s_nop 0
	v_cmp_eq_u32_e32 vcc, 0, v0
	s_and_saveexec_b64 s[0:1], vcc
	s_cbranch_execz .LBB0_132
	v_mov_b64_e32 v[2:3], s[4:5]
	global_atomic_add v0, v[2:3], v229, off sc0
	v_mov_b32_e32 v2, s33
	s_waitcnt vmcnt(0) lgkmcnt(0)
	ds_write_b32 v2, v0

.LBB0_163:
	s_or_b64 exec, exec, s[16:17]
	v_pk_mul_f32 v[66:67], v[30:31], v[30:31]
	v_pk_mul_f32 v[68:69], v[26:27], v[26:27]
	v_pk_mul_f32 v[62:63], v[32:33], v[32:33]
	v_pk_mul_f32 v[64:65], v[28:29], v[28:29]
	v_mov_b32_e32 v70, v66
	v_mov_b32_e32 v71, v68
	v_mov_b32_e32 v68, v67
	v_pk_add_f32 v[66:67], v[70:71], v[68:69]
	v_mov_b32_e32 v68, v62
	v_mov_b32_e32 v69, v64
	v_pk_mul_f32 v[58:59], v[2:3], v[2:3]
	v_pk_mul_f32 v[60:61], v[10:11], v[10:11]
	v_pk_add_f32 v[66:67], v[68:69], v[66:67]
	v_mov_b32_e32 v64, v63
	v_pk_mul_f32 v[48:49], v[4:5], v[4:5]
	v_pk_mul_f32 v[50:51], v[12:13], v[12:13]
	v_pk_add_f32 v[62:63], v[64:65], v[66:67]
	v_mov_b32_e32 v64, v58
	v_mov_b32_e32 v65, v60
	v_mov_b32_e32 v60, v59
	v_pk_add_f32 v[58:59], v[64:65], v[60:61]
	v_mov_b32_e32 v60, v48
	v_mov_b32_e32 v61, v50
	s_and_b64 s[0:1], exec, s[0:1]
	v_add_u32_e32 v41, 0xfffff000, v46
	v_pk_add_f32 v[58:59], v[60:61], v[58:59]
	v_mov_b32_e32 v50, v49
	s_or_b64 s[14:15], s[0:1], s[14:15]
	v_lshrrev_b32_e32 v41, 12, v41
	s_movk_i32 s0, 0xfff
	v_pk_add_f32 v[48:49], v[50:51], v[58:59]
	v_add_f32_e32 v43, v62, v63
	v_add_u32_e32 v41, 1, v41
	v_cmp_lt_i32_e64 s[0:1], s0, v46
	v_add_f32_e32 v43, v49, v43
	v_add_f32_e32 v43, v48, v43
	v_cndmask_b32_e64 v41, 0, v41, s[0:1]
	v_mov_b64_e32 v[48:49], s[10:11]
	v_mad_u64_u32 v[48:49], s[0:1], v41, s89, v[48:49]
	ds_bpermute_b32 v41, v35, v43
	v_mov_b32_e32 v45, v1
	s_waitcnt lgkmcnt(0)
	v_add_f32_e32 v41, v43, v41
	ds_bpermute_b32 v43, v52, v41
	s_waitcnt lgkmcnt(0)
	v_add_f32_e32 v41, v41, v43
	ds_bpermute_b32 v43, v53, v41
	s_waitcnt lgkmcnt(0)
	v_add_f32_e32 v41, v41, v43
	ds_bpermute_b32 v43, v54, v41
	s_waitcnt lgkmcnt(0)
	v_add_f32_e32 v41, v41, v43
	ds_bpermute_b32 v43, v55, v41
	s_waitcnt lgkmcnt(0)
	v_add_f32_e32 v41, v41, v43
	ds_bpermute_b32 v43, v56, v41
	s_waitcnt lgkmcnt(0)
	v_add_f32_e32 v41, v41, v43
	v_fmamk_f32 v41, v41, 0x3a800000, v230
	v_cmp_gt_f32_e64 s[0:1], s95, v41
	v_mul_f32_e32 v43, 0x4b800000, v41
	s_nop 0
	v_cndmask_b32_e64 v41, v41, v43, s[0:1]
	v_rsq_f32_e32 v41, v41
	s_nop 0
	v_mul_f32_e32 v43, 0x45800000, v41
	v_cndmask_b32_e64 v46, v41, v43, s[0:1]
	s_mov_b64 s[0:1], 0x1000
	v_lshl_add_u64 v[50:51], v[48:49], 0, s[0:1]
	v_lshl_add_u64 v[66:67], v[50:51], 0, v[0:1]
	v_lshl_add_u64 v[48:49], v[48:49], 0, v[0:1]
	global_load_dwordx4 v[58:61], v[36:37], off
	global_load_dwordx4 v[62:65], v[48:49], off
	s_nop 0
	global_load_dwordx4 v[66:69], v[66:67], off
	v_pk_mul_f32 v[30:31], v[30:31], v[46:47] op_sel_hi:[1,0]
	v_pk_mul_f32 v[32:33], v[32:33], v[46:47] op_sel_hi:[1,0]
	v_mov_b32_e32 v41, v1
	v_pk_mul_f32 v[26:27], v[26:27], v[46:47] op_sel_hi:[1,0]
	v_pk_mul_f32 v[28:29], v[28:29], v[46:47] op_sel_hi:[1,0]
	v_mov_b32_e32 v43, v1
	v_pk_mul_f32 v[10:11], v[10:11], v[46:47] op_sel_hi:[1,0]
	v_pk_mul_f32 v[12:13], v[12:13], v[46:47] op_sel_hi:[1,0]
	v_pk_mul_f32 v[2:3], v[2:3], v[46:47] op_sel_hi:[1,0]
	v_pk_mul_f32 v[4:5], v[4:5], v[46:47] op_sel_hi:[1,0]
	v_mov_b32_e32 v46, v47
	s_waitcnt vmcnt(0)
	v_pk_mul_f32 v[30:31], v[58:59], v[30:31]
	v_pk_mul_f32 v[32:33], v[60:61], v[32:33]
	s_waitcnt lgkmcnt(0)
	v_pk_add_f32 v[58:59], v[66:67], 1.0 op_sel_hi:[1,0]
	s_nop 0
	v_pk_fma_f32 v[30:31], v[58:59], v[30:31], v[62:63]
	v_pk_add_f32 v[58:59], v[68:69], 1.0 op_sel_hi:[1,0]
	v_cvt_pk_bf16_f32 v30, v30, v31
	v_pk_fma_f32 v[32:33], v[32:33], v[58:59], v[64:65]
	v_lshl_add_u64 v[62:63], v[50:51], 0, v[40:41]
	v_cvt_pk_bf16_f32 v31, v32, v33
	global_store_dwordx2 v[38:39], v[30:31], off
	global_load_dwordx4 v[30:33], v[36:37], off offset:1024
	s_nop 0
	global_load_dwordx4 v[58:61], v[48:49], off offset:1024
	s_nop 0
	global_load_dwordx4 v[62:65], v[62:63], off
	s_waitcnt vmcnt(0)
	v_pk_mul_f32 v[26:27], v[26:27], v[30:31]
	v_pk_mul_f32 v[28:29], v[28:29], v[32:33]
	s_waitcnt lgkmcnt(0)
	v_pk_add_f32 v[30:31], v[62:63], 1.0 op_sel_hi:[1,0]
	s_nop 0
	v_pk_fma_f32 v[26:27], v[26:27], v[30:31], v[58:59]
	v_pk_add_f32 v[30:31], v[64:65], 1.0 op_sel_hi:[1,0]
	v_cvt_pk_bf16_f32 v26, v26, v27
	v_pk_fma_f32 v[28:29], v[28:29], v[30:31], v[60:61]
	v_lshl_add_u64 v[58:59], v[50:51], 0, v[42:43]
	v_cvt_pk_bf16_f32 v27, v28, v29
	global_store_dwordx2 v[38:39], v[26:27], off offset:512
	global_load_dwordx4 v[26:29], v[36:37], off offset:2048
	s_nop 0
	global_load_dwordx4 v[30:33], v[48:49], off offset:2048
	s_nop 0
	global_load_dwordx4 v[58:61], v[58:59], off
	s_waitcnt vmcnt(0)
	v_pk_mul_f32 v[10:11], v[10:11], v[26:27]
	v_pk_mul_f32 v[12:13], v[12:13], v[28:29]
	s_waitcnt lgkmcnt(0)
	v_pk_add_f32 v[26:27], v[58:59], 1.0 op_sel_hi:[1,0]
	s_nop 0
	v_pk_fma_f32 v[10:11], v[10:11], v[26:27], v[30:31]
	v_pk_add_f32 v[26:27], v[60:61], 1.0 op_sel_hi:[1,0]
	v_cvt_pk_bf16_f32 v10, v10, v11
	v_pk_fma_f32 v[12:13], v[12:13], v[26:27], v[32:33]
	v_lshl_add_u64 v[30:31], v[50:51], 0, v[44:45]
	v_cvt_pk_bf16_f32 v11, v12, v13
	global_store_dwordx2 v[38:39], v[10:11], off offset:1024
	global_load_dwordx4 v[10:13], v[36:37], off offset:3072
	s_nop 0
	global_load_dwordx4 v[26:29], v[48:49], off offset:3072
	s_nop 0
	global_load_dwordx4 v[30:33], v[30:31], off
	s_waitcnt vmcnt(0)
	v_pk_mul_f32 v[2:3], v[2:3], v[10:11]
	v_pk_mul_f32 v[4:5], v[4:5], v[12:13]
	s_waitcnt lgkmcnt(0)
	v_pk_add_f32 v[10:11], v[30:31], 1.0 op_sel_hi:[1,0]
	v_mov_b32_e32 v30, v14
	v_pk_fma_f32 v[2:3], v[2:3], v[10:11], v[26:27]
	v_pk_add_f32 v[10:11], v[32:33], 1.0 op_sel_hi:[1,0]
	v_cvt_pk_bf16_f32 v2, v2, v3
	v_pk_fma_f32 v[4:5], v[4:5], v[10:11], v[28:29]
	v_mov_b32_e32 v31, v15
	v_cvt_pk_bf16_f32 v3, v4, v5
	global_store_dwordx2 v[38:39], v[2:3], off offset:1536
	v_lshl_add_u64 v[38:39], v[38:39], 0, s[12:13]
	v_mov_b32_e32 v32, v16
	v_mov_b32_e32 v33, v17
	v_mov_b32_e32 v26, v18
	v_mov_b32_e32 v27, v19
	v_mov_b32_e32 v28, v20
	v_mov_b32_e32 v29, v21
	v_mov_b32_e32 v10, v22
	v_mov_b32_e32 v11, v23
	v_mov_b32_e32 v12, v24
	v_mov_b32_e32 v13, v25
	v_mov_b32_e32 v2, v6
	v_mov_b32_e32 v3, v7
	v_mov_b32_e32 v4, v8
	v_mov_b32_e32 v5, v9
	s_andn2_b64 exec, exec, s[14:15]
	s_cbranch_execz .LBB0_166

.LBB0_168:
	s_or_b64 exec, exec, s[12:13]
	v_lshlrev_b32_e32 v40, 16, v29
	v_and_b32_e32 v41, 0xffff0000, v29
	v_lshlrev_b32_e32 v42, 16, v33
	v_and_b32_e32 v43, 0xffff0000, v33
	v_pk_add_f32 v[40:41], v[40:41], v[42:43]
	v_lshlrev_b32_e32 v42, 16, v28
	v_and_b32_e32 v43, 0xffff0000, v28
	v_lshlrev_b32_e32 v28, 16, v32
	v_and_b32_e32 v29, 0xffff0000, v32
	v_pk_add_f32 v[28:29], v[42:43], v[28:29]
	v_mov_b32_e32 v32, v40
	v_mov_b32_e32 v33, v28
	v_pk_mul_f32 v[32:33], v[32:33], v[32:33]
	v_mov_b32_e32 v42, v41
	v_mov_b32_e32 v43, v29
	v_lshlrev_b32_e32 v44, 16, v12
	v_and_b32_e32 v12, 0xffff0000, v12
	v_pk_fma_f32 v[42:43], v[42:43], v[42:43], v[32:33]
	v_mul_f32_e32 v32, 0xbfb8aa3b, v44
	v_mul_f32_e32 v33, 0xbfb8aa3b, v12
	v_exp_f32_e32 v32, v32
	v_exp_f32_e32 v33, v33
	s_and_b64 s[0:1], exec, s[0:1]
	s_or_b64 s[10:11], s[0:1], s[10:11]
	v_lshl_add_u64 v[36:37], v[36:37], 0, s[8:9]
	v_pk_add_f32 v[32:33], v[32:33], 1.0 op_sel_hi:[1,0]
	s_nop 0
	v_div_scale_f32 v45, s[0:1], v33, v33, v12
	v_rcp_f32_e32 v46, v45
	s_nop 0
	v_fma_f32 v47, -v45, v46, 1.0
	v_fmac_f32_e32 v46, v47, v46
	v_div_scale_f32 v47, vcc, v12, v33, v12
	v_mul_f32_e32 v51, v47, v46
	v_fma_f32 v52, -v45, v51, v47
	v_fmac_f32_e32 v51, v52, v46
	v_fma_f32 v45, -v45, v51, v47
	v_div_fmas_f32 v45, v45, v46, v51
	v_div_fixup_f32 v33, v45, v33, v12
	v_div_scale_f32 v12, s[0:1], v32, v32, v44
	v_rcp_f32_e32 v45, v12
	s_nop 0
	v_fma_f32 v46, -v12, v45, 1.0
	v_fmac_f32_e32 v45, v46, v45
	v_div_scale_f32 v46, vcc, v44, v32, v44
	v_mul_f32_e32 v47, v46, v45
	v_fma_f32 v51, -v12, v47, v46
	v_fmac_f32_e32 v47, v51, v45
	v_fma_f32 v12, -v12, v47, v46
	v_div_fmas_f32 v12, v12, v45, v47
	v_div_fixup_f32 v32, v12, v32, v44
	v_lshlrev_b32_e32 v12, 16, v11
	v_lshlrev_b32_e32 v44, 16, v27
	v_and_b32_e32 v45, 0xffff0000, v27
	v_lshlrev_b32_e32 v46, 16, v31
	v_and_b32_e32 v47, 0xffff0000, v31
	v_and_b32_e32 v11, 0xffff0000, v11
	v_mul_f32_e32 v27, 0xbfb8aa3b, v12
	v_pk_add_f32 v[44:45], v[44:45], v[46:47]
	v_exp_f32_e32 v46, v27
	v_mul_f32_e32 v27, 0xbfb8aa3b, v11
	v_exp_f32_e32 v47, v27
	s_nop 0
	v_pk_add_f32 v[46:47], v[46:47], 1.0 op_sel_hi:[1,0]
	s_nop 0
	v_div_scale_f32 v27, s[0:1], v47, v47, v11
	v_rcp_f32_e32 v31, v27
	s_nop 0
	v_fma_f32 v51, -v27, v31, 1.0
	v_fmac_f32_e32 v31, v51, v31
	v_div_scale_f32 v51, vcc, v11, v47, v11
	v_mul_f32_e32 v52, v51, v31
	v_fma_f32 v53, -v27, v52, v51
	v_fmac_f32_e32 v52, v53, v31
	v_fma_f32 v27, -v27, v52, v51
	v_div_fmas_f32 v27, v27, v31, v52
	v_div_fixup_f32 v47, v27, v47, v11
	v_div_scale_f32 v11, s[0:1], v46, v46, v12
	v_rcp_f32_e32 v27, v11
	v_and_b32_e32 v53, 0xffff0000, v26
	v_fma_f32 v31, -v11, v27, 1.0
	v_fmac_f32_e32 v27, v31, v27
	v_div_scale_f32 v31, vcc, v12, v46, v12
	v_mul_f32_e32 v51, v31, v27
	v_fma_f32 v52, -v11, v51, v31
	v_fmac_f32_e32 v51, v52, v27
	v_fma_f32 v11, -v11, v51, v31
	v_div_fmas_f32 v11, v11, v27, v51
	v_div_fixup_f32 v46, v11, v46, v12
	v_lshlrev_b32_e32 v12, 16, v10
	v_and_b32_e32 v51, 0xffff0000, v10
	v_mul_f32_e32 v10, 0xbfb8aa3b, v12
	v_mul_f32_e32 v11, 0xbfb8aa3b, v51
	v_exp_f32_e32 v10, v10
	v_exp_f32_e32 v11, v11
	v_lshlrev_b32_e32 v52, 16, v26
	v_lshlrev_b32_e32 v26, 16, v30
	v_and_b32_e32 v27, 0xffff0000, v30
	v_pk_add_f32 v[26:27], v[52:53], v[26:27]
	v_mov_b32_e32 v31, v44
	v_mov_b32_e32 v30, v26
	v_pk_mul_f32 v[30:31], v[30:31], v[30:31]
	v_mov_b32_e32 v52, v27
	v_mov_b32_e32 v53, v45
	v_pk_add_f32 v[10:11], v[10:11], 1.0 op_sel_hi:[1,0]
	v_pk_fma_f32 v[30:31], v[52:53], v[52:53], v[30:31]
	v_div_scale_f32 v52, s[0:1], v11, v11, v51
	v_rcp_f32_e32 v53, v52
	s_nop 0
	v_fma_f32 v54, -v52, v53, 1.0
	v_fmac_f32_e32 v53, v54, v53
	v_div_scale_f32 v54, vcc, v51, v11, v51
	v_mul_f32_e32 v55, v54, v53
	v_fma_f32 v56, -v52, v55, v54
	v_fmac_f32_e32 v55, v56, v53
	v_fma_f32 v52, -v52, v55, v54
	v_div_fmas_f32 v52, v52, v53, v55
	v_div_fixup_f32 v11, v52, v11, v51
	v_div_scale_f32 v51, s[0:1], v10, v10, v12
	v_rcp_f32_e32 v52, v51
	s_nop 0
	v_fma_f32 v53, -v51, v52, 1.0
	v_fmac_f32_e32 v52, v53, v52
	v_div_scale_f32 v53, vcc, v12, v10, v12
	v_mul_f32_e32 v54, v53, v52
	v_fma_f32 v55, -v51, v54, v53
	v_fmac_f32_e32 v54, v55, v52
	v_fma_f32 v51, -v51, v54, v53
	v_div_fmas_f32 v51, v51, v52, v54
	v_div_fixup_f32 v10, v51, v10, v12
	v_add_f32_e32 v12, v30, v31
	v_add_f32_e32 v12, v43, v12
	v_add_f32_e32 v12, v42, v12
	ds_bpermute_b32 v30, v35, v12
	s_waitcnt lgkmcnt(0)
	v_add_f32_e32 v12, v12, v30
	ds_bpermute_b32 v30, v48, v12
	s_waitcnt lgkmcnt(0)
	v_add_f32_e32 v12, v12, v30
	ds_bpermute_b32 v30, v49, v12
	s_waitcnt lgkmcnt(0)
	v_add_f32_e32 v12, v12, v30
	ds_bpermute_b32 v30, v50, v12
	s_waitcnt lgkmcnt(0)
	v_add_f32_e32 v12, v12, v30
	v_fmamk_f32 v12, v12, 0x3c000000, v230
	v_cmp_gt_f32_e32 vcc, s95, v12
	v_mul_f32_e32 v30, 0x4b800000, v12
	s_nop 0
	v_cndmask_b32_e32 v12, v12, v30, vcc
	v_rsq_f32_e32 v12, v12
	s_nop 0
	v_mul_f32_e32 v30, 0x45800000, v12
	v_cndmask_b32_e32 v30, v12, v30, vcc
	v_pk_mul_f32 v[26:27], v[26:27], v[30:31] op_sel_hi:[1,0]
	s_nop 0
	v_pk_mul_f32 v[26:27], v[6:7], v[26:27]
	s_nop 0
	v_pk_mul_f32 v[10:11], v[10:11], v[26:27]
	v_pk_mul_f32 v[26:27], v[44:45], v[30:31] op_sel_hi:[1,0]
	v_cvt_pk_bf16_f32 v10, v10, v11
	v_pk_mul_f32 v[26:27], v[8:9], v[26:27]
	s_nop 0
	v_pk_mul_f32 v[26:27], v[46:47], v[26:27]
	s_nop 0
	v_cvt_pk_bf16_f32 v11, v26, v27
	v_pk_mul_f32 v[26:27], v[28:29], v[30:31] op_sel_hi:[1,0]
	v_lshlrev_b32_e32 v31, 16, v13
	v_pk_mul_f32 v[26:27], v[2:3], v[26:27]
	v_and_b32_e32 v13, 0xffff0000, v13
	v_pk_mul_f32 v[26:27], v[32:33], v[26:27]
	v_pk_mul_f32 v[28:29], v[40:41], v[30:31] op_sel_hi:[1,0]
	v_cvt_pk_bf16_f32 v12, v26, v27
	v_mul_f32_e32 v26, 0xbfb8aa3b, v31
	v_mul_f32_e32 v27, 0xbfb8aa3b, v13
	v_exp_f32_e32 v26, v26
	v_exp_f32_e32 v27, v27
	v_pk_mul_f32 v[28:29], v[4:5], v[28:29]
	v_pk_add_f32 v[26:27], v[26:27], 1.0 op_sel_hi:[1,0]
	s_nop 0
	v_div_scale_f32 v30, s[0:1], v27, v27, v13
	v_rcp_f32_e32 v32, v30
	s_nop 0
	v_fma_f32 v33, -v30, v32, 1.0
	v_fmac_f32_e32 v32, v33, v32
	v_div_scale_f32 v33, vcc, v13, v27, v13
	v_mul_f32_e32 v40, v33, v32
	v_fma_f32 v41, -v30, v40, v33
	v_fmac_f32_e32 v40, v41, v32
	v_fma_f32 v30, -v30, v40, v33
	v_div_fmas_f32 v30, v30, v32, v40
	v_div_fixup_f32 v27, v30, v27, v13
	v_div_scale_f32 v13, s[0:1], v26, v26, v31
	v_rcp_f32_e32 v30, v13
	s_nop 0
	v_fma_f32 v32, -v13, v30, 1.0
	v_fmac_f32_e32 v30, v32, v30
	v_div_scale_f32 v32, vcc, v31, v26, v31
	v_mul_f32_e32 v33, v32, v30
	v_fma_f32 v40, -v13, v33, v32
	v_fmac_f32_e32 v33, v40, v30
	v_fma_f32 v13, -v13, v33, v32
	v_div_fmas_f32 v13, v13, v30, v33
	v_div_fixup_f32 v26, v13, v26, v31
	v_pk_mul_f32 v[26:27], v[26:27], v[28:29]
	s_waitcnt vmcnt(1)
	v_mov_b64_e32 v[32:33], v[20:21]
	v_cvt_pk_bf16_f32 v13, v26, v27
	v_lshl_add_u64 v[26:27], v[38:39], 0, v[0:1]
	global_store_dwordx4 v[26:27], v[10:13], off
	v_mov_b64_e32 v[28:29], v[16:17]
	v_lshl_add_u64 v[38:39], v[38:39], 0, s[8:9]
	s_waitcnt vmcnt(0)
	v_mov_b64_e32 v[10:11], v[22:23]
	v_mov_b64_e32 v[26:27], v[14:15]
	v_mov_b64_e32 v[30:31], v[18:19]
	v_mov_b64_e32 v[12:13], v[24:25]
	s_andn2_b64 exec, exec, s[10:11]
	s_cbranch_execz .LBB0_171

.LBB0_179:
	v_mov_b32_e32 v0, v228
	s_waitcnt lgkmcnt(0)
	s_barrier
	s_nop 0
	v_cmp_eq_u32_e32 vcc, 0, v0
	s_and_saveexec_b64 s[0:1], vcc
	s_cbranch_execz .LBB0_181
	v_mov_b64_e32 v[2:3], s[44:45]
	global_atomic_add v0, v[2:3], v229, off sc0
	v_mov_b32_e32 v2, s33
	s_waitcnt vmcnt(0) lgkmcnt(0)
	ds_write_b32 v2, v0

.LBB0_197:
	s_waitcnt vmcnt(5)
	v_ashrrev_i32_e32 v66, 1, v102
	v_and_b32_e32 v66, 0xffffffc0, v66
	v_lshl_add_u32 v66, s4, 8, v66
	v_lshrrev_b32_e32 v67, 3, v102
	v_and_b32_e32 v0, 64, v102
	v_and_or_b32 v66, v102, 31, v66
	s_lshl_b32 s0, s2, 7
	v_and_b32_e32 v67, 4, v67
	v_or3_b32 v0, v0, s0, v67
	v_ashrrev_i32_e32 v67, 31, v66
	v_lshlrev_b64 v[68:69], 10, v[66:67]
	v_lshl_add_u64 v[68:69], s[52:53], 0, v[68:69]
	v_lshlrev_b32_e32 v0, 1, v0
	v_cvt_pk_bf16_f32 v50, v50, v51
	v_cvt_pk_bf16_f32 v51, v52, v53
	v_lshl_add_u64 v[52:53], v[68:69], 0, v[0:1]
	v_cvt_pk_bf16_f32 v34, v34, v35
	v_cvt_pk_bf16_f32 v35, v36, v37
	global_store_dwordx2 v[52:53], v[34:35], off offset:64
	v_cvt_pk_bf16_f32 v34, v38, v39
	v_cvt_pk_bf16_f32 v35, v40, v41
	global_store_dwordx2 v[52:53], v[34:35], off offset:80
	v_cvt_pk_bf16_f32 v34, v42, v43
	v_cvt_pk_bf16_f32 v35, v44, v45
	global_store_dwordx2 v[52:53], v[34:35], off offset:96
	v_cvt_pk_bf16_f32 v34, v46, v47
	v_cvt_pk_bf16_f32 v35, v48, v49
	global_store_dwordx2 v[52:53], v[34:35], off offset:112
	v_or_b32_e32 v34, 32, v66
	v_ashrrev_i32_e32 v35, 31, v34
	v_lshlrev_b64 v[34:35], 10, v[34:35]
	v_lshl_add_u64 v[34:35], s[52:53], 0, v[34:35]
	v_cvt_pk_bf16_f32 v18, v18, v19
	v_cvt_pk_bf16_f32 v19, v20, v21
	v_lshl_add_u64 v[20:21], v[34:35], 0, v[0:1]
	v_cvt_pk_bf16_f32 v2, v2, v3
	v_cvt_pk_bf16_f32 v3, v4, v5
	global_store_dwordx2 v[52:53], v[50:51], off
	v_cvt_pk_bf16_f32 v50, v54, v55
	v_cvt_pk_bf16_f32 v51, v56, v57
	global_store_dwordx2 v[20:21], v[18:19], off
	v_cvt_pk_bf16_f32 v18, v22, v23
	v_cvt_pk_bf16_f32 v19, v24, v25
	global_store_dwordx2 v[20:21], v[2:3], off offset:64
	v_cvt_pk_bf16_f32 v2, v6, v7
	v_cvt_pk_bf16_f32 v3, v8, v9
	global_store_dwordx2 v[52:53], v[50:51], off offset:16
	v_cvt_pk_bf16_f32 v50, v58, v59
	v_cvt_pk_bf16_f32 v51, v60, v61
	global_store_dwordx2 v[20:21], v[18:19], off offset:16
	v_cvt_pk_bf16_f32 v18, v26, v27
	v_cvt_pk_bf16_f32 v19, v28, v29
	global_store_dwordx2 v[20:21], v[2:3], off offset:80
	v_cvt_pk_bf16_f32 v2, v10, v11
	v_cvt_pk_bf16_f32 v3, v12, v13
	global_store_dwordx2 v[52:53], v[50:51], off offset:32
	v_cvt_pk_bf16_f32 v50, v62, v63
	v_cvt_pk_bf16_f32 v51, v64, v65
	global_store_dwordx2 v[20:21], v[18:19], off offset:32
	v_cvt_pk_bf16_f32 v18, v30, v31
	v_cvt_pk_bf16_f32 v19, v32, v33
	global_store_dwordx2 v[20:21], v[2:3], off offset:96
	v_cvt_pk_bf16_f32 v2, v14, v15
	v_cvt_pk_bf16_f32 v3, v16, v17
	global_store_dwordx2 v[52:53], v[50:51], off offset:48
	global_store_dwordx2 v[20:21], v[18:19], off offset:48
	global_store_dwordx2 v[20:21], v[2:3], off offset:112
	s_mov_b64 s[0:1], 0
.LBB0_198:
	s_and_b64 vcc, exec, s[0:1]
	s_cbranch_vccz .LBB0_213
	v_readlane_b32 s0, v254, 53
	s_add_i32 s0, s0, s3
	s_lshr_b32 s0, s0, 3
	s_lshl_b32 s4, s3, 7
	v_mov_b32_e32 v34, v228
	s_lshl_b32 s1, s0, 8
	s_and_b32 s4, s4, 0x80
	s_or_b32 s6, s1, s4
	v_and_b32_e32 v36, 31, v34
	s_waitcnt vmcnt(0)
	v_ashrrev_i32_e32 v162, 7, v34
	v_or_b32_e32 v0, s6, v36
	s_bfe_u32 s2, s3, 0x20001
	s_lshl_b32 s4, s0, 17
	s_lshl_b32 s0, s0, 18
	v_readlane_b32 s1, v254, 62
	v_lshl_add_u32 v2, v162, 5, v0
	s_add_u32 s0, s1, s0
	v_readlane_b32 s1, v254, 63
	v_ashrrev_i32_e32 v3, 31, v2
	v_readlane_b32 s6, v254, 50
	s_addc_u32 s1, s1, 0
	s_lshl_b32 s38, s2, 8
	v_lshlrev_b64 v[2:3], 10, v[2:3]
	v_readlane_b32 s7, v254, 51
	v_bfe_u32 v153, v34, 6, 1
	s_add_u32 s0, s0, s38
	v_lshl_add_u64 v[2:3], s[6:7], 0, v[2:3]
	v_bfe_u32 v35, v34, 5, 1
	s_addc_u32 s1, s1, 0
	s_lshl_b32 s2, s2, 15
	v_lshl_add_u64 v[150:151], v[2:3], 0, s[38:39]
	v_lshlrev_b32_e32 v0, 7, v153
	s_or_b32 s4, s4, s2
	v_lshl_add_u64 v[2:3], v[150:151], 0, v[0:1]
	v_lshlrev_b32_e32 v148, 4, v35
	v_mov_b32_e32 v149, v1
	v_ashrrev_i32_e32 v18, 4, v34
	v_lshlrev_b32_e32 v4, 4, v34
	s_lshl_b32 s4, s4, 1
	v_readlane_b32 s5, v255, 0
	v_lshl_add_u64 v[2:3], v[2:3], 0, v[148:149]
	v_and_b32_e32 v154, 0xf0, v4
	v_mov_b32_e32 v155, v1
	v_ashrrev_i32_e32 v19, 31, v18
	s_add_u32 s4, s5, s4
	v_readlane_b32 s5, v255, 1
	global_load_dwordx4 v[124:127], v[2:3], off
	global_load_dwordx4 v[120:123], v[2:3], off offset:32
	global_load_dwordx4 v[116:119], v[2:3], off offset:64
	global_load_dwordx4 v[112:115], v[2:3], off offset:96
	v_ashrrev_i32_e32 v20, 3, v34
	v_lshl_add_u64 v[2:3], s[0:1], 0, v[154:155]
	v_lshlrev_b64 v[22:23], 10, v[18:19]
	s_addc_u32 s5, s5, 0
	v_and_b32_e32 v156, 0x70, v4
	v_mov_b32_e32 v157, v1
	v_lshl_add_u64 v[24:25], v[2:3], 0, v[22:23]
	v_ashrrev_i32_e32 v21, 31, v20
	s_mov_b32 s0, 0x8000
	v_lshl_add_u64 v[14:15], s[4:5], 0, v[156:157]
	v_lshlrev_b64 v[26:27], 9, v[20:21]
	v_add_co_u32_e32 v10, vcc, s0, v24
	s_mov_b64 s[0:1], 0x8000
	v_lshl_add_u64 v[6:7], v[14:15], 0, v[26:27]
	v_lshl_add_u64 v[28:29], v[26:27], 0, s[0:1]
	s_waitcnt lgkmcnt(0)
	s_barrier
	global_load_dwordx4 v[2:5], v[24:25], off
	s_nop 0
	global_load_dwordx4 v[6:9], v[6:7], off
	v_addc_co_u32_e32 v11, vcc, 0, v25, vcc
	v_lshl_add_u64 v[14:15], v[14:15], 0, v[28:29]
	global_load_dwordx4 v[10:13], v[10:11], off
	s_mov_b32 s0, 0x10000
	global_load_dwordx4 v[14:17], v[14:15], off
	v_add_co_u32_e32 v30, vcc, s0, v24
	s_mov_b32 s0, 0x18000
	s_nop 0
	v_addc_co_u32_e32 v31, vcc, 0, v25, vcc
	v_add_co_u32_e32 v24, vcc, s0, v24
	v_lshl_add_u64 v[32:33], s[4:5], 0, v[26:27]
	s_nop 0
	v_addc_co_u32_e32 v25, vcc, 0, v25, vcc
	v_lshl_add_u64 v[28:29], s[4:5], 0, v[28:29]
	v_lshl_add_u64 v[32:33], v[32:33], 0, v[156:157]
	global_load_dwordx4 v[128:131], v[30:31], off
	global_load_dwordx4 v[132:135], v[32:33], off offset:128
	v_lshl_add_u64 v[28:29], v[28:29], 0, v[156:157]
	global_load_dwordx4 v[136:139], v[24:25], off
	global_load_dwordx4 v[140:143], v[28:29], off offset:128
	s_movk_i32 s1, 0x110
	v_mul_lo_u32 v164, v18, s1
	s_movk_i32 s1, 0x88
	v_mul_lo_u32 v165, v20, s1
	v_add3_u32 v18, 0, v154, v164
	v_add3_u32 v19, 0, v156, v165
	v_readlane_b32 s1, v254, 58
	v_add_u32_e32 v20, 0x4400, v19
	s_waitcnt vmcnt(0)
	ds_write_b128 v18, v[2:5]
	ds_write2_b64 v20, v[6:7], v[8:9] offset1:1
	ds_write_b128 v18, v[10:13] offset:8704
	v_add_u32_e32 v2, 0x6600, v19
	v_and_b32_e32 v3, 64, v231
	v_or_b32_e32 v167, v0, v148
	v_and_b32_e32 v0, 7, v34
	s_add_i32 s1, s1, s3
	ds_write2_b64 v2, v[14:15], v[16:17] offset1:1
	v_xor_b32_e32 v2, 32, v231
	v_add_u32_e32 v3, 64, v3
	v_lshl_or_b32 v26, v0, 4, v26
	s_lshl_b32 s1, s1, 14
	v_and_b32_e32 v0, 15, v34
	v_cmp_lt_i32_e32 vcc, v2, v3
	s_and_b32 s4, s1, 0xfffe0000
	v_lshlrev_b32_e32 v0, 4, v0
	s_waitcnt lgkmcnt(0)
	s_barrier
	v_cndmask_b32_e32 v2, v231, v2, vcc
	s_or_b32 s6, s4, s2
	s_mov_b32 s7, s39
	v_or3_b32 v22, v22, s38, v0
	s_mov_b32 s5, s39
	v_mov_b32_e32 v14, v1
	v_mov_b32_e32 v15, v1
	v_and_b32_e32 v155, 63, v34
	v_lshlrev_b32_e32 v152, 3, v35
	v_mul_u32_u24_e32 v163, 0x88, v36
	v_lshlrev_b32_e32 v149, 2, v2
	v_mul_u32_u24_e32 v166, 0x110, v36
	v_lshl_add_u64 v[158:159], s[6:7], 1, v[26:27]
	v_lshl_add_u64 v[160:161], s[4:5], 1, v[22:23]
	v_mov_b32_e32 v0, v1
	v_mov_b32_e32 v2, v1
	v_mov_b32_e32 v3, v1
	v_mov_b32_e32 v4, v1
	v_mov_b32_e32 v5, v1
	v_mov_b32_e32 v6, v1
	v_mov_b32_e32 v7, v1
	v_mov_b32_e32 v8, v1
	v_mov_b32_e32 v9, v1
	v_mov_b32_e32 v10, v1
	v_mov_b32_e32 v11, v1
	v_mov_b32_e32 v12, v1
	v_mov_b32_e32 v13, v1
	v_mov_b64_e32 v[30:31], v[14:15]
	v_mov_b64_e32 v[46:47], v[14:15]
	v_mov_b64_e32 v[62:63], v[14:15]
	v_mov_b64_e32 v[78:79], v[14:15]
	s_mov_b32 s0, 1
	v_mov_b32_e32 v157, 0xf149f2ca
	v_mov_b32_e32 v168, 0
	v_mov_b64_e32 v[28:29], v[12:13]
	v_mov_b64_e32 v[26:27], v[10:11]
	v_mov_b64_e32 v[24:25], v[8:9]
	v_mov_b64_e32 v[22:23], v[6:7]
	v_mov_b64_e32 v[20:21], v[4:5]
	v_mov_b64_e32 v[18:19], v[2:3]
	v_mov_b64_e32 v[16:17], v[0:1]
	v_mov_b64_e32 v[44:45], v[12:13]
	v_mov_b64_e32 v[42:43], v[10:11]
	v_mov_b64_e32 v[40:41], v[8:9]
	v_mov_b64_e32 v[38:39], v[6:7]
	v_mov_b64_e32 v[36:37], v[4:5]
	v_mov_b64_e32 v[34:35], v[2:3]
	v_mov_b64_e32 v[32:33], v[0:1]
	v_mov_b64_e32 v[60:61], v[12:13]
	v_mov_b64_e32 v[58:59], v[10:11]
	v_mov_b64_e32 v[56:57], v[8:9]
	v_mov_b64_e32 v[54:55], v[6:7]
	v_mov_b64_e32 v[52:53], v[4:5]
	v_mov_b64_e32 v[50:51], v[2:3]
	v_mov_b64_e32 v[48:49], v[0:1]
	v_mov_b64_e32 v[76:77], v[12:13]
	v_mov_b64_e32 v[74:75], v[10:11]
	v_mov_b64_e32 v[72:73], v[8:9]
	v_mov_b64_e32 v[70:71], v[6:7]
	v_mov_b64_e32 v[68:69], v[4:5]
	v_mov_b64_e32 v[66:67], v[2:3]
	v_mov_b64_e32 v[64:65], v[0:1]
	s_mov_b64 s[4:5], 0x10000

.LBB0_210:
	s_or_b64 exec, exec, s[4:5]
	s_waitcnt lgkmcnt(0)
	s_barrier
	s_and_saveexec_b64 s[0:1], vcc
	s_cbranch_execz .LBB0_212
	v_readlane_b32 s4, v255, 2
	v_readlane_b32 s5, v255, 3
	s_nop 1
	v_mov_b64_e32 v[2:3], s[4:5]
	global_load_dword v82, v[2:3], off
	ds_read2st64_b32 v[120:121], v0 offset1:1
	ds_read2st64_b32 v[6:7], v0 offset0:2 offset1:3
	ds_read2st64_b32 v[8:9], v0 offset0:4 offset1:5
	ds_read2st64_b32 v[2:3], v0 offset0:6 offset1:7
	ds_read2st64_b32 v[126:127], v0 offset0:8 offset1:9
	s_waitcnt vmcnt(0)
	ds_read2st64_b32 v[140:141], v0 offset0:10 offset1:11
	ds_read2st64_b32 v[134:135], v0 offset0:12 offset1:13
	ds_read2st64_b32 v[130:131], v0 offset0:14 offset1:15
	ds_read2st64_b32 v[136:137], v0 offset0:16 offset1:17
	ds_read2st64_b32 v[142:143], v0 offset0:18 offset1:19
	ds_read2st64_b32 v[154:155], v0 offset0:20 offset1:21
	ds_read2st64_b32 v[146:147], v0 offset0:22 offset1:23
	ds_read2st64_b32 v[112:113], v0 offset0:24 offset1:25
	ds_read2st64_b32 v[116:117], v0 offset0:26 offset1:27
	ds_read2st64_b32 v[132:133], v0 offset0:28 offset1:29
	ds_read2st64_b32 v[138:139], v0 offset0:30 offset1:31
	ds_read2st64_b32 v[104:105], v0 offset0:32 offset1:33
	ds_read2st64_b32 v[108:109], v0 offset0:34 offset1:35
	ds_read2st64_b32 v[114:115], v0 offset0:36 offset1:37
	ds_read2st64_b32 v[118:119], v0 offset0:38 offset1:39
	ds_read2st64_b32 v[96:97], v0 offset0:40 offset1:41
	ds_read2st64_b32 v[102:103], v0 offset0:42 offset1:43
	ds_read2st64_b32 v[106:107], v0 offset0:44 offset1:45
	ds_read2st64_b32 v[110:111], v0 offset0:46 offset1:47
	ds_read2st64_b32 v[88:89], v0 offset0:48 offset1:49
	ds_read2st64_b32 v[90:91], v0 offset0:50 offset1:51
	ds_read2st64_b32 v[94:95], v0 offset0:52 offset1:53
	ds_read2st64_b32 v[100:101], v0 offset0:54 offset1:55
	ds_read2st64_b32 v[92:93], v0 offset0:56 offset1:57
	ds_read2st64_b32 v[98:99], v0 offset0:58 offset1:59
	ds_read2st64_b32 v[4:5], v0 offset0:60 offset1:61
	v_readlane_b32 s4, v255, 4
	v_readlane_b32 s5, v255, 5
	s_waitcnt lgkmcnt(0)
	v_pk_mul_f32 v[4:5], v[82:83], v[4:5] op_sel_hi:[0,1]
	v_pk_fma_f32 v[12:13], v[28:29], v[80:81], v[4:5] op_sel_hi:[1,0,1] neg_lo:[0,0,1] neg_hi:[0,0,1]
	ds_read2st64_b32 v[4:5], v0 offset0:62 offset1:63
	v_pk_mul_f32 v[6:7], v[82:83], v[6:7] op_sel_hi:[0,1]
	v_lshlrev_b32_e32 v0, 1, v152
	v_pk_mul_f32 v[2:3], v[82:83], v[2:3] op_sel_hi:[0,1]
	v_pk_mul_f32 v[8:9], v[82:83], v[8:9] op_sel_hi:[0,1]
	s_waitcnt lgkmcnt(0)
	v_pk_mul_f32 v[4:5], v[82:83], v[4:5] op_sel_hi:[0,1]
	v_pk_fma_f32 v[14:15], v[30:31], v[80:81], v[4:5] op_sel_hi:[1,0,1] neg_lo:[0,0,1] neg_hi:[0,0,1]
	v_pk_mul_f32 v[30:31], v[82:83], v[120:121] op_sel_hi:[0,1]
	v_pk_fma_f32 v[120:121], v[64:65], v[80:81], v[30:31] op_sel_hi:[1,0,1] neg_lo:[0,0,1] neg_hi:[0,0,1]
	v_pk_fma_f32 v[66:67], v[66:67], v[80:81], v[6:7] op_sel_hi:[1,0,1] neg_lo:[0,0,1] neg_hi:[0,0,1]
	v_pk_mul_f32 v[128:129], v[120:121], v[120:121]
	v_lshl_add_u64 v[10:11], v[150:151], 0, v[0:1]
	v_pk_fma_f32 v[28:29], v[70:71], v[80:81], v[2:3] op_sel_hi:[1,0,1] neg_lo:[0,0,1] neg_hi:[0,0,1]
	global_load_dwordx4 v[2:5], v148, s[4:5] offset:32
	v_pk_fma_f32 v[68:69], v[68:69], v[80:81], v[8:9] op_sel_hi:[1,0,1] neg_lo:[0,0,1] neg_hi:[0,0,1]
	v_pk_mul_f32 v[124:125], v[66:67], v[66:67]
	global_load_dwordx4 v[6:9], v148, s[4:5]
	v_add_f32_e32 v0, v128, v129
	v_pk_mul_f32 v[30:31], v[82:83], v[130:131] op_sel_hi:[0,1]
	v_add_f32_e32 v0, v0, v124
	v_pk_mul_f32 v[122:123], v[68:69], v[68:69]
	v_pk_fma_f32 v[64:65], v[78:79], v[80:81], v[30:31] op_sel_hi:[1,0,1] neg_lo:[0,0,1] neg_hi:[0,0,1]
	v_pk_mul_f32 v[30:31], v[82:83], v[134:135] op_sel_hi:[0,1]
	v_add_f32_e32 v0, v0, v125
	v_pk_fma_f32 v[76:77], v[76:77], v[80:81], v[30:31] op_sel_hi:[1,0,1] neg_lo:[0,0,1] neg_hi:[0,0,1]
	v_pk_mul_f32 v[30:31], v[82:83], v[140:141] op_sel_hi:[0,1]
	v_add_f32_e32 v0, v0, v122
	v_pk_mul_f32 v[70:71], v[28:29], v[28:29]
	v_pk_fma_f32 v[78:79], v[74:75], v[80:81], v[30:31] op_sel_hi:[1,0,1] neg_lo:[0,0,1] neg_hi:[0,0,1]
	v_pk_mul_f32 v[30:31], v[82:83], v[126:127] op_sel_hi:[0,1]
	v_add_f32_e32 v0, v0, v123
	v_pk_fma_f32 v[126:127], v[72:73], v[80:81], v[30:31] op_sel_hi:[1,0,1] neg_lo:[0,0,1] neg_hi:[0,0,1]
	v_add_f32_e32 v0, v0, v70
	v_pk_mul_f32 v[144:145], v[126:127], v[126:127]
	v_add_f32_e32 v0, v0, v71
	v_add_f32_e32 v0, v0, v144
	v_pk_mul_f32 v[140:141], v[78:79], v[78:79]
	v_add_f32_e32 v0, v0, v145
	v_pk_mul_f32 v[30:31], v[82:83], v[146:147] op_sel_hi:[0,1]
	v_add_f32_e32 v0, v0, v140
	v_pk_mul_f32 v[134:135], v[76:77], v[76:77]
	v_pk_fma_f32 v[54:55], v[54:55], v[80:81], v[30:31] op_sel_hi:[1,0,1] neg_lo:[0,0,1] neg_hi:[0,0,1]
	v_pk_mul_f32 v[30:31], v[82:83], v[154:155] op_sel_hi:[0,1]
	v_add_f32_e32 v0, v0, v141
	v_pk_fma_f32 v[52:53], v[52:53], v[80:81], v[30:31] op_sel_hi:[1,0,1] neg_lo:[0,0,1] neg_hi:[0,0,1]
	v_pk_mul_f32 v[30:31], v[82:83], v[142:143] op_sel_hi:[0,1]
	v_add_f32_e32 v0, v0, v134
	v_pk_mul_f32 v[130:131], v[64:65], v[64:65]
	v_pk_fma_f32 v[72:73], v[50:51], v[80:81], v[30:31] op_sel_hi:[1,0,1] neg_lo:[0,0,1] neg_hi:[0,0,1]
	v_pk_mul_f32 v[30:31], v[82:83], v[136:137] op_sel_hi:[0,1]
	v_add_f32_e32 v0, v0, v135
	v_pk_fma_f32 v[74:75], v[48:49], v[80:81], v[30:31] op_sel_hi:[1,0,1] neg_lo:[0,0,1] neg_hi:[0,0,1]
	v_add_f32_e32 v0, v0, v130
	v_pk_mul_f32 v[136:137], v[74:75], v[74:75]
	v_add_f32_e32 v0, v0, v131
	v_add_f32_e32 v0, v0, v136
	v_pk_mul_f32 v[142:143], v[72:73], v[72:73]
	v_add_f32_e32 v0, v0, v137
	v_pk_mul_f32 v[30:31], v[82:83], v[138:139] op_sel_hi:[0,1]
	v_add_f32_e32 v0, v0, v142
	v_pk_mul_f32 v[150:151], v[52:53], v[52:53]
	v_pk_fma_f32 v[48:49], v[62:63], v[80:81], v[30:31] op_sel_hi:[1,0,1] neg_lo:[0,0,1] neg_hi:[0,0,1]
	v_pk_mul_f32 v[30:31], v[82:83], v[132:133] op_sel_hi:[0,1]
	v_add_f32_e32 v0, v0, v143
	v_pk_fma_f32 v[60:61], v[60:61], v[80:81], v[30:31] op_sel_hi:[1,0,1] neg_lo:[0,0,1] neg_hi:[0,0,1]
	v_pk_mul_f32 v[30:31], v[82:83], v[116:117] op_sel_hi:[0,1]
	v_add_f32_e32 v0, v0, v150
	v_pk_mul_f32 v[146:147], v[54:55], v[54:55]
	v_pk_fma_f32 v[116:117], v[58:59], v[80:81], v[30:31] op_sel_hi:[1,0,1] neg_lo:[0,0,1] neg_hi:[0,0,1]
	v_pk_mul_f32 v[30:31], v[82:83], v[112:113] op_sel_hi:[0,1]
	v_add_f32_e32 v0, v0, v151
	v_pk_fma_f32 v[112:113], v[56:57], v[80:81], v[30:31] op_sel_hi:[1,0,1] neg_lo:[0,0,1] neg_hi:[0,0,1]
	v_add_f32_e32 v0, v0, v146
	v_pk_mul_f32 v[154:155], v[112:113], v[112:113]
	v_add_f32_e32 v0, v0, v147
	v_add_f32_e32 v0, v0, v154
	v_pk_mul_f32 v[152:153], v[116:117], v[116:117]
	v_add_f32_e32 v0, v0, v155
	v_pk_mul_f32 v[30:31], v[82:83], v[118:119] op_sel_hi:[0,1]
	v_add_f32_e32 v0, v0, v152
	v_pk_mul_f32 v[132:133], v[60:61], v[60:61]
	v_pk_fma_f32 v[50:51], v[38:39], v[80:81], v[30:31] op_sel_hi:[1,0,1] neg_lo:[0,0,1] neg_hi:[0,0,1]
	v_pk_mul_f32 v[30:31], v[82:83], v[114:115] op_sel_hi:[0,1]
	v_add_f32_e32 v0, v0, v153
	v_pk_fma_f32 v[56:57], v[36:37], v[80:81], v[30:31] op_sel_hi:[1,0,1] neg_lo:[0,0,1] neg_hi:[0,0,1]
	v_pk_mul_f32 v[30:31], v[82:83], v[108:109] op_sel_hi:[0,1]
	v_add_f32_e32 v0, v0, v132
	v_pk_mul_f32 v[138:139], v[48:49], v[48:49]
	v_pk_fma_f32 v[58:59], v[34:35], v[80:81], v[30:31] op_sel_hi:[1,0,1] neg_lo:[0,0,1] neg_hi:[0,0,1]
	v_pk_mul_f32 v[30:31], v[82:83], v[104:105] op_sel_hi:[0,1]
	v_add_f32_e32 v0, v0, v133
	v_pk_fma_f32 v[62:63], v[32:33], v[80:81], v[30:31] op_sel_hi:[1,0,1] neg_lo:[0,0,1] neg_hi:[0,0,1]
	v_add_f32_e32 v0, v0, v138
	v_pk_mul_f32 v[104:105], v[62:63], v[62:63]
	v_add_f32_e32 v0, v0, v139
	v_add_f32_e32 v0, v0, v104
	v_pk_mul_f32 v[108:109], v[58:59], v[58:59]
	v_add_f32_e32 v0, v0, v105
	v_add_f32_e32 v0, v0, v108
	v_pk_mul_f32 v[114:115], v[56:57], v[56:57]
	v_pk_mul_f32 v[32:33], v[82:83], v[106:107] op_sel_hi:[0,1]
	v_add_f32_e32 v0, v0, v109
	v_pk_fma_f32 v[36:37], v[44:45], v[80:81], v[32:33] op_sel_hi:[1,0,1] neg_lo:[0,0,1] neg_hi:[0,0,1]
	v_pk_mul_f32 v[32:33], v[82:83], v[102:103] op_sel_hi:[0,1]
	v_add_f32_e32 v0, v0, v114
	v_pk_mul_f32 v[118:119], v[50:51], v[50:51]
	v_pk_fma_f32 v[38:39], v[42:43], v[80:81], v[32:33] op_sel_hi:[1,0,1] neg_lo:[0,0,1] neg_hi:[0,0,1]
	v_pk_mul_f32 v[32:33], v[82:83], v[96:97] op_sel_hi:[0,1]
	v_add_f32_e32 v0, v0, v115
	v_pk_fma_f32 v[40:41], v[40:41], v[80:81], v[32:33] op_sel_hi:[1,0,1] neg_lo:[0,0,1] neg_hi:[0,0,1]
	v_add_f32_e32 v0, v0, v118
	v_pk_mul_f32 v[96:97], v[40:41], v[40:41]
	v_add_f32_e32 v0, v0, v119
	v_add_f32_e32 v0, v0, v96
	v_pk_mul_f32 v[42:43], v[38:39], v[38:39]
	v_add_f32_e32 v0, v0, v97
	v_pk_mul_f32 v[32:33], v[82:83], v[100:101] op_sel_hi:[0,1]
	v_add_f32_e32 v0, v0, v42
	v_pk_mul_f32 v[30:31], v[82:83], v[110:111] op_sel_hi:[0,1]
	v_pk_mul_f32 v[44:45], v[36:37], v[36:37]
	v_pk_fma_f32 v[22:23], v[22:23], v[80:81], v[32:33] op_sel_hi:[1,0,1] neg_lo:[0,0,1] neg_hi:[0,0,1]
	v_pk_mul_f32 v[32:33], v[82:83], v[94:95] op_sel_hi:[0,1]
	v_add_f32_e32 v0, v0, v43
	v_pk_fma_f32 v[30:31], v[46:47], v[80:81], v[30:31] op_sel_hi:[1,0,1] neg_lo:[0,0,1] neg_hi:[0,0,1]
	v_pk_fma_f32 v[20:21], v[20:21], v[80:81], v[32:33] op_sel_hi:[1,0,1] neg_lo:[0,0,1] neg_hi:[0,0,1]
	v_pk_mul_f32 v[32:33], v[82:83], v[90:91] op_sel_hi:[0,1]
	v_add_f32_e32 v0, v0, v44
	v_pk_mul_f32 v[46:47], v[30:31], v[30:31]
	v_pk_fma_f32 v[32:33], v[18:19], v[80:81], v[32:33] op_sel_hi:[1,0,1] neg_lo:[0,0,1] neg_hi:[0,0,1]
	v_pk_mul_f32 v[18:19], v[82:83], v[88:89] op_sel_hi:[0,1]
	v_add_f32_e32 v0, v0, v45
	v_pk_fma_f32 v[34:35], v[16:17], v[80:81], v[18:19] op_sel_hi:[1,0,1] neg_lo:[0,0,1] neg_hi:[0,0,1]
	v_add_f32_e32 v0, v0, v46
	v_pk_mul_f32 v[88:89], v[34:35], v[34:35]
	v_add_f32_e32 v0, v0, v47
	v_add_f32_e32 v0, v0, v88
	v_pk_mul_f32 v[90:91], v[32:33], v[32:33]
	v_add_f32_e32 v0, v0, v89
	v_add_f32_e32 v0, v0, v90
	v_pk_mul_f32 v[94:95], v[20:21], v[20:21]
	v_add_f32_e32 v0, v0, v91
	v_add_f32_e32 v0, v0, v94
	v_pk_mul_f32 v[100:101], v[22:23], v[22:23]
	v_pk_mul_f32 v[18:19], v[82:83], v[92:93] op_sel_hi:[0,1]
	v_add_f32_e32 v0, v0, v95
	v_pk_fma_f32 v[18:19], v[24:25], v[80:81], v[18:19] op_sel_hi:[1,0,1] neg_lo:[0,0,1] neg_hi:[0,0,1]
	v_add_f32_e32 v0, v0, v100
	v_pk_mul_f32 v[16:17], v[82:83], v[98:99] op_sel_hi:[0,1]
	v_pk_mul_f32 v[24:25], v[18:19], v[18:19]
	v_add_f32_e32 v0, v0, v101
	v_pk_fma_f32 v[16:17], v[26:27], v[80:81], v[16:17] op_sel_hi:[1,0,1] neg_lo:[0,0,1] neg_hi:[0,0,1]
	v_add_f32_e32 v0, v0, v24
	v_pk_mul_f32 v[26:27], v[16:17], v[16:17]
	v_add_f32_e32 v0, v0, v25
	v_add_f32_e32 v0, v0, v26
	v_pk_mul_f32 v[84:85], v[12:13], v[12:13]
	v_add_f32_e32 v0, v0, v27
	v_add_f32_e32 v0, v0, v84
	v_pk_mul_f32 v[86:87], v[14:15], v[14:15]
	v_add_f32_e32 v0, v0, v85
	v_add_f32_e32 v0, v0, v86
	v_add_f32_e32 v0, v0, v87
	ds_bpermute_b32 v24, v149, v0
	s_waitcnt lgkmcnt(0)
	v_add_f32_e32 v0, v0, v24
	v_fmamk_f32 v0, v0, 0x3c000000, v230
	v_cmp_gt_f32_e32 vcc, s95, v0
	v_mul_f32_e32 v24, 0x4b800000, v0
	s_nop 0
	v_cndmask_b32_e32 v0, v0, v24, vcc
	v_rsq_f32_e32 v0, v0
	s_nop 0
	v_mul_f32_e32 v24, 0x45800000, v0
	v_cndmask_b32_e32 v0, v0, v24, vcc
	v_mul_f32_e32 v0, v198, v0
	v_pk_mul_f32 v[24:25], v[120:121], v[0:1] op_sel_hi:[1,0]
	s_waitcnt vmcnt(0)
	v_pk_mul_f32 v[6:7], v[6:7], v[24:25]
	v_pk_mul_f32 v[24:25], v[66:67], v[0:1] op_sel_hi:[1,0]
	v_cvt_pk_bf16_f32 v6, v6, v7
	v_pk_mul_f32 v[8:9], v[8:9], v[24:25]
	s_nop 0
	v_cvt_pk_bf16_f32 v7, v8, v9
	v_pk_mul_f32 v[8:9], v[68:69], v[0:1] op_sel_hi:[1,0]
	s_nop 0
	v_pk_mul_f32 v[2:3], v[2:3], v[8:9]
	s_nop 0
	v_cvt_pk_bf16_f32 v8, v2, v3
	v_pk_mul_f32 v[2:3], v[28:29], v[0:1] op_sel_hi:[1,0]
	s_nop 0
	v_permlane32_swap_b32_e32 v6, v8
	v_pk_mul_f32 v[2:3], v[4:5], v[2:3]
	s_nop 0
	v_cvt_pk_bf16_f32 v9, v2, v3
	s_nop 1
	v_permlane32_swap_b32_e32 v7, v9
	global_store_dwordx4 v[10:11], v[6:9], off
	global_load_dwordx4 v[2:5], v148, s[4:5] offset:64
	s_nop 0
	v_pk_mul_f32 v[6:7], v[126:127], v[0:1] op_sel_hi:[1,0]
	v_pk_mul_f32 v[8:9], v[76:77], v[0:1] op_sel_hi:[1,0]
	s_waitcnt vmcnt(0)
	v_pk_mul_f32 v[2:3], v[2:3], v[6:7]
	v_pk_mul_f32 v[6:7], v[78:79], v[0:1] op_sel_hi:[1,0]
	v_cvt_pk_bf16_f32 v2, v2, v3
	v_pk_mul_f32 v[4:5], v[6:7], v[4:5]
	s_nop 0
	v_cvt_pk_bf16_f32 v3, v4, v5
	global_load_dwordx4 v[4:7], v148, s[4:5] offset:96
	s_waitcnt vmcnt(0)
	v_pk_mul_f32 v[4:5], v[8:9], v[4:5]
	v_pk_mul_f32 v[8:9], v[64:65], v[0:1] op_sel_hi:[1,0]
	v_cvt_pk_bf16_f32 v4, v4, v5
	v_pk_mul_f32 v[6:7], v[8:9], v[6:7]
	s_nop 0
	v_permlane32_swap_b32_e32 v2, v4
	v_cvt_pk_bf16_f32 v5, v6, v7
	s_nop 1
	v_permlane32_swap_b32_e32 v3, v5
	global_store_dwordx4 v[10:11], v[2:5], off offset:32
	global_load_dwordx4 v[2:5], v148, s[4:5] offset:128
	v_pk_mul_f32 v[6:7], v[74:75], v[0:1] op_sel_hi:[1,0]
	v_pk_mul_f32 v[8:9], v[52:53], v[0:1] op_sel_hi:[1,0]
	s_waitcnt vmcnt(0)
	v_pk_mul_f32 v[2:3], v[6:7], v[2:3]
	v_pk_mul_f32 v[6:7], v[72:73], v[0:1] op_sel_hi:[1,0]
	v_cvt_pk_bf16_f32 v2, v2, v3
	v_pk_mul_f32 v[4:5], v[6:7], v[4:5]
	s_nop 0
	v_cvt_pk_bf16_f32 v3, v4, v5
	global_load_dwordx4 v[4:7], v148, s[4:5] offset:160
	s_waitcnt vmcnt(0)
	v_pk_mul_f32 v[4:5], v[8:9], v[4:5]
	v_pk_mul_f32 v[8:9], v[54:55], v[0:1] op_sel_hi:[1,0]
	v_cvt_pk_bf16_f32 v4, v4, v5
	v_pk_mul_f32 v[6:7], v[8:9], v[6:7]
	s_nop 0
	v_permlane32_swap_b32_e32 v2, v4
	v_cvt_pk_bf16_f32 v5, v6, v7
	s_nop 1
	v_permlane32_swap_b32_e32 v3, v5
	global_store_dwordx4 v[10:11], v[2:5], off offset:64
	global_load_dwordx4 v[2:5], v148, s[4:5] offset:192
	v_pk_mul_f32 v[6:7], v[112:113], v[0:1] op_sel_hi:[1,0]
	v_pk_mul_f32 v[8:9], v[60:61], v[0:1] op_sel_hi:[1,0]
	s_waitcnt vmcnt(0)
	v_pk_mul_f32 v[2:3], v[6:7], v[2:3]
	v_pk_mul_f32 v[6:7], v[116:117], v[0:1] op_sel_hi:[1,0]
	v_cvt_pk_bf16_f32 v2, v2, v3
	v_pk_mul_f32 v[4:5], v[6:7], v[4:5]
	s_nop 0
	v_cvt_pk_bf16_f32 v3, v4, v5
	global_load_dwordx4 v[4:7], v148, s[4:5] offset:224
	s_waitcnt vmcnt(0)
	v_pk_mul_f32 v[4:5], v[8:9], v[4:5]
	v_pk_mul_f32 v[8:9], v[48:49], v[0:1] op_sel_hi:[1,0]
	v_cvt_pk_bf16_f32 v4, v4, v5
	v_pk_mul_f32 v[6:7], v[8:9], v[6:7]
	s_nop 0
	v_permlane32_swap_b32_e32 v2, v4
	v_cvt_pk_bf16_f32 v5, v6, v7
	s_nop 1
	v_permlane32_swap_b32_e32 v3, v5
	global_store_dwordx4 v[10:11], v[2:5], off offset:96
	global_load_dwordx4 v[2:5], v148, s[4:5] offset:256
	v_pk_mul_f32 v[6:7], v[62:63], v[0:1] op_sel_hi:[1,0]
	v_pk_mul_f32 v[8:9], v[56:57], v[0:1] op_sel_hi:[1,0]
	s_waitcnt vmcnt(0)
	v_pk_mul_f32 v[2:3], v[6:7], v[2:3]
	v_pk_mul_f32 v[6:7], v[58:59], v[0:1] op_sel_hi:[1,0]
	v_cvt_pk_bf16_f32 v2, v2, v3
	v_pk_mul_f32 v[4:5], v[6:7], v[4:5]
	s_nop 0
	v_cvt_pk_bf16_f32 v3, v4, v5
	global_load_dwordx4 v[4:7], v148, s[4:5] offset:288
	s_waitcnt vmcnt(0)
	v_pk_mul_f32 v[4:5], v[8:9], v[4:5]
	v_pk_mul_f32 v[8:9], v[50:51], v[0:1] op_sel_hi:[1,0]
	v_cvt_pk_bf16_f32 v4, v4, v5
	v_pk_mul_f32 v[6:7], v[8:9], v[6:7]
	s_nop 0
	v_permlane32_swap_b32_e32 v2, v4
	v_cvt_pk_bf16_f32 v5, v6, v7
	s_nop 1
	v_permlane32_swap_b32_e32 v3, v5
	global_store_dwordx4 v[10:11], v[2:5], off offset:128
	global_load_dwordx4 v[2:5], v148, s[4:5] offset:320
	v_pk_mul_f32 v[6:7], v[40:41], v[0:1] op_sel_hi:[1,0]
	v_pk_mul_f32 v[8:9], v[36:37], v[0:1] op_sel_hi:[1,0]
	s_waitcnt vmcnt(0)
	v_pk_mul_f32 v[2:3], v[6:7], v[2:3]
	v_pk_mul_f32 v[6:7], v[38:39], v[0:1] op_sel_hi:[1,0]
	v_cvt_pk_bf16_f32 v2, v2, v3
	v_pk_mul_f32 v[4:5], v[6:7], v[4:5]
	s_nop 0
	v_cvt_pk_bf16_f32 v3, v4, v5
	global_load_dwordx4 v[4:7], v148, s[4:5] offset:352
	s_waitcnt vmcnt(0)
	v_pk_mul_f32 v[4:5], v[8:9], v[4:5]
	v_pk_mul_f32 v[8:9], v[30:31], v[0:1] op_sel_hi:[1,0]
	v_cvt_pk_bf16_f32 v4, v4, v5
	v_pk_mul_f32 v[6:7], v[8:9], v[6:7]
	s_nop 0
	v_permlane32_swap_b32_e32 v2, v4
	v_cvt_pk_bf16_f32 v5, v6, v7
	s_nop 1
	v_permlane32_swap_b32_e32 v3, v5
	global_store_dwordx4 v[10:11], v[2:5], off offset:160
	global_load_dwordx4 v[2:5], v148, s[4:5] offset:384
	v_pk_mul_f32 v[6:7], v[34:35], v[0:1] op_sel_hi:[1,0]
	v_pk_mul_f32 v[8:9], v[20:21], v[0:1] op_sel_hi:[1,0]
	s_waitcnt vmcnt(0)
	v_pk_mul_f32 v[2:3], v[6:7], v[2:3]
	v_pk_mul_f32 v[6:7], v[32:33], v[0:1] op_sel_hi:[1,0]
	v_cvt_pk_bf16_f32 v2, v2, v3
	v_pk_mul_f32 v[4:5], v[6:7], v[4:5]
	s_nop 0
	v_cvt_pk_bf16_f32 v3, v4, v5
	global_load_dwordx4 v[4:7], v148, s[4:5] offset:416
	s_waitcnt vmcnt(0)
	v_pk_mul_f32 v[4:5], v[8:9], v[4:5]
	v_pk_mul_f32 v[8:9], v[22:23], v[0:1] op_sel_hi:[1,0]
	v_cvt_pk_bf16_f32 v4, v4, v5
	v_pk_mul_f32 v[6:7], v[8:9], v[6:7]
	s_nop 0
	v_permlane32_swap_b32_e32 v2, v4
	v_cvt_pk_bf16_f32 v5, v6, v7
	s_nop 1
	v_permlane32_swap_b32_e32 v3, v5
	global_store_dwordx4 v[10:11], v[2:5], off offset:192
	global_load_dwordx4 v[2:5], v148, s[4:5] offset:448
	v_pk_mul_f32 v[6:7], v[18:19], v[0:1] op_sel_hi:[1,0]
	v_pk_mul_f32 v[8:9], v[12:13], v[0:1] op_sel_hi:[1,0]
	s_waitcnt vmcnt(0)
	v_pk_mul_f32 v[2:3], v[6:7], v[2:3]
	v_pk_mul_f32 v[6:7], v[16:17], v[0:1] op_sel_hi:[1,0]
	v_cvt_pk_bf16_f32 v2, v2, v3
	v_pk_mul_f32 v[4:5], v[6:7], v[4:5]
	s_nop 0
	v_cvt_pk_bf16_f32 v3, v4, v5
	global_load_dwordx4 v[4:7], v148, s[4:5] offset:480
	s_waitcnt vmcnt(0)
	v_pk_mul_f32 v[4:5], v[8:9], v[4:5]
	v_pk_mul_f32 v[8:9], v[14:15], v[0:1] op_sel_hi:[1,0]
	v_cvt_pk_bf16_f32 v4, v4, v5
	v_pk_mul_f32 v[6:7], v[8:9], v[6:7]
	s_nop 0
	v_permlane32_swap_b32_e32 v2, v4
	v_cvt_pk_bf16_f32 v5, v6, v7
	s_nop 1
	v_permlane32_swap_b32_e32 v3, v5
	global_store_dwordx4 v[10:11], v[2:5], off offset:224

.LBB0_214:
	s_andn2_b64 vcc, exec, s[0:1]
	s_cbranch_vccnz .LBB0_229
	s_sub_i32 s2, s3, 56
	s_lshl_b32 s0, s2, 7
	s_and_b32 s0, s0, 0xf80
	s_or_b32 s6, s65, s0
	s_lshl_b32 s0, s2, 2
	s_and_b32 s4, s0, 0x7fffff80
	s_lshl_b32 s38, s4, 1
	v_readlane_b32 s0, v254, 41
	s_add_u32 s0, s0, s38
	v_readlane_b32 s1, v254, 45
	v_readlane_b32 s5, v254, 37
	v_mov_b32_e32 v30, v228
	s_addc_u32 s1, s1, 0
	s_add_i32 s4, s4, s5
	s_mulk_i32 s4, 0x1100
	v_and_b32_e32 v32, 31, v30
	s_mov_b32 s5, s39
	s_waitcnt vmcnt(0)
	v_ashrrev_i32_e32 v153, 7, v30
	s_lshl_b64 s[4:5], s[4:5], 1
	v_readlane_b32 s7, v254, 29
	v_or_b32_e32 v0, s6, v32
	s_add_u32 s4, s7, s4
	v_readlane_b32 s7, v254, 30
	v_lshl_add_u32 v2, v153, 5, v0
	s_addc_u32 s5, s7, s5
	v_ashrrev_i32_e32 v3, 31, v2
	v_readlane_b32 s6, v254, 50
	v_lshlrev_b64 v[2:3], 10, v[2:3]
	v_readlane_b32 s7, v254, 51
	v_bfe_u32 v162, v30, 6, 1
	v_bfe_u32 v31, v30, 5, 1
	v_lshl_add_u64 v[2:3], s[6:7], 0, v[2:3]
	v_lshl_add_u64 v[150:151], v[2:3], 0, s[38:39]
	v_lshlrev_b32_e32 v0, 7, v162
	v_lshlrev_b32_e32 v4, 4, v30
	v_lshl_add_u64 v[2:3], v[150:151], 0, v[0:1]
	v_lshlrev_b32_e32 v148, 4, v31
	v_mov_b32_e32 v149, v1
	v_ashrrev_i32_e32 v18, 4, v30
	v_and_b32_e32 v156, 0x70, v4
	v_mov_b32_e32 v157, v1
	v_lshl_add_u64 v[2:3], v[2:3], 0, v[148:149]
	v_ashrrev_i32_e32 v33, 3, v30
	v_and_b32_e32 v154, 0xf0, v4
	v_mov_b32_e32 v155, v1
	v_lshl_add_u64 v[14:15], s[4:5], 0, v[156:157]
	v_ashrrev_i32_e32 v19, 31, v18
	s_movk_i32 s6, 0x2200
	global_load_dwordx4 v[124:127], v[2:3], off
	global_load_dwordx4 v[120:123], v[2:3], off offset:32
	global_load_dwordx4 v[116:119], v[2:3], off offset:64
	global_load_dwordx4 v[112:115], v[2:3], off offset:96
	v_lshl_add_u64 v[2:3], s[0:1], 0, v[154:155]
	v_lshlrev_b64 v[20:21], 10, v[18:19]
	v_mad_i64_i32 v[6:7], s[0:1], v33, s6, v[14:15]
	v_lshl_add_u64 v[22:23], v[2:3], 0, v[20:21]
	s_mov_b32 s0, 0x8000
	v_add_co_u32_e32 v10, vcc, s0, v22
	v_add_u32_e32 v19, 64, v33
	s_waitcnt lgkmcnt(0)
	s_barrier
	global_load_dwordx4 v[2:5], v[22:23], off
	s_nop 0
	global_load_dwordx4 v[6:9], v[6:7], off
	v_addc_co_u32_e32 v11, vcc, 0, v23, vcc
	v_mad_i64_i32 v[14:15], s[0:1], v19, s6, v[14:15]
	global_load_dwordx4 v[10:13], v[10:11], off
	s_mov_b32 s0, 0x10000
	global_load_dwordx4 v[14:17], v[14:15], off
	v_mov_b64_e32 v[26:27], s[4:5]
	v_add_co_u32_e32 v24, vcc, s0, v22
	v_mad_i64_i32 v[28:29], s[0:1], v33, s6, v[26:27]
	s_nop 0
	v_addc_co_u32_e32 v25, vcc, 0, v23, vcc
	s_mov_b32 s0, 0x18000
	v_add_co_u32_e32 v22, vcc, s0, v22
	v_lshl_add_u64 v[28:29], v[28:29], 0, v[156:157]
	global_load_dwordx4 v[128:131], v[24:25], off
	global_load_dwordx4 v[132:135], v[28:29], off offset:128
	v_addc_co_u32_e32 v23, vcc, 0, v23, vcc
	v_mad_i64_i32 v[24:25], s[0:1], v19, s6, v[26:27]
	v_lshl_add_u64 v[24:25], v[24:25], 0, v[156:157]
	global_load_dwordx4 v[136:139], v[22:23], off
	global_load_dwordx4 v[140:143], v[24:25], off offset:128
	s_movk_i32 s1, 0x110
	v_mul_lo_u32 v164, v18, s1
	s_movk_i32 s1, 0x88
	v_mul_lo_u32 v165, v33, s1
	v_add3_u32 v18, 0, v154, v164
	v_add3_u32 v19, 0, v156, v165
	v_add_u32_e32 v22, 0x4400, v19
	s_bfe_u32 s1, s2, 0x190005
	s_lshl_b32 s2, s1, 8
	v_readlane_b32 s4, v254, 35
	s_add_u32 s4, s2, s4
	s_waitcnt vmcnt(0)
	ds_write_b128 v18, v[2:5]
	ds_write2_b64 v22, v[6:7], v[8:9] offset1:1
	ds_write_b128 v18, v[10:13] offset:8704
	v_add_u32_e32 v2, 0x6600, v19
	v_and_b32_e32 v3, 64, v231
	v_add_u32_e32 v3, 64, v3
	ds_write2_b64 v2, v[14:15], v[16:17] offset1:1
	v_xor_b32_e32 v2, 32, v231
	v_cmp_lt_i32_e32 vcc, v2, v3
	v_or_b32_e32 v167, v0, v148
	s_addc_u32 s5, 0, 0
	v_cndmask_b32_e32 v2, v231, v2, vcc
	v_and_b32_e32 v0, 15, v30
	v_lshlrev_b32_e32 v149, 2, v2
	v_lshl_add_u64 v[2:3], s[4:5], 0, v[20:21]
	v_lshlrev_b32_e32 v0, 4, v0
	v_lshl_add_u64 v[158:159], v[2:3], 0, v[0:1]
	v_mad_i64_i32 v[2:3], s[4:5], v33, s6, 0
	v_and_b32_e32 v0, 7, v30
	s_mul_i32 s1, s1, 0x88000
	v_readlane_b32 s2, v254, 36
	s_waitcnt lgkmcnt(0)
	s_barrier
	v_lshl_or_b32 v2, v0, 4, v2
	s_add_i32 s38, s2, s1
	v_mov_b32_e32 v14, v1
	v_mov_b32_e32 v15, v1
	v_and_b32_e32 v155, 63, v30
	v_lshlrev_b32_e32 v152, 3, v31
	v_mul_u32_u24_e32 v163, 0x88, v32
	v_mul_u32_u24_e32 v166, 0x110, v32
	v_lshl_add_u64 v[160:161], s[38:39], 1, v[2:3]
	v_mov_b32_e32 v0, v1
	v_mov_b32_e32 v2, v1
	v_mov_b32_e32 v3, v1
	v_mov_b32_e32 v4, v1
	v_mov_b32_e32 v5, v1
	v_mov_b32_e32 v6, v1
	v_mov_b32_e32 v7, v1
	v_mov_b32_e32 v8, v1
	v_mov_b32_e32 v9, v1
	v_mov_b32_e32 v10, v1
	v_mov_b32_e32 v11, v1
	v_mov_b32_e32 v12, v1
	v_mov_b32_e32 v13, v1
	v_mov_b64_e32 v[30:31], v[14:15]
	v_mov_b64_e32 v[46:47], v[14:15]
	v_mov_b64_e32 v[62:63], v[14:15]
	v_mov_b64_e32 v[78:79], v[14:15]
	s_mov_b32 s0, 1
	v_mov_b32_e32 v157, 0xf149f2ca
	v_mov_b32_e32 v168, 0
	v_mov_b64_e32 v[28:29], v[12:13]
	v_mov_b64_e32 v[26:27], v[10:11]
	v_mov_b64_e32 v[24:25], v[8:9]
	v_mov_b64_e32 v[22:23], v[6:7]
	v_mov_b64_e32 v[20:21], v[4:5]
	v_mov_b64_e32 v[18:19], v[2:3]
	v_mov_b64_e32 v[16:17], v[0:1]
	v_mov_b64_e32 v[44:45], v[12:13]
	v_mov_b64_e32 v[42:43], v[10:11]
	v_mov_b64_e32 v[40:41], v[8:9]
	v_mov_b64_e32 v[38:39], v[6:7]
	v_mov_b64_e32 v[36:37], v[4:5]
	v_mov_b64_e32 v[34:35], v[2:3]
	v_mov_b64_e32 v[32:33], v[0:1]
	v_mov_b64_e32 v[60:61], v[12:13]
	v_mov_b64_e32 v[58:59], v[10:11]
	v_mov_b64_e32 v[56:57], v[8:9]
	v_mov_b64_e32 v[54:55], v[6:7]
	v_mov_b64_e32 v[52:53], v[4:5]
	v_mov_b64_e32 v[50:51], v[2:3]
	v_mov_b64_e32 v[48:49], v[0:1]
	v_mov_b64_e32 v[76:77], v[12:13]
	v_mov_b64_e32 v[74:75], v[10:11]
	v_mov_b64_e32 v[72:73], v[8:9]
	v_mov_b64_e32 v[70:71], v[6:7]
	v_mov_b64_e32 v[68:69], v[4:5]
	v_mov_b64_e32 v[66:67], v[2:3]
	v_mov_b64_e32 v[64:65], v[0:1]
	s_mov_b64 s[4:5], 0x10000

.LBB0_220:
	ds_read2_b64 v[212:215], v14 offset0:132 offset1:134
	ds_read2_b64 v[216:219], v15 offset0:164 offset1:166
	ds_read2_b64 v[220:223], v169 offset0:196 offset1:198
	ds_read2_b64 v[224:227], v170 offset0:228 offset1:230
	v_sub_f32_e32 v97, v97, v157
	v_sub_f32_e32 v96, v96, v157
	v_exp_f32_e32 v177, v97
	v_sub_f32_e32 v97, v98, v157
	v_exp_f32_e32 v176, v96
	v_exp_f32_e32 v178, v97
	v_sub_f32_e32 v97, v99, v157
	v_sub_f32_e32 v96, v100, v157
	v_exp_f32_e32 v179, v97
	v_exp_f32_e32 v180, v96
	v_sub_f32_e32 v97, v101, v157
	v_sub_f32_e32 v96, v102, v157
	v_exp_f32_e32 v181, v97
	v_exp_f32_e32 v182, v96
	v_sub_f32_e32 v97, v103, v157
	v_add_f32_e32 v208, v176, v177
	v_exp_f32_e32 v183, v97
	v_add_f32_e32 v208, v178, v208
	v_add_f32_e32 v208, v179, v208
	v_add_f32_e32 v208, v180, v208
	v_add_f32_e32 v208, v181, v208
	v_add_f32_e32 v208, v182, v208
	v_add_f32_e32 v208, v183, v208
	v_cvt_pk_bf16_f32 v176, v176, v177
	v_cvt_pk_bf16_f32 v177, v178, v179
	v_cvt_pk_bf16_f32 v178, v180, v181
	v_cvt_pk_bf16_f32 v179, v182, v183
	s_nop 0
	v_sub_f32_e32 v97, v104, v157
	v_sub_f32_e32 v96, v105, v157
	v_mfma_f32_32x32x16_bf16 v[64:79], v[144:147], v[176:179], v[64:79]
	v_exp_f32_e32 v184, v97
	v_exp_f32_e32 v185, v96
	v_sub_f32_e32 v97, v106, v157
	v_sub_f32_e32 v96, v107, v157
	v_mfma_f32_32x32x16_bf16 v[48:63], v[10:13], v[176:179], v[48:63]
	v_exp_f32_e32 v186, v97
	v_exp_f32_e32 v187, v96
	v_sub_f32_e32 v97, v108, v157
	v_sub_f32_e32 v96, v109, v157
	v_mfma_f32_32x32x16_bf16 v[32:47], v[6:9], v[176:179], v[32:47]
	v_exp_f32_e32 v188, v97
	v_exp_f32_e32 v189, v96
	v_sub_f32_e32 v97, v110, v157
	v_sub_f32_e32 v96, v111, v157
	s_waitcnt lgkmcnt(4)
	v_mfma_f32_32x32x16_bf16 v[16:31], v[2:5], v[176:179], v[16:31]
	v_exp_f32_e32 v190, v97
	v_exp_f32_e32 v191, v96
	ds_read2_b64 v[6:9], v15 offset0:168 offset1:170
	ds_read2_b64 v[10:13], v169 offset0:200 offset1:202
	ds_read2_b64 v[2:5], v170 offset0:232 offset1:234
	v_add_f32_e32 v208, v184, v208
	v_add_f32_e32 v208, v185, v208
	v_add_f32_e32 v208, v186, v208
	v_add_f32_e32 v208, v187, v208
	v_add_f32_e32 v208, v188, v208
	v_add_f32_e32 v208, v189, v208
	v_add_f32_e32 v208, v190, v208
	v_add_f32_e32 v208, v191, v208
	v_cvt_pk_bf16_f32 v144, v184, v185
	v_cvt_pk_bf16_f32 v145, v186, v187
	v_cvt_pk_bf16_f32 v146, v188, v189
	v_cvt_pk_bf16_f32 v147, v190, v191
	v_sub_f32_e32 v97, v80, v157
	v_sub_f32_e32 v96, v81, v157
	s_waitcnt lgkmcnt(3)
	v_mfma_f32_32x32x16_bf16 v[64:79], v[212:215], v[144:147], v[64:79]
	v_exp_f32_e32 v102, v97
	v_exp_f32_e32 v104, v96
	v_sub_f32_e32 v97, v82, v157
	v_sub_f32_e32 v96, v83, v157
	v_mfma_f32_32x32x16_bf16 v[48:63], v[216:219], v[144:147], v[48:63]
	v_exp_f32_e32 v106, v97
	v_exp_f32_e32 v101, v96
	ds_read2_b64 v[80:83], v14 offset0:136 offset1:138
	v_sub_f32_e32 v97, v84, v157
	v_sub_f32_e32 v96, v85, v157
	v_mfma_f32_32x32x16_bf16 v[32:47], v[220:223], v[144:147], v[32:47]
	v_exp_f32_e32 v103, v97
	v_exp_f32_e32 v105, v96
	v_sub_f32_e32 v97, v86, v157
	v_sub_f32_e32 v96, v87, v157
	v_mfma_f32_32x32x16_bf16 v[16:31], v[224:227], v[144:147], v[16:31]
	v_exp_f32_e32 v107, v97
	v_exp_f32_e32 v108, v96
	v_add_f32_e32 v208, v102, v208
	v_add_f32_e32 v208, v104, v208
	v_add_f32_e32 v208, v106, v208
	v_add_f32_e32 v208, v101, v208
	v_add_f32_e32 v208, v103, v208
	v_add_f32_e32 v208, v105, v208
	v_add_f32_e32 v208, v107, v208
	v_add_f32_e32 v208, v108, v208
	v_cvt_pk_bf16_f32 v144, v102, v104
	v_cvt_pk_bf16_f32 v145, v106, v101
	v_cvt_pk_bf16_f32 v146, v103, v105
	v_cvt_pk_bf16_f32 v147, v107, v108
	v_sub_f32_e32 v97, v88, v157
	v_sub_f32_e32 v96, v89, v157
	s_waitcnt lgkmcnt(0)
	v_mfma_f32_32x32x16_bf16 v[64:79], v[80:83], v[144:147], v[64:79]
	v_exp_f32_e32 v109, v97
	v_exp_f32_e32 v110, v96
	v_sub_f32_e32 v97, v90, v157
	v_sub_f32_e32 v96, v91, v157
	v_mfma_f32_32x32x16_bf16 v[48:63], v[6:9], v[144:147], v[48:63]
	v_exp_f32_e32 v111, v97
	v_exp_f32_e32 v171, v96
	v_sub_f32_e32 v97, v92, v157
	v_sub_f32_e32 v96, v93, v157
	v_mfma_f32_32x32x16_bf16 v[32:47], v[10:13], v[144:147], v[32:47]
	v_exp_f32_e32 v172, v97
	v_exp_f32_e32 v173, v96
	v_sub_f32_e32 v97, v94, v157
	v_sub_f32_e32 v96, v95, v157
	v_mfma_f32_32x32x16_bf16 v[16:31], v[2:5], v[144:147], v[16:31]
	v_exp_f32_e32 v174, v97
	v_exp_f32_e32 v175, v96
	ds_read2_b64 v[84:87], v14 offset0:140 offset1:142
	ds_read2_b64 v[88:91], v15 offset0:172 offset1:174
	ds_read2_b64 v[92:95], v169 offset0:204 offset1:206
	ds_read2_b64 v[96:99], v170 offset0:236 offset1:238
	v_add_f32_e32 v208, v109, v208
	v_add_f32_e32 v208, v110, v208
	v_add_f32_e32 v208, v111, v208
	v_add_f32_e32 v208, v171, v208
	v_add_f32_e32 v208, v172, v208
	v_add_f32_e32 v208, v173, v208
	v_add_f32_e32 v208, v174, v208
	v_add_f32_e32 v208, v175, v208
	v_cvt_pk_bf16_f32 v2, v109, v110
	v_cvt_pk_bf16_f32 v3, v111, v171
	v_cvt_pk_bf16_f32 v4, v172, v173
	v_cvt_pk_bf16_f32 v5, v174, v175
	s_mov_b64 s[6:7], 0x80
	v_lshl_add_u64 v[158:159], v[158:159], 0, s[4:5]
	v_lshl_add_u64 v[160:161], v[160:161], 0, s[6:7]
	s_waitcnt lgkmcnt(0)
	s_barrier
	v_mfma_f32_32x32x16_bf16 v[64:79], v[84:87], v[2:5], v[64:79]
	v_mfma_f32_32x32x16_bf16 v[48:63], v[88:91], v[2:5], v[48:63]
	v_mfma_f32_32x32x16_bf16 v[32:47], v[92:95], v[2:5], v[32:47]
	v_mfma_f32_32x32x16_bf16 v[16:31], v[96:99], v[2:5], v[16:31]
	v_mov_b32_e32 v14, v208
	s_add_i32 s0, s0, 1
	s_cmpk_eq_i32 s0, 0x44
	v_fmac_f32_e32 v14, v168, v0
	s_cbranch_scc1 .LBB0_222
	v_mov_b32_e32 v168, v14
	s_branch .LBB0_216

.LBB0_226:
	s_or_b64 exec, exec, s[4:5]
	s_waitcnt lgkmcnt(0)
	s_barrier
	s_and_saveexec_b64 s[0:1], vcc
	s_cbranch_execz .LBB0_228
	v_readlane_b32 s4, v255, 2
	v_readlane_b32 s5, v255, 3
	v_lshlrev_b32_e32 v0, 14, v153
	s_nop 0
	v_mov_b64_e32 v[2:3], s[4:5]
	global_load_dword v84, v[2:3], off
	v_lshlrev_b32_e32 v2, 2, v155
	v_add3_u32 v0, 0, v0, v2
	s_waitcnt vmcnt(0)
	ds_read2st64_b32 v[142:143], v0 offset1:1
	ds_read2st64_b32 v[6:7], v0 offset0:2 offset1:3
	ds_read2st64_b32 v[8:9], v0 offset0:4 offset1:5
	ds_read2st64_b32 v[2:3], v0 offset0:6 offset1:7
	ds_read2st64_b32 v[134:135], v0 offset0:8 offset1:9
	ds_read2st64_b32 v[136:137], v0 offset0:10 offset1:11
	ds_read2st64_b32 v[138:139], v0 offset0:12 offset1:13
	ds_read2st64_b32 v[140:141], v0 offset0:14 offset1:15
	ds_read2st64_b32 v[122:123], v0 offset0:16 offset1:17
	ds_read2st64_b32 v[124:125], v0 offset0:18 offset1:19
	ds_read2st64_b32 v[126:127], v0 offset0:20 offset1:21
	ds_read2st64_b32 v[128:129], v0 offset0:22 offset1:23
	ds_read2st64_b32 v[114:115], v0 offset0:24 offset1:25
	ds_read2st64_b32 v[116:117], v0 offset0:26 offset1:27
	ds_read2st64_b32 v[118:119], v0 offset0:28 offset1:29
	ds_read2st64_b32 v[120:121], v0 offset0:30 offset1:31
	ds_read2st64_b32 v[106:107], v0 offset0:32 offset1:33
	ds_read2st64_b32 v[108:109], v0 offset0:34 offset1:35
	ds_read2st64_b32 v[110:111], v0 offset0:36 offset1:37
	ds_read2st64_b32 v[112:113], v0 offset0:38 offset1:39
	ds_read2st64_b32 v[98:99], v0 offset0:40 offset1:41
	ds_read2st64_b32 v[100:101], v0 offset0:42 offset1:43
	ds_read2st64_b32 v[102:103], v0 offset0:44 offset1:45
	ds_read2st64_b32 v[104:105], v0 offset0:46 offset1:47
	ds_read2st64_b32 v[90:91], v0 offset0:48 offset1:49
	ds_read2st64_b32 v[92:93], v0 offset0:50 offset1:51
	ds_read2st64_b32 v[94:95], v0 offset0:52 offset1:53
	ds_read2st64_b32 v[96:97], v0 offset0:54 offset1:55
	ds_read2st64_b32 v[86:87], v0 offset0:56 offset1:57
	ds_read2st64_b32 v[88:89], v0 offset0:58 offset1:59
	ds_read2st64_b32 v[4:5], v0 offset0:60 offset1:61
	v_readlane_b32 s4, v255, 4
	v_readlane_b32 s5, v255, 5
	s_waitcnt lgkmcnt(0)
	v_pk_mul_f32 v[4:5], v[84:85], v[4:5] op_sel_hi:[0,1]
	v_pk_fma_f32 v[14:15], v[28:29], v[80:81], v[4:5] op_sel_hi:[1,0,1] neg_lo:[0,0,1] neg_hi:[0,0,1]
	ds_read2st64_b32 v[4:5], v0 offset0:62 offset1:63
	v_pk_mul_f32 v[142:143], v[84:85], v[142:143] op_sel_hi:[0,1]
	v_pk_mul_f32 v[6:7], v[84:85], v[6:7] op_sel_hi:[0,1]
	v_pk_fma_f32 v[142:143], v[64:65], v[80:81], v[142:143] op_sel_hi:[1,0,1] neg_lo:[0,0,1] neg_hi:[0,0,1]
	v_lshlrev_b32_e32 v0, 1, v152
	s_waitcnt lgkmcnt(0)
	v_pk_mul_f32 v[4:5], v[84:85], v[4:5] op_sel_hi:[0,1]
	v_pk_mul_f32 v[2:3], v[84:85], v[2:3] op_sel_hi:[0,1]
	v_pk_mul_f32 v[8:9], v[84:85], v[8:9] op_sel_hi:[0,1]
	v_pk_fma_f32 v[66:67], v[66:67], v[80:81], v[6:7] op_sel_hi:[1,0,1] neg_lo:[0,0,1] neg_hi:[0,0,1]
	v_pk_mul_f32 v[144:145], v[142:143], v[142:143]
	v_pk_fma_f32 v[12:13], v[30:31], v[80:81], v[4:5] op_sel_hi:[1,0,1] neg_lo:[0,0,1] neg_hi:[0,0,1]
	v_lshl_add_u64 v[10:11], v[150:151], 0, v[0:1]
	v_pk_fma_f32 v[28:29], v[70:71], v[80:81], v[2:3] op_sel_hi:[1,0,1] neg_lo:[0,0,1] neg_hi:[0,0,1]
	global_load_dwordx4 v[2:5], v148, s[4:5] offset:32
	v_pk_fma_f32 v[68:69], v[68:69], v[80:81], v[8:9] op_sel_hi:[1,0,1] neg_lo:[0,0,1] neg_hi:[0,0,1]
	v_pk_mul_f32 v[132:133], v[66:67], v[66:67]
	global_load_dwordx4 v[6:9], v148, s[4:5]
	v_add_f32_e32 v0, v144, v145
	v_pk_mul_f32 v[64:65], v[84:85], v[140:141] op_sel_hi:[0,1]
	v_add_f32_e32 v0, v0, v132
	v_pk_mul_f32 v[130:131], v[68:69], v[68:69]
	v_pk_fma_f32 v[64:65], v[78:79], v[80:81], v[64:65] op_sel_hi:[1,0,1] neg_lo:[0,0,1] neg_hi:[0,0,1]
	v_pk_mul_f32 v[78:79], v[84:85], v[138:139] op_sel_hi:[0,1]
	v_add_f32_e32 v0, v0, v133
	v_pk_fma_f32 v[76:77], v[76:77], v[80:81], v[78:79] op_sel_hi:[1,0,1] neg_lo:[0,0,1] neg_hi:[0,0,1]
	v_pk_mul_f32 v[78:79], v[84:85], v[136:137] op_sel_hi:[0,1]
	v_add_f32_e32 v0, v0, v130
	v_pk_mul_f32 v[70:71], v[28:29], v[28:29]
	v_pk_fma_f32 v[78:79], v[74:75], v[80:81], v[78:79] op_sel_hi:[1,0,1] neg_lo:[0,0,1] neg_hi:[0,0,1]
	v_pk_mul_f32 v[74:75], v[84:85], v[134:135] op_sel_hi:[0,1]
	v_add_f32_e32 v0, v0, v131
	v_pk_fma_f32 v[134:135], v[72:73], v[80:81], v[74:75] op_sel_hi:[1,0,1] neg_lo:[0,0,1] neg_hi:[0,0,1]
	v_add_f32_e32 v0, v0, v70
	v_pk_mul_f32 v[146:147], v[134:135], v[134:135]
	v_add_f32_e32 v0, v0, v71
	v_add_f32_e32 v0, v0, v146
	v_pk_mul_f32 v[136:137], v[78:79], v[78:79]
	v_add_f32_e32 v0, v0, v147
	v_pk_mul_f32 v[72:73], v[84:85], v[128:129] op_sel_hi:[0,1]
	v_add_f32_e32 v0, v0, v136
	v_pk_mul_f32 v[138:139], v[76:77], v[76:77]
	v_pk_fma_f32 v[54:55], v[54:55], v[80:81], v[72:73] op_sel_hi:[1,0,1] neg_lo:[0,0,1] neg_hi:[0,0,1]
	v_pk_mul_f32 v[72:73], v[84:85], v[126:127] op_sel_hi:[0,1]
	v_add_f32_e32 v0, v0, v137
	v_pk_fma_f32 v[52:53], v[52:53], v[80:81], v[72:73] op_sel_hi:[1,0,1] neg_lo:[0,0,1] neg_hi:[0,0,1]
	v_pk_mul_f32 v[72:73], v[84:85], v[124:125] op_sel_hi:[0,1]
	v_add_f32_e32 v0, v0, v138
	v_pk_mul_f32 v[140:141], v[64:65], v[64:65]
	v_pk_fma_f32 v[72:73], v[50:51], v[80:81], v[72:73] op_sel_hi:[1,0,1] neg_lo:[0,0,1] neg_hi:[0,0,1]
	v_pk_mul_f32 v[50:51], v[84:85], v[122:123] op_sel_hi:[0,1]
	v_add_f32_e32 v0, v0, v139
	v_pk_fma_f32 v[74:75], v[48:49], v[80:81], v[50:51] op_sel_hi:[1,0,1] neg_lo:[0,0,1] neg_hi:[0,0,1]
	v_add_f32_e32 v0, v0, v140
	v_pk_mul_f32 v[122:123], v[74:75], v[74:75]
	v_add_f32_e32 v0, v0, v141
	v_add_f32_e32 v0, v0, v122
	v_pk_mul_f32 v[124:125], v[72:73], v[72:73]
	v_add_f32_e32 v0, v0, v123
	v_pk_mul_f32 v[48:49], v[84:85], v[120:121] op_sel_hi:[0,1]
	v_add_f32_e32 v0, v0, v124
	v_pk_mul_f32 v[126:127], v[52:53], v[52:53]
	v_pk_fma_f32 v[50:51], v[62:63], v[80:81], v[48:49] op_sel_hi:[1,0,1] neg_lo:[0,0,1] neg_hi:[0,0,1]
	v_pk_mul_f32 v[48:49], v[84:85], v[118:119] op_sel_hi:[0,1]
	v_add_f32_e32 v0, v0, v125
	v_pk_fma_f32 v[62:63], v[60:61], v[80:81], v[48:49] op_sel_hi:[1,0,1] neg_lo:[0,0,1] neg_hi:[0,0,1]
	v_pk_mul_f32 v[48:49], v[84:85], v[116:117] op_sel_hi:[0,1]
	v_add_f32_e32 v0, v0, v126
	v_pk_mul_f32 v[128:129], v[54:55], v[54:55]
	v_pk_fma_f32 v[116:117], v[58:59], v[80:81], v[48:49] op_sel_hi:[1,0,1] neg_lo:[0,0,1] neg_hi:[0,0,1]
	v_pk_mul_f32 v[48:49], v[84:85], v[114:115] op_sel_hi:[0,1]
	v_add_f32_e32 v0, v0, v127
	v_pk_fma_f32 v[114:115], v[56:57], v[80:81], v[48:49] op_sel_hi:[1,0,1] neg_lo:[0,0,1] neg_hi:[0,0,1]
	v_add_f32_e32 v0, v0, v128
	v_pk_mul_f32 v[152:153], v[114:115], v[114:115]
	v_add_f32_e32 v0, v0, v129
	v_add_f32_e32 v0, v0, v152
	v_pk_mul_f32 v[150:151], v[116:117], v[116:117]
	v_add_f32_e32 v0, v0, v153
	v_pk_mul_f32 v[48:49], v[84:85], v[112:113] op_sel_hi:[0,1]
	v_add_f32_e32 v0, v0, v150
	v_pk_mul_f32 v[118:119], v[62:63], v[62:63]
	v_pk_fma_f32 v[48:49], v[38:39], v[80:81], v[48:49] op_sel_hi:[1,0,1] neg_lo:[0,0,1] neg_hi:[0,0,1]
	v_pk_mul_f32 v[38:39], v[84:85], v[110:111] op_sel_hi:[0,1]
	v_add_f32_e32 v0, v0, v151
	v_pk_fma_f32 v[56:57], v[36:37], v[80:81], v[38:39] op_sel_hi:[1,0,1] neg_lo:[0,0,1] neg_hi:[0,0,1]
	v_pk_mul_f32 v[36:37], v[84:85], v[108:109] op_sel_hi:[0,1]
	v_add_f32_e32 v0, v0, v118
	v_pk_mul_f32 v[120:121], v[50:51], v[50:51]
	v_pk_fma_f32 v[58:59], v[34:35], v[80:81], v[36:37] op_sel_hi:[1,0,1] neg_lo:[0,0,1] neg_hi:[0,0,1]
	v_pk_mul_f32 v[34:35], v[84:85], v[106:107] op_sel_hi:[0,1]
	v_add_f32_e32 v0, v0, v119
	v_pk_fma_f32 v[60:61], v[32:33], v[80:81], v[34:35] op_sel_hi:[1,0,1] neg_lo:[0,0,1] neg_hi:[0,0,1]
	v_add_f32_e32 v0, v0, v120
	v_pk_mul_f32 v[106:107], v[60:61], v[60:61]
	v_add_f32_e32 v0, v0, v121
	v_add_f32_e32 v0, v0, v106
	v_pk_mul_f32 v[108:109], v[58:59], v[58:59]
	v_add_f32_e32 v0, v0, v107
	v_add_f32_e32 v0, v0, v108
	v_pk_mul_f32 v[110:111], v[56:57], v[56:57]
	v_pk_mul_f32 v[34:35], v[84:85], v[102:103] op_sel_hi:[0,1]
	v_add_f32_e32 v0, v0, v109
	v_pk_fma_f32 v[38:39], v[44:45], v[80:81], v[34:35] op_sel_hi:[1,0,1] neg_lo:[0,0,1] neg_hi:[0,0,1]
	v_pk_mul_f32 v[34:35], v[84:85], v[100:101] op_sel_hi:[0,1]
	v_add_f32_e32 v0, v0, v110
	v_pk_mul_f32 v[112:113], v[48:49], v[48:49]
	v_pk_fma_f32 v[42:43], v[42:43], v[80:81], v[34:35] op_sel_hi:[1,0,1] neg_lo:[0,0,1] neg_hi:[0,0,1]
	v_pk_mul_f32 v[34:35], v[84:85], v[98:99] op_sel_hi:[0,1]
	v_add_f32_e32 v0, v0, v111
	v_pk_fma_f32 v[40:41], v[40:41], v[80:81], v[34:35] op_sel_hi:[1,0,1] neg_lo:[0,0,1] neg_hi:[0,0,1]
	v_add_f32_e32 v0, v0, v112
	v_pk_mul_f32 v[98:99], v[40:41], v[40:41]
	v_add_f32_e32 v0, v0, v113
	v_add_f32_e32 v0, v0, v98
	v_pk_mul_f32 v[100:101], v[42:43], v[42:43]
	v_add_f32_e32 v0, v0, v99
	v_pk_mul_f32 v[34:35], v[84:85], v[96:97] op_sel_hi:[0,1]
	v_add_f32_e32 v0, v0, v100
	v_pk_mul_f32 v[32:33], v[84:85], v[104:105] op_sel_hi:[0,1]
	v_pk_mul_f32 v[44:45], v[38:39], v[38:39]
	v_pk_fma_f32 v[22:23], v[22:23], v[80:81], v[34:35] op_sel_hi:[1,0,1] neg_lo:[0,0,1] neg_hi:[0,0,1]
	v_pk_mul_f32 v[34:35], v[84:85], v[94:95] op_sel_hi:[0,1]
	v_add_f32_e32 v0, v0, v101
	v_pk_fma_f32 v[32:33], v[46:47], v[80:81], v[32:33] op_sel_hi:[1,0,1] neg_lo:[0,0,1] neg_hi:[0,0,1]
	v_pk_fma_f32 v[20:21], v[20:21], v[80:81], v[34:35] op_sel_hi:[1,0,1] neg_lo:[0,0,1] neg_hi:[0,0,1]
	v_pk_mul_f32 v[34:35], v[84:85], v[92:93] op_sel_hi:[0,1]
	v_add_f32_e32 v0, v0, v44
	v_pk_mul_f32 v[46:47], v[32:33], v[32:33]
	v_pk_fma_f32 v[34:35], v[18:19], v[80:81], v[34:35] op_sel_hi:[1,0,1] neg_lo:[0,0,1] neg_hi:[0,0,1]
	v_pk_mul_f32 v[18:19], v[84:85], v[90:91] op_sel_hi:[0,1]
	v_add_f32_e32 v0, v0, v45
	v_pk_fma_f32 v[36:37], v[16:17], v[80:81], v[18:19] op_sel_hi:[1,0,1] neg_lo:[0,0,1] neg_hi:[0,0,1]
	v_add_f32_e32 v0, v0, v46
	v_pk_mul_f32 v[90:91], v[36:37], v[36:37]
	v_add_f32_e32 v0, v0, v47
	v_add_f32_e32 v0, v0, v90
	v_pk_mul_f32 v[92:93], v[34:35], v[34:35]
	v_add_f32_e32 v0, v0, v91
	v_add_f32_e32 v0, v0, v92
	v_pk_mul_f32 v[94:95], v[20:21], v[20:21]
	v_add_f32_e32 v0, v0, v93
	v_add_f32_e32 v0, v0, v94
	v_pk_mul_f32 v[96:97], v[22:23], v[22:23]
	v_pk_mul_f32 v[18:19], v[84:85], v[86:87] op_sel_hi:[0,1]
	v_add_f32_e32 v0, v0, v95
	v_pk_fma_f32 v[18:19], v[24:25], v[80:81], v[18:19] op_sel_hi:[1,0,1] neg_lo:[0,0,1] neg_hi:[0,0,1]
	v_add_f32_e32 v0, v0, v96
	v_pk_mul_f32 v[16:17], v[84:85], v[88:89] op_sel_hi:[0,1]
	v_pk_mul_f32 v[24:25], v[18:19], v[18:19]
	v_add_f32_e32 v0, v0, v97
	v_pk_fma_f32 v[16:17], v[26:27], v[80:81], v[16:17] op_sel_hi:[1,0,1] neg_lo:[0,0,1] neg_hi:[0,0,1]
	v_add_f32_e32 v0, v0, v24
	v_pk_mul_f32 v[26:27], v[16:17], v[16:17]
	v_add_f32_e32 v0, v0, v25
	v_add_f32_e32 v0, v0, v26
	v_pk_mul_f32 v[82:83], v[14:15], v[14:15]
	v_add_f32_e32 v0, v0, v27
	v_add_f32_e32 v0, v0, v82
	v_pk_mul_f32 v[30:31], v[12:13], v[12:13]
	v_add_f32_e32 v0, v0, v83
	v_add_f32_e32 v0, v0, v30
	v_add_f32_e32 v0, v0, v31
	ds_bpermute_b32 v24, v149, v0
	s_waitcnt lgkmcnt(0)
	v_add_f32_e32 v0, v0, v24
	v_fmamk_f32 v0, v0, 0x3c000000, v230
	v_cmp_gt_f32_e32 vcc, s95, v0
	v_mul_f32_e32 v24, 0x4b800000, v0
	s_nop 0
	v_cndmask_b32_e32 v0, v0, v24, vcc
	v_rsq_f32_e32 v0, v0
	s_nop 0
	v_mul_f32_e32 v24, 0x45800000, v0
	v_cndmask_b32_e32 v0, v0, v24, vcc
	v_mul_f32_e32 v0, v198, v0
	v_pk_mul_f32 v[24:25], v[142:143], v[0:1] op_sel_hi:[1,0]
	s_waitcnt vmcnt(0)
	v_pk_mul_f32 v[6:7], v[6:7], v[24:25]
	v_pk_mul_f32 v[24:25], v[66:67], v[0:1] op_sel_hi:[1,0]
	v_cvt_pk_bf16_f32 v6, v6, v7
	v_pk_mul_f32 v[8:9], v[8:9], v[24:25]
	s_nop 0
	v_cvt_pk_bf16_f32 v7, v8, v9
	v_pk_mul_f32 v[8:9], v[68:69], v[0:1] op_sel_hi:[1,0]
	s_nop 0
	v_pk_mul_f32 v[2:3], v[2:3], v[8:9]
	s_nop 0
	v_cvt_pk_bf16_f32 v8, v2, v3
	v_pk_mul_f32 v[2:3], v[28:29], v[0:1] op_sel_hi:[1,0]
	s_nop 0
	v_permlane32_swap_b32_e32 v6, v8
	v_pk_mul_f32 v[2:3], v[4:5], v[2:3]
	s_nop 0
	v_cvt_pk_bf16_f32 v9, v2, v3
	s_nop 1
	v_permlane32_swap_b32_e32 v7, v9
	global_store_dwordx4 v[10:11], v[6:9], off
	global_load_dwordx4 v[2:5], v148, s[4:5] offset:64
	s_nop 0
	v_pk_mul_f32 v[6:7], v[134:135], v[0:1] op_sel_hi:[1,0]
	v_pk_mul_f32 v[8:9], v[76:77], v[0:1] op_sel_hi:[1,0]
	s_waitcnt vmcnt(0)
	v_pk_mul_f32 v[2:3], v[2:3], v[6:7]
	v_pk_mul_f32 v[6:7], v[78:79], v[0:1] op_sel_hi:[1,0]
	v_cvt_pk_bf16_f32 v2, v2, v3
	v_pk_mul_f32 v[4:5], v[6:7], v[4:5]
	s_nop 0
	v_cvt_pk_bf16_f32 v3, v4, v5
	global_load_dwordx4 v[4:7], v148, s[4:5] offset:96
	s_waitcnt vmcnt(0)
	v_pk_mul_f32 v[4:5], v[8:9], v[4:5]
	v_pk_mul_f32 v[8:9], v[64:65], v[0:1] op_sel_hi:[1,0]
	v_cvt_pk_bf16_f32 v4, v4, v5
	v_pk_mul_f32 v[6:7], v[8:9], v[6:7]
	s_nop 0
	v_permlane32_swap_b32_e32 v2, v4
	v_cvt_pk_bf16_f32 v5, v6, v7
	s_nop 1
	v_permlane32_swap_b32_e32 v3, v5
	global_store_dwordx4 v[10:11], v[2:5], off offset:32
	global_load_dwordx4 v[2:5], v148, s[4:5] offset:128
	v_pk_mul_f32 v[6:7], v[74:75], v[0:1] op_sel_hi:[1,0]
	v_pk_mul_f32 v[8:9], v[52:53], v[0:1] op_sel_hi:[1,0]
	s_waitcnt vmcnt(0)
	v_pk_mul_f32 v[2:3], v[6:7], v[2:3]
	v_pk_mul_f32 v[6:7], v[72:73], v[0:1] op_sel_hi:[1,0]
	v_cvt_pk_bf16_f32 v2, v2, v3
	v_pk_mul_f32 v[4:5], v[6:7], v[4:5]
	s_nop 0
	v_cvt_pk_bf16_f32 v3, v4, v5
	global_load_dwordx4 v[4:7], v148, s[4:5] offset:160
	s_waitcnt vmcnt(0)
	v_pk_mul_f32 v[4:5], v[8:9], v[4:5]
	v_pk_mul_f32 v[8:9], v[54:55], v[0:1] op_sel_hi:[1,0]
	v_cvt_pk_bf16_f32 v4, v4, v5
	v_pk_mul_f32 v[6:7], v[8:9], v[6:7]
	s_nop 0
	v_permlane32_swap_b32_e32 v2, v4
	v_cvt_pk_bf16_f32 v5, v6, v7
	s_nop 1
	v_permlane32_swap_b32_e32 v3, v5
	global_store_dwordx4 v[10:11], v[2:5], off offset:64
	global_load_dwordx4 v[2:5], v148, s[4:5] offset:192
	v_pk_mul_f32 v[6:7], v[114:115], v[0:1] op_sel_hi:[1,0]
	v_pk_mul_f32 v[8:9], v[62:63], v[0:1] op_sel_hi:[1,0]
	s_waitcnt vmcnt(0)
	v_pk_mul_f32 v[2:3], v[6:7], v[2:3]
	v_pk_mul_f32 v[6:7], v[116:117], v[0:1] op_sel_hi:[1,0]
	v_cvt_pk_bf16_f32 v2, v2, v3
	v_pk_mul_f32 v[4:5], v[6:7], v[4:5]
	s_nop 0
	v_cvt_pk_bf16_f32 v3, v4, v5
	global_load_dwordx4 v[4:7], v148, s[4:5] offset:224
	s_waitcnt vmcnt(0)
	v_pk_mul_f32 v[4:5], v[8:9], v[4:5]
	v_pk_mul_f32 v[8:9], v[50:51], v[0:1] op_sel_hi:[1,0]
	v_cvt_pk_bf16_f32 v4, v4, v5
	v_pk_mul_f32 v[6:7], v[8:9], v[6:7]
	s_nop 0
	v_permlane32_swap_b32_e32 v2, v4
	v_cvt_pk_bf16_f32 v5, v6, v7
	s_nop 1
	v_permlane32_swap_b32_e32 v3, v5
	global_store_dwordx4 v[10:11], v[2:5], off offset:96
	global_load_dwordx4 v[2:5], v148, s[4:5] offset:256
	v_pk_mul_f32 v[6:7], v[60:61], v[0:1] op_sel_hi:[1,0]
	v_pk_mul_f32 v[8:9], v[56:57], v[0:1] op_sel_hi:[1,0]
	s_waitcnt vmcnt(0)
	v_pk_mul_f32 v[2:3], v[6:7], v[2:3]
	v_pk_mul_f32 v[6:7], v[58:59], v[0:1] op_sel_hi:[1,0]
	v_cvt_pk_bf16_f32 v2, v2, v3
	v_pk_mul_f32 v[4:5], v[6:7], v[4:5]
	s_nop 0
	v_cvt_pk_bf16_f32 v3, v4, v5
	global_load_dwordx4 v[4:7], v148, s[4:5] offset:288
	s_waitcnt vmcnt(0)
	v_pk_mul_f32 v[4:5], v[8:9], v[4:5]
	v_pk_mul_f32 v[8:9], v[48:49], v[0:1] op_sel_hi:[1,0]
	v_cvt_pk_bf16_f32 v4, v4, v5
	v_pk_mul_f32 v[6:7], v[8:9], v[6:7]
	s_nop 0
	v_permlane32_swap_b32_e32 v2, v4
	v_cvt_pk_bf16_f32 v5, v6, v7
	s_nop 1
	v_permlane32_swap_b32_e32 v3, v5
	global_store_dwordx4 v[10:11], v[2:5], off offset:128
	global_load_dwordx4 v[2:5], v148, s[4:5] offset:320
	v_pk_mul_f32 v[6:7], v[40:41], v[0:1] op_sel_hi:[1,0]
	v_pk_mul_f32 v[8:9], v[38:39], v[0:1] op_sel_hi:[1,0]
	s_waitcnt vmcnt(0)
	v_pk_mul_f32 v[2:3], v[6:7], v[2:3]
	v_pk_mul_f32 v[6:7], v[42:43], v[0:1] op_sel_hi:[1,0]
	v_cvt_pk_bf16_f32 v2, v2, v3
	v_pk_mul_f32 v[4:5], v[6:7], v[4:5]
	s_nop 0
	v_cvt_pk_bf16_f32 v3, v4, v5
	global_load_dwordx4 v[4:7], v148, s[4:5] offset:352
	s_waitcnt vmcnt(0)
	v_pk_mul_f32 v[4:5], v[8:9], v[4:5]
	v_pk_mul_f32 v[8:9], v[32:33], v[0:1] op_sel_hi:[1,0]
	v_cvt_pk_bf16_f32 v4, v4, v5
	v_pk_mul_f32 v[6:7], v[8:9], v[6:7]
	s_nop 0
	v_permlane32_swap_b32_e32 v2, v4
	v_cvt_pk_bf16_f32 v5, v6, v7
	s_nop 1
	v_permlane32_swap_b32_e32 v3, v5
	global_store_dwordx4 v[10:11], v[2:5], off offset:160
	global_load_dwordx4 v[2:5], v148, s[4:5] offset:384
	v_pk_mul_f32 v[6:7], v[36:37], v[0:1] op_sel_hi:[1,0]
	v_pk_mul_f32 v[8:9], v[20:21], v[0:1] op_sel_hi:[1,0]
	s_waitcnt vmcnt(0)
	v_pk_mul_f32 v[2:3], v[6:7], v[2:3]
	v_pk_mul_f32 v[6:7], v[34:35], v[0:1] op_sel_hi:[1,0]
	v_cvt_pk_bf16_f32 v2, v2, v3
	v_pk_mul_f32 v[4:5], v[6:7], v[4:5]
	s_nop 0
	v_cvt_pk_bf16_f32 v3, v4, v5
	global_load_dwordx4 v[4:7], v148, s[4:5] offset:416
	s_waitcnt vmcnt(0)
	v_pk_mul_f32 v[4:5], v[8:9], v[4:5]
	v_pk_mul_f32 v[8:9], v[22:23], v[0:1] op_sel_hi:[1,0]
	v_cvt_pk_bf16_f32 v4, v4, v5
	v_pk_mul_f32 v[6:7], v[8:9], v[6:7]
	s_nop 0
	v_permlane32_swap_b32_e32 v2, v4
	v_cvt_pk_bf16_f32 v5, v6, v7
	s_nop 1
	v_permlane32_swap_b32_e32 v3, v5
	global_store_dwordx4 v[10:11], v[2:5], off offset:192
	global_load_dwordx4 v[2:5], v148, s[4:5] offset:448
	v_pk_mul_f32 v[6:7], v[18:19], v[0:1] op_sel_hi:[1,0]
	v_pk_mul_f32 v[8:9], v[14:15], v[0:1] op_sel_hi:[1,0]
	s_waitcnt vmcnt(0)
	v_pk_mul_f32 v[2:3], v[6:7], v[2:3]
	v_pk_mul_f32 v[6:7], v[16:17], v[0:1] op_sel_hi:[1,0]
	v_cvt_pk_bf16_f32 v2, v2, v3
	v_pk_mul_f32 v[4:5], v[6:7], v[4:5]
	s_nop 0
	v_cvt_pk_bf16_f32 v3, v4, v5
	global_load_dwordx4 v[4:7], v148, s[4:5] offset:480
	s_waitcnt vmcnt(0)
	v_pk_mul_f32 v[4:5], v[8:9], v[4:5]
	v_pk_mul_f32 v[8:9], v[12:13], v[0:1] op_sel_hi:[1,0]
	v_cvt_pk_bf16_f32 v4, v4, v5
	v_pk_mul_f32 v[6:7], v[8:9], v[6:7]
	s_nop 0
	v_permlane32_swap_b32_e32 v2, v4
	v_cvt_pk_bf16_f32 v5, v6, v7
	s_nop 1
	v_permlane32_swap_b32_e32 v3, v5
	global_store_dwordx4 v[10:11], v[2:5], off offset:224

.LBB0_257:
	s_movk_i32 s0, 0x100
	v_cmp_gt_u32_e32 vcc, s0, v98
	s_and_saveexec_b64 s[0:1], vcc
	s_cbranch_execz .LBB0_259
	s_lshl_b32 s4, s64, 2
	v_readlane_b32 s6, v254, 23
	v_readlane_b32 s7, v254, 24
	s_add_u32 s4, s4, s6
	s_addc_u32 s5, 0, s7
	s_lshl_b32 s2, s2, 17
	s_lshl_b32 s6, s93, 15
	s_lshl_b64 s[4:5], s[4:5], 18
	s_or_b32 s2, s6, s2
	v_readlane_b32 s6, v254, 39
	s_add_u32 s4, s6, s4
	v_readlane_b32 s6, v254, 43
	s_addc_u32 s5, s6, s5
	s_add_u32 s4, s4, s2
	v_lshlrev_b32_e32 v0, 9, v99
	s_addc_u32 s5, s5, 0
	v_or3_b32 v0, v0, v114, v116
	v_lshl_add_u64 v[34:35], v[0:1], 2, s[4:5]
	s_movk_i32 s2, 0x1000
	global_store_dword v[34:35], v18, off
	global_store_dword v[34:35], v19, off offset:512
	global_store_dword v[34:35], v20, off offset:1024
	global_store_dword v[34:35], v21, off offset:1536
	v_add_co_u32_e32 v18, vcc, s2, v34
	s_nop 1
	v_addc_co_u32_e32 v19, vcc, 0, v35, vcc
	global_store_dword v[18:19], v22, off
	global_store_dword v[18:19], v23, off offset:512
	global_store_dword v[18:19], v24, off offset:1024
	global_store_dword v[18:19], v25, off offset:1536
	v_add_co_u32_e32 v18, vcc, s82, v34
	s_nop 1
	v_addc_co_u32_e32 v19, vcc, 0, v35, vcc
	global_store_dword v[18:19], v26, off
	global_store_dword v[18:19], v27, off offset:512
	global_store_dword v[18:19], v28, off offset:1024
	global_store_dword v[18:19], v29, off offset:1536
	v_add_co_u32_e32 v18, vcc, 0x3000, v34
	s_nop 1
	v_addc_co_u32_e32 v19, vcc, 0, v35, vcc
	global_store_dword v[18:19], v30, off
	global_store_dword v[18:19], v31, off offset:512
	global_store_dword v[18:19], v32, off offset:1024
	global_store_dword v[18:19], v33, off offset:1536
	v_add_co_u32_e32 v18, vcc, 0x4000, v34
	s_nop 1
	v_addc_co_u32_e32 v19, vcc, 0, v35, vcc
	global_store_dword v[18:19], v2, off
	global_store_dword v[18:19], v3, off offset:512
	global_store_dword v[18:19], v4, off offset:1024
	global_store_dword v[18:19], v5, off offset:1536
	v_add_co_u32_e32 v2, vcc, 0x5000, v34
	s_nop 1
	v_addc_co_u32_e32 v3, vcc, 0, v35, vcc
	global_store_dword v[2:3], v6, off
	global_store_dword v[2:3], v7, off offset:512
	global_store_dword v[2:3], v8, off offset:1024
	global_store_dword v[2:3], v9, off offset:1536
	v_add_co_u32_e32 v2, vcc, 0x6000, v34
	s_nop 1
	v_addc_co_u32_e32 v3, vcc, 0, v35, vcc
	global_store_dword v[2:3], v10, off
	global_store_dword v[2:3], v11, off offset:512
	global_store_dword v[2:3], v12, off offset:1024
	global_store_dword v[2:3], v13, off offset:1536
	v_add_co_u32_e32 v2, vcc, 0x7000, v34
	s_nop 1
	v_addc_co_u32_e32 v3, vcc, 0, v35, vcc
	global_store_dword v[2:3], v14, off
	global_store_dword v[2:3], v15, off offset:512
	global_store_dword v[2:3], v16, off offset:1024
	global_store_dword v[2:3], v17, off offset:1536

.LBB0_284:
	v_ashrrev_i32_e32 v0, 1, v199
	v_and_b32_e32 v0, 0xffffffc0, v0
	s_waitcnt vmcnt(5)
	s_nop 0
	v_pk_add_f32 v[130:131], v[50:51], v[114:115]
	v_pk_add_f32 v[50:51], v[50:51], v[114:115] neg_lo:[0,1] neg_hi:[0,1]
	v_pk_add_f32 v[114:115], v[52:53], v[116:117]
	v_pk_add_f32 v[52:53], v[52:53], v[116:117] neg_lo:[0,1] neg_hi:[0,1]
	v_lshl_add_u32 v116, s7, 8, v0
	v_and_or_b32 v117, v199, 31, v116
	s_waitcnt vmcnt(4)
	v_pk_add_f32 v[136:137], v[56:57], v[120:121]
	s_waitcnt vmcnt(3)
	v_pk_add_f32 v[138:139], v[56:57], v[120:121] neg_lo:[0,1] neg_hi:[0,1]
	v_lshrrev_b32_e32 v0, 1, v199
	v_add_u32_e32 v56, s65, v117
	v_and_b32_e32 v0, 16, v0
	v_ashrrev_i32_e32 v57, 31, v56
	v_pk_add_f32 v[132:133], v[54:55], v[118:119]
	v_pk_add_f32 v[134:135], v[54:55], v[118:119] neg_lo:[0,1] neg_hi:[0,1]
	v_lshl_add_u64 v[54:55], s[52:53], 0, v[0:1]
	v_lshlrev_b64 v[56:57], 10, v[56:57]
	s_lshl_b32 s4, s6, 7
	v_lshl_add_u64 v[140:141], v[54:55], 0, v[56:57]
	v_sub_u32_e32 v56, s54, v117
	s_waitcnt vmcnt(2)
	v_and_or_b32 v142, v199, 64, s4
	v_ashrrev_i32_e32 v57, 31, v56
	v_lshlrev_b64 v[56:57], 10, v[56:57]
	v_cvt_pk_bf16_f32 v118, v130, v131
	v_cvt_pk_bf16_f32 v119, v114, v115
	v_cvt_pk_bf16_f32 v120, v132, v133
	v_cvt_pk_bf16_f32 v121, v136, v137
	v_cvt_pk_bf16_f32 v50, v50, v51
	v_cvt_pk_bf16_f32 v51, v52, v53
	v_cvt_pk_bf16_f32 v52, v134, v135
	v_cvt_pk_bf16_f32 v53, v138, v139
	v_lshlrev_b32_e32 v0, 1, v142
	v_cmp_lt_i32_e32 vcc, 0, v117
	v_lshl_add_u64 v[56:57], v[54:55], 0, v[56:57]
	v_permlane32_swap_b32_e32 v118, v120
	v_permlane32_swap_b32_e32 v119, v121
	v_lshl_add_u64 v[114:115], v[140:141], 0, v[0:1]
	v_permlane32_swap_b32_e32 v50, v52
	v_permlane32_swap_b32_e32 v51, v53
	global_store_dwordx4 v[114:115], v[118:121], off
	s_and_saveexec_b64 s[0:1], vcc
	s_cbranch_execz .LBB0_286
	v_lshl_add_u64 v[118:119], v[56:57], 0, v[0:1]
	global_store_dwordx4 v[118:119], v[50:53], off
.LBB0_286:
	s_or_b64 exec, exec, s[0:1]
	s_nop 0
	v_pk_add_f32 v[50:51], v[58:59], v[122:123]
	v_pk_add_f32 v[52:53], v[58:59], v[122:123] neg_lo:[0,1] neg_hi:[0,1]
	v_pk_add_f32 v[118:119], v[60:61], v[124:125]
	v_pk_add_f32 v[120:121], v[60:61], v[124:125] neg_lo:[0,1] neg_hi:[0,1]
	v_pk_add_f32 v[60:61], v[62:63], v[126:127]
	v_pk_add_f32 v[62:63], v[62:63], v[126:127] neg_lo:[0,1] neg_hi:[0,1]
	v_pk_add_f32 v[122:123], v[64:65], v[128:129]
	v_pk_add_f32 v[64:65], v[64:65], v[128:129] neg_lo:[0,1] neg_hi:[0,1]
	v_cvt_pk_bf16_f32 v58, v50, v51
	v_cvt_pk_bf16_f32 v59, v118, v119
	v_cvt_pk_bf16_f32 v60, v60, v61
	v_cvt_pk_bf16_f32 v61, v122, v123
	v_cvt_pk_bf16_f32 v50, v52, v53
	v_cvt_pk_bf16_f32 v51, v120, v121
	v_cvt_pk_bf16_f32 v52, v62, v63
	v_cvt_pk_bf16_f32 v53, v64, v65
	v_permlane32_swap_b32_e32 v58, v60
	v_permlane32_swap_b32_e32 v59, v61
	v_permlane32_swap_b32_e32 v50, v52
	v_permlane32_swap_b32_e32 v51, v53
	global_store_dwordx4 v[114:115], v[58:61], off offset:32
	s_and_saveexec_b64 s[0:1], vcc
	s_cbranch_execz .LBB0_288
	v_lshl_add_u64 v[58:59], v[56:57], 0, v[0:1]
	global_store_dwordx4 v[58:59], v[50:53], off offset:32
.LBB0_288:
	s_or_b64 exec, exec, s[0:1]
	s_nop 0
	v_pk_add_f32 v[50:51], v[34:35], v[98:99]
	v_pk_add_f32 v[34:35], v[34:35], v[98:99] neg_lo:[0,1] neg_hi:[0,1]
	v_pk_add_f32 v[52:53], v[36:37], v[100:101]
	v_pk_add_f32 v[36:37], v[36:37], v[100:101] neg_lo:[0,1] neg_hi:[0,1]
	v_pk_add_f32 v[58:59], v[38:39], v[102:103]
	v_pk_add_f32 v[60:61], v[38:39], v[102:103] neg_lo:[0,1] neg_hi:[0,1]
	v_pk_add_f32 v[62:63], v[40:41], v[104:105]
	v_pk_add_f32 v[64:65], v[40:41], v[104:105] neg_lo:[0,1] neg_hi:[0,1]
	v_cvt_pk_bf16_f32 v38, v50, v51
	v_cvt_pk_bf16_f32 v39, v52, v53
	v_cvt_pk_bf16_f32 v40, v58, v59
	v_cvt_pk_bf16_f32 v41, v62, v63
	v_cvt_pk_bf16_f32 v34, v34, v35
	v_cvt_pk_bf16_f32 v35, v36, v37
	v_cvt_pk_bf16_f32 v36, v60, v61
	v_cvt_pk_bf16_f32 v37, v64, v65
	v_permlane32_swap_b32_e32 v38, v40
	v_permlane32_swap_b32_e32 v39, v41
	v_permlane32_swap_b32_e32 v34, v36
	v_permlane32_swap_b32_e32 v35, v37
	global_store_dwordx4 v[114:115], v[38:41], off offset:64
	s_and_saveexec_b64 s[0:1], vcc
	s_cbranch_execz .LBB0_290
	v_lshl_add_u64 v[38:39], v[56:57], 0, v[0:1]
	global_store_dwordx4 v[38:39], v[34:37], off offset:64
.LBB0_290:
	s_or_b64 exec, exec, s[0:1]
	s_nop 0
	v_pk_add_f32 v[34:35], v[42:43], v[106:107]
	v_pk_add_f32 v[36:37], v[42:43], v[106:107] neg_lo:[0,1] neg_hi:[0,1]
	v_pk_add_f32 v[40:41], v[44:45], v[108:109]
	v_pk_add_f32 v[42:43], v[44:45], v[108:109] neg_lo:[0,1] neg_hi:[0,1]
	v_pk_add_f32 v[44:45], v[46:47], v[110:111]
	v_pk_add_f32 v[46:47], v[46:47], v[110:111] neg_lo:[0,1] neg_hi:[0,1]
	v_pk_add_f32 v[50:51], v[48:49], v[112:113]
	v_pk_add_f32 v[48:49], v[48:49], v[112:113] neg_lo:[0,1] neg_hi:[0,1]
	v_cvt_pk_bf16_f32 v38, v34, v35
	v_cvt_pk_bf16_f32 v39, v40, v41
	v_cvt_pk_bf16_f32 v40, v44, v45
	v_cvt_pk_bf16_f32 v41, v50, v51
	v_cvt_pk_bf16_f32 v34, v36, v37
	v_cvt_pk_bf16_f32 v35, v42, v43
	v_cvt_pk_bf16_f32 v36, v46, v47
	v_cvt_pk_bf16_f32 v37, v48, v49
	v_permlane32_swap_b32_e32 v38, v40
	v_permlane32_swap_b32_e32 v39, v41
	v_permlane32_swap_b32_e32 v34, v36
	v_permlane32_swap_b32_e32 v35, v37
	global_store_dwordx4 v[114:115], v[38:41], off offset:96
	s_and_saveexec_b64 s[0:1], vcc
	s_cbranch_execz .LBB0_292
	v_lshl_add_u64 v[38:39], v[56:57], 0, v[0:1]
	global_store_dwordx4 v[38:39], v[34:37], off offset:96
.LBB0_292:
	s_or_b64 exec, exec, s[0:1]
	v_or_b32_e32 v46, 32, v117
	v_pk_add_f32 v[38:39], v[22:23], v[86:87]
	v_pk_add_f32 v[40:41], v[22:23], v[86:87] neg_lo:[0,1] neg_hi:[0,1]
	v_add_u32_e32 v22, s65, v46
	v_ashrrev_i32_e32 v23, 31, v22
	v_lshlrev_b64 v[22:23], 10, v[22:23]
	v_lshl_add_u64 v[44:45], v[54:55], 0, v[22:23]
	v_sub_u32_e32 v22, s54, v46
	v_pk_add_f32 v[34:35], v[18:19], v[82:83]
	v_pk_add_f32 v[18:19], v[18:19], v[82:83] neg_lo:[0,1] neg_hi:[0,1]
	v_pk_add_f32 v[36:37], v[20:21], v[84:85]
	v_pk_add_f32 v[20:21], v[20:21], v[84:85] neg_lo:[0,1] neg_hi:[0,1]
	v_pk_add_f32 v[42:43], v[24:25], v[88:89]
	v_pk_add_f32 v[24:25], v[24:25], v[88:89] neg_lo:[0,1] neg_hi:[0,1]
	v_ashrrev_i32_e32 v23, 31, v22
	v_lshlrev_b64 v[22:23], 10, v[22:23]
	v_cvt_pk_bf16_f32 v34, v34, v35
	v_cvt_pk_bf16_f32 v35, v36, v37
	v_cvt_pk_bf16_f32 v36, v38, v39
	v_cvt_pk_bf16_f32 v37, v42, v43
	v_cvt_pk_bf16_f32 v18, v18, v19
	v_cvt_pk_bf16_f32 v19, v20, v21
	v_cvt_pk_bf16_f32 v20, v40, v41
	v_cvt_pk_bf16_f32 v21, v24, v25
	v_cmp_lt_i32_e32 vcc, -1, v116
	v_lshl_add_u64 v[22:23], v[54:55], 0, v[22:23]
	v_permlane32_swap_b32_e32 v34, v36
	v_permlane32_swap_b32_e32 v35, v37
	v_lshl_add_u64 v[24:25], v[44:45], 0, v[0:1]
	v_permlane32_swap_b32_e32 v18, v20
	v_permlane32_swap_b32_e32 v19, v21
	global_store_dwordx4 v[24:25], v[34:37], off
	s_and_saveexec_b64 s[0:1], vcc
	s_cbranch_execz .LBB0_294
	v_lshl_add_u64 v[34:35], v[22:23], 0, v[0:1]
	global_store_dwordx4 v[34:35], v[18:21], off
.LBB0_294:
	s_or_b64 exec, exec, s[0:1]
	s_nop 0
	v_pk_add_f32 v[18:19], v[26:27], v[90:91]
	v_pk_add_f32 v[20:21], v[26:27], v[90:91] neg_lo:[0,1] neg_hi:[0,1]
	v_pk_add_f32 v[34:35], v[28:29], v[92:93]
	v_pk_add_f32 v[36:37], v[28:29], v[92:93] neg_lo:[0,1] neg_hi:[0,1]
	v_pk_add_f32 v[28:29], v[30:31], v[94:95]
	v_pk_add_f32 v[30:31], v[30:31], v[94:95] neg_lo:[0,1] neg_hi:[0,1]
	v_pk_add_f32 v[38:39], v[32:33], v[96:97]
	v_pk_add_f32 v[32:33], v[32:33], v[96:97] neg_lo:[0,1] neg_hi:[0,1]
	v_cvt_pk_bf16_f32 v26, v18, v19
	v_cvt_pk_bf16_f32 v27, v34, v35
	v_cvt_pk_bf16_f32 v28, v28, v29
	v_cvt_pk_bf16_f32 v29, v38, v39
	v_cvt_pk_bf16_f32 v18, v20, v21
	v_cvt_pk_bf16_f32 v19, v36, v37
	v_cvt_pk_bf16_f32 v20, v30, v31
	v_cvt_pk_bf16_f32 v21, v32, v33
	v_permlane32_swap_b32_e32 v26, v28
	v_permlane32_swap_b32_e32 v27, v29
	v_permlane32_swap_b32_e32 v18, v20
	v_permlane32_swap_b32_e32 v19, v21
	global_store_dwordx4 v[24:25], v[26:29], off offset:32
	s_and_saveexec_b64 s[0:1], vcc
	s_cbranch_execz .LBB0_296
	v_lshl_add_u64 v[26:27], v[22:23], 0, v[0:1]
	global_store_dwordx4 v[26:27], v[18:21], off offset:32
.LBB0_296:
	s_or_b64 exec, exec, s[0:1]
	s_nop 0
	v_pk_add_f32 v[18:19], v[2:3], v[66:67]
	v_pk_add_f32 v[2:3], v[2:3], v[66:67] neg_lo:[0,1] neg_hi:[0,1]
	v_pk_add_f32 v[20:21], v[4:5], v[68:69]
	v_pk_add_f32 v[4:5], v[4:5], v[68:69] neg_lo:[0,1] neg_hi:[0,1]
	v_pk_add_f32 v[26:27], v[6:7], v[70:71]
	v_pk_add_f32 v[28:29], v[6:7], v[70:71] neg_lo:[0,1] neg_hi:[0,1]
	v_pk_add_f32 v[30:31], v[8:9], v[72:73]
	v_pk_add_f32 v[32:33], v[8:9], v[72:73] neg_lo:[0,1] neg_hi:[0,1]
	v_cvt_pk_bf16_f32 v6, v18, v19
	v_cvt_pk_bf16_f32 v7, v20, v21
	v_cvt_pk_bf16_f32 v8, v26, v27
	v_cvt_pk_bf16_f32 v9, v30, v31
	v_cvt_pk_bf16_f32 v2, v2, v3
	v_cvt_pk_bf16_f32 v3, v4, v5
	v_cvt_pk_bf16_f32 v4, v28, v29
	v_cvt_pk_bf16_f32 v5, v32, v33
	v_permlane32_swap_b32_e32 v6, v8
	v_permlane32_swap_b32_e32 v7, v9
	v_permlane32_swap_b32_e32 v2, v4
	v_permlane32_swap_b32_e32 v3, v5
	global_store_dwordx4 v[24:25], v[6:9], off offset:64
	s_and_saveexec_b64 s[0:1], vcc
	s_cbranch_execz .LBB0_298
	v_lshl_add_u64 v[6:7], v[22:23], 0, v[0:1]
	global_store_dwordx4 v[6:7], v[2:5], off offset:64
.LBB0_298:
	s_or_b64 exec, exec, s[0:1]
	s_nop 0
	v_pk_add_f32 v[2:3], v[10:11], v[74:75]
	v_pk_add_f32 v[4:5], v[10:11], v[74:75] neg_lo:[0,1] neg_hi:[0,1]
	v_pk_add_f32 v[8:9], v[12:13], v[76:77]
	v_pk_add_f32 v[10:11], v[12:13], v[76:77] neg_lo:[0,1] neg_hi:[0,1]
	v_pk_add_f32 v[12:13], v[14:15], v[78:79]
	v_pk_add_f32 v[14:15], v[14:15], v[78:79] neg_lo:[0,1] neg_hi:[0,1]
	v_pk_add_f32 v[18:19], v[16:17], v[80:81]
	v_pk_add_f32 v[16:17], v[16:17], v[80:81] neg_lo:[0,1] neg_hi:[0,1]
	v_cvt_pk_bf16_f32 v6, v2, v3
	v_cvt_pk_bf16_f32 v7, v8, v9
	v_cvt_pk_bf16_f32 v8, v12, v13
	v_cvt_pk_bf16_f32 v9, v18, v19
	v_cvt_pk_bf16_f32 v2, v4, v5
	v_cvt_pk_bf16_f32 v3, v10, v11
	v_cvt_pk_bf16_f32 v4, v14, v15
	v_cvt_pk_bf16_f32 v5, v16, v17
	v_permlane32_swap_b32_e32 v6, v8
	v_permlane32_swap_b32_e32 v7, v9
	v_permlane32_swap_b32_e32 v2, v4
	v_permlane32_swap_b32_e32 v3, v5
	global_store_dwordx4 v[24:25], v[6:9], off offset:96
	s_and_saveexec_b64 s[0:1], vcc
	s_cbranch_execz .LBB0_300
	v_lshl_add_u64 v[6:7], v[22:23], 0, v[0:1]
	global_store_dwordx4 v[6:7], v[2:5], off offset:96

.LBB0_302:
	v_lshl_add_u64 v[16:17], v[4:5], 0, s[0:1]
	s_mov_b64 s[6:7], 0xb400000
	v_lshl_add_u64 v[20:21], v[16:17], 0, s[6:7]
	v_add_co_u32_e32 v16, vcc, 0xb400000, v16
	global_load_dwordx4 v[8:11], v[20:21], off offset:16
	global_load_dwordx4 v[12:15], v[20:21], off offset:32
	v_addc_co_u32_e32 v17, vcc, 0, v17, vcc
	global_load_dwordx4 v[16:19], v[16:17], off
	s_nop 0
	global_load_dwordx4 v[20:23], v[20:21], off offset:48
	s_add_u32 s0, s0, 64
	s_addc_u32 s1, s1, 0
	s_cmpk_eq_i32 s0, 0x800
	s_waitcnt vmcnt(0)
	v_lshlrev_b32_e32 v7, 16, v8
	v_and_b32_e32 v28, 0xffff0000, v8
	v_lshlrev_b32_e32 v25, 16, v10
	v_lshlrev_b32_e32 v24, 16, v9
	v_and_b32_e32 v27, 0xffff0000, v10
	v_and_b32_e32 v26, 0xffff0000, v9
	v_lshlrev_b32_e32 v29, 16, v11
	v_and_b32_e32 v30, 0xffff0000, v11
	v_lshlrev_b32_e32 v9, 16, v14
	v_lshlrev_b32_e32 v8, 16, v13
	v_and_b32_e32 v11, 0xffff0000, v14
	v_and_b32_e32 v10, 0xffff0000, v13
	v_lshlrev_b32_e32 v35, 16, v16
	v_and_b32_e32 v36, 0xffff0000, v16
	v_lshlrev_b32_e32 v31, 16, v12
	v_and_b32_e32 v32, 0xffff0000, v12
	v_lshlrev_b32_e32 v33, 16, v15
	v_and_b32_e32 v34, 0xffff0000, v15
	v_lshlrev_b32_e32 v13, 16, v18
	v_lshlrev_b32_e32 v12, 16, v17
	v_and_b32_e32 v15, 0xffff0000, v18
	v_and_b32_e32 v14, 0xffff0000, v17
	v_lshlrev_b32_e32 v37, 16, v19
	v_and_b32_e32 v38, 0xffff0000, v19
	v_pk_add_f32 v[8:9], v[8:9], v[10:11] neg_lo:[0,1] neg_hi:[0,1]
	v_lshlrev_b32_e32 v11, 16, v22
	v_lshlrev_b32_e32 v10, 16, v21
	v_and_b32_e32 v19, 0xffff0000, v22
	v_and_b32_e32 v18, 0xffff0000, v21
	v_lshlrev_b32_e32 v21, 16, v23
	v_and_b32_e32 v22, 0xffff0000, v23
	v_sub_f32_e32 v23, v35, v36
	v_pk_add_f32 v[12:13], v[12:13], v[14:15] neg_lo:[0,1] neg_hi:[0,1]
	v_add_f32_e32 v6, v6, v23
	v_add_f32_e32 v6, v12, v6
	v_sub_f32_e32 v14, v37, v38
	v_add_f32_e32 v6, v13, v6
	v_sub_f32_e32 v7, v7, v28
	v_add_f32_e32 v6, v14, v6
	v_pk_add_f32 v[16:17], v[24:25], v[26:27] neg_lo:[0,1] neg_hi:[0,1]
	v_add_f32_e32 v6, v6, v7
	v_add_f32_e32 v6, v16, v6
	v_sub_f32_e32 v24, v29, v30
	v_add_f32_e32 v6, v17, v6
	v_sub_f32_e32 v25, v31, v32
	v_add_f32_e32 v6, v24, v6
	v_add_f32_e32 v6, v6, v25
	v_add_f32_e32 v6, v8, v6
	v_sub_f32_e32 v26, v33, v34
	v_lshlrev_b32_e32 v27, 16, v20
	v_and_b32_e32 v20, 0xffff0000, v20
	v_add_f32_e32 v6, v9, v6
	v_sub_f32_e32 v15, v27, v20
	v_add_f32_e32 v6, v26, v6
	v_pk_add_f32 v[10:11], v[10:11], v[18:19] neg_lo:[0,1] neg_hi:[0,1]
	v_add_f32_e32 v6, v6, v15
	v_add_f32_e32 v6, v10, v6
	v_sub_f32_e32 v18, v21, v22
	v_add_f32_e32 v6, v11, v6
	v_add_f32_e32 v6, v18, v6
	s_cbranch_scc0 .LBB0_302
	v_and_b32_e32 v5, 64, v231
	v_xor_b32_e32 v4, 1, v231
	v_add_u32_e32 v5, 64, v5
	v_cmp_lt_i32_e32 vcc, v4, v5
	s_nop 1
	v_cndmask_b32_e32 v4, v231, v4, vcc
	v_lshlrev_b32_e32 v4, 2, v4
	ds_bpermute_b32 v4, v4, v6
	s_waitcnt lgkmcnt(0)
	v_add_f32_e32 v4, v6, v4
	v_xor_b32_e32 v6, 2, v231
	v_cmp_lt_i32_e32 vcc, v6, v5
	s_nop 1
	v_cndmask_b32_e32 v5, v231, v6, vcc
	v_lshlrev_b32_e32 v5, 2, v5
	ds_bpermute_b32 v5, v5, v4
	v_cmp_eq_u32_e32 vcc, 0, v0
	s_and_saveexec_b64 s[0:1], vcc
	s_xor_b64 s[0:1], exec, s[0:1]
	s_cbranch_execz .LBB0_305
	v_readlane_b32 s2, v254, 38
	s_or_b32 s2, s4, s2
	s_lshl_b32 s2, s2, 1
	s_waitcnt lgkmcnt(0)
	v_add_f32_e32 v0, v4, v5
	s_add_u32 s4, s52, s2
	v_mul_f32_e32 v0, 0x3c800000, v0
	s_addc_u32 s5, s53, 0
	v_cvt_pk_bf16_f32 v0, v0, s0
	v_lshl_add_u64 v[2:3], v[2:3], 1, s[4:5]
	global_store_short v[2:3], v0, off

.LBB0_342:
	v_mov_b32_e32 v0, v228
	s_waitcnt lgkmcnt(0)
	s_barrier
	s_nop 0
	v_cmp_eq_u32_e32 vcc, 0, v0
	s_and_saveexec_b64 s[0:1], vcc
	s_cbranch_execz .LBB0_344
	v_mov_b64_e32 v[2:3], s[38:39]
	global_atomic_add v0, v[2:3], v229, off sc0
	v_mov_b32_e32 v2, s33
	s_waitcnt vmcnt(0) lgkmcnt(0)
	ds_write_b32 v2, v0

.LBB0_360:
	s_and_saveexec_b64 s[0:1], s[70:71]
	s_xor_b64 s[74:75], exec, s[0:1]
	s_cbranch_execz .LBB0_397
	s_and_saveexec_b64 s[0:1], s[16:17]
	s_xor_b64 s[30:31], exec, s[0:1]
	s_cbranch_execz .LBB0_394
	s_and_saveexec_b64 s[0:1], s[14:15]
	s_xor_b64 s[0:1], exec, s[0:1]
	v_writelane_b32 v254, s0, 58
	s_nop 1
	v_writelane_b32 v254, s1, 59
	s_cbranch_execz .LBB0_391
	s_and_saveexec_b64 s[0:1], s[12:13]
	s_xor_b64 s[20:21], exec, s[0:1]
	s_cbranch_execz .LBB0_374
	s_and_saveexec_b64 s[90:91], s[10:11]
	s_cbranch_execz .LBB0_373
	s_and_b64 s[0:1], s[6:7], exec
	s_cselect_b32 s0, s26, s28
	s_cselect_b32 s1, s29, s35
	v_mov_b32_e32 v130, s1
	v_mov_b32_e32 v131, s0
	v_ashrrev_i32_e32 v147, 31, v146
	s_waitcnt vmcnt(0)
	v_lshl_add_u64 v[160:161], v[146:147], 1, v[130:131]
	v_lshl_add_u64 v[130:131], s[62:63], 0, v[146:147]
	v_lshlrev_b64 v[180:181], 11, v[130:131]
	v_mul_hi_i32_i24_e32 v131, s34, v198
	v_mul_i32_i24_e32 v130, s34, v198
	v_cvt_pk_bf16_f32 v0, v114, s0
	v_lshl_add_u64 v[130:131], v[130:131], 1, v[160:161]
	global_store_short v[130:131], v0, off
	v_or_b32_e32 v0, 1, v198
	v_mul_hi_i32_i24_e32 v133, s34, v0
	v_mul_i32_i24_e32 v132, s34, v0
	v_cvt_pk_bf16_f32 v134, v115, s0
	v_lshl_add_u64 v[132:133], v[132:133], 1, v[160:161]
	v_or_b32_e32 v0, 2, v198
	global_store_short v[132:133], v134, off
	v_mul_hi_i32_i24_e32 v135, s34, v0
	v_mul_i32_i24_e32 v134, s34, v0
	v_cvt_pk_bf16_f32 v136, v116, s0
	v_lshl_add_u64 v[134:135], v[134:135], 1, v[160:161]
	v_or_b32_e32 v0, 3, v198
	global_store_short v[134:135], v136, off
	v_mul_hi_i32_i24_e32 v137, s34, v0
	v_mul_i32_i24_e32 v136, s34, v0
	v_or_b32_e32 v0, 8, v198
	v_cvt_pk_bf16_f32 v139, v117, s0
	v_lshl_add_u64 v[136:137], v[136:137], 1, v[160:161]
	v_mul_hi_i32_i24_e32 v155, s34, v0
	v_mul_i32_i24_e32 v154, s34, v0
	v_or_b32_e32 v0, 9, v198
	global_store_short v[136:137], v139, off
	v_cvt_pk_bf16_f32 v139, v118, s0
	v_lshl_add_u64 v[154:155], v[154:155], 1, v[160:161]
	v_mul_hi_i32_i24_e32 v157, s34, v0
	v_mul_i32_i24_e32 v156, s34, v0
	v_or_b32_e32 v0, 10, v198
	global_store_short v[154:155], v139, off
	v_cvt_pk_bf16_f32 v139, v119, s0
	v_lshl_add_u64 v[156:157], v[156:157], 1, v[160:161]
	v_mul_hi_i32_i24_e32 v159, s34, v0
	v_mul_i32_i24_e32 v158, s34, v0
	v_or_b32_e32 v0, 11, v198
	global_store_short v[156:157], v139, off
	v_cvt_pk_bf16_f32 v139, v120, s0
	v_lshl_add_u64 v[158:159], v[158:159], 1, v[160:161]
	v_mul_hi_i32_i24_e32 v163, s34, v0
	v_mul_i32_i24_e32 v162, s34, v0
	v_or_b32_e32 v0, 16, v198
	global_store_short v[158:159], v139, off
	v_cvt_pk_bf16_f32 v139, v121, s0
	v_lshl_add_u64 v[162:163], v[162:163], 1, v[160:161]
	v_mul_hi_i32_i24_e32 v165, s34, v0
	v_mul_i32_i24_e32 v164, s34, v0
	v_or_b32_e32 v0, 17, v198
	global_store_short v[162:163], v139, off
	v_cvt_pk_bf16_f32 v139, v122, s0
	v_lshl_add_u64 v[164:165], v[164:165], 1, v[160:161]
	v_mul_hi_i32_i24_e32 v167, s34, v0
	v_mul_i32_i24_e32 v166, s34, v0
	v_or_b32_e32 v0, 18, v198
	global_store_short v[164:165], v139, off
	v_cvt_pk_bf16_f32 v139, v123, s0
	v_lshl_add_u64 v[166:167], v[166:167], 1, v[160:161]
	v_mul_hi_i32_i24_e32 v169, s34, v0
	v_mul_i32_i24_e32 v168, s34, v0
	v_or_b32_e32 v0, 19, v198
	global_store_short v[166:167], v139, off
	v_cvt_pk_bf16_f32 v139, v124, s0
	v_lshl_add_u64 v[168:169], v[168:169], 1, v[160:161]
	v_mul_hi_i32_i24_e32 v171, s34, v0
	v_mul_i32_i24_e32 v170, s34, v0
	v_or_b32_e32 v0, 24, v198
	global_store_short v[168:169], v139, off
	v_cvt_pk_bf16_f32 v139, v125, s0
	v_lshl_add_u64 v[170:171], v[170:171], 1, v[160:161]
	v_mul_hi_i32_i24_e32 v173, s34, v0
	v_mul_i32_i24_e32 v172, s34, v0
	v_or_b32_e32 v0, 25, v198
	global_store_short v[170:171], v139, off
	v_cvt_pk_bf16_f32 v139, v126, s0
	v_lshl_add_u64 v[172:173], v[172:173], 1, v[160:161]
	v_mul_hi_i32_i24_e32 v175, s34, v0
	v_mul_i32_i24_e32 v174, s34, v0
	v_or_b32_e32 v0, 26, v198
	v_readlane_b32 s44, v254, 21
	global_store_short v[172:173], v139, off
	v_cvt_pk_bf16_f32 v139, v127, s0
	v_lshl_add_u64 v[174:175], v[174:175], 1, v[160:161]
	v_mul_hi_i32_i24_e32 v177, s34, v0
	v_mul_i32_i24_e32 v176, s34, v0
	v_or_b32_e32 v0, 27, v198
	v_readlane_b32 s45, v254, 22
	global_store_short v[174:175], v139, off
	v_cvt_pk_bf16_f32 v139, v128, s0
	v_lshl_add_u64 v[176:177], v[176:177], 1, v[160:161]
	v_mul_hi_i32_i24_e32 v179, s34, v0
	v_mul_i32_i24_e32 v178, s34, v0
	v_cndmask_b32_e64 v0, 0, 1, s[6:7]
	v_lshl_add_u64 v[180:181], s[44:45], 0, v[180:181]
	global_store_short v[176:177], v139, off
	v_cvt_pk_bf16_f32 v139, v129, s0
	v_lshl_add_u64 v[178:179], v[178:179], 1, v[160:161]
	v_cmp_ne_u32_e64 s[0:1], 1, v0
	s_andn2_b64 vcc, exec, s[6:7]
	v_lshl_add_u64 v[188:189], v[144:145], 2, v[180:181]
	global_store_short v[178:179], v139, off
	s_cbranch_vccnz .LBB0_367
	v_lshlrev_b32_e32 v0, 2, v196
	v_lshl_add_u64 v[180:181], v[188:189], 0, v[0:1]
	s_mov_b64 vcc, 0xaffc600
	v_lshl_add_u64 v[182:183], v[180:181], 0, vcc
	v_add_co_u32_e32 v180, vcc, 0xaffc000, v180
	s_nop 1
	v_addc_co_u32_e32 v181, vcc, 0, v181, vcc
	global_store_dwordx4 v[180:181], v[114:117], off offset:1536
	global_store_dwordx4 v[182:183], v[118:121], off offset:32
	global_store_dwordx4 v[182:183], v[122:125], off offset:64
	global_store_dwordx4 v[182:183], v[126:129], off offset:96
.LBB0_367:
	v_or_b32_e32 v0, 32, v198
	v_mul_hi_i32_i24_e32 v115, s34, v0
	v_mul_i32_i24_e32 v114, s34, v0
	v_cvt_pk_bf16_f32 v116, v98, s0
	v_lshl_add_u64 v[114:115], v[114:115], 1, v[160:161]
	v_or_b32_e32 v0, 33, v198
	global_store_short v[114:115], v116, off
	v_mul_hi_i32_i24_e32 v117, s34, v0
	v_mul_i32_i24_e32 v116, s34, v0
	v_cvt_pk_bf16_f32 v118, v99, s0
	v_lshl_add_u64 v[116:117], v[116:117], 1, v[160:161]
	v_or_b32_e32 v0, 34, v198
	global_store_short v[116:117], v118, off
	v_mul_hi_i32_i24_e32 v119, s34, v0
	v_mul_i32_i24_e32 v118, s34, v0
	v_cvt_pk_bf16_f32 v120, v100, s0
	v_lshl_add_u64 v[118:119], v[118:119], 1, v[160:161]
	v_or_b32_e32 v0, 35, v198
	global_store_short v[118:119], v120, off
	v_mul_hi_i32_i24_e32 v121, s34, v0
	v_mul_i32_i24_e32 v120, s34, v0
	v_cvt_pk_bf16_f32 v122, v101, s0
	v_lshl_add_u64 v[120:121], v[120:121], 1, v[160:161]
	v_or_b32_e32 v0, 40, v198
	global_store_short v[120:121], v122, off
	v_mul_hi_i32_i24_e32 v123, s34, v0
	v_mul_i32_i24_e32 v122, s34, v0
	v_cvt_pk_bf16_f32 v124, v102, s0
	v_lshl_add_u64 v[122:123], v[122:123], 1, v[160:161]
	v_or_b32_e32 v0, 41, v198
	global_store_short v[122:123], v124, off
	v_mul_hi_i32_i24_e32 v125, s34, v0
	v_mul_i32_i24_e32 v124, s34, v0
	v_cvt_pk_bf16_f32 v126, v103, s0
	v_lshl_add_u64 v[124:125], v[124:125], 1, v[160:161]
	v_or_b32_e32 v0, 42, v198
	global_store_short v[124:125], v126, off
	v_mul_hi_i32_i24_e32 v127, s34, v0
	v_mul_i32_i24_e32 v126, s34, v0
	v_cvt_pk_bf16_f32 v128, v104, s0
	v_lshl_add_u64 v[126:127], v[126:127], 1, v[160:161]
	v_or_b32_e32 v0, 43, v198
	global_store_short v[126:127], v128, off
	v_mul_hi_i32_i24_e32 v129, s34, v0
	v_mul_i32_i24_e32 v128, s34, v0
	v_or_b32_e32 v0, 48, v198
	v_cvt_pk_bf16_f32 v139, v105, s0
	v_lshl_add_u64 v[128:129], v[128:129], 1, v[160:161]
	v_mul_hi_i32_i24_e32 v181, s34, v0
	v_mul_i32_i24_e32 v180, s34, v0
	v_or_b32_e32 v0, 49, v198
	global_store_short v[128:129], v139, off
	v_cvt_pk_bf16_f32 v139, v106, s0
	v_lshl_add_u64 v[180:181], v[180:181], 1, v[160:161]
	v_mul_hi_i32_i24_e32 v183, s34, v0
	v_mul_i32_i24_e32 v182, s34, v0
	v_or_b32_e32 v0, 50, v198
	global_store_short v[180:181], v139, off
	v_cvt_pk_bf16_f32 v139, v107, s0
	v_lshl_add_u64 v[182:183], v[182:183], 1, v[160:161]
	v_mul_hi_i32_i24_e32 v185, s34, v0
	v_mul_i32_i24_e32 v184, s34, v0
	v_or_b32_e32 v0, 51, v198
	global_store_short v[182:183], v139, off
	v_cvt_pk_bf16_f32 v139, v108, s0
	v_lshl_add_u64 v[184:185], v[184:185], 1, v[160:161]
	v_mul_hi_i32_i24_e32 v187, s34, v0
	v_mul_i32_i24_e32 v186, s34, v0
	v_or_b32_e32 v0, 56, v198
	global_store_short v[184:185], v139, off
	v_cvt_pk_bf16_f32 v139, v109, s0
	v_lshl_add_u64 v[186:187], v[186:187], 1, v[160:161]
	v_mul_hi_i32_i24_e32 v191, s34, v0
	v_mul_i32_i24_e32 v190, s34, v0
	v_or_b32_e32 v0, 57, v198
	global_store_short v[186:187], v139, off
	v_cvt_pk_bf16_f32 v139, v110, s0
	v_lshl_add_u64 v[190:191], v[190:191], 1, v[160:161]
	v_mul_hi_i32_i24_e32 v193, s34, v0
	v_mul_i32_i24_e32 v192, s34, v0
	v_or_b32_e32 v0, 58, v198
	global_store_short v[190:191], v139, off
	v_cvt_pk_bf16_f32 v139, v111, s0
	v_lshl_add_u64 v[192:193], v[192:193], 1, v[160:161]
	v_mul_hi_i32_i24_e32 v195, s34, v0
	v_mul_i32_i24_e32 v194, s34, v0
	v_or_b32_e32 v0, 59, v198
	global_store_short v[192:193], v139, off
	v_cvt_pk_bf16_f32 v139, v112, s0
	v_lshl_add_u64 v[194:195], v[194:195], 1, v[160:161]
	v_mul_hi_i32_i24_e32 v201, s34, v0
	v_mul_i32_i24_e32 v200, s34, v0
	global_store_short v[194:195], v139, off
	v_cvt_pk_bf16_f32 v139, v113, s0
	v_lshl_add_u64 v[160:161], v[200:201], 1, v[160:161]
	s_and_b64 vcc, exec, s[0:1]
	global_store_short v[160:161], v139, off
	s_cbranch_vccnz .LBB0_369
	v_lshlrev_b32_e32 v0, 2, v196
	v_lshl_add_u64 v[188:189], v[188:189], 0, v[0:1]
	s_mov_b64 vcc, 0xaffc680
	v_lshl_add_u64 v[200:201], v[188:189], 0, vcc
	v_add_co_u32_e32 v188, vcc, 0xaffc000, v188
	s_nop 1
	v_addc_co_u32_e32 v189, vcc, 0, v189, vcc
	global_store_dwordx4 v[188:189], v[98:101], off offset:1664
	global_store_dwordx4 v[200:201], v[102:105], off offset:32
	global_store_dwordx4 v[200:201], v[106:109], off offset:64
	global_store_dwordx4 v[200:201], v[110:113], off offset:96
.LBB0_369:
	v_cvt_pk_bf16_f32 v0, v82, s0
	global_store_short v[130:131], v0, off offset:64
	v_cvt_pk_bf16_f32 v0, v83, s0
	global_store_short v[132:133], v0, off offset:64
	v_cvt_pk_bf16_f32 v0, v84, s0
	global_store_short v[134:135], v0, off offset:64
	v_cvt_pk_bf16_f32 v0, v85, s0
	global_store_short v[136:137], v0, off offset:64
	v_cvt_pk_bf16_f32 v0, v86, s0
	global_store_short v[154:155], v0, off offset:64
	v_cvt_pk_bf16_f32 v0, v87, s0
	global_store_short v[156:157], v0, off offset:64
	v_cvt_pk_bf16_f32 v0, v88, s0
	global_store_short v[158:159], v0, off offset:64
	v_cvt_pk_bf16_f32 v0, v89, s0
	global_store_short v[162:163], v0, off offset:64
	v_cvt_pk_bf16_f32 v0, v90, s0
	global_store_short v[164:165], v0, off offset:64
	v_cvt_pk_bf16_f32 v0, v91, s0
	v_or_b32_e32 v98, 32, v146
	global_store_short v[166:167], v0, off offset:64
	v_cvt_pk_bf16_f32 v0, v92, s0
	v_ashrrev_i32_e32 v99, 31, v98
	global_store_short v[168:169], v0, off offset:64
	v_cvt_pk_bf16_f32 v0, v93, s0
	v_lshl_add_u64 v[98:99], s[62:63], 0, v[98:99]
	global_store_short v[170:171], v0, off offset:64
	v_cvt_pk_bf16_f32 v0, v94, s0
	v_readlane_b32 s44, v254, 21
	v_lshlrev_b64 v[98:99], 11, v[98:99]
	global_store_short v[172:173], v0, off offset:64
	v_cvt_pk_bf16_f32 v0, v95, s0
	v_readlane_b32 s45, v254, 22
	global_store_short v[174:175], v0, off offset:64
	v_cvt_pk_bf16_f32 v0, v96, s0
	v_lshl_add_u64 v[98:99], s[44:45], 0, v[98:99]
	global_store_short v[176:177], v0, off offset:64
	v_cvt_pk_bf16_f32 v0, v97, s0
	s_and_b64 vcc, exec, s[0:1]
	v_lshl_add_u64 v[98:99], v[144:145], 2, v[98:99]
	global_store_short v[178:179], v0, off offset:64
	s_cbranch_vccnz .LBB0_371
	v_lshlrev_b32_e32 v0, 2, v196
	v_lshl_add_u64 v[100:101], v[98:99], 0, v[0:1]
	s_mov_b64 vcc, 0xaffc600
	v_lshl_add_u64 v[102:103], v[100:101], 0, vcc
	v_add_co_u32_e32 v100, vcc, 0xaffc000, v100
	s_nop 1
	v_addc_co_u32_e32 v101, vcc, 0, v101, vcc
	global_store_dwordx4 v[100:101], v[82:85], off offset:1536
	global_store_dwordx4 v[102:103], v[86:89], off offset:32
	global_store_dwordx4 v[102:103], v[90:93], off offset:64
	global_store_dwordx4 v[102:103], v[94:97], off offset:96
.LBB0_371:
	v_cvt_pk_bf16_f32 v0, v66, s0
	global_store_short v[114:115], v0, off offset:64
	v_cvt_pk_bf16_f32 v0, v67, s0
	global_store_short v[116:117], v0, off offset:64
	v_cvt_pk_bf16_f32 v0, v68, s0
	global_store_short v[118:119], v0, off offset:64
	v_cvt_pk_bf16_f32 v0, v69, s0
	global_store_short v[120:121], v0, off offset:64
	v_cvt_pk_bf16_f32 v0, v70, s0
	global_store_short v[122:123], v0, off offset:64
	v_cvt_pk_bf16_f32 v0, v71, s0
	global_store_short v[124:125], v0, off offset:64
	v_cvt_pk_bf16_f32 v0, v72, s0
	global_store_short v[126:127], v0, off offset:64
	v_cvt_pk_bf16_f32 v0, v73, s0
	global_store_short v[128:129], v0, off offset:64
	v_cvt_pk_bf16_f32 v0, v74, s0
	global_store_short v[180:181], v0, off offset:64
	v_cvt_pk_bf16_f32 v0, v75, s0
	global_store_short v[182:183], v0, off offset:64
	v_cvt_pk_bf16_f32 v0, v76, s0
	global_store_short v[184:185], v0, off offset:64
	v_cvt_pk_bf16_f32 v0, v77, s0
	global_store_short v[186:187], v0, off offset:64
	v_cvt_pk_bf16_f32 v0, v78, s0
	global_store_short v[190:191], v0, off offset:64
	v_cvt_pk_bf16_f32 v0, v79, s0
	global_store_short v[192:193], v0, off offset:64
	v_cvt_pk_bf16_f32 v0, v80, s0
	global_store_short v[194:195], v0, off offset:64
	v_cvt_pk_bf16_f32 v0, v81, s0
	s_and_b64 vcc, exec, s[0:1]
	global_store_short v[160:161], v0, off offset:64
	s_cbranch_vccnz .LBB0_373
	v_lshlrev_b32_e32 v0, 2, v196
	v_lshl_add_u64 v[82:83], v[98:99], 0, v[0:1]
	s_mov_b64 s[0:1], 0xaffc680
	v_lshl_add_u64 v[84:85], v[82:83], 0, s[0:1]
	v_add_co_u32_e32 v82, vcc, 0xaffc000, v82
	s_nop 1
	v_addc_co_u32_e32 v83, vcc, 0, v83, vcc
	global_store_dwordx4 v[82:83], v[66:69], off offset:1664
	global_store_dwordx4 v[84:85], v[70:73], off offset:32
	global_store_dwordx4 v[84:85], v[74:77], off offset:64
	global_store_dwordx4 v[84:85], v[78:81], off offset:96

.LBB0_374:
	s_andn2_saveexec_b64 s[0:1], s[20:21]
	s_cbranch_execz .LBB0_390
	v_and_b32_e32 v132, 64, v231
	v_xor_b32_e32 v0, 32, v231
	v_add_u32_e32 v132, 64, v132
	v_cmp_lt_i32_e32 vcc, v0, v132
	s_waitcnt vmcnt(0)
	v_pk_mul_f32 v[156:157], v[104:105], v[104:105]
	v_pk_mul_f32 v[154:155], v[106:107], v[106:107]
	v_cndmask_b32_e32 v0, v231, v0, vcc
	v_lshlrev_b32_e32 v165, 2, v0
	v_mul_f32_e32 v0, v115, v115
	v_fmac_f32_e32 v0, v114, v114
	v_fmac_f32_e32 v0, v116, v116
	v_fmac_f32_e32 v0, v117, v117
	v_fmac_f32_e32 v0, v118, v118
	v_fmac_f32_e32 v0, v119, v119
	v_fmac_f32_e32 v0, v120, v120
	v_fmac_f32_e32 v0, v121, v121
	v_fmac_f32_e32 v0, v122, v122
	v_fmac_f32_e32 v0, v123, v123
	v_fmac_f32_e32 v0, v124, v124
	v_fmac_f32_e32 v0, v125, v125
	v_fmac_f32_e32 v0, v126, v126
	v_fmac_f32_e32 v0, v127, v127
	v_fmac_f32_e32 v0, v128, v128
	v_fmac_f32_e32 v0, v129, v129
	v_fmac_f32_e32 v0, v98, v98
	v_fmac_f32_e32 v0, v99, v99
	v_fmac_f32_e32 v0, v100, v100
	v_fmac_f32_e32 v0, v101, v101
	v_fmac_f32_e32 v0, v102, v102
	v_fmac_f32_e32 v0, v103, v103
	v_add_f32_e32 v0, v156, v0
	v_add_f32_e32 v0, v157, v0
	v_add_f32_e32 v0, v154, v0
	v_pk_mul_f32 v[136:137], v[108:109], v[108:109]
	v_add_f32_e32 v0, v155, v0
	v_add_f32_e32 v0, v136, v0
	v_pk_mul_f32 v[134:135], v[110:111], v[110:111]
	v_add_f32_e32 v0, v137, v0
	v_add_f32_e32 v0, v134, v0
	v_pk_mul_f32 v[132:133], v[112:113], v[112:113]
	v_add_f32_e32 v0, v135, v0
	v_add_f32_e32 v0, v132, v0
	v_add_f32_e32 v0, v133, v0
	ds_bpermute_b32 v132, v165, v0
	v_readlane_b32 s44, v253, 51
	v_readlane_b32 s58, v254, 1
	v_readlane_b32 s59, v254, 2
	v_readlane_b32 s45, v253, 52
	s_waitcnt lgkmcnt(0)
	v_add_f32_e32 v0, v0, v132
	v_fmamk_f32 v0, v0, 0x3c800000, v230
	v_cmp_gt_f32_e32 vcc, s95, v0
	v_mul_f32_e32 v132, 0x4b800000, v0
	v_lshl_add_u64 v[130:131], v[150:151], 2, s[58:59]
	v_cndmask_b32_e32 v0, v0, v132, vcc
	v_rsq_f32_e32 v0, v0
	v_or_b32_e32 v164, 2, v196
	v_or_b32_e32 v149, 8, v196
	v_or_b32_e32 v147, 10, v196
	v_mul_f32_e32 v132, 0x45800000, v0
	v_cndmask_b32_e32 v156, v0, v132, vcc
	v_lshlrev_b32_e32 v0, 2, v196
	v_lshl_add_u64 v[154:155], v[130:131], 0, v[0:1]
	global_load_dwordx4 v[130:133], v[154:155], off
	global_load_dwordx4 v[134:137], v[154:155], off offset:64
	v_pk_mul_f32 v[114:115], v[114:115], v[156:157] op_sel_hi:[1,0]
	v_pk_mul_f32 v[116:117], v[116:117], v[156:157] op_sel_hi:[1,0]
	v_pk_mul_f32 v[118:119], v[118:119], v[156:157] op_sel_hi:[1,0]
	v_pk_mul_f32 v[120:121], v[120:121], v[156:157] op_sel_hi:[1,0]
	v_pk_mul_f32 v[98:99], v[98:99], v[156:157] op_sel_hi:[1,0]
	v_pk_mul_f32 v[100:101], v[100:101], v[156:157] op_sel_hi:[1,0]
	v_pk_mul_f32 v[102:103], v[102:103], v[156:157] op_sel_hi:[1,0]
	v_pk_mul_f32 v[104:105], v[104:105], v[156:157] op_sel_hi:[1,0]
	s_andn2_b64 vcc, exec, s[68:69]
	v_readlane_b32 s46, v253, 53
	v_readlane_b32 s47, v253, 54
	v_readlane_b32 s48, v253, 55
	v_readlane_b32 s49, v253, 56
	v_readlane_b32 s50, v253, 57
	v_readlane_b32 s51, v253, 58
	v_readlane_b32 s52, v253, 59
	v_readlane_b32 s53, v253, 60
	v_readlane_b32 s54, v253, 61
	v_readlane_b32 s55, v253, 62
	v_readlane_b32 s56, v253, 63
	v_readlane_b32 s57, v254, 0
	global_load_dwordx4 v[158:161], v[154:155], off offset:96
	s_waitcnt vmcnt(2)
	v_pk_mul_f32 v[130:131], v[130:131], v[114:115]
	v_pk_mul_f32 v[114:115], v[122:123], v[156:157] op_sel_hi:[1,0]
	v_pk_mul_f32 v[132:133], v[132:133], v[116:117]
	v_pk_mul_f32 v[116:117], v[124:125], v[156:157] op_sel_hi:[1,0]
	global_load_dwordx4 v[122:125], v[154:155], off offset:32
	s_waitcnt vmcnt(2)
	v_pk_mul_f32 v[114:115], v[134:135], v[114:115]
	v_pk_mul_f32 v[116:117], v[116:117], v[136:137]
	s_waitcnt vmcnt(0)
	v_pk_mul_f32 v[134:135], v[122:123], v[118:119]
	v_pk_mul_f32 v[136:137], v[124:125], v[120:121]
	global_load_dwordx4 v[122:125], v[154:155], off offset:128
	v_pk_mul_f32 v[118:119], v[126:127], v[156:157] op_sel_hi:[1,0]
	v_pk_mul_f32 v[120:121], v[128:129], v[156:157] op_sel_hi:[1,0]
	global_load_dwordx4 v[126:129], v[154:155], off offset:192
	v_pk_mul_f32 v[118:119], v[118:119], v[158:159]
	v_pk_mul_f32 v[120:121], v[120:121], v[160:161]
	s_waitcnt vmcnt(1)
	v_pk_mul_f32 v[122:123], v[98:99], v[122:123]
	v_pk_mul_f32 v[98:99], v[106:107], v[156:157] op_sel_hi:[1,0]
	v_pk_mul_f32 v[124:125], v[100:101], v[124:125]
	v_pk_mul_f32 v[100:101], v[108:109], v[156:157] op_sel_hi:[1,0]
	global_load_dwordx4 v[106:109], v[154:155], off offset:160
	s_waitcnt vmcnt(1)
	v_pk_mul_f32 v[98:99], v[98:99], v[126:127]
	v_pk_mul_f32 v[100:101], v[100:101], v[128:129]
	global_load_dwordx4 v[126:129], v[154:155], off offset:224
	s_waitcnt vmcnt(1)
	v_pk_mul_f32 v[102:103], v[102:103], v[106:107]
	v_pk_mul_f32 v[106:107], v[110:111], v[156:157] op_sel_hi:[1,0]
	v_pk_mul_f32 v[104:105], v[104:105], v[108:109]
	v_pk_mul_f32 v[108:109], v[112:113], v[156:157] op_sel_hi:[1,0]
	v_cndmask_b32_e64 v110, 0, 1, s[68:69]
	s_waitcnt vmcnt(0)
	v_pk_mul_f32 v[106:107], v[106:107], v[126:127]
	v_pk_mul_f32 v[108:109], v[108:109], v[128:129]
	v_subrev_u32_e32 v126, s64, v140
	v_cmp_ne_u32_e64 s[44:45], 1, v110
	s_cbranch_vccnz .LBB0_377
	v_ashrrev_i32_e32 v110, 2, v126
	v_and_b32_e32 v127, -16, v110
	v_or_b32_e32 v110, v127, v196
	v_readlane_b32 s20, v254, 39
	v_ashrrev_i32_e32 v111, 31, v110
	v_readlane_b32 s21, v254, 40
	s_nop 1
	v_lshl_add_u64 v[110:111], v[110:111], 3, s[20:21]
	global_load_dwordx4 v[110:113], v[110:111], off
	s_waitcnt vmcnt(0) lgkmcnt(0)
	v_mov_b32_e32 v129, v112
	v_mov_b32_e32 v112, v111
	v_mov_b32_e32 v128, v110
	v_pk_mul_f32 v[110:111], v[114:115], v[112:113]
	v_pk_mul_f32 v[112:113], v[130:131], v[112:113]
	v_pk_fma_f32 v[110:111], v[130:131], v[128:129], v[110:111] neg_lo:[0,0,1] neg_hi:[0,0,1]
	v_pk_fma_f32 v[114:115], v[114:115], v[128:129], v[112:113]
	v_or_b32_e32 v112, v127, v164
	v_ashrrev_i32_e32 v113, 31, v112
	v_lshl_add_u64 v[112:113], v[112:113], 3, s[20:21]
	global_load_dwordx4 v[128:131], v[112:113], off
	s_waitcnt vmcnt(0) lgkmcnt(0)
	v_mov_b32_e32 v157, v130
	v_mov_b32_e32 v130, v129
	v_mov_b32_e32 v156, v128
	v_pk_mul_f32 v[128:129], v[132:133], v[130:131]
	v_pk_mul_f32 v[112:113], v[116:117], v[130:131]
	v_pk_fma_f32 v[116:117], v[116:117], v[156:157], v[128:129]
	v_or_b32_e32 v128, v127, v149
	v_ashrrev_i32_e32 v129, 31, v128
	v_lshl_add_u64 v[128:129], v[128:129], 3, s[20:21]
	global_load_dwordx4 v[128:131], v[128:129], off
	v_pk_fma_f32 v[112:113], v[132:133], v[156:157], v[112:113] neg_lo:[0,0,1] neg_hi:[0,0,1]
	s_waitcnt vmcnt(0) lgkmcnt(0)
	v_mov_b32_e32 v133, v130
	v_mov_b32_e32 v130, v129
	v_mov_b32_e32 v132, v128
	v_pk_mul_f32 v[128:129], v[118:119], v[130:131]
	v_pk_mul_f32 v[130:131], v[134:135], v[130:131]
	v_pk_fma_f32 v[128:129], v[134:135], v[132:133], v[128:129] neg_lo:[0,0,1] neg_hi:[0,0,1]
	v_pk_fma_f32 v[118:119], v[118:119], v[132:133], v[130:131]
	v_or_b32_e32 v130, v127, v147
	v_ashrrev_i32_e32 v131, 31, v130
	v_lshl_add_u64 v[130:131], v[130:131], 3, s[20:21]
	global_load_dwordx4 v[130:133], v[130:131], off
	v_lshlrev_b32_e32 v127, 4, v197
	s_waitcnt vmcnt(0) lgkmcnt(0)
	v_mov_b32_e32 v135, v132
	v_mov_b32_e32 v132, v131
	v_mov_b32_e32 v134, v130
	v_pk_mul_f32 v[130:131], v[120:121], v[132:133]
	s_nop 0
	v_pk_fma_f32 v[156:157], v[136:137], v[134:135], v[130:131] neg_lo:[0,0,1] neg_hi:[0,0,1]
	v_pk_mul_f32 v[130:131], v[136:137], v[132:133]
	v_mov_b64_e32 v[136:137], v[156:157]
	v_pk_fma_f32 v[120:121], v[120:121], v[134:135], v[130:131]
	v_or_b32_e32 v130, v196, v127
	v_lshlrev_b32_e32 v130, 3, v130
	v_mov_b32_e32 v131, v1
	v_lshl_add_u64 v[130:131], s[20:21], 0, v[130:131]
	global_load_dwordx4 v[130:133], v[130:131], off
	s_waitcnt vmcnt(0) lgkmcnt(0)
	v_mov_b32_e32 v135, v132
	v_mov_b32_e32 v132, v131
	v_mov_b32_e32 v134, v130
	v_pk_mul_f32 v[130:131], v[98:99], v[132:133]
	s_nop 0
	v_pk_fma_f32 v[158:159], v[122:123], v[134:135], v[130:131] neg_lo:[0,0,1] neg_hi:[0,0,1]
	v_pk_mul_f32 v[122:123], v[122:123], v[132:133]
	s_nop 0
	v_pk_fma_f32 v[98:99], v[98:99], v[134:135], v[122:123]
	v_or_b32_e32 v122, v164, v127
	v_lshlrev_b32_e32 v122, 3, v122
	v_mov_b32_e32 v123, v1
	v_lshl_add_u64 v[122:123], s[20:21], 0, v[122:123]
	global_load_dwordx4 v[130:133], v[122:123], off
	v_mov_b64_e32 v[134:135], v[128:129]
	s_waitcnt vmcnt(0) lgkmcnt(0)
	v_mov_b32_e32 v123, v132
	v_mov_b32_e32 v132, v131
	v_mov_b32_e32 v122, v130
	v_pk_mul_f32 v[130:131], v[100:101], v[132:133]
	s_nop 0
	v_pk_fma_f32 v[160:161], v[124:125], v[122:123], v[130:131] neg_lo:[0,0,1] neg_hi:[0,0,1]
	v_pk_mul_f32 v[124:125], v[124:125], v[132:133]
	v_mov_b64_e32 v[132:133], v[112:113]
	v_pk_fma_f32 v[100:101], v[100:101], v[122:123], v[124:125]
	v_or_b32_e32 v122, v149, v127
	v_lshlrev_b32_e32 v122, 3, v122
	v_mov_b32_e32 v123, v1
	v_lshl_add_u64 v[122:123], s[20:21], 0, v[122:123]
	global_load_dwordx4 v[122:125], v[122:123], off
	s_waitcnt vmcnt(0) lgkmcnt(0)
	v_mov_b32_e32 v131, v124
	v_mov_b32_e32 v124, v123
	v_mov_b32_e32 v130, v122
	v_pk_mul_f32 v[122:123], v[106:107], v[124:125]
	s_nop 0
	v_pk_fma_f32 v[162:163], v[102:103], v[130:131], v[122:123] neg_lo:[0,0,1] neg_hi:[0,0,1]
	v_pk_mul_f32 v[102:103], v[102:103], v[124:125]
	s_nop 0
	v_pk_fma_f32 v[106:107], v[106:107], v[130:131], v[102:103]
	v_or_b32_e32 v102, v147, v127
	v_lshlrev_b32_e32 v102, 3, v102
	v_mov_b32_e32 v103, v1
	v_lshl_add_u64 v[102:103], s[20:21], 0, v[102:103]
	global_load_dwordx4 v[122:125], v[102:103], off
	v_mov_b64_e32 v[130:131], v[110:111]
	s_waitcnt vmcnt(0) lgkmcnt(0)
	v_mov_b32_e32 v103, v124
	v_mov_b32_e32 v124, v123
	v_mov_b32_e32 v102, v122
	v_pk_mul_f32 v[122:123], v[108:109], v[124:125]
	s_nop 0
	v_pk_fma_f32 v[166:167], v[104:105], v[102:103], v[122:123] neg_lo:[0,0,1] neg_hi:[0,0,1]
	v_pk_mul_f32 v[104:105], v[104:105], v[124:125]
	v_mov_b64_e32 v[122:123], v[158:159]
	v_pk_fma_f32 v[108:109], v[108:109], v[102:103], v[104:105]
	v_mov_b64_e32 v[124:125], v[160:161]
	v_mov_b64_e32 v[102:103], v[162:163]
	v_mov_b64_e32 v[104:105], v[166:167]
.LBB0_377:
	v_ashrrev_i32_e32 v139, 31, v138
	v_lshlrev_b64 v[112:113], 1, v[138:139]
	v_lshl_add_u64 v[110:111], v[142:143], 0, v[112:113]
	s_and_saveexec_b64 s[90:91], s[8:9]
	s_xor_b64 s[90:91], exec, s[90:91]
	s_cbranch_execz .LBB0_379
	s_mov_b32 s20, 0x3e38aa3b
	v_pk_mul_f32 v[114:115], v[114:115], s[20:21] op_sel_hi:[1,0]
	v_pk_mul_f32 v[116:117], v[116:117], s[20:21] op_sel_hi:[1,0]
	v_ashrrev_i32_e32 v141, 31, v140
	v_cvt_pk_bf16_f32 v114, v114, v115
	v_cvt_pk_bf16_f32 v115, v116, v117
	v_pk_mul_f32 v[116:117], v[118:119], s[20:21] op_sel_hi:[1,0]
	v_pk_mul_f32 v[118:119], v[120:121], s[20:21] op_sel_hi:[1,0]
	v_lshlrev_b64 v[126:127], 10, v[140:141]
	v_cvt_pk_bf16_f32 v116, v116, v117
	v_cvt_pk_bf16_f32 v117, v118, v119
	v_lshl_add_u64 v[156:157], v[110:111], 0, v[126:127]
	v_permlane32_swap_b32_e32 v114, v116
	v_permlane32_swap_b32_e32 v115, v117
	global_store_dwordx4 v[156:157], v[114:117], off offset:32
	v_pk_mul_f32 v[102:103], v[102:103], s[20:21] op_sel_hi:[1,0]
	v_pk_mul_f32 v[126:127], v[130:131], s[20:21] op_sel_hi:[1,0]
	v_pk_mul_f32 v[114:115], v[122:123], s[20:21] op_sel_hi:[1,0]
	v_pk_mul_f32 v[116:117], v[124:125], s[20:21] op_sel_hi:[1,0]
	v_pk_mul_f32 v[128:129], v[132:133], s[20:21] op_sel_hi:[1,0]
	v_cvt_pk_bf16_f32 v114, v114, v115
	v_cvt_pk_bf16_f32 v115, v116, v117
	v_cvt_pk_bf16_f32 v116, v102, v103
	v_pk_mul_f32 v[102:103], v[104:105], s[20:21] op_sel_hi:[1,0]
	v_pk_mul_f32 v[98:99], v[98:99], s[20:21] op_sel_hi:[1,0]
	v_pk_mul_f32 v[100:101], v[100:101], s[20:21] op_sel_hi:[1,0]
	v_cvt_pk_bf16_f32 v126, v126, v127
	v_cvt_pk_bf16_f32 v127, v128, v129
	v_pk_mul_f32 v[128:129], v[134:135], s[20:21] op_sel_hi:[1,0]
	v_pk_mul_f32 v[130:131], v[136:137], s[20:21] op_sel_hi:[1,0]
	v_cvt_pk_bf16_f32 v117, v102, v103
	v_cvt_pk_bf16_f32 v98, v98, v99
	v_cvt_pk_bf16_f32 v99, v100, v101
	v_pk_mul_f32 v[100:101], v[106:107], s[20:21] op_sel_hi:[1,0]
	v_pk_mul_f32 v[102:103], v[108:109], s[20:21] op_sel_hi:[1,0]
	v_cvt_pk_bf16_f32 v128, v128, v129
	v_cvt_pk_bf16_f32 v129, v130, v131
	v_cvt_pk_bf16_f32 v100, v100, v101
	v_cvt_pk_bf16_f32 v101, v102, v103
	v_permlane32_swap_b32_e32 v126, v128
	v_permlane32_swap_b32_e32 v127, v129
	v_permlane32_swap_b32_e32 v114, v116
	v_permlane32_swap_b32_e32 v115, v117
	v_permlane32_swap_b32_e32 v98, v100
	v_permlane32_swap_b32_e32 v99, v101
	global_store_dwordx4 v[156:157], v[126:129], off
	global_store_dwordx4 v[156:157], v[114:117], off offset:64
	global_store_dwordx4 v[156:157], v[98:101], off offset:96
.LBB0_379:
	s_or_saveexec_b64 s[90:91], s[90:91]
	v_readlane_b32 s20, v254, 43
	v_readlane_b32 s21, v254, 44
	s_nop 1
	v_lshl_add_u64 v[128:129], s[20:21], 0, v[112:113]
	v_lshl_add_u64 v[112:113], s[66:67], 0, v[112:113]
	v_cndmask_b32_e64 v113, v129, v113, s[6:7]
	v_cndmask_b32_e64 v112, v128, v112, s[6:7]
	s_xor_b64 exec, exec, s[90:91]
	s_cbranch_execz .LBB0_382
	s_and_b64 vcc, s[6:7], exec
	v_ashrrev_i32_e32 v127, 31, v126
	s_cselect_b32 vcc_hi, 0, s3
	s_cselect_b32 vcc_lo, 0, s2
	v_lshl_add_u64 v[128:129], vcc, 0, v[126:127]
	v_lshlrev_b64 v[128:129], 10, v[128:129]
	v_lshl_add_u64 v[128:129], v[112:113], 0, v[128:129]
	v_lshlrev_b32_e32 v156, 1, v153
	v_mov_b32_e32 v157, v1
	v_lshl_add_u64 v[128:129], v[128:129], 0, v[156:157]
	v_cvt_pk_bf16_f32 v156, v130, v131
	v_cvt_pk_bf16_f32 v157, v132, v133
	v_cvt_pk_bf16_f32 v158, v134, v135
	v_cvt_pk_bf16_f32 v159, v136, v137
	s_nop 0
	v_permlane32_swap_b32_e32 v156, v158
	v_permlane32_swap_b32_e32 v157, v159
	global_store_dwordx4 v[128:129], v[156:159], off
	s_andn2_b64 vcc, exec, s[6:7]
	s_nop 0
	v_cvt_pk_bf16_f32 v156, v114, v115
	v_cvt_pk_bf16_f32 v157, v116, v117
	v_cvt_pk_bf16_f32 v158, v118, v119
	v_cvt_pk_bf16_f32 v159, v120, v121
	s_nop 0
	v_permlane32_swap_b32_e32 v156, v158
	v_permlane32_swap_b32_e32 v157, v159
	global_store_dwordx4 v[128:129], v[156:159], off offset:32
	s_nop 1
	v_cvt_pk_bf16_f32 v156, v122, v123
	v_cvt_pk_bf16_f32 v157, v124, v125
	v_cvt_pk_bf16_f32 v158, v102, v103
	v_cvt_pk_bf16_f32 v159, v104, v105
	s_nop 0
	v_permlane32_swap_b32_e32 v156, v158
	v_permlane32_swap_b32_e32 v157, v159
	global_store_dwordx4 v[128:129], v[156:159], off offset:64
	s_nop 1
	v_cvt_pk_bf16_f32 v156, v98, v99
	v_cvt_pk_bf16_f32 v157, v100, v101
	v_cvt_pk_bf16_f32 v158, v106, v107
	v_cvt_pk_bf16_f32 v159, v108, v109
	s_nop 0
	v_permlane32_swap_b32_e32 v156, v158
	v_permlane32_swap_b32_e32 v157, v159
	global_store_dwordx4 v[128:129], v[156:159], off offset:96
	s_cbranch_vccnz .LBB0_382
	v_lshl_add_u64 v[126:127], s[62:63], 0, v[126:127]
	v_readlane_b32 s20, v254, 54
	v_lshlrev_b64 v[126:127], 11, v[126:127]
	v_readlane_b32 s21, v254, 55
	s_nop 1
	v_lshl_add_u64 v[126:127], s[20:21], 0, v[126:127]
	v_lshl_add_u64 v[126:127], v[138:139], 2, v[126:127]
	v_lshl_add_u64 v[126:127], v[126:127], 0, v[0:1]
	global_store_dwordx4 v[126:127], v[130:133], off
	global_store_dwordx4 v[126:127], v[134:137], off offset:32
	global_store_dwordx4 v[126:127], v[114:117], off offset:64
	global_store_dwordx4 v[126:127], v[118:121], off offset:96
	global_store_dwordx4 v[126:127], v[122:125], off offset:128
	global_store_dwordx4 v[126:127], v[102:105], off offset:160
	global_store_dwordx4 v[126:127], v[98:101], off offset:192
	global_store_dwordx4 v[126:127], v[106:109], off offset:224

.LBB0_385:
	v_ashrrev_i32_e32 v79, 2, v78
	v_and_b32_e32 v79, -16, v79
	v_or_b32_e32 v80, v79, v196
	v_readlane_b32 s20, v254, 39
	v_ashrrev_i32_e32 v81, 31, v80
	v_readlane_b32 s21, v254, 40
	s_nop 1
	v_lshl_add_u64 v[80:81], v[80:81], 3, s[20:21]
	global_load_dwordx4 v[94:97], v[80:81], off
	s_waitcnt vmcnt(0) lgkmcnt(0)
	v_mov_b32_e32 v109, v96
	v_mov_b32_e32 v96, v95
	v_mov_b32_e32 v108, v94
	v_pk_mul_f32 v[94:95], v[102:103], v[96:97]
	v_pk_mul_f32 v[80:81], v[82:83], v[96:97]
	v_pk_fma_f32 v[82:83], v[82:83], v[108:109], v[94:95]
	v_or_b32_e32 v94, v79, v164
	v_ashrrev_i32_e32 v95, 31, v94
	v_lshl_add_u64 v[94:95], v[94:95], 3, s[20:21]
	global_load_dwordx4 v[94:97], v[94:95], off
	v_pk_fma_f32 v[80:81], v[102:103], v[108:109], v[80:81] neg_lo:[0,0,1] neg_hi:[0,0,1]
	s_waitcnt vmcnt(0) lgkmcnt(0)
	v_mov_b32_e32 v103, v96
	v_mov_b32_e32 v96, v95
	v_mov_b32_e32 v102, v94
	v_pk_mul_f32 v[94:95], v[84:85], v[96:97]
	v_pk_mul_f32 v[96:97], v[104:105], v[96:97]
	v_pk_fma_f32 v[94:95], v[104:105], v[102:103], v[94:95] neg_lo:[0,0,1] neg_hi:[0,0,1]
	v_pk_fma_f32 v[84:85], v[84:85], v[102:103], v[96:97]
	v_or_b32_e32 v96, v79, v149
	v_ashrrev_i32_e32 v97, 31, v96
	v_lshl_add_u64 v[96:97], v[96:97], 3, s[20:21]
	global_load_dwordx4 v[102:105], v[96:97], off
	s_waitcnt vmcnt(0) lgkmcnt(0)
	v_mov_b32_e32 v109, v104
	v_mov_b32_e32 v104, v103
	v_mov_b32_e32 v108, v102
	v_pk_mul_f32 v[96:97], v[86:87], v[104:105]
	s_nop 0
	v_pk_fma_f32 v[96:97], v[98:99], v[108:109], v[96:97] neg_lo:[0,0,1] neg_hi:[0,0,1]
	v_pk_mul_f32 v[98:99], v[98:99], v[104:105]
	s_nop 0
	v_pk_fma_f32 v[86:87], v[86:87], v[108:109], v[98:99]
	v_or_b32_e32 v98, v79, v147
	v_ashrrev_i32_e32 v99, 31, v98
	v_lshl_add_u64 v[98:99], v[98:99], 3, s[20:21]
	global_load_dwordx4 v[102:105], v[98:99], off
	v_lshlrev_b32_e32 v79, 4, v106
	v_and_b32_e32 v79, 0x3f0, v79
	s_waitcnt vmcnt(0) lgkmcnt(0)
	v_mov_b32_e32 v99, v104
	v_mov_b32_e32 v104, v103
	v_mov_b32_e32 v98, v102
	v_pk_mul_f32 v[102:103], v[88:89], v[104:105]
	s_nop 0
	v_pk_fma_f32 v[108:109], v[100:101], v[98:99], v[102:103] neg_lo:[0,0,1] neg_hi:[0,0,1]
	v_pk_mul_f32 v[100:101], v[100:101], v[104:105]
	v_mov_b64_e32 v[104:105], v[94:95]
	v_pk_fma_f32 v[88:89], v[88:89], v[98:99], v[100:101]
	v_or_b32_e32 v98, v79, v196
	v_lshlrev_b32_e32 v98, 3, v98
	v_mov_b32_e32 v99, v1
	v_lshl_add_u64 v[98:99], s[20:21], 0, v[98:99]
	global_load_dwordx4 v[98:101], v[98:99], off
	s_waitcnt vmcnt(0) lgkmcnt(0)
	v_mov_b32_e32 v103, v100
	v_mov_b32_e32 v100, v99
	v_mov_b32_e32 v102, v98
	v_pk_mul_f32 v[98:99], v[66:67], v[100:101]
	s_nop 0
	v_pk_fma_f32 v[114:115], v[90:91], v[102:103], v[98:99] neg_lo:[0,0,1] neg_hi:[0,0,1]
	v_pk_mul_f32 v[90:91], v[90:91], v[100:101]
	s_nop 0
	v_pk_fma_f32 v[66:67], v[66:67], v[102:103], v[90:91]
	v_or_b32_e32 v90, v79, v164
	v_lshlrev_b32_e32 v90, 3, v90
	v_mov_b32_e32 v91, v1
	v_lshl_add_u64 v[90:91], s[20:21], 0, v[90:91]
	global_load_dwordx4 v[98:101], v[90:91], off
	v_mov_b64_e32 v[102:103], v[80:81]
	s_waitcnt vmcnt(0) lgkmcnt(0)
	v_mov_b32_e32 v91, v100
	v_mov_b32_e32 v100, v99
	v_mov_b32_e32 v90, v98
	v_pk_mul_f32 v[98:99], v[68:69], v[100:101]
	s_nop 0
	v_pk_fma_f32 v[116:117], v[92:93], v[90:91], v[98:99] neg_lo:[0,0,1] neg_hi:[0,0,1]
	v_pk_mul_f32 v[92:93], v[92:93], v[100:101]
	v_mov_b64_e32 v[100:101], v[108:109]
	v_pk_fma_f32 v[68:69], v[68:69], v[90:91], v[92:93]
	v_or_b32_e32 v90, v79, v149
	v_lshlrev_b32_e32 v90, 3, v90
	v_mov_b32_e32 v91, v1
	v_lshl_add_u64 v[90:91], s[20:21], 0, v[90:91]
	global_load_dwordx4 v[90:93], v[90:91], off
	s_waitcnt vmcnt(0) lgkmcnt(0)
	v_mov_b32_e32 v99, v92
	v_mov_b32_e32 v92, v91
	v_mov_b32_e32 v98, v90
	v_pk_mul_f32 v[90:91], v[74:75], v[92:93]
	s_nop 0
	v_pk_fma_f32 v[118:119], v[70:71], v[98:99], v[90:91] neg_lo:[0,0,1] neg_hi:[0,0,1]
	v_pk_mul_f32 v[70:71], v[70:71], v[92:93]
	s_nop 0
	v_pk_fma_f32 v[74:75], v[74:75], v[98:99], v[70:71]
	v_or_b32_e32 v70, v79, v147
	v_lshlrev_b32_e32 v70, 3, v70
	v_mov_b32_e32 v71, v1
	v_lshl_add_u64 v[70:71], s[20:21], 0, v[70:71]
	global_load_dwordx4 v[90:93], v[70:71], off
	v_mov_b64_e32 v[98:99], v[96:97]
	s_waitcnt vmcnt(0) lgkmcnt(0)
	v_mov_b32_e32 v71, v92
	v_mov_b32_e32 v92, v91
	v_mov_b32_e32 v70, v90
	v_pk_mul_f32 v[90:91], v[76:77], v[92:93]
	s_nop 0
	v_pk_fma_f32 v[120:121], v[72:73], v[70:71], v[90:91] neg_lo:[0,0,1] neg_hi:[0,0,1]
	v_pk_mul_f32 v[72:73], v[72:73], v[92:93]
	v_mov_b64_e32 v[90:91], v[114:115]
	v_pk_fma_f32 v[76:77], v[76:77], v[70:71], v[72:73]
	v_mov_b64_e32 v[92:93], v[116:117]
	v_mov_b64_e32 v[70:71], v[118:119]
	v_mov_b64_e32 v[72:73], v[120:121]
	s_and_saveexec_b64 s[20:21], s[8:9]
	s_xor_b64 s[20:21], exec, s[20:21]
	s_cbranch_execz .LBB0_384
.LBB0_386:
	v_ashrrev_i32_e32 v107, 31, v106
	v_lshlrev_b64 v[78:79], 10, v[106:107]
	s_mov_b32 s90, 0x3e38aa3b
	v_lshl_add_u64 v[94:95], v[110:111], 0, v[78:79]
	v_pk_mul_f32 v[78:79], v[102:103], s[90:91] op_sel_hi:[1,0]
	v_pk_mul_f32 v[80:81], v[104:105], s[90:91] op_sel_hi:[1,0]
	v_cvt_pk_bf16_f32 v78, v78, v79
	v_cvt_pk_bf16_f32 v79, v80, v81
	v_pk_mul_f32 v[80:81], v[98:99], s[90:91] op_sel_hi:[1,0]
	v_pk_mul_f32 v[96:97], v[100:101], s[90:91] op_sel_hi:[1,0]
	v_cvt_pk_bf16_f32 v80, v80, v81
	v_cvt_pk_bf16_f32 v81, v96, v97
	s_nop 0
	v_permlane32_swap_b32_e32 v78, v80
	v_permlane32_swap_b32_e32 v79, v81
	global_store_dwordx4 v[94:95], v[78:81], off
	v_pk_mul_f32 v[70:71], v[70:71], s[90:91] op_sel_hi:[1,0]
	v_pk_mul_f32 v[66:67], v[66:67], s[90:91] op_sel_hi:[1,0]
	v_pk_mul_f32 v[78:79], v[82:83], s[90:91] op_sel_hi:[1,0]
	v_pk_mul_f32 v[80:81], v[84:85], s[90:91] op_sel_hi:[1,0]
	v_cvt_pk_bf16_f32 v78, v78, v79
	v_cvt_pk_bf16_f32 v79, v80, v81
	v_pk_mul_f32 v[80:81], v[86:87], s[90:91] op_sel_hi:[1,0]
	v_pk_mul_f32 v[82:83], v[88:89], s[90:91] op_sel_hi:[1,0]
	v_cvt_pk_bf16_f32 v80, v80, v81
	v_cvt_pk_bf16_f32 v81, v82, v83
	s_nop 0
	v_permlane32_swap_b32_e32 v78, v80
	v_permlane32_swap_b32_e32 v79, v81
	global_store_dwordx4 v[94:95], v[78:81], off offset:32
	v_pk_mul_f32 v[68:69], v[68:69], s[90:91] op_sel_hi:[1,0]
	v_cvt_pk_bf16_f32 v66, v66, v67
	v_pk_mul_f32 v[78:79], v[90:91], s[90:91] op_sel_hi:[1,0]
	v_pk_mul_f32 v[80:81], v[92:93], s[90:91] op_sel_hi:[1,0]
	v_cvt_pk_bf16_f32 v78, v78, v79
	v_cvt_pk_bf16_f32 v79, v80, v81
	v_cvt_pk_bf16_f32 v80, v70, v71
	v_pk_mul_f32 v[70:71], v[72:73], s[90:91] op_sel_hi:[1,0]
	v_cvt_pk_bf16_f32 v67, v68, v69
	v_cvt_pk_bf16_f32 v81, v70, v71
	v_pk_mul_f32 v[68:69], v[74:75], s[90:91] op_sel_hi:[1,0]
	v_pk_mul_f32 v[70:71], v[76:77], s[90:91] op_sel_hi:[1,0]
	v_cvt_pk_bf16_f32 v68, v68, v69
	v_cvt_pk_bf16_f32 v69, v70, v71
	v_permlane32_swap_b32_e32 v78, v80
	v_permlane32_swap_b32_e32 v79, v81
	v_permlane32_swap_b32_e32 v66, v68
	v_permlane32_swap_b32_e32 v67, v69
	global_store_dwordx4 v[94:95], v[78:81], off offset:64
	global_store_dwordx4 v[94:95], v[66:69], off offset:96
	s_andn2_saveexec_b64 s[20:21], s[20:21]
	s_cbranch_execz .LBB0_389
.LBB0_387:
	s_and_b64 s[90:91], s[6:7], exec
	v_ashrrev_i32_e32 v79, 31, v78
	s_cselect_b32 s91, 0, s3
	s_cselect_b32 s90, 0, s2
	v_lshl_add_u64 v[80:81], s[90:91], 0, v[78:79]
	v_lshlrev_b64 v[80:81], 10, v[80:81]
	v_lshl_add_u64 v[80:81], v[112:113], 0, v[80:81]
	v_lshlrev_b32_e32 v94, 1, v153
	v_mov_b32_e32 v95, v1
	v_lshl_add_u64 v[80:81], v[80:81], 0, v[94:95]
	v_cvt_pk_bf16_f32 v94, v102, v103
	v_cvt_pk_bf16_f32 v95, v104, v105
	v_cvt_pk_bf16_f32 v96, v98, v99
	v_cvt_pk_bf16_f32 v97, v100, v101
	s_nop 0
	v_permlane32_swap_b32_e32 v94, v96
	v_permlane32_swap_b32_e32 v95, v97
	global_store_dwordx4 v[80:81], v[94:97], off
	s_andn2_b64 vcc, exec, s[6:7]
	s_nop 0
	v_cvt_pk_bf16_f32 v94, v82, v83
	v_cvt_pk_bf16_f32 v95, v84, v85
	v_cvt_pk_bf16_f32 v96, v86, v87
	v_cvt_pk_bf16_f32 v97, v88, v89
	s_nop 0
	v_permlane32_swap_b32_e32 v94, v96
	v_permlane32_swap_b32_e32 v95, v97
	global_store_dwordx4 v[80:81], v[94:97], off offset:32
	s_nop 1
	v_cvt_pk_bf16_f32 v94, v90, v91
	v_cvt_pk_bf16_f32 v95, v92, v93
	v_cvt_pk_bf16_f32 v96, v70, v71
	v_cvt_pk_bf16_f32 v97, v72, v73
	s_nop 0
	v_permlane32_swap_b32_e32 v94, v96
	v_permlane32_swap_b32_e32 v95, v97
	global_store_dwordx4 v[80:81], v[94:97], off offset:64
	s_nop 1
	v_cvt_pk_bf16_f32 v94, v66, v67
	v_cvt_pk_bf16_f32 v95, v68, v69
	v_cvt_pk_bf16_f32 v96, v74, v75
	v_cvt_pk_bf16_f32 v97, v76, v77
	s_nop 0
	v_permlane32_swap_b32_e32 v94, v96
	v_permlane32_swap_b32_e32 v95, v97
	global_store_dwordx4 v[80:81], v[94:97], off offset:96
	s_cbranch_vccnz .LBB0_389
	v_lshl_add_u64 v[78:79], s[62:63], 0, v[78:79]
	v_readlane_b32 s44, v254, 54
	v_lshlrev_b64 v[78:79], 11, v[78:79]
	v_readlane_b32 s45, v254, 55
	s_nop 1
	v_lshl_add_u64 v[78:79], s[44:45], 0, v[78:79]
	v_lshl_add_u64 v[78:79], v[138:139], 2, v[78:79]
	v_lshl_add_u64 v[78:79], v[78:79], 0, v[0:1]
	global_store_dwordx4 v[78:79], v[102:105], off
	global_store_dwordx4 v[78:79], v[98:101], off offset:32
	global_store_dwordx4 v[78:79], v[82:85], off offset:64
	global_store_dwordx4 v[78:79], v[86:89], off offset:96
	global_store_dwordx4 v[78:79], v[90:93], off offset:128
	global_store_dwordx4 v[78:79], v[70:73], off offset:160
	global_store_dwordx4 v[78:79], v[66:69], off offset:192
	global_store_dwordx4 v[78:79], v[74:77], off offset:224

.LBB0_391:
	v_readlane_b32 s0, v254, 58
	v_readlane_b32 s1, v254, 59
	s_andn2_saveexec_b64 s[0:1], s[0:1]
	s_cbranch_execz .LBB0_393
	v_ashrrev_i32_e32 v141, 31, v140
	v_readlane_b32 s20, v254, 47
	v_lshlrev_b64 v[66:67], 7, v[140:141]
	v_readlane_b32 s21, v254, 48
	v_lshlrev_b32_e32 v0, 2, v196
	s_nop 0
	v_lshl_add_u64 v[66:67], s[20:21], 0, v[66:67]
	v_lshl_add_u64 v[66:67], v[66:67], 0, v[0:1]
	global_store_dwordx4 v[66:67], v[114:117], off
	global_store_dwordx4 v[66:67], v[118:121], off offset:32
	global_store_dwordx4 v[66:67], v[122:125], off offset:64
	global_store_dwordx4 v[66:67], v[126:129], off offset:96
	v_or_b32_e32 v66, 32, v140
	v_ashrrev_i32_e32 v67, 31, v66
	v_lshlrev_b64 v[66:67], 7, v[66:67]
	v_lshl_add_u64 v[66:67], s[20:21], 0, v[66:67]
	v_lshl_add_u64 v[66:67], v[66:67], 0, v[0:1]
	global_store_dwordx4 v[66:67], v[82:85], off
	global_store_dwordx4 v[66:67], v[86:89], off offset:32
	global_store_dwordx4 v[66:67], v[90:93], off offset:64
	global_store_dwordx4 v[66:67], v[94:97], off offset:96

.LBB0_394:
	s_andn2_saveexec_b64 s[0:1], s[30:31]
	s_cbranch_execz .LBB0_396
	v_ashrrev_i32_e32 v147, 31, v146
	v_ashrrev_i32_e32 v149, 31, v148
	v_lshl_add_u64 v[130:131], v[146:147], 1, s[60:61]
	v_lshlrev_b64 v[132:133], s93, v[148:149]
	v_cvt_pk_bf16_f32 v0, v114, s0
	v_lshl_add_u64 v[132:133], v[132:133], 1, v[130:131]
	v_or_b32_e32 v114, 1, v148
	global_store_short v[132:133], v0, off
	v_cvt_pk_bf16_f32 v0, v115, s0
	v_ashrrev_i32_e32 v115, 31, v114
	v_or_b32_e32 v134, 2, v148
	v_lshlrev_b64 v[114:115], s93, v[114:115]
	v_ashrrev_i32_e32 v135, 31, v134
	v_lshl_add_u64 v[114:115], v[114:115], 1, v[130:131]
	v_lshlrev_b64 v[134:135], s93, v[134:135]
	global_store_short v[114:115], v0, off
	v_cvt_pk_bf16_f32 v0, v116, s0
	v_lshl_add_u64 v[134:135], v[134:135], 1, v[130:131]
	v_or_b32_e32 v116, 3, v148
	global_store_short v[134:135], v0, off
	v_cvt_pk_bf16_f32 v0, v117, s0
	v_ashrrev_i32_e32 v117, 31, v116
	v_or_b32_e32 v136, 8, v148
	v_lshlrev_b64 v[116:117], s93, v[116:117]
	v_ashrrev_i32_e32 v137, 31, v136
	v_lshl_add_u64 v[116:117], v[116:117], 1, v[130:131]
	v_lshlrev_b64 v[136:137], s93, v[136:137]
	global_store_short v[116:117], v0, off
	v_cvt_pk_bf16_f32 v0, v118, s0
	v_lshl_add_u64 v[136:137], v[136:137], 1, v[130:131]
	v_or_b32_e32 v118, 9, v148
	global_store_short v[136:137], v0, off
	v_cvt_pk_bf16_f32 v0, v119, s0
	v_ashrrev_i32_e32 v119, 31, v118
	s_waitcnt vmcnt(0)
	v_or_b32_e32 v154, 10, v148
	v_lshlrev_b64 v[118:119], s93, v[118:119]
	v_ashrrev_i32_e32 v155, 31, v154
	v_lshl_add_u64 v[118:119], v[118:119], 1, v[130:131]
	v_lshlrev_b64 v[154:155], s93, v[154:155]
	global_store_short v[118:119], v0, off
	v_cvt_pk_bf16_f32 v0, v120, s0
	v_lshl_add_u64 v[154:155], v[154:155], 1, v[130:131]
	v_or_b32_e32 v120, 11, v148
	global_store_short v[154:155], v0, off
	v_cvt_pk_bf16_f32 v0, v121, s0
	v_ashrrev_i32_e32 v121, 31, v120
	v_or_b32_e32 v156, 16, v148
	v_lshlrev_b64 v[120:121], s93, v[120:121]
	v_ashrrev_i32_e32 v157, 31, v156
	v_lshl_add_u64 v[120:121], v[120:121], 1, v[130:131]
	v_lshlrev_b64 v[156:157], s93, v[156:157]
	global_store_short v[120:121], v0, off
	v_cvt_pk_bf16_f32 v0, v122, s0
	v_lshl_add_u64 v[156:157], v[156:157], 1, v[130:131]
	v_or_b32_e32 v122, 17, v148
	global_store_short v[156:157], v0, off
	v_cvt_pk_bf16_f32 v0, v123, s0
	v_ashrrev_i32_e32 v123, 31, v122
	v_or_b32_e32 v158, 18, v148
	v_lshlrev_b64 v[122:123], s93, v[122:123]
	v_ashrrev_i32_e32 v159, 31, v158
	v_lshl_add_u64 v[122:123], v[122:123], 1, v[130:131]
	v_lshlrev_b64 v[158:159], s93, v[158:159]
	global_store_short v[122:123], v0, off
	v_cvt_pk_bf16_f32 v0, v124, s0
	v_lshl_add_u64 v[158:159], v[158:159], 1, v[130:131]
	v_or_b32_e32 v124, 19, v148
	global_store_short v[158:159], v0, off
	v_cvt_pk_bf16_f32 v0, v125, s0
	v_ashrrev_i32_e32 v125, 31, v124
	v_or_b32_e32 v160, 24, v148
	v_lshlrev_b64 v[124:125], s93, v[124:125]
	v_ashrrev_i32_e32 v161, 31, v160
	v_lshl_add_u64 v[124:125], v[124:125], 1, v[130:131]
	v_lshlrev_b64 v[160:161], s93, v[160:161]
	global_store_short v[124:125], v0, off
	v_cvt_pk_bf16_f32 v0, v126, s0
	v_lshl_add_u64 v[160:161], v[160:161], 1, v[130:131]
	v_or_b32_e32 v126, 25, v148
	global_store_short v[160:161], v0, off
	v_cvt_pk_bf16_f32 v0, v127, s0
	v_ashrrev_i32_e32 v127, 31, v126
	v_or_b32_e32 v162, 26, v148
	v_lshlrev_b64 v[126:127], s93, v[126:127]
	v_ashrrev_i32_e32 v163, 31, v162
	v_lshl_add_u64 v[126:127], v[126:127], 1, v[130:131]
	v_lshlrev_b64 v[162:163], s93, v[162:163]
	global_store_short v[126:127], v0, off
	v_cvt_pk_bf16_f32 v0, v128, s0
	v_lshl_add_u64 v[162:163], v[162:163], 1, v[130:131]
	v_or_b32_e32 v128, 27, v148
	global_store_short v[162:163], v0, off
	v_cvt_pk_bf16_f32 v0, v129, s0
	v_ashrrev_i32_e32 v129, 31, v128
	v_or_b32_e32 v164, 32, v148
	v_lshlrev_b64 v[128:129], s93, v[128:129]
	v_ashrrev_i32_e32 v165, 31, v164
	v_lshl_add_u64 v[128:129], v[128:129], 1, v[130:131]
	v_lshlrev_b64 v[164:165], s93, v[164:165]
	global_store_short v[128:129], v0, off
	v_cvt_pk_bf16_f32 v0, v98, s0
	v_lshl_add_u64 v[164:165], v[164:165], 1, v[130:131]
	v_or_b32_e32 v98, 33, v148
	global_store_short v[164:165], v0, off
	v_cvt_pk_bf16_f32 v0, v99, s0
	v_ashrrev_i32_e32 v99, 31, v98
	v_or_b32_e32 v166, 34, v148
	v_lshlrev_b64 v[98:99], s93, v[98:99]
	v_ashrrev_i32_e32 v167, 31, v166
	v_lshl_add_u64 v[98:99], v[98:99], 1, v[130:131]
	v_lshlrev_b64 v[166:167], s93, v[166:167]
	global_store_short v[98:99], v0, off
	v_cvt_pk_bf16_f32 v0, v100, s0
	v_lshl_add_u64 v[166:167], v[166:167], 1, v[130:131]
	v_or_b32_e32 v100, 35, v148
	global_store_short v[166:167], v0, off
	v_cvt_pk_bf16_f32 v0, v101, s0
	v_ashrrev_i32_e32 v101, 31, v100
	v_or_b32_e32 v168, 40, v148
	v_lshlrev_b64 v[100:101], s93, v[100:101]
	v_ashrrev_i32_e32 v169, 31, v168
	v_lshl_add_u64 v[100:101], v[100:101], 1, v[130:131]
	v_lshlrev_b64 v[168:169], s93, v[168:169]
	global_store_short v[100:101], v0, off
	v_cvt_pk_bf16_f32 v0, v102, s0
	v_lshl_add_u64 v[168:169], v[168:169], 1, v[130:131]
	v_or_b32_e32 v102, 41, v148
	global_store_short v[168:169], v0, off
	v_cvt_pk_bf16_f32 v0, v103, s0
	v_ashrrev_i32_e32 v103, 31, v102
	v_or_b32_e32 v170, 42, v148
	v_lshlrev_b64 v[102:103], s93, v[102:103]
	v_ashrrev_i32_e32 v171, 31, v170
	v_lshl_add_u64 v[102:103], v[102:103], 1, v[130:131]
	v_lshlrev_b64 v[170:171], s93, v[170:171]
	global_store_short v[102:103], v0, off
	v_cvt_pk_bf16_f32 v0, v104, s0
	v_lshl_add_u64 v[170:171], v[170:171], 1, v[130:131]
	v_or_b32_e32 v104, 43, v148
	global_store_short v[170:171], v0, off
	v_cvt_pk_bf16_f32 v0, v105, s0
	v_ashrrev_i32_e32 v105, 31, v104
	v_or_b32_e32 v172, 48, v148
	v_lshlrev_b64 v[104:105], s93, v[104:105]
	v_ashrrev_i32_e32 v173, 31, v172
	v_lshl_add_u64 v[104:105], v[104:105], 1, v[130:131]
	v_lshlrev_b64 v[172:173], s93, v[172:173]
	global_store_short v[104:105], v0, off
	v_cvt_pk_bf16_f32 v0, v106, s0
	v_lshl_add_u64 v[172:173], v[172:173], 1, v[130:131]
	v_or_b32_e32 v106, 49, v148
	global_store_short v[172:173], v0, off
	v_cvt_pk_bf16_f32 v0, v107, s0
	v_ashrrev_i32_e32 v107, 31, v106
	v_or_b32_e32 v174, 50, v148
	v_lshlrev_b64 v[106:107], s93, v[106:107]
	v_ashrrev_i32_e32 v175, 31, v174
	v_lshl_add_u64 v[106:107], v[106:107], 1, v[130:131]
	v_lshlrev_b64 v[174:175], s93, v[174:175]
	global_store_short v[106:107], v0, off
	v_cvt_pk_bf16_f32 v0, v108, s0
	v_lshl_add_u64 v[174:175], v[174:175], 1, v[130:131]
	v_or_b32_e32 v108, 51, v148
	global_store_short v[174:175], v0, off
	v_cvt_pk_bf16_f32 v0, v109, s0
	v_ashrrev_i32_e32 v109, 31, v108
	v_or_b32_e32 v176, 56, v148
	v_lshlrev_b64 v[108:109], s93, v[108:109]
	v_ashrrev_i32_e32 v177, 31, v176
	v_lshl_add_u64 v[108:109], v[108:109], 1, v[130:131]
	v_lshlrev_b64 v[176:177], s93, v[176:177]
	global_store_short v[108:109], v0, off
	v_cvt_pk_bf16_f32 v0, v110, s0
	v_lshl_add_u64 v[176:177], v[176:177], 1, v[130:131]
	v_or_b32_e32 v110, 57, v148
	global_store_short v[176:177], v0, off
	v_cvt_pk_bf16_f32 v0, v111, s0
	v_ashrrev_i32_e32 v111, 31, v110
	v_or_b32_e32 v178, 58, v148
	v_lshlrev_b64 v[110:111], s93, v[110:111]
	v_ashrrev_i32_e32 v179, 31, v178
	v_lshl_add_u64 v[110:111], v[110:111], 1, v[130:131]
	v_lshlrev_b64 v[178:179], s93, v[178:179]
	global_store_short v[110:111], v0, off
	v_cvt_pk_bf16_f32 v0, v112, s0
	v_lshl_add_u64 v[178:179], v[178:179], 1, v[130:131]
	v_or_b32_e32 v112, 59, v148
	global_store_short v[178:179], v0, off
	v_cvt_pk_bf16_f32 v0, v113, s0
	v_ashrrev_i32_e32 v113, 31, v112
	v_lshlrev_b64 v[112:113], s93, v[112:113]
	v_lshl_add_u64 v[112:113], v[112:113], 1, v[130:131]
	global_store_short v[112:113], v0, off
	v_cvt_pk_bf16_f32 v0, v82, s0
	global_store_short v[132:133], v0, off offset:64
	v_cvt_pk_bf16_f32 v0, v83, s0
	global_store_short v[114:115], v0, off offset:64
	v_cvt_pk_bf16_f32 v0, v84, s0
	global_store_short v[134:135], v0, off offset:64
	v_cvt_pk_bf16_f32 v0, v85, s0
	global_store_short v[116:117], v0, off offset:64
	v_cvt_pk_bf16_f32 v0, v86, s0
	global_store_short v[136:137], v0, off offset:64
	v_cvt_pk_bf16_f32 v0, v87, s0
	global_store_short v[118:119], v0, off offset:64
	v_cvt_pk_bf16_f32 v0, v88, s0
	global_store_short v[154:155], v0, off offset:64
	v_cvt_pk_bf16_f32 v0, v89, s0
	global_store_short v[120:121], v0, off offset:64
	v_cvt_pk_bf16_f32 v0, v90, s0
	global_store_short v[156:157], v0, off offset:64
	v_cvt_pk_bf16_f32 v0, v91, s0
	global_store_short v[122:123], v0, off offset:64
	v_cvt_pk_bf16_f32 v0, v92, s0
	global_store_short v[158:159], v0, off offset:64
	v_cvt_pk_bf16_f32 v0, v93, s0
	global_store_short v[124:125], v0, off offset:64
	v_cvt_pk_bf16_f32 v0, v94, s0
	global_store_short v[160:161], v0, off offset:64
	v_cvt_pk_bf16_f32 v0, v95, s0
	global_store_short v[126:127], v0, off offset:64
	v_cvt_pk_bf16_f32 v0, v96, s0
	global_store_short v[162:163], v0, off offset:64
	v_cvt_pk_bf16_f32 v0, v97, s0
	global_store_short v[128:129], v0, off offset:64
	v_cvt_pk_bf16_f32 v0, v66, s0
	global_store_short v[164:165], v0, off offset:64
	v_cvt_pk_bf16_f32 v0, v67, s0
	global_store_short v[98:99], v0, off offset:64
	v_cvt_pk_bf16_f32 v0, v68, s0
	global_store_short v[166:167], v0, off offset:64
	v_cvt_pk_bf16_f32 v0, v69, s0
	global_store_short v[100:101], v0, off offset:64
	v_cvt_pk_bf16_f32 v0, v70, s0
	global_store_short v[168:169], v0, off offset:64
	v_cvt_pk_bf16_f32 v0, v71, s0
	global_store_short v[102:103], v0, off offset:64
	v_cvt_pk_bf16_f32 v0, v72, s0
	global_store_short v[170:171], v0, off offset:64
	v_cvt_pk_bf16_f32 v0, v73, s0
	global_store_short v[104:105], v0, off offset:64
	v_cvt_pk_bf16_f32 v0, v74, s0
	global_store_short v[172:173], v0, off offset:64
	v_cvt_pk_bf16_f32 v0, v75, s0
	global_store_short v[106:107], v0, off offset:64
	v_cvt_pk_bf16_f32 v0, v76, s0
	global_store_short v[174:175], v0, off offset:64
	v_cvt_pk_bf16_f32 v0, v77, s0
	global_store_short v[108:109], v0, off offset:64
	v_cvt_pk_bf16_f32 v0, v78, s0
	global_store_short v[176:177], v0, off offset:64
	v_cvt_pk_bf16_f32 v0, v79, s0
	global_store_short v[110:111], v0, off offset:64
	v_cvt_pk_bf16_f32 v0, v80, s0
	global_store_short v[178:179], v0, off offset:64
	v_cvt_pk_bf16_f32 v0, v81, s0
	global_store_short v[112:113], v0, off offset:64

.LBB0_397:
	s_andn2_saveexec_b64 s[0:1], s[74:75]
	s_cbranch_execz .LBB0_401
	v_mov_b64_e32 v[136:137], 0xf400000
	v_mov_b64_e32 v[132:133], 0x100
	v_mov_b32_e32 v130, 0x3e000000
	v_mov_b32_e32 v134, v152
	s_and_saveexec_b64 s[20:21], s[4:5]
	v_cndmask_b32_e64 v0, v233, v234, s[22:23]
	v_cndmask_b32_e64 v130, v235, v236, s[22:23]
	v_add_u32_e32 v134, v130, v144
	v_cndmask_b32_e64 v132, v237, v238, s[22:23]
	v_mov_b32_e32 v130, 1.0
	v_mov_b64_e32 v[136:137], v[0:1]
	s_or_b64 exec, exec, s[20:21]
	v_lshl_add_u64 v[136:137], s[78:79], 0, v[136:137]
	v_lshlrev_b32_e32 v0, 1, v153
	v_pk_mul_f32 v[114:115], v[114:115], v[130:131] op_sel_hi:[1,0]
	v_pk_mul_f32 v[116:117], v[116:117], v[130:131] op_sel_hi:[1,0]
	v_pk_mul_f32 v[98:99], v[98:99], v[130:131] op_sel_hi:[1,0]
	v_pk_mul_f32 v[100:101], v[100:101], v[130:131] op_sel_hi:[1,0]
	v_lshl_add_u64 v[136:137], v[136:137], 0, v[0:1]
	s_waitcnt vmcnt(0)
	v_mad_i64_i32 v[154:155], s[20:21], v132, v140, 0
	v_cvt_pk_bf16_f32 v114, v114, v115
	v_cvt_pk_bf16_f32 v115, v116, v117
	v_pk_mul_f32 v[116:117], v[118:119], v[130:131] op_sel_hi:[1,0]
	v_pk_mul_f32 v[118:119], v[120:121], v[130:131] op_sel_hi:[1,0]
	v_ashrrev_i32_e32 v135, 31, v134
	v_cvt_pk_bf16_f32 v98, v98, v99
	v_cvt_pk_bf16_f32 v99, v100, v101
	v_pk_mul_f32 v[100:101], v[102:103], v[130:131] op_sel_hi:[1,0]
	v_pk_mul_f32 v[102:103], v[104:105], v[130:131] op_sel_hi:[1,0]
	v_lshl_add_u64 v[154:155], v[154:155], 1, v[136:137]
	v_cvt_pk_bf16_f32 v116, v116, v117
	v_cvt_pk_bf16_f32 v117, v118, v119
	v_lshlrev_b64 v[118:119], 1, v[134:135]
	v_cvt_pk_bf16_f32 v100, v100, v101
	v_cvt_pk_bf16_f32 v101, v102, v103
	v_lshl_add_u64 v[120:121], v[154:155], 0, v[118:119]
	v_permlane32_swap_b32_e32 v98, v100
	v_permlane32_swap_b32_e32 v99, v101
	global_store_dwordx4 v[120:121], v[98:101], off offset:64
	v_pk_mul_f32 v[102:103], v[112:113], v[130:131] op_sel_hi:[1,0]
	v_permlane32_swap_b32_e32 v114, v116
	v_pk_mul_f32 v[98:99], v[106:107], v[130:131] op_sel_hi:[1,0]
	v_pk_mul_f32 v[100:101], v[108:109], v[130:131] op_sel_hi:[1,0]
	v_cvt_pk_bf16_f32 v98, v98, v99
	v_cvt_pk_bf16_f32 v99, v100, v101
	v_pk_mul_f32 v[100:101], v[110:111], v[130:131] op_sel_hi:[1,0]
	v_permlane32_swap_b32_e32 v115, v117
	v_cvt_pk_bf16_f32 v100, v100, v101
	v_cvt_pk_bf16_f32 v101, v102, v103
	global_store_dwordx4 v[120:121], v[114:117], off
	v_permlane32_swap_b32_e32 v98, v100
	s_nop 0
	v_pk_mul_f32 v[114:115], v[122:123], v[130:131] op_sel_hi:[1,0]
	v_pk_mul_f32 v[116:117], v[124:125], v[130:131] op_sel_hi:[1,0]
	v_permlane32_swap_b32_e32 v99, v101
	v_or_b32_e32 v0, 32, v140
	v_pk_mul_f32 v[82:83], v[82:83], v[130:131] op_sel_hi:[1,0]
	v_pk_mul_f32 v[84:85], v[84:85], v[130:131] op_sel_hi:[1,0]
	v_pk_mul_f32 v[66:67], v[66:67], v[130:131] op_sel_hi:[1,0]
	v_pk_mul_f32 v[68:69], v[68:69], v[130:131] op_sel_hi:[1,0]
	v_cvt_pk_bf16_f32 v114, v114, v115
	v_cvt_pk_bf16_f32 v115, v116, v117
	v_pk_mul_f32 v[116:117], v[126:127], v[130:131] op_sel_hi:[1,0]
	v_pk_mul_f32 v[122:123], v[128:129], v[130:131] op_sel_hi:[1,0]
	global_store_dwordx4 v[120:121], v[98:101], off offset:96
	v_cvt_pk_bf16_f32 v82, v82, v83
	v_cvt_pk_bf16_f32 v83, v84, v85
	v_mad_i64_i32 v[98:99], s[20:21], v132, v0, 0
	v_pk_mul_f32 v[84:85], v[86:87], v[130:131] op_sel_hi:[1,0]
	v_pk_mul_f32 v[86:87], v[88:89], v[130:131] op_sel_hi:[1,0]
	v_cvt_pk_bf16_f32 v66, v66, v67
	v_cvt_pk_bf16_f32 v67, v68, v69
	v_pk_mul_f32 v[68:69], v[70:71], v[130:131] op_sel_hi:[1,0]
	v_pk_mul_f32 v[70:71], v[72:73], v[130:131] op_sel_hi:[1,0]
	v_cvt_pk_bf16_f32 v116, v116, v117
	v_cvt_pk_bf16_f32 v117, v122, v123
	v_lshl_add_u64 v[98:99], v[98:99], 1, v[136:137]
	v_cvt_pk_bf16_f32 v84, v84, v85
	v_cvt_pk_bf16_f32 v85, v86, v87
	v_cvt_pk_bf16_f32 v68, v68, v69
	v_cvt_pk_bf16_f32 v69, v70, v71
	v_permlane32_swap_b32_e32 v114, v116
	v_permlane32_swap_b32_e32 v115, v117
	v_permlane32_swap_b32_e32 v82, v84
	v_permlane32_swap_b32_e32 v83, v85
	v_lshl_add_u64 v[86:87], v[98:99], 0, v[118:119]
	v_permlane32_swap_b32_e32 v66, v68
	v_permlane32_swap_b32_e32 v67, v69
	global_store_dwordx4 v[120:121], v[114:117], off offset:32
	global_store_dwordx4 v[86:87], v[82:85], off
	global_store_dwordx4 v[86:87], v[66:69], off offset:64
	v_pk_mul_f32 v[88:89], v[96:97], v[130:131] op_sel_hi:[1,0]
	v_pk_mul_f32 v[82:83], v[90:91], v[130:131] op_sel_hi:[1,0]
	v_pk_mul_f32 v[84:85], v[92:93], v[130:131] op_sel_hi:[1,0]
	v_pk_mul_f32 v[66:67], v[74:75], v[130:131] op_sel_hi:[1,0]
	v_pk_mul_f32 v[68:69], v[76:77], v[130:131] op_sel_hi:[1,0]
	v_cvt_pk_bf16_f32 v82, v82, v83
	v_cvt_pk_bf16_f32 v83, v84, v85
	v_pk_mul_f32 v[84:85], v[94:95], v[130:131] op_sel_hi:[1,0]
	v_cvt_pk_bf16_f32 v66, v66, v67
	v_cvt_pk_bf16_f32 v67, v68, v69
	v_pk_mul_f32 v[68:69], v[78:79], v[130:131] op_sel_hi:[1,0]
	v_pk_mul_f32 v[70:71], v[80:81], v[130:131] op_sel_hi:[1,0]
	v_cvt_pk_bf16_f32 v84, v84, v85
	v_cvt_pk_bf16_f32 v85, v88, v89
	v_cvt_pk_bf16_f32 v68, v68, v69
	v_cvt_pk_bf16_f32 v69, v70, v71
	v_permlane32_swap_b32_e32 v82, v84
	v_permlane32_swap_b32_e32 v83, v85
	v_permlane32_swap_b32_e32 v66, v68
	v_permlane32_swap_b32_e32 v67, v69
	global_store_dwordx4 v[86:87], v[82:85], off offset:32
	global_store_dwordx4 v[86:87], v[66:69], off offset:96

.LBB0_402:
	s_movk_i32 s21, 0x180
	s_ashr_i32 s20, s37, 1
	v_and_or_b32 v139, v144, s21, v196
	v_lshlrev_b32_e32 v0, s36, v139
	s_lshl_b32 s20, s20, s93
	s_ashr_i32 s21, s20, 31
	v_lshlrev_b32_e32 v0, 1, v0
	v_ashrrev_i32_e32 v147, 31, v146
	v_lshl_add_u64 v[130:131], s[40:41], 0, v[0:1]
	s_lshl_b64 s[20:21], s[20:21], 1
	v_or_b32_e32 v0, 1, v139
	v_lshl_add_u64 v[130:131], v[130:131], 0, s[20:21]
	v_lshlrev_b64 v[132:133], 1, v[146:147]
	v_lshlrev_b32_e32 v0, s36, v0
	v_cvt_pk_bf16_f32 v114, v114, s0
	v_lshl_add_u64 v[130:131], v[130:131], 0, v[132:133]
	v_lshlrev_b32_e32 v0, 1, v0
	global_store_short v[130:131], v114, off
	v_cvt_pk_bf16_f32 v134, v115, s0
	v_lshl_add_u64 v[114:115], s[40:41], 0, v[0:1]
	v_or_b32_e32 v0, 2, v139
	v_lshl_add_u64 v[114:115], v[114:115], 0, s[20:21]
	v_lshlrev_b32_e32 v0, s36, v0
	v_lshl_add_u64 v[114:115], v[114:115], 0, v[132:133]
	v_lshlrev_b32_e32 v0, 1, v0
	global_store_short v[114:115], v134, off
	v_lshl_add_u64 v[134:135], s[40:41], 0, v[0:1]
	v_or_b32_e32 v0, 3, v139
	v_lshl_add_u64 v[134:135], v[134:135], 0, s[20:21]
	v_lshlrev_b32_e32 v0, s36, v0
	v_cvt_pk_bf16_f32 v116, v116, s0
	v_lshl_add_u64 v[134:135], v[134:135], 0, v[132:133]
	v_lshlrev_b32_e32 v0, 1, v0
	global_store_short v[134:135], v116, off
	v_cvt_pk_bf16_f32 v136, v117, s0
	v_lshl_add_u64 v[116:117], s[40:41], 0, v[0:1]
	v_or_b32_e32 v0, 8, v139
	v_lshl_add_u64 v[116:117], v[116:117], 0, s[20:21]
	v_lshlrev_b32_e32 v0, s36, v0
	v_lshl_add_u64 v[116:117], v[116:117], 0, v[132:133]
	v_lshlrev_b32_e32 v0, 1, v0
	global_store_short v[116:117], v136, off
	v_lshl_add_u64 v[136:137], s[40:41], 0, v[0:1]
	v_or_b32_e32 v0, 9, v139
	v_lshl_add_u64 v[136:137], v[136:137], 0, s[20:21]
	v_lshlrev_b32_e32 v0, s36, v0
	v_cvt_pk_bf16_f32 v118, v118, s0
	v_lshl_add_u64 v[136:137], v[136:137], 0, v[132:133]
	v_lshlrev_b32_e32 v0, 1, v0
	global_store_short v[136:137], v118, off
	v_cvt_pk_bf16_f32 v147, v119, s0
	v_lshl_add_u64 v[118:119], s[40:41], 0, v[0:1]
	v_or_b32_e32 v0, 10, v139
	v_lshlrev_b32_e32 v0, s36, v0
	v_lshlrev_b32_e32 v0, 1, v0
	s_waitcnt vmcnt(0)
	v_lshl_add_u64 v[154:155], s[40:41], 0, v[0:1]
	v_or_b32_e32 v0, 11, v139
	v_lshl_add_u64 v[118:119], v[118:119], 0, s[20:21]
	v_lshl_add_u64 v[154:155], v[154:155], 0, s[20:21]
	v_lshlrev_b32_e32 v0, s36, v0
	v_lshl_add_u64 v[118:119], v[118:119], 0, v[132:133]
	v_cvt_pk_bf16_f32 v120, v120, s0
	v_lshl_add_u64 v[154:155], v[154:155], 0, v[132:133]
	v_lshlrev_b32_e32 v0, 1, v0
	global_store_short v[118:119], v147, off
	global_store_short v[154:155], v120, off
	v_cvt_pk_bf16_f32 v147, v121, s0
	v_lshl_add_u64 v[120:121], s[40:41], 0, v[0:1]
	v_or_b32_e32 v0, 16, v139
	v_lshlrev_b32_e32 v0, s36, v0
	v_lshlrev_b32_e32 v0, 1, v0
	v_lshl_add_u64 v[156:157], s[40:41], 0, v[0:1]
	v_or_b32_e32 v0, 17, v139
	v_lshl_add_u64 v[120:121], v[120:121], 0, s[20:21]
	v_lshl_add_u64 v[156:157], v[156:157], 0, s[20:21]
	v_lshlrev_b32_e32 v0, s36, v0
	v_lshl_add_u64 v[120:121], v[120:121], 0, v[132:133]
	v_cvt_pk_bf16_f32 v122, v122, s0
	v_lshl_add_u64 v[156:157], v[156:157], 0, v[132:133]
	v_lshlrev_b32_e32 v0, 1, v0
	global_store_short v[120:121], v147, off
	global_store_short v[156:157], v122, off
	v_cvt_pk_bf16_f32 v147, v123, s0
	v_lshl_add_u64 v[122:123], s[40:41], 0, v[0:1]
	v_or_b32_e32 v0, 18, v139
	v_lshlrev_b32_e32 v0, s36, v0
	v_lshlrev_b32_e32 v0, 1, v0
	v_lshl_add_u64 v[158:159], s[40:41], 0, v[0:1]
	v_or_b32_e32 v0, 19, v139
	v_lshl_add_u64 v[122:123], v[122:123], 0, s[20:21]
	v_lshl_add_u64 v[158:159], v[158:159], 0, s[20:21]
	v_lshlrev_b32_e32 v0, s36, v0
	v_lshl_add_u64 v[122:123], v[122:123], 0, v[132:133]
	v_cvt_pk_bf16_f32 v124, v124, s0
	v_lshl_add_u64 v[158:159], v[158:159], 0, v[132:133]
	v_lshlrev_b32_e32 v0, 1, v0
	global_store_short v[122:123], v147, off
	global_store_short v[158:159], v124, off
	v_cvt_pk_bf16_f32 v147, v125, s0
	v_lshl_add_u64 v[124:125], s[40:41], 0, v[0:1]
	v_or_b32_e32 v0, 24, v139
	v_lshlrev_b32_e32 v0, s36, v0
	v_lshlrev_b32_e32 v0, 1, v0
	v_lshl_add_u64 v[160:161], s[40:41], 0, v[0:1]
	v_or_b32_e32 v0, 25, v139
	v_lshl_add_u64 v[124:125], v[124:125], 0, s[20:21]
	v_lshl_add_u64 v[160:161], v[160:161], 0, s[20:21]
	v_lshlrev_b32_e32 v0, s36, v0
	v_lshl_add_u64 v[124:125], v[124:125], 0, v[132:133]
	v_cvt_pk_bf16_f32 v126, v126, s0
	v_lshl_add_u64 v[160:161], v[160:161], 0, v[132:133]
	v_lshlrev_b32_e32 v0, 1, v0
	global_store_short v[124:125], v147, off
	global_store_short v[160:161], v126, off
	v_cvt_pk_bf16_f32 v147, v127, s0
	v_lshl_add_u64 v[126:127], s[40:41], 0, v[0:1]
	v_or_b32_e32 v0, 26, v139
	v_lshlrev_b32_e32 v0, s36, v0
	v_lshlrev_b32_e32 v0, 1, v0
	v_lshl_add_u64 v[162:163], s[40:41], 0, v[0:1]
	v_or_b32_e32 v0, 27, v139
	v_lshl_add_u64 v[126:127], v[126:127], 0, s[20:21]
	v_lshl_add_u64 v[162:163], v[162:163], 0, s[20:21]
	v_lshlrev_b32_e32 v0, s36, v0
	v_or_b32_e32 v141, 32, v139
	v_lshl_add_u64 v[126:127], v[126:127], 0, v[132:133]
	v_cvt_pk_bf16_f32 v128, v128, s0
	v_lshl_add_u64 v[162:163], v[162:163], 0, v[132:133]
	v_lshlrev_b32_e32 v0, 1, v0
	global_store_short v[126:127], v147, off
	global_store_short v[162:163], v128, off
	v_cvt_pk_bf16_f32 v147, v129, s0
	v_lshl_add_u64 v[128:129], s[40:41], 0, v[0:1]
	v_lshlrev_b32_e32 v0, s36, v141
	v_lshlrev_b32_e32 v0, 1, v0
	v_lshl_add_u64 v[164:165], s[40:41], 0, v[0:1]
	v_or_b32_e32 v0, 33, v139
	v_lshl_add_u64 v[164:165], v[164:165], 0, s[20:21]
	v_lshlrev_b32_e32 v0, s36, v0
	v_cvt_pk_bf16_f32 v98, v98, s0
	v_lshl_add_u64 v[164:165], v[164:165], 0, v[132:133]
	v_lshlrev_b32_e32 v0, 1, v0
	global_store_short v[164:165], v98, off
	v_cvt_pk_bf16_f32 v141, v99, s0
	v_lshl_add_u64 v[98:99], s[40:41], 0, v[0:1]
	v_or_b32_e32 v0, 34, v139
	v_lshlrev_b32_e32 v0, s36, v0
	v_lshlrev_b32_e32 v0, 1, v0
	v_lshl_add_u64 v[166:167], s[40:41], 0, v[0:1]
	v_or_b32_e32 v0, 35, v139
	v_lshl_add_u64 v[98:99], v[98:99], 0, s[20:21]
	v_lshl_add_u64 v[166:167], v[166:167], 0, s[20:21]
	v_lshlrev_b32_e32 v0, s36, v0
	v_lshl_add_u64 v[98:99], v[98:99], 0, v[132:133]
	v_cvt_pk_bf16_f32 v100, v100, s0
	v_lshl_add_u64 v[166:167], v[166:167], 0, v[132:133]
	v_lshlrev_b32_e32 v0, 1, v0
	global_store_short v[98:99], v141, off
	global_store_short v[166:167], v100, off
	v_cvt_pk_bf16_f32 v141, v101, s0
	v_lshl_add_u64 v[100:101], s[40:41], 0, v[0:1]
	v_or_b32_e32 v0, 40, v139
	v_lshlrev_b32_e32 v0, s36, v0
	v_lshlrev_b32_e32 v0, 1, v0
	v_lshl_add_u64 v[168:169], s[40:41], 0, v[0:1]
	v_or_b32_e32 v0, 41, v139
	v_lshl_add_u64 v[100:101], v[100:101], 0, s[20:21]
	v_lshl_add_u64 v[168:169], v[168:169], 0, s[20:21]
	v_lshlrev_b32_e32 v0, s36, v0
	v_lshl_add_u64 v[100:101], v[100:101], 0, v[132:133]
	v_cvt_pk_bf16_f32 v102, v102, s0
	v_lshl_add_u64 v[168:169], v[168:169], 0, v[132:133]
	v_lshlrev_b32_e32 v0, 1, v0
	global_store_short v[100:101], v141, off
	global_store_short v[168:169], v102, off
	v_cvt_pk_bf16_f32 v141, v103, s0
	v_lshl_add_u64 v[102:103], s[40:41], 0, v[0:1]
	v_or_b32_e32 v0, 42, v139
	v_lshlrev_b32_e32 v0, s36, v0
	v_lshlrev_b32_e32 v0, 1, v0
	v_lshl_add_u64 v[170:171], s[40:41], 0, v[0:1]
	v_or_b32_e32 v0, 43, v139
	v_lshl_add_u64 v[102:103], v[102:103], 0, s[20:21]
	v_lshl_add_u64 v[170:171], v[170:171], 0, s[20:21]
	v_lshlrev_b32_e32 v0, s36, v0
	v_lshl_add_u64 v[102:103], v[102:103], 0, v[132:133]
	v_cvt_pk_bf16_f32 v104, v104, s0
	v_lshl_add_u64 v[170:171], v[170:171], 0, v[132:133]
	v_lshlrev_b32_e32 v0, 1, v0
	global_store_short v[102:103], v141, off
	global_store_short v[170:171], v104, off
	v_cvt_pk_bf16_f32 v141, v105, s0
	v_lshl_add_u64 v[104:105], s[40:41], 0, v[0:1]
	v_or_b32_e32 v0, 48, v139
	v_lshlrev_b32_e32 v0, s36, v0
	v_lshlrev_b32_e32 v0, 1, v0
	v_lshl_add_u64 v[172:173], s[40:41], 0, v[0:1]
	v_or_b32_e32 v0, 49, v139
	v_lshl_add_u64 v[104:105], v[104:105], 0, s[20:21]
	v_lshl_add_u64 v[172:173], v[172:173], 0, s[20:21]
	v_lshlrev_b32_e32 v0, s36, v0
	v_lshl_add_u64 v[104:105], v[104:105], 0, v[132:133]
	v_cvt_pk_bf16_f32 v106, v106, s0
	v_lshl_add_u64 v[172:173], v[172:173], 0, v[132:133]
	v_lshlrev_b32_e32 v0, 1, v0
	global_store_short v[104:105], v141, off
	global_store_short v[172:173], v106, off
	v_cvt_pk_bf16_f32 v141, v107, s0
	v_lshl_add_u64 v[106:107], s[40:41], 0, v[0:1]
	v_or_b32_e32 v0, 50, v139
	v_lshlrev_b32_e32 v0, s36, v0
	v_lshlrev_b32_e32 v0, 1, v0
	v_lshl_add_u64 v[174:175], s[40:41], 0, v[0:1]
	v_or_b32_e32 v0, 51, v139
	v_lshl_add_u64 v[106:107], v[106:107], 0, s[20:21]
	v_lshl_add_u64 v[174:175], v[174:175], 0, s[20:21]
	v_lshlrev_b32_e32 v0, s36, v0
	v_lshl_add_u64 v[106:107], v[106:107], 0, v[132:133]
	v_cvt_pk_bf16_f32 v108, v108, s0
	v_lshl_add_u64 v[174:175], v[174:175], 0, v[132:133]
	v_lshlrev_b32_e32 v0, 1, v0
	global_store_short v[106:107], v141, off
	global_store_short v[174:175], v108, off
	v_cvt_pk_bf16_f32 v141, v109, s0
	v_lshl_add_u64 v[108:109], s[40:41], 0, v[0:1]
	v_or_b32_e32 v0, 56, v139
	v_lshlrev_b32_e32 v0, s36, v0
	v_lshlrev_b32_e32 v0, 1, v0
	v_lshl_add_u64 v[176:177], s[40:41], 0, v[0:1]
	v_or_b32_e32 v0, 57, v139
	v_lshl_add_u64 v[108:109], v[108:109], 0, s[20:21]
	v_lshl_add_u64 v[176:177], v[176:177], 0, s[20:21]
	v_lshlrev_b32_e32 v0, s36, v0
	v_lshl_add_u64 v[108:109], v[108:109], 0, v[132:133]
	v_cvt_pk_bf16_f32 v110, v110, s0
	v_lshl_add_u64 v[176:177], v[176:177], 0, v[132:133]
	v_lshlrev_b32_e32 v0, 1, v0
	global_store_short v[108:109], v141, off
	global_store_short v[176:177], v110, off
	v_cvt_pk_bf16_f32 v141, v111, s0
	v_lshl_add_u64 v[110:111], s[40:41], 0, v[0:1]
	v_or_b32_e32 v0, 58, v139
	v_lshlrev_b32_e32 v0, s36, v0
	v_lshlrev_b32_e32 v0, 1, v0
	v_lshl_add_u64 v[178:179], s[40:41], 0, v[0:1]
	v_or_b32_e32 v0, 59, v139
	v_lshl_add_u64 v[178:179], v[178:179], 0, s[20:21]
	v_lshlrev_b32_e32 v0, s36, v0
	v_cvt_pk_bf16_f32 v112, v112, s0
	v_lshl_add_u64 v[178:179], v[178:179], 0, v[132:133]
	v_lshlrev_b32_e32 v0, 1, v0
	global_store_short v[178:179], v112, off
	v_cvt_pk_bf16_f32 v139, v113, s0
	v_lshl_add_u64 v[112:113], s[40:41], 0, v[0:1]
	v_lshl_add_u64 v[128:129], v[128:129], 0, s[20:21]
	v_lshl_add_u64 v[110:111], v[110:111], 0, s[20:21]
	v_lshl_add_u64 v[112:113], v[112:113], 0, s[20:21]
	v_lshl_add_u64 v[128:129], v[128:129], 0, v[132:133]
	v_lshl_add_u64 v[110:111], v[110:111], 0, v[132:133]
	v_lshl_add_u64 v[112:113], v[112:113], 0, v[132:133]
	v_cvt_pk_bf16_f32 v0, v82, s0
	global_store_short v[128:129], v147, off
	global_store_short v[110:111], v141, off
	global_store_short v[112:113], v139, off
	global_store_short v[130:131], v0, off offset:64
	v_cvt_pk_bf16_f32 v0, v83, s0
	global_store_short v[114:115], v0, off offset:64
	v_cvt_pk_bf16_f32 v0, v84, s0
	global_store_short v[134:135], v0, off offset:64
	v_cvt_pk_bf16_f32 v0, v85, s0
	global_store_short v[116:117], v0, off offset:64
	v_cvt_pk_bf16_f32 v0, v86, s0
	global_store_short v[136:137], v0, off offset:64
	v_cvt_pk_bf16_f32 v0, v87, s0
	global_store_short v[118:119], v0, off offset:64
	v_cvt_pk_bf16_f32 v0, v88, s0
	global_store_short v[154:155], v0, off offset:64
	v_cvt_pk_bf16_f32 v0, v89, s0
	global_store_short v[120:121], v0, off offset:64
	v_cvt_pk_bf16_f32 v0, v90, s0
	global_store_short v[156:157], v0, off offset:64
	v_cvt_pk_bf16_f32 v0, v91, s0
	global_store_short v[122:123], v0, off offset:64
	v_cvt_pk_bf16_f32 v0, v92, s0
	global_store_short v[158:159], v0, off offset:64
	v_cvt_pk_bf16_f32 v0, v93, s0
	global_store_short v[124:125], v0, off offset:64
	v_cvt_pk_bf16_f32 v0, v94, s0
	global_store_short v[160:161], v0, off offset:64
	v_cvt_pk_bf16_f32 v0, v95, s0
	global_store_short v[126:127], v0, off offset:64
	v_cvt_pk_bf16_f32 v0, v96, s0
	global_store_short v[162:163], v0, off offset:64
	v_cvt_pk_bf16_f32 v0, v97, s0
	global_store_short v[128:129], v0, off offset:64
	v_cvt_pk_bf16_f32 v0, v66, s0
	global_store_short v[164:165], v0, off offset:64
	v_cvt_pk_bf16_f32 v0, v67, s0
	global_store_short v[98:99], v0, off offset:64
	v_cvt_pk_bf16_f32 v0, v68, s0
	global_store_short v[166:167], v0, off offset:64
	v_cvt_pk_bf16_f32 v0, v69, s0
	global_store_short v[100:101], v0, off offset:64
	v_cvt_pk_bf16_f32 v0, v70, s0
	global_store_short v[168:169], v0, off offset:64
	v_cvt_pk_bf16_f32 v0, v71, s0
	global_store_short v[102:103], v0, off offset:64
	v_cvt_pk_bf16_f32 v0, v72, s0
	global_store_short v[170:171], v0, off offset:64
	v_cvt_pk_bf16_f32 v0, v73, s0
	global_store_short v[104:105], v0, off offset:64
	v_cvt_pk_bf16_f32 v0, v74, s0
	global_store_short v[172:173], v0, off offset:64
	v_cvt_pk_bf16_f32 v0, v75, s0
	global_store_short v[106:107], v0, off offset:64
	v_cvt_pk_bf16_f32 v0, v76, s0
	global_store_short v[174:175], v0, off offset:64
	v_cvt_pk_bf16_f32 v0, v77, s0
	global_store_short v[108:109], v0, off offset:64
	v_cvt_pk_bf16_f32 v0, v78, s0
	global_store_short v[176:177], v0, off offset:64
	v_cvt_pk_bf16_f32 v0, v79, s0
	global_store_short v[110:111], v0, off offset:64
	v_cvt_pk_bf16_f32 v0, v80, s0
	global_store_short v[178:179], v0, off offset:64
	v_cvt_pk_bf16_f32 v0, v81, s0
	global_store_short v[112:113], v0, off offset:64
	s_or_b64 exec, exec, s[0:1]
	s_and_saveexec_b64 s[0:1], s[18:19]
	s_xor_b64 s[18:19], exec, s[0:1]
	s_cbranch_execz .LBB0_359
.LBB0_403:
	s_and_saveexec_b64 s[0:1], s[70:71]
	s_xor_b64 s[20:21], exec, s[0:1]
	s_cbranch_execz .LBB0_438
	s_and_saveexec_b64 s[0:1], s[16:17]
	s_xor_b64 s[16:17], exec, s[0:1]
	s_cbranch_execz .LBB0_435
	s_and_saveexec_b64 s[0:1], s[14:15]
	s_xor_b64 s[14:15], exec, s[0:1]
	s_cbranch_execz .LBB0_434
	s_and_saveexec_b64 s[0:1], s[12:13]
	s_xor_b64 s[12:13], exec, s[0:1]
	s_cbranch_execz .LBB0_417
	s_and_saveexec_b64 s[70:71], s[10:11]
	s_cbranch_execz .LBB0_416
	s_and_b64 s[0:1], s[6:7], exec
	s_cselect_b32 s0, s26, s28
	s_cselect_b32 s1, s29, s35
	v_mov_b32_e32 v66, s1
	v_mov_b32_e32 v67, s0
	v_ashrrev_i32_e32 v147, 31, v146
	v_or_b32_e32 v0, 64, v198
	v_lshl_add_u64 v[80:81], v[146:147], 1, v[66:67]
	v_lshl_add_u64 v[66:67], s[62:63], 0, v[146:147]
	v_lshlrev_b64 v[100:101], 11, v[66:67]
	v_mul_hi_i32_i24_e32 v67, s34, v0
	v_mul_i32_i24_e32 v66, s34, v0
	v_cvt_pk_bf16_f32 v68, v50, s0
	v_lshl_add_u64 v[66:67], v[66:67], 1, v[80:81]
	v_or_b32_e32 v0, 0x41, v198
	global_store_short v[66:67], v68, off
	v_mul_hi_i32_i24_e32 v69, s34, v0
	v_mul_i32_i24_e32 v68, s34, v0
	v_cvt_pk_bf16_f32 v70, v51, s0
	v_lshl_add_u64 v[68:69], v[68:69], 1, v[80:81]
	v_or_b32_e32 v0, 0x42, v198
	global_store_short v[68:69], v70, off
	v_mul_hi_i32_i24_e32 v71, s34, v0
	v_mul_i32_i24_e32 v70, s34, v0
	v_cvt_pk_bf16_f32 v72, v52, s0
	v_lshl_add_u64 v[70:71], v[70:71], 1, v[80:81]
	v_or_b32_e32 v0, 0x43, v198
	global_store_short v[70:71], v72, off
	v_mul_hi_i32_i24_e32 v73, s34, v0
	v_mul_i32_i24_e32 v72, s34, v0
	v_cvt_pk_bf16_f32 v74, v53, s0
	v_lshl_add_u64 v[72:73], v[72:73], 1, v[80:81]
	v_or_b32_e32 v0, 0x48, v198
	global_store_short v[72:73], v74, off
	v_mul_hi_i32_i24_e32 v75, s34, v0
	v_mul_i32_i24_e32 v74, s34, v0
	v_cvt_pk_bf16_f32 v76, v54, s0
	v_lshl_add_u64 v[74:75], v[74:75], 1, v[80:81]
	v_or_b32_e32 v0, 0x49, v198
	global_store_short v[74:75], v76, off
	v_mul_hi_i32_i24_e32 v77, s34, v0
	v_mul_i32_i24_e32 v76, s34, v0
	v_cvt_pk_bf16_f32 v78, v55, s0
	v_lshl_add_u64 v[76:77], v[76:77], 1, v[80:81]
	v_or_b32_e32 v0, 0x4a, v198
	global_store_short v[76:77], v78, off
	v_mul_hi_i32_i24_e32 v79, s34, v0
	v_mul_i32_i24_e32 v78, s34, v0
	v_cvt_pk_bf16_f32 v82, v56, s0
	v_lshl_add_u64 v[78:79], v[78:79], 1, v[80:81]
	v_or_b32_e32 v0, 0x4b, v198
	global_store_short v[78:79], v82, off
	v_mul_hi_i32_i24_e32 v83, s34, v0
	v_mul_i32_i24_e32 v82, s34, v0
	v_cvt_pk_bf16_f32 v84, v57, s0
	v_lshl_add_u64 v[82:83], v[82:83], 1, v[80:81]
	v_or_b32_e32 v0, 0x50, v198
	global_store_short v[82:83], v84, off
	v_mul_hi_i32_i24_e32 v85, s34, v0
	v_mul_i32_i24_e32 v84, s34, v0
	v_cvt_pk_bf16_f32 v86, v58, s0
	v_lshl_add_u64 v[84:85], v[84:85], 1, v[80:81]
	v_or_b32_e32 v0, 0x51, v198
	global_store_short v[84:85], v86, off
	v_mul_hi_i32_i24_e32 v87, s34, v0
	v_mul_i32_i24_e32 v86, s34, v0
	v_cvt_pk_bf16_f32 v88, v59, s0
	v_lshl_add_u64 v[86:87], v[86:87], 1, v[80:81]
	v_or_b32_e32 v0, 0x52, v198
	global_store_short v[86:87], v88, off
	v_mul_hi_i32_i24_e32 v89, s34, v0
	v_mul_i32_i24_e32 v88, s34, v0
	v_cvt_pk_bf16_f32 v90, v60, s0
	v_lshl_add_u64 v[88:89], v[88:89], 1, v[80:81]
	v_or_b32_e32 v0, 0x53, v198
	global_store_short v[88:89], v90, off
	v_mul_hi_i32_i24_e32 v91, s34, v0
	v_mul_i32_i24_e32 v90, s34, v0
	v_cvt_pk_bf16_f32 v92, v61, s0
	v_lshl_add_u64 v[90:91], v[90:91], 1, v[80:81]
	v_or_b32_e32 v0, 0x58, v198
	global_store_short v[90:91], v92, off
	v_mul_hi_i32_i24_e32 v93, s34, v0
	v_mul_i32_i24_e32 v92, s34, v0
	v_cvt_pk_bf16_f32 v94, v62, s0
	v_lshl_add_u64 v[92:93], v[92:93], 1, v[80:81]
	v_or_b32_e32 v0, 0x59, v198
	global_store_short v[92:93], v94, off
	v_mul_hi_i32_i24_e32 v95, s34, v0
	v_mul_i32_i24_e32 v94, s34, v0
	v_cvt_pk_bf16_f32 v96, v63, s0
	v_lshl_add_u64 v[94:95], v[94:95], 1, v[80:81]
	v_or_b32_e32 v0, 0x5a, v198
	global_store_short v[94:95], v96, off
	v_mul_hi_i32_i24_e32 v97, s34, v0
	v_mul_i32_i24_e32 v96, s34, v0
	v_readlane_b32 s10, v254, 21
	v_cvt_pk_bf16_f32 v98, v64, s0
	v_lshl_add_u64 v[96:97], v[96:97], 1, v[80:81]
	v_or_b32_e32 v0, 0x5b, v198
	v_readlane_b32 s11, v254, 22
	global_store_short v[96:97], v98, off
	v_mul_hi_i32_i24_e32 v99, s34, v0
	v_mul_i32_i24_e32 v98, s34, v0
	v_cndmask_b32_e64 v0, 0, 1, s[6:7]
	v_lshl_add_u64 v[100:101], s[10:11], 0, v[100:101]
	v_cvt_pk_bf16_f32 v102, v65, s0
	v_lshl_add_u64 v[98:99], v[98:99], 1, v[80:81]
	v_cmp_ne_u32_e64 s[0:1], 1, v0
	s_andn2_b64 vcc, exec, s[6:7]
	v_lshl_add_u64 v[108:109], v[144:145], 2, v[100:101]
	global_store_short v[98:99], v102, off
	s_cbranch_vccnz .LBB0_410
	v_lshlrev_b32_e32 v0, 2, v196
	v_lshl_add_u64 v[100:101], v[108:109], 0, v[0:1]
	s_mov_b64 s[10:11], 0xaffc700
	v_lshl_add_u64 v[102:103], v[100:101], 0, s[10:11]
	v_add_co_u32_e32 v100, vcc, 0xaffc000, v100
	s_nop 1
	v_addc_co_u32_e32 v101, vcc, 0, v101, vcc
	global_store_dwordx4 v[100:101], v[50:53], off offset:1792
	global_store_dwordx4 v[102:103], v[54:57], off offset:32
	global_store_dwordx4 v[102:103], v[58:61], off offset:64
	global_store_dwordx4 v[102:103], v[62:65], off offset:96
.LBB0_410:
	v_or_b32_e32 v0, 0x60, v198
	v_mul_hi_i32_i24_e32 v51, s34, v0
	v_mul_i32_i24_e32 v50, s34, v0
	v_cvt_pk_bf16_f32 v52, v34, s0
	v_lshl_add_u64 v[50:51], v[50:51], 1, v[80:81]
	v_or_b32_e32 v0, 0x61, v198
	global_store_short v[50:51], v52, off
	v_mul_hi_i32_i24_e32 v53, s34, v0
	v_mul_i32_i24_e32 v52, s34, v0
	v_cvt_pk_bf16_f32 v54, v35, s0
	v_lshl_add_u64 v[52:53], v[52:53], 1, v[80:81]
	v_or_b32_e32 v0, 0x62, v198
	global_store_short v[52:53], v54, off
	v_mul_hi_i32_i24_e32 v55, s34, v0
	v_mul_i32_i24_e32 v54, s34, v0
	v_cvt_pk_bf16_f32 v56, v36, s0
	v_lshl_add_u64 v[54:55], v[54:55], 1, v[80:81]
	v_or_b32_e32 v0, 0x63, v198
	global_store_short v[54:55], v56, off
	v_mul_hi_i32_i24_e32 v57, s34, v0
	v_mul_i32_i24_e32 v56, s34, v0
	v_cvt_pk_bf16_f32 v58, v37, s0
	v_lshl_add_u64 v[56:57], v[56:57], 1, v[80:81]
	v_or_b32_e32 v0, 0x68, v198
	global_store_short v[56:57], v58, off
	v_mul_hi_i32_i24_e32 v59, s34, v0
	v_mul_i32_i24_e32 v58, s34, v0
	v_cvt_pk_bf16_f32 v60, v38, s0
	v_lshl_add_u64 v[58:59], v[58:59], 1, v[80:81]
	v_or_b32_e32 v0, 0x69, v198
	global_store_short v[58:59], v60, off
	v_mul_hi_i32_i24_e32 v61, s34, v0
	v_mul_i32_i24_e32 v60, s34, v0
	v_cvt_pk_bf16_f32 v62, v39, s0
	v_lshl_add_u64 v[60:61], v[60:61], 1, v[80:81]
	v_or_b32_e32 v0, 0x6a, v198
	global_store_short v[60:61], v62, off
	v_mul_hi_i32_i24_e32 v63, s34, v0
	v_mul_i32_i24_e32 v62, s34, v0
	v_cvt_pk_bf16_f32 v64, v40, s0
	v_lshl_add_u64 v[62:63], v[62:63], 1, v[80:81]
	v_or_b32_e32 v0, 0x6b, v198
	global_store_short v[62:63], v64, off
	v_mul_hi_i32_i24_e32 v65, s34, v0
	v_mul_i32_i24_e32 v64, s34, v0
	v_cvt_pk_bf16_f32 v100, v41, s0
	v_lshl_add_u64 v[64:65], v[64:65], 1, v[80:81]
	v_or_b32_e32 v0, 0x70, v198
	global_store_short v[64:65], v100, off
	v_mul_hi_i32_i24_e32 v101, s34, v0
	v_mul_i32_i24_e32 v100, s34, v0
	v_cvt_pk_bf16_f32 v102, v42, s0
	v_lshl_add_u64 v[100:101], v[100:101], 1, v[80:81]
	v_or_b32_e32 v0, 0x71, v198
	global_store_short v[100:101], v102, off
	v_mul_hi_i32_i24_e32 v103, s34, v0
	v_mul_i32_i24_e32 v102, s34, v0
	v_cvt_pk_bf16_f32 v104, v43, s0
	v_lshl_add_u64 v[102:103], v[102:103], 1, v[80:81]
	v_or_b32_e32 v0, 0x72, v198
	global_store_short v[102:103], v104, off
	v_mul_hi_i32_i24_e32 v105, s34, v0
	v_mul_i32_i24_e32 v104, s34, v0
	v_cvt_pk_bf16_f32 v106, v44, s0
	v_lshl_add_u64 v[104:105], v[104:105], 1, v[80:81]
	v_or_b32_e32 v0, 0x73, v198
	global_store_short v[104:105], v106, off
	v_mul_hi_i32_i24_e32 v107, s34, v0
	v_mul_i32_i24_e32 v106, s34, v0
	v_cvt_pk_bf16_f32 v110, v45, s0
	v_lshl_add_u64 v[106:107], v[106:107], 1, v[80:81]
	v_or_b32_e32 v0, 0x78, v198
	global_store_short v[106:107], v110, off
	v_mul_hi_i32_i24_e32 v111, s34, v0
	v_mul_i32_i24_e32 v110, s34, v0
	v_cvt_pk_bf16_f32 v112, v46, s0
	v_lshl_add_u64 v[110:111], v[110:111], 1, v[80:81]
	v_or_b32_e32 v0, 0x79, v198
	global_store_short v[110:111], v112, off
	v_mul_hi_i32_i24_e32 v113, s34, v0
	v_mul_i32_i24_e32 v112, s34, v0
	v_cvt_pk_bf16_f32 v114, v47, s0
	v_lshl_add_u64 v[112:113], v[112:113], 1, v[80:81]
	v_or_b32_e32 v0, 0x7a, v198
	global_store_short v[112:113], v114, off
	v_mul_hi_i32_i24_e32 v115, s34, v0
	v_mul_i32_i24_e32 v114, s34, v0
	v_cvt_pk_bf16_f32 v116, v48, s0
	v_lshl_add_u64 v[114:115], v[114:115], 1, v[80:81]
	v_or_b32_e32 v0, 0x7b, v198
	global_store_short v[114:115], v116, off
	v_mul_hi_i32_i24_e32 v117, s34, v0
	v_mul_i32_i24_e32 v116, s34, v0
	v_cvt_pk_bf16_f32 v118, v49, s0
	v_lshl_add_u64 v[80:81], v[116:117], 1, v[80:81]
	s_and_b64 vcc, exec, s[0:1]
	global_store_short v[80:81], v118, off
	s_cbranch_vccnz .LBB0_412
	v_lshlrev_b32_e32 v0, 2, v196
	v_lshl_add_u64 v[108:109], v[108:109], 0, v[0:1]
	s_mov_b64 s[10:11], 0xaffc780
	v_lshl_add_u64 v[116:117], v[108:109], 0, s[10:11]
	v_add_co_u32_e32 v108, vcc, 0xaffc000, v108
	s_nop 1
	v_addc_co_u32_e32 v109, vcc, 0, v109, vcc
	global_store_dwordx4 v[108:109], v[34:37], off offset:1920
	global_store_dwordx4 v[116:117], v[38:41], off offset:32
	global_store_dwordx4 v[116:117], v[42:45], off offset:64
	global_store_dwordx4 v[116:117], v[46:49], off offset:96
.LBB0_412:
	v_cvt_pk_bf16_f32 v0, v18, s0
	global_store_short v[66:67], v0, off offset:64
	v_cvt_pk_bf16_f32 v0, v19, s0
	global_store_short v[68:69], v0, off offset:64
	v_cvt_pk_bf16_f32 v0, v20, s0
	global_store_short v[70:71], v0, off offset:64
	v_cvt_pk_bf16_f32 v0, v21, s0
	global_store_short v[72:73], v0, off offset:64
	v_cvt_pk_bf16_f32 v0, v22, s0
	global_store_short v[74:75], v0, off offset:64
	v_cvt_pk_bf16_f32 v0, v23, s0
	global_store_short v[76:77], v0, off offset:64
	v_cvt_pk_bf16_f32 v0, v24, s0
	global_store_short v[78:79], v0, off offset:64
	v_cvt_pk_bf16_f32 v0, v25, s0
	global_store_short v[82:83], v0, off offset:64
	v_cvt_pk_bf16_f32 v0, v26, s0
	global_store_short v[84:85], v0, off offset:64
	v_cvt_pk_bf16_f32 v0, v27, s0
	v_or_b32_e32 v34, 32, v146
	global_store_short v[86:87], v0, off offset:64
	v_cvt_pk_bf16_f32 v0, v28, s0
	v_ashrrev_i32_e32 v35, 31, v34
	global_store_short v[88:89], v0, off offset:64
	v_cvt_pk_bf16_f32 v0, v29, s0
	v_lshl_add_u64 v[34:35], s[62:63], 0, v[34:35]
	global_store_short v[90:91], v0, off offset:64
	v_cvt_pk_bf16_f32 v0, v30, s0
	v_readlane_b32 s10, v254, 21
	v_lshlrev_b64 v[34:35], 11, v[34:35]
	global_store_short v[92:93], v0, off offset:64
	v_cvt_pk_bf16_f32 v0, v31, s0
	v_readlane_b32 s11, v254, 22
	global_store_short v[94:95], v0, off offset:64
	v_cvt_pk_bf16_f32 v0, v32, s0
	v_lshl_add_u64 v[34:35], s[10:11], 0, v[34:35]
	global_store_short v[96:97], v0, off offset:64
	v_cvt_pk_bf16_f32 v0, v33, s0
	s_and_b64 vcc, exec, s[0:1]
	v_lshl_add_u64 v[34:35], v[144:145], 2, v[34:35]
	global_store_short v[98:99], v0, off offset:64
	s_cbranch_vccnz .LBB0_414
	v_lshlrev_b32_e32 v0, 2, v196
	v_lshl_add_u64 v[36:37], v[34:35], 0, v[0:1]
	s_mov_b64 s[10:11], 0xaffc700
	v_lshl_add_u64 v[38:39], v[36:37], 0, s[10:11]
	v_add_co_u32_e32 v36, vcc, 0xaffc000, v36
	s_nop 1
	v_addc_co_u32_e32 v37, vcc, 0, v37, vcc
	global_store_dwordx4 v[36:37], v[18:21], off offset:1792
	global_store_dwordx4 v[38:39], v[22:25], off offset:32
	global_store_dwordx4 v[38:39], v[26:29], off offset:64
	global_store_dwordx4 v[38:39], v[30:33], off offset:96
.LBB0_414:
	v_cvt_pk_bf16_f32 v0, v2, s0
	global_store_short v[50:51], v0, off offset:64
	v_cvt_pk_bf16_f32 v0, v3, s0
	global_store_short v[52:53], v0, off offset:64
	v_cvt_pk_bf16_f32 v0, v4, s0
	global_store_short v[54:55], v0, off offset:64
	v_cvt_pk_bf16_f32 v0, v5, s0
	global_store_short v[56:57], v0, off offset:64
	v_cvt_pk_bf16_f32 v0, v6, s0
	global_store_short v[58:59], v0, off offset:64
	v_cvt_pk_bf16_f32 v0, v7, s0
	global_store_short v[60:61], v0, off offset:64
	v_cvt_pk_bf16_f32 v0, v8, s0
	global_store_short v[62:63], v0, off offset:64
	v_cvt_pk_bf16_f32 v0, v9, s0
	global_store_short v[64:65], v0, off offset:64
	v_cvt_pk_bf16_f32 v0, v10, s0
	global_store_short v[100:101], v0, off offset:64
	v_cvt_pk_bf16_f32 v0, v11, s0
	global_store_short v[102:103], v0, off offset:64
	v_cvt_pk_bf16_f32 v0, v12, s0
	global_store_short v[104:105], v0, off offset:64
	v_cvt_pk_bf16_f32 v0, v13, s0
	global_store_short v[106:107], v0, off offset:64
	v_cvt_pk_bf16_f32 v0, v14, s0
	global_store_short v[110:111], v0, off offset:64
	v_cvt_pk_bf16_f32 v0, v15, s0
	global_store_short v[112:113], v0, off offset:64
	v_cvt_pk_bf16_f32 v0, v16, s0
	global_store_short v[114:115], v0, off offset:64
	v_cvt_pk_bf16_f32 v0, v17, s0
	s_and_b64 vcc, exec, s[0:1]
	global_store_short v[80:81], v0, off offset:64
	s_cbranch_vccnz .LBB0_416
	v_lshlrev_b32_e32 v0, 2, v196
	v_lshl_add_u64 v[18:19], v[34:35], 0, v[0:1]
	s_mov_b64 s[0:1], 0xaffc780
	v_lshl_add_u64 v[20:21], v[18:19], 0, s[0:1]
	v_add_co_u32_e32 v18, vcc, 0xaffc000, v18
	s_nop 1
	v_addc_co_u32_e32 v19, vcc, 0, v19, vcc
	global_store_dwordx4 v[18:19], v[2:5], off offset:1920
	global_store_dwordx4 v[20:21], v[6:9], off offset:32
	global_store_dwordx4 v[20:21], v[10:13], off offset:64
	global_store_dwordx4 v[20:21], v[14:17], off offset:96

.LBB0_417:
	s_andn2_saveexec_b64 s[0:1], s[12:13]
	s_cbranch_execz .LBB0_433
	v_and_b32_e32 v68, 64, v231
	v_xor_b32_e32 v0, 32, v231
	v_add_u32_e32 v68, 64, v68
	v_cmp_lt_i32_e32 vcc, v0, v68
	v_pk_mul_f32 v[76:77], v[40:41], v[40:41]
	v_pk_mul_f32 v[74:75], v[42:43], v[42:43]
	v_cndmask_b32_e32 v0, v231, v0, vcc
	v_lshlrev_b32_e32 v87, 2, v0
	v_mul_f32_e32 v0, v51, v51
	v_fmac_f32_e32 v0, v50, v50
	v_fmac_f32_e32 v0, v52, v52
	v_fmac_f32_e32 v0, v53, v53
	v_fmac_f32_e32 v0, v54, v54
	v_fmac_f32_e32 v0, v55, v55
	v_fmac_f32_e32 v0, v56, v56
	v_fmac_f32_e32 v0, v57, v57
	v_fmac_f32_e32 v0, v58, v58
	v_fmac_f32_e32 v0, v59, v59
	v_fmac_f32_e32 v0, v60, v60
	v_fmac_f32_e32 v0, v61, v61
	v_fmac_f32_e32 v0, v62, v62
	v_fmac_f32_e32 v0, v63, v63
	v_fmac_f32_e32 v0, v64, v64
	v_fmac_f32_e32 v0, v65, v65
	v_fmac_f32_e32 v0, v34, v34
	v_fmac_f32_e32 v0, v35, v35
	v_fmac_f32_e32 v0, v36, v36
	v_fmac_f32_e32 v0, v37, v37
	v_fmac_f32_e32 v0, v38, v38
	v_fmac_f32_e32 v0, v39, v39
	v_add_f32_e32 v0, v76, v0
	v_add_f32_e32 v0, v77, v0
	v_add_f32_e32 v0, v74, v0
	v_pk_mul_f32 v[72:73], v[44:45], v[44:45]
	v_add_f32_e32 v0, v75, v0
	v_add_f32_e32 v0, v72, v0
	v_pk_mul_f32 v[70:71], v[46:47], v[46:47]
	v_add_f32_e32 v0, v73, v0
	v_add_f32_e32 v0, v70, v0
	v_pk_mul_f32 v[68:69], v[48:49], v[48:49]
	v_add_f32_e32 v0, v71, v0
	v_add_f32_e32 v0, v68, v0
	v_add_f32_e32 v0, v69, v0
	ds_bpermute_b32 v68, v87, v0
	v_readlane_b32 s44, v253, 51
	v_readlane_b32 s58, v254, 1
	v_readlane_b32 s59, v254, 2
	v_or_b32_e32 v86, 2, v196
	s_waitcnt lgkmcnt(0)
	v_add_f32_e32 v0, v0, v68
	v_fmamk_f32 v0, v0, 0x3c800000, v230
	v_cmp_gt_f32_e32 vcc, s95, v0
	v_mul_f32_e32 v68, 0x4b800000, v0
	v_lshl_add_u64 v[66:67], v[150:151], 2, s[58:59]
	v_cndmask_b32_e32 v0, v0, v68, vcc
	v_rsq_f32_e32 v0, v0
	v_or_b32_e32 v85, 8, v196
	v_or_b32_e32 v84, 10, v196
	v_readlane_b32 s45, v253, 52
	v_mul_f32_e32 v68, 0x45800000, v0
	v_cndmask_b32_e32 v76, v0, v68, vcc
	v_lshlrev_b32_e32 v0, 2, v196
	v_lshl_add_u64 v[74:75], v[66:67], 0, v[0:1]
	global_load_dwordx4 v[66:69], v[74:75], off
	global_load_dwordx4 v[70:73], v[74:75], off offset:64
	v_pk_mul_f32 v[50:51], v[50:51], v[76:77] op_sel_hi:[1,0]
	v_pk_mul_f32 v[52:53], v[52:53], v[76:77] op_sel_hi:[1,0]
	v_pk_mul_f32 v[54:55], v[54:55], v[76:77] op_sel_hi:[1,0]
	v_pk_mul_f32 v[56:57], v[56:57], v[76:77] op_sel_hi:[1,0]
	v_pk_mul_f32 v[34:35], v[34:35], v[76:77] op_sel_hi:[1,0]
	v_pk_mul_f32 v[36:37], v[36:37], v[76:77] op_sel_hi:[1,0]
	v_pk_mul_f32 v[38:39], v[38:39], v[76:77] op_sel_hi:[1,0]
	v_pk_mul_f32 v[40:41], v[40:41], v[76:77] op_sel_hi:[1,0]
	s_andn2_b64 vcc, exec, s[68:69]
	v_readlane_b32 s46, v253, 53
	v_readlane_b32 s47, v253, 54
	v_readlane_b32 s48, v253, 55
	v_readlane_b32 s49, v253, 56
	v_readlane_b32 s50, v253, 57
	v_readlane_b32 s51, v253, 58
	v_readlane_b32 s52, v253, 59
	v_readlane_b32 s53, v253, 60
	v_readlane_b32 s54, v253, 61
	v_readlane_b32 s55, v253, 62
	v_readlane_b32 s56, v253, 63
	v_readlane_b32 s57, v254, 0
	global_load_dwordx4 v[78:81], v[74:75], off offset:96
	s_waitcnt vmcnt(0)
	v_pk_mul_f32 v[66:67], v[66:67], v[50:51]
	v_pk_mul_f32 v[50:51], v[58:59], v[76:77] op_sel_hi:[1,0]
	v_pk_mul_f32 v[68:69], v[68:69], v[52:53]
	v_pk_mul_f32 v[52:53], v[60:61], v[76:77] op_sel_hi:[1,0]
	global_load_dwordx4 v[58:61], v[74:75], off offset:32
	v_pk_mul_f32 v[50:51], v[70:71], v[50:51]
	v_pk_mul_f32 v[52:53], v[52:53], v[72:73]
	s_waitcnt vmcnt(0)
	v_pk_mul_f32 v[70:71], v[58:59], v[54:55]
	v_pk_mul_f32 v[72:73], v[60:61], v[56:57]
	global_load_dwordx4 v[58:61], v[74:75], off offset:128
	v_pk_mul_f32 v[54:55], v[62:63], v[76:77] op_sel_hi:[1,0]
	v_pk_mul_f32 v[56:57], v[64:65], v[76:77] op_sel_hi:[1,0]
	global_load_dwordx4 v[62:65], v[74:75], off offset:192
	v_pk_mul_f32 v[54:55], v[54:55], v[78:79]
	v_pk_mul_f32 v[56:57], v[56:57], v[80:81]
	s_waitcnt vmcnt(1)
	v_pk_mul_f32 v[58:59], v[34:35], v[58:59]
	v_pk_mul_f32 v[34:35], v[42:43], v[76:77] op_sel_hi:[1,0]
	v_pk_mul_f32 v[60:61], v[36:37], v[60:61]
	v_pk_mul_f32 v[36:37], v[44:45], v[76:77] op_sel_hi:[1,0]
	global_load_dwordx4 v[42:45], v[74:75], off offset:160
	s_waitcnt vmcnt(1)
	v_pk_mul_f32 v[34:35], v[34:35], v[62:63]
	v_pk_mul_f32 v[36:37], v[36:37], v[64:65]
	global_load_dwordx4 v[62:65], v[74:75], off offset:224
	s_waitcnt vmcnt(1)
	v_pk_mul_f32 v[38:39], v[38:39], v[42:43]
	v_pk_mul_f32 v[42:43], v[46:47], v[76:77] op_sel_hi:[1,0]
	v_pk_mul_f32 v[40:41], v[40:41], v[44:45]
	v_pk_mul_f32 v[44:45], v[48:49], v[76:77] op_sel_hi:[1,0]
	v_cndmask_b32_e64 v46, 0, 1, s[68:69]
	s_waitcnt vmcnt(0)
	v_pk_mul_f32 v[42:43], v[42:43], v[62:63]
	v_pk_mul_f32 v[44:45], v[44:45], v[64:65]
	v_subrev_u32_e32 v62, s64, v140
	v_cmp_ne_u32_e64 s[10:11], 1, v46
	s_cbranch_vccnz .LBB0_420
	v_ashrrev_i32_e32 v46, 2, v62
	v_and_b32_e32 v63, -16, v46
	v_or_b32_e32 v46, v63, v196
	v_readlane_b32 s12, v254, 39
	v_ashrrev_i32_e32 v47, 31, v46
	v_readlane_b32 s13, v254, 40
	s_nop 1
	v_lshl_add_u64 v[46:47], v[46:47], 3, s[12:13]
	global_load_dwordx4 v[46:49], v[46:47], off
	s_waitcnt vmcnt(0) lgkmcnt(0)
	v_mov_b32_e32 v65, v48
	v_mov_b32_e32 v48, v47
	v_mov_b32_e32 v64, v46
	v_pk_mul_f32 v[46:47], v[50:51], v[48:49]
	v_pk_mul_f32 v[48:49], v[66:67], v[48:49]
	v_pk_fma_f32 v[46:47], v[66:67], v[64:65], v[46:47] neg_lo:[0,0,1] neg_hi:[0,0,1]
	v_pk_fma_f32 v[50:51], v[50:51], v[64:65], v[48:49]
	v_or_b32_e32 v48, v63, v86
	v_ashrrev_i32_e32 v49, 31, v48
	v_lshl_add_u64 v[48:49], v[48:49], 3, s[12:13]
	global_load_dwordx4 v[64:67], v[48:49], off
	s_waitcnt vmcnt(0) lgkmcnt(0)
	v_mov_b32_e32 v77, v66
	v_mov_b32_e32 v66, v65
	v_mov_b32_e32 v76, v64
	v_pk_mul_f32 v[64:65], v[68:69], v[66:67]
	v_pk_mul_f32 v[48:49], v[52:53], v[66:67]
	v_pk_fma_f32 v[52:53], v[52:53], v[76:77], v[64:65]
	v_or_b32_e32 v64, v63, v85
	v_ashrrev_i32_e32 v65, 31, v64
	v_lshl_add_u64 v[64:65], v[64:65], 3, s[12:13]
	global_load_dwordx4 v[64:67], v[64:65], off
	v_pk_fma_f32 v[48:49], v[68:69], v[76:77], v[48:49] neg_lo:[0,0,1] neg_hi:[0,0,1]
	s_waitcnt vmcnt(0) lgkmcnt(0)
	v_mov_b32_e32 v69, v66
	v_mov_b32_e32 v66, v65
	v_mov_b32_e32 v68, v64
	v_pk_mul_f32 v[64:65], v[54:55], v[66:67]
	v_pk_mul_f32 v[66:67], v[70:71], v[66:67]
	v_pk_fma_f32 v[64:65], v[70:71], v[68:69], v[64:65] neg_lo:[0,0,1] neg_hi:[0,0,1]
	v_pk_fma_f32 v[54:55], v[54:55], v[68:69], v[66:67]
	v_or_b32_e32 v66, v63, v84
	v_ashrrev_i32_e32 v67, 31, v66
	v_lshl_add_u64 v[66:67], v[66:67], 3, s[12:13]
	global_load_dwordx4 v[66:69], v[66:67], off
	v_lshlrev_b32_e32 v63, 4, v197
	s_waitcnt vmcnt(0) lgkmcnt(0)
	v_mov_b32_e32 v71, v68
	v_mov_b32_e32 v68, v67
	v_mov_b32_e32 v70, v66
	v_pk_mul_f32 v[66:67], v[56:57], v[68:69]
	s_nop 0
	v_pk_fma_f32 v[76:77], v[72:73], v[70:71], v[66:67] neg_lo:[0,0,1] neg_hi:[0,0,1]
	v_pk_mul_f32 v[66:67], v[72:73], v[68:69]
	v_mov_b64_e32 v[72:73], v[76:77]
	v_pk_fma_f32 v[56:57], v[56:57], v[70:71], v[66:67]
	v_or_b32_e32 v66, v196, v63
	v_lshlrev_b32_e32 v66, 3, v66
	v_mov_b32_e32 v67, v1
	v_lshl_add_u64 v[66:67], s[12:13], 0, v[66:67]
	global_load_dwordx4 v[66:69], v[66:67], off
	s_waitcnt vmcnt(0) lgkmcnt(0)
	v_mov_b32_e32 v71, v68
	v_mov_b32_e32 v68, v67
	v_mov_b32_e32 v70, v66
	v_pk_mul_f32 v[66:67], v[34:35], v[68:69]
	s_nop 0
	v_pk_fma_f32 v[78:79], v[58:59], v[70:71], v[66:67] neg_lo:[0,0,1] neg_hi:[0,0,1]
	v_pk_mul_f32 v[58:59], v[58:59], v[68:69]
	s_nop 0
	v_pk_fma_f32 v[34:35], v[34:35], v[70:71], v[58:59]
	v_or_b32_e32 v58, v86, v63
	v_lshlrev_b32_e32 v58, 3, v58
	v_mov_b32_e32 v59, v1
	v_lshl_add_u64 v[58:59], s[12:13], 0, v[58:59]
	global_load_dwordx4 v[66:69], v[58:59], off
	v_mov_b64_e32 v[70:71], v[64:65]
	s_waitcnt vmcnt(0) lgkmcnt(0)
	v_mov_b32_e32 v59, v68
	v_mov_b32_e32 v68, v67
	v_mov_b32_e32 v58, v66
	v_pk_mul_f32 v[66:67], v[36:37], v[68:69]
	s_nop 0
	v_pk_fma_f32 v[80:81], v[60:61], v[58:59], v[66:67] neg_lo:[0,0,1] neg_hi:[0,0,1]
	v_pk_mul_f32 v[60:61], v[60:61], v[68:69]
	v_mov_b64_e32 v[68:69], v[48:49]
	v_pk_fma_f32 v[36:37], v[36:37], v[58:59], v[60:61]
	v_or_b32_e32 v58, v85, v63
	v_lshlrev_b32_e32 v58, 3, v58
	v_mov_b32_e32 v59, v1
	v_lshl_add_u64 v[58:59], s[12:13], 0, v[58:59]
	global_load_dwordx4 v[58:61], v[58:59], off
	s_waitcnt vmcnt(0) lgkmcnt(0)
	v_mov_b32_e32 v67, v60
	v_mov_b32_e32 v60, v59
	v_mov_b32_e32 v66, v58
	v_pk_mul_f32 v[58:59], v[42:43], v[60:61]
	s_nop 0
	v_pk_fma_f32 v[82:83], v[38:39], v[66:67], v[58:59] neg_lo:[0,0,1] neg_hi:[0,0,1]
	v_pk_mul_f32 v[38:39], v[38:39], v[60:61]
	s_nop 0
	v_pk_fma_f32 v[42:43], v[42:43], v[66:67], v[38:39]
	v_or_b32_e32 v38, v84, v63
	v_lshlrev_b32_e32 v38, 3, v38
	v_mov_b32_e32 v39, v1
	v_lshl_add_u64 v[38:39], s[12:13], 0, v[38:39]
	global_load_dwordx4 v[58:61], v[38:39], off
	v_mov_b64_e32 v[66:67], v[46:47]
	s_waitcnt vmcnt(0) lgkmcnt(0)
	v_mov_b32_e32 v39, v60
	v_mov_b32_e32 v60, v59
	v_mov_b32_e32 v38, v58
	v_pk_mul_f32 v[58:59], v[44:45], v[60:61]
	s_nop 0
	v_pk_fma_f32 v[88:89], v[40:41], v[38:39], v[58:59] neg_lo:[0,0,1] neg_hi:[0,0,1]
	v_pk_mul_f32 v[40:41], v[40:41], v[60:61]
	v_mov_b64_e32 v[58:59], v[78:79]
	v_pk_fma_f32 v[44:45], v[44:45], v[38:39], v[40:41]
	v_mov_b64_e32 v[60:61], v[80:81]
	v_mov_b64_e32 v[38:39], v[82:83]
	v_mov_b64_e32 v[40:41], v[88:89]
.LBB0_420:
	v_ashrrev_i32_e32 v139, 31, v138
	v_lshlrev_b64 v[48:49], 1, v[138:139]
	v_lshl_add_u64 v[46:47], v[142:143], 0, v[48:49]
	s_and_saveexec_b64 s[12:13], s[8:9]
	s_xor_b64 s[12:13], exec, s[12:13]
	s_cbranch_execz .LBB0_422
	s_mov_b32 s26, 0x3e38aa3b
	v_pk_mul_f32 v[50:51], v[50:51], s[26:27] op_sel_hi:[1,0]
	v_pk_mul_f32 v[52:53], v[52:53], s[26:27] op_sel_hi:[1,0]
	v_ashrrev_i32_e32 v141, 31, v140
	v_cvt_pk_bf16_f32 v50, v50, v51
	v_cvt_pk_bf16_f32 v51, v52, v53
	v_pk_mul_f32 v[52:53], v[54:55], s[26:27] op_sel_hi:[1,0]
	v_pk_mul_f32 v[54:55], v[56:57], s[26:27] op_sel_hi:[1,0]
	v_lshlrev_b64 v[62:63], 10, v[140:141]
	v_cvt_pk_bf16_f32 v52, v52, v53
	v_cvt_pk_bf16_f32 v53, v54, v55
	v_lshl_add_u64 v[76:77], v[46:47], 0, v[62:63]
	v_permlane32_swap_b32_e32 v50, v52
	v_permlane32_swap_b32_e32 v51, v53
	global_store_dwordx4 v[76:77], v[50:53], off offset:160
	v_pk_mul_f32 v[38:39], v[38:39], s[26:27] op_sel_hi:[1,0]
	v_pk_mul_f32 v[62:63], v[66:67], s[26:27] op_sel_hi:[1,0]
	v_pk_mul_f32 v[50:51], v[58:59], s[26:27] op_sel_hi:[1,0]
	v_pk_mul_f32 v[52:53], v[60:61], s[26:27] op_sel_hi:[1,0]
	v_pk_mul_f32 v[64:65], v[68:69], s[26:27] op_sel_hi:[1,0]
	v_cvt_pk_bf16_f32 v50, v50, v51
	v_cvt_pk_bf16_f32 v51, v52, v53
	v_cvt_pk_bf16_f32 v52, v38, v39
	v_pk_mul_f32 v[38:39], v[40:41], s[26:27] op_sel_hi:[1,0]
	v_pk_mul_f32 v[34:35], v[34:35], s[26:27] op_sel_hi:[1,0]
	v_pk_mul_f32 v[36:37], v[36:37], s[26:27] op_sel_hi:[1,0]
	v_cvt_pk_bf16_f32 v62, v62, v63
	v_cvt_pk_bf16_f32 v63, v64, v65
	v_pk_mul_f32 v[64:65], v[70:71], s[26:27] op_sel_hi:[1,0]
	v_pk_mul_f32 v[66:67], v[72:73], s[26:27] op_sel_hi:[1,0]
	v_cvt_pk_bf16_f32 v53, v38, v39
	v_cvt_pk_bf16_f32 v34, v34, v35
	v_cvt_pk_bf16_f32 v35, v36, v37
	v_pk_mul_f32 v[36:37], v[42:43], s[26:27] op_sel_hi:[1,0]
	v_pk_mul_f32 v[38:39], v[44:45], s[26:27] op_sel_hi:[1,0]
	v_cvt_pk_bf16_f32 v64, v64, v65
	v_cvt_pk_bf16_f32 v65, v66, v67
	v_cvt_pk_bf16_f32 v36, v36, v37
	v_cvt_pk_bf16_f32 v37, v38, v39
	v_permlane32_swap_b32_e32 v62, v64
	v_permlane32_swap_b32_e32 v63, v65
	v_permlane32_swap_b32_e32 v50, v52
	v_permlane32_swap_b32_e32 v51, v53
	v_permlane32_swap_b32_e32 v34, v36
	v_permlane32_swap_b32_e32 v35, v37
	global_store_dwordx4 v[76:77], v[62:65], off offset:128
	global_store_dwordx4 v[76:77], v[50:53], off offset:192
	global_store_dwordx4 v[76:77], v[34:37], off offset:224
.LBB0_422:
	s_or_saveexec_b64 s[68:69], s[12:13]
	v_or_b32_e32 v64, 64, v138
	v_readlane_b32 s12, v254, 43
	v_ashrrev_i32_e32 v65, 31, v64
	v_readlane_b32 s13, v254, 44
	v_lshl_add_u64 v[48:49], s[66:67], 0, v[48:49]
	v_cndmask_b32_e64 v63, 0, 1, s[6:7]
	v_lshl_add_u64 v[64:65], v[64:65], 1, s[12:13]
	s_mov_b64 s[12:13], 0x80
	v_lshl_add_u64 v[48:49], v[48:49], 0, s[12:13]
	v_cndmask_b32_e64 v49, v65, v49, s[6:7]
	v_cndmask_b32_e64 v48, v64, v48, s[6:7]
	v_cmp_ne_u32_e64 s[12:13], 1, v63
	s_xor_b64 exec, exec, s[68:69]
	s_cbranch_execz .LBB0_425
	s_and_b64 s[28:29], s[6:7], exec
	v_ashrrev_i32_e32 v63, 31, v62
	s_cselect_b32 s29, 0, s3
	s_cselect_b32 s28, 0, s2
	v_lshl_add_u64 v[64:65], s[28:29], 0, v[62:63]
	v_lshlrev_b64 v[64:65], 10, v[64:65]
	v_lshl_add_u64 v[64:65], v[48:49], 0, v[64:65]
	v_lshlrev_b32_e32 v76, 1, v153
	v_mov_b32_e32 v77, v1
	v_lshl_add_u64 v[64:65], v[64:65], 0, v[76:77]
	v_cvt_pk_bf16_f32 v76, v66, v67
	v_cvt_pk_bf16_f32 v77, v68, v69
	v_cvt_pk_bf16_f32 v78, v70, v71
	v_cvt_pk_bf16_f32 v79, v72, v73
	s_nop 0
	v_permlane32_swap_b32_e32 v76, v78
	v_permlane32_swap_b32_e32 v77, v79
	global_store_dwordx4 v[64:65], v[76:79], off
	s_and_b64 vcc, exec, s[12:13]
	s_nop 0
	v_cvt_pk_bf16_f32 v76, v50, v51
	v_cvt_pk_bf16_f32 v77, v52, v53
	v_cvt_pk_bf16_f32 v78, v54, v55
	v_cvt_pk_bf16_f32 v79, v56, v57
	s_nop 0
	v_permlane32_swap_b32_e32 v76, v78
	v_permlane32_swap_b32_e32 v77, v79
	global_store_dwordx4 v[64:65], v[76:79], off offset:32
	s_nop 1
	v_cvt_pk_bf16_f32 v76, v58, v59
	v_cvt_pk_bf16_f32 v77, v60, v61
	v_cvt_pk_bf16_f32 v78, v38, v39
	v_cvt_pk_bf16_f32 v79, v40, v41
	s_nop 0
	v_permlane32_swap_b32_e32 v76, v78
	v_permlane32_swap_b32_e32 v77, v79
	global_store_dwordx4 v[64:65], v[76:79], off offset:64
	s_nop 1
	v_cvt_pk_bf16_f32 v76, v34, v35
	v_cvt_pk_bf16_f32 v77, v36, v37
	v_cvt_pk_bf16_f32 v78, v42, v43
	v_cvt_pk_bf16_f32 v79, v44, v45
	s_nop 0
	v_permlane32_swap_b32_e32 v76, v78
	v_permlane32_swap_b32_e32 v77, v79
	global_store_dwordx4 v[64:65], v[76:79], off offset:96
	s_cbranch_vccnz .LBB0_425
	v_lshl_add_u64 v[62:63], s[62:63], 0, v[62:63]
	v_readlane_b32 s28, v254, 54
	v_lshlrev_b64 v[62:63], 11, v[62:63]
	v_readlane_b32 s29, v254, 55
	s_nop 1
	v_lshl_add_u64 v[62:63], s[28:29], 0, v[62:63]
	v_lshl_add_u64 v[62:63], v[138:139], 2, v[62:63]
	v_lshl_add_u64 v[62:63], v[62:63], 0, v[0:1]
	global_store_dwordx4 v[62:63], v[66:69], off offset:256
	global_store_dwordx4 v[62:63], v[70:73], off offset:288
	global_store_dwordx4 v[62:63], v[50:53], off offset:320
	global_store_dwordx4 v[62:63], v[54:57], off offset:352
	global_store_dwordx4 v[62:63], v[58:61], off offset:384
	global_store_dwordx4 v[62:63], v[38:41], off offset:416
	global_store_dwordx4 v[62:63], v[34:37], off offset:448
	global_store_dwordx4 v[62:63], v[42:45], off offset:480

.LBB0_428:
	v_ashrrev_i32_e32 v15, 2, v14
	v_and_b32_e32 v15, -16, v15
	v_or_b32_e32 v16, v15, v196
	v_readlane_b32 s10, v254, 39
	v_ashrrev_i32_e32 v17, 31, v16
	v_readlane_b32 s11, v254, 40
	s_nop 1
	v_lshl_add_u64 v[16:17], v[16:17], 3, s[10:11]
	global_load_dwordx4 v[30:33], v[16:17], off
	s_waitcnt vmcnt(0) lgkmcnt(0)
	v_mov_b32_e32 v45, v32
	v_mov_b32_e32 v32, v31
	v_mov_b32_e32 v44, v30
	v_pk_mul_f32 v[30:31], v[38:39], v[32:33]
	v_pk_mul_f32 v[16:17], v[18:19], v[32:33]
	v_pk_fma_f32 v[18:19], v[18:19], v[44:45], v[30:31]
	v_or_b32_e32 v30, v15, v86
	v_ashrrev_i32_e32 v31, 31, v30
	v_lshl_add_u64 v[30:31], v[30:31], 3, s[10:11]
	global_load_dwordx4 v[30:33], v[30:31], off
	v_pk_fma_f32 v[16:17], v[38:39], v[44:45], v[16:17] neg_lo:[0,0,1] neg_hi:[0,0,1]
	s_waitcnt vmcnt(0) lgkmcnt(0)
	v_mov_b32_e32 v39, v32
	v_mov_b32_e32 v32, v31
	v_mov_b32_e32 v38, v30
	v_pk_mul_f32 v[30:31], v[20:21], v[32:33]
	v_pk_mul_f32 v[32:33], v[40:41], v[32:33]
	v_pk_fma_f32 v[30:31], v[40:41], v[38:39], v[30:31] neg_lo:[0,0,1] neg_hi:[0,0,1]
	v_pk_fma_f32 v[20:21], v[20:21], v[38:39], v[32:33]
	v_or_b32_e32 v32, v15, v85
	v_ashrrev_i32_e32 v33, 31, v32
	v_lshl_add_u64 v[32:33], v[32:33], 3, s[10:11]
	global_load_dwordx4 v[38:41], v[32:33], off
	s_waitcnt vmcnt(0) lgkmcnt(0)
	v_mov_b32_e32 v45, v40
	v_mov_b32_e32 v40, v39
	v_mov_b32_e32 v44, v38
	v_pk_mul_f32 v[32:33], v[22:23], v[40:41]
	s_nop 0
	v_pk_fma_f32 v[32:33], v[34:35], v[44:45], v[32:33] neg_lo:[0,0,1] neg_hi:[0,0,1]
	v_pk_mul_f32 v[34:35], v[34:35], v[40:41]
	s_nop 0
	v_pk_fma_f32 v[22:23], v[22:23], v[44:45], v[34:35]
	v_or_b32_e32 v34, v15, v84
	v_ashrrev_i32_e32 v35, 31, v34
	v_lshl_add_u64 v[34:35], v[34:35], 3, s[10:11]
	global_load_dwordx4 v[38:41], v[34:35], off
	v_lshlrev_b32_e32 v15, 4, v42
	v_and_b32_e32 v15, 0x3f0, v15
	s_waitcnt vmcnt(0) lgkmcnt(0)
	v_mov_b32_e32 v35, v40
	v_mov_b32_e32 v40, v39
	v_mov_b32_e32 v34, v38
	v_pk_mul_f32 v[38:39], v[24:25], v[40:41]
	s_nop 0
	v_pk_fma_f32 v[44:45], v[36:37], v[34:35], v[38:39] neg_lo:[0,0,1] neg_hi:[0,0,1]
	v_pk_mul_f32 v[36:37], v[36:37], v[40:41]
	v_mov_b64_e32 v[40:41], v[30:31]
	v_pk_fma_f32 v[24:25], v[24:25], v[34:35], v[36:37]
	v_or_b32_e32 v34, v15, v196
	v_lshlrev_b32_e32 v34, 3, v34
	v_mov_b32_e32 v35, v1
	v_lshl_add_u64 v[34:35], s[10:11], 0, v[34:35]
	global_load_dwordx4 v[34:37], v[34:35], off
	s_waitcnt vmcnt(0) lgkmcnt(0)
	v_mov_b32_e32 v39, v36
	v_mov_b32_e32 v36, v35
	v_mov_b32_e32 v38, v34
	v_pk_mul_f32 v[34:35], v[2:3], v[36:37]
	s_nop 0
	v_pk_fma_f32 v[50:51], v[26:27], v[38:39], v[34:35] neg_lo:[0,0,1] neg_hi:[0,0,1]
	v_pk_mul_f32 v[26:27], v[26:27], v[36:37]
	s_nop 0
	v_pk_fma_f32 v[2:3], v[2:3], v[38:39], v[26:27]
	v_or_b32_e32 v26, v15, v86
	v_lshlrev_b32_e32 v26, 3, v26
	v_mov_b32_e32 v27, v1
	v_lshl_add_u64 v[26:27], s[10:11], 0, v[26:27]
	global_load_dwordx4 v[34:37], v[26:27], off
	v_mov_b64_e32 v[38:39], v[16:17]
	s_waitcnt vmcnt(0) lgkmcnt(0)
	v_mov_b32_e32 v27, v36
	v_mov_b32_e32 v36, v35
	v_mov_b32_e32 v26, v34
	v_pk_mul_f32 v[34:35], v[4:5], v[36:37]
	s_nop 0
	v_pk_fma_f32 v[52:53], v[28:29], v[26:27], v[34:35] neg_lo:[0,0,1] neg_hi:[0,0,1]
	v_pk_mul_f32 v[28:29], v[28:29], v[36:37]
	v_mov_b64_e32 v[36:37], v[44:45]
	v_pk_fma_f32 v[4:5], v[4:5], v[26:27], v[28:29]
	v_or_b32_e32 v26, v15, v85
	v_lshlrev_b32_e32 v26, 3, v26
	v_mov_b32_e32 v27, v1
	v_lshl_add_u64 v[26:27], s[10:11], 0, v[26:27]
	global_load_dwordx4 v[26:29], v[26:27], off
	s_waitcnt vmcnt(0) lgkmcnt(0)
	v_mov_b32_e32 v35, v28
	v_mov_b32_e32 v28, v27
	v_mov_b32_e32 v34, v26
	v_pk_mul_f32 v[26:27], v[10:11], v[28:29]
	s_nop 0
	v_pk_fma_f32 v[54:55], v[6:7], v[34:35], v[26:27] neg_lo:[0,0,1] neg_hi:[0,0,1]
	v_pk_mul_f32 v[6:7], v[6:7], v[28:29]
	s_nop 0
	v_pk_fma_f32 v[10:11], v[10:11], v[34:35], v[6:7]
	v_or_b32_e32 v6, v15, v84
	v_lshlrev_b32_e32 v6, 3, v6
	v_mov_b32_e32 v7, v1
	v_lshl_add_u64 v[6:7], s[10:11], 0, v[6:7]
	global_load_dwordx4 v[26:29], v[6:7], off
	v_mov_b64_e32 v[34:35], v[32:33]
	s_waitcnt vmcnt(0) lgkmcnt(0)
	v_mov_b32_e32 v7, v28
	v_mov_b32_e32 v28, v27
	v_mov_b32_e32 v6, v26
	v_pk_mul_f32 v[26:27], v[12:13], v[28:29]
	s_nop 0
	v_pk_fma_f32 v[56:57], v[8:9], v[6:7], v[26:27] neg_lo:[0,0,1] neg_hi:[0,0,1]
	v_pk_mul_f32 v[8:9], v[8:9], v[28:29]
	v_mov_b64_e32 v[26:27], v[50:51]
	v_pk_fma_f32 v[12:13], v[12:13], v[6:7], v[8:9]
	v_mov_b64_e32 v[28:29], v[52:53]
	v_mov_b64_e32 v[6:7], v[54:55]
	v_mov_b64_e32 v[8:9], v[56:57]
	s_and_saveexec_b64 s[10:11], s[8:9]
	s_xor_b64 s[8:9], exec, s[10:11]
	s_cbranch_execz .LBB0_427
.LBB0_429:
	v_ashrrev_i32_e32 v43, 31, v42
	v_lshlrev_b64 v[14:15], 10, v[42:43]
	s_mov_b32 s10, 0x3e38aa3b
	v_lshl_add_u64 v[30:31], v[46:47], 0, v[14:15]
	v_pk_mul_f32 v[14:15], v[38:39], s[10:11] op_sel_hi:[1,0]
	v_pk_mul_f32 v[16:17], v[40:41], s[10:11] op_sel_hi:[1,0]
	v_cvt_pk_bf16_f32 v14, v14, v15
	v_cvt_pk_bf16_f32 v15, v16, v17
	v_pk_mul_f32 v[16:17], v[34:35], s[10:11] op_sel_hi:[1,0]
	v_pk_mul_f32 v[32:33], v[36:37], s[10:11] op_sel_hi:[1,0]
	v_cvt_pk_bf16_f32 v16, v16, v17
	v_cvt_pk_bf16_f32 v17, v32, v33
	s_nop 0
	v_permlane32_swap_b32_e32 v14, v16
	v_permlane32_swap_b32_e32 v15, v17
	global_store_dwordx4 v[30:31], v[14:17], off offset:128
	v_pk_mul_f32 v[6:7], v[6:7], s[10:11] op_sel_hi:[1,0]
	v_pk_mul_f32 v[2:3], v[2:3], s[10:11] op_sel_hi:[1,0]
	v_pk_mul_f32 v[14:15], v[18:19], s[10:11] op_sel_hi:[1,0]
	v_pk_mul_f32 v[16:17], v[20:21], s[10:11] op_sel_hi:[1,0]
	v_cvt_pk_bf16_f32 v14, v14, v15
	v_cvt_pk_bf16_f32 v15, v16, v17
	v_pk_mul_f32 v[16:17], v[22:23], s[10:11] op_sel_hi:[1,0]
	v_pk_mul_f32 v[18:19], v[24:25], s[10:11] op_sel_hi:[1,0]
	v_cvt_pk_bf16_f32 v16, v16, v17
	v_cvt_pk_bf16_f32 v17, v18, v19
	s_nop 0
	v_permlane32_swap_b32_e32 v14, v16
	v_permlane32_swap_b32_e32 v15, v17
	global_store_dwordx4 v[30:31], v[14:17], off offset:160
	v_pk_mul_f32 v[4:5], v[4:5], s[10:11] op_sel_hi:[1,0]
	v_cvt_pk_bf16_f32 v2, v2, v3
	v_pk_mul_f32 v[14:15], v[26:27], s[10:11] op_sel_hi:[1,0]
	v_pk_mul_f32 v[16:17], v[28:29], s[10:11] op_sel_hi:[1,0]
	v_cvt_pk_bf16_f32 v14, v14, v15
	v_cvt_pk_bf16_f32 v15, v16, v17
	v_cvt_pk_bf16_f32 v16, v6, v7
	v_pk_mul_f32 v[6:7], v[8:9], s[10:11] op_sel_hi:[1,0]
	v_cvt_pk_bf16_f32 v3, v4, v5
	v_cvt_pk_bf16_f32 v17, v6, v7
	v_pk_mul_f32 v[4:5], v[10:11], s[10:11] op_sel_hi:[1,0]
	v_pk_mul_f32 v[6:7], v[12:13], s[10:11] op_sel_hi:[1,0]
	v_cvt_pk_bf16_f32 v4, v4, v5
	v_cvt_pk_bf16_f32 v5, v6, v7
	v_permlane32_swap_b32_e32 v14, v16
	v_permlane32_swap_b32_e32 v15, v17
	v_permlane32_swap_b32_e32 v2, v4
	v_permlane32_swap_b32_e32 v3, v5
	global_store_dwordx4 v[30:31], v[14:17], off offset:192
	global_store_dwordx4 v[30:31], v[2:5], off offset:224
	s_andn2_saveexec_b64 s[8:9], s[8:9]
	s_cbranch_execz .LBB0_432
.LBB0_430:
	s_and_b64 s[6:7], s[6:7], exec
	v_ashrrev_i32_e32 v15, 31, v14
	s_cselect_b32 s3, 0, s3
	s_cselect_b32 s2, 0, s2
	v_lshl_add_u64 v[16:17], s[2:3], 0, v[14:15]
	v_lshlrev_b64 v[16:17], 10, v[16:17]
	v_lshl_add_u64 v[16:17], v[48:49], 0, v[16:17]
	v_lshlrev_b32_e32 v30, 1, v153
	v_mov_b32_e32 v31, v1
	v_lshl_add_u64 v[16:17], v[16:17], 0, v[30:31]
	v_cvt_pk_bf16_f32 v30, v38, v39
	v_cvt_pk_bf16_f32 v31, v40, v41
	v_cvt_pk_bf16_f32 v32, v34, v35
	v_cvt_pk_bf16_f32 v33, v36, v37
	s_nop 0
	v_permlane32_swap_b32_e32 v30, v32
	v_permlane32_swap_b32_e32 v31, v33
	global_store_dwordx4 v[16:17], v[30:33], off
	s_and_b64 vcc, exec, s[12:13]
	s_nop 0
	v_cvt_pk_bf16_f32 v30, v18, v19
	v_cvt_pk_bf16_f32 v31, v20, v21
	v_cvt_pk_bf16_f32 v32, v22, v23
	v_cvt_pk_bf16_f32 v33, v24, v25
	s_nop 0
	v_permlane32_swap_b32_e32 v30, v32
	v_permlane32_swap_b32_e32 v31, v33
	global_store_dwordx4 v[16:17], v[30:33], off offset:32
	s_nop 1
	v_cvt_pk_bf16_f32 v30, v26, v27
	v_cvt_pk_bf16_f32 v31, v28, v29
	v_cvt_pk_bf16_f32 v32, v6, v7
	v_cvt_pk_bf16_f32 v33, v8, v9
	s_nop 0
	v_permlane32_swap_b32_e32 v30, v32
	v_permlane32_swap_b32_e32 v31, v33
	global_store_dwordx4 v[16:17], v[30:33], off offset:64
	s_nop 1
	v_cvt_pk_bf16_f32 v30, v2, v3
	v_cvt_pk_bf16_f32 v31, v4, v5
	v_cvt_pk_bf16_f32 v32, v10, v11
	v_cvt_pk_bf16_f32 v33, v12, v13
	s_nop 0
	v_permlane32_swap_b32_e32 v30, v32
	v_permlane32_swap_b32_e32 v31, v33
	global_store_dwordx4 v[16:17], v[30:33], off offset:96
	s_cbranch_vccnz .LBB0_432
	v_lshl_add_u64 v[14:15], s[62:63], 0, v[14:15]
	v_readlane_b32 s2, v254, 54
	v_lshlrev_b64 v[14:15], 11, v[14:15]
	v_readlane_b32 s3, v254, 55
	s_nop 1
	v_lshl_add_u64 v[14:15], s[2:3], 0, v[14:15]
	v_lshl_add_u64 v[14:15], v[138:139], 2, v[14:15]
	v_lshl_add_u64 v[14:15], v[14:15], 0, v[0:1]
	global_store_dwordx4 v[14:15], v[38:41], off offset:256
	global_store_dwordx4 v[14:15], v[34:37], off offset:288
	global_store_dwordx4 v[14:15], v[18:21], off offset:320
	global_store_dwordx4 v[14:15], v[22:25], off offset:352
	global_store_dwordx4 v[14:15], v[26:29], off offset:384
	global_store_dwordx4 v[14:15], v[6:9], off offset:416
	global_store_dwordx4 v[14:15], v[2:5], off offset:448
	global_store_dwordx4 v[14:15], v[10:13], off offset:480

.LBB0_435:
	s_andn2_saveexec_b64 s[0:1], s[16:17]
	s_cbranch_execz .LBB0_437
	v_or_b32_e32 v68, 64, v148
	v_ashrrev_i32_e32 v147, 31, v146
	v_ashrrev_i32_e32 v69, 31, v68
	v_lshl_add_u64 v[66:67], v[146:147], 1, s[60:61]
	v_lshlrev_b64 v[68:69], s93, v[68:69]
	v_cvt_pk_bf16_f32 v0, v50, s0
	v_lshl_add_u64 v[68:69], v[68:69], 1, v[66:67]
	v_or_b32_e32 v50, 0x41, v148
	global_store_short v[68:69], v0, off
	v_cvt_pk_bf16_f32 v0, v51, s0
	v_ashrrev_i32_e32 v51, 31, v50
	v_or_b32_e32 v70, 0x42, v148
	v_lshlrev_b64 v[50:51], s93, v[50:51]
	v_ashrrev_i32_e32 v71, 31, v70
	v_lshl_add_u64 v[50:51], v[50:51], 1, v[66:67]
	v_lshlrev_b64 v[70:71], s93, v[70:71]
	global_store_short v[50:51], v0, off
	v_cvt_pk_bf16_f32 v0, v52, s0
	v_lshl_add_u64 v[70:71], v[70:71], 1, v[66:67]
	v_or_b32_e32 v52, 0x43, v148
	global_store_short v[70:71], v0, off
	v_cvt_pk_bf16_f32 v0, v53, s0
	v_ashrrev_i32_e32 v53, 31, v52
	v_or_b32_e32 v72, 0x48, v148
	v_lshlrev_b64 v[52:53], s93, v[52:53]
	v_ashrrev_i32_e32 v73, 31, v72
	v_lshl_add_u64 v[52:53], v[52:53], 1, v[66:67]
	v_lshlrev_b64 v[72:73], s93, v[72:73]
	global_store_short v[52:53], v0, off
	v_cvt_pk_bf16_f32 v0, v54, s0
	v_lshl_add_u64 v[72:73], v[72:73], 1, v[66:67]
	v_or_b32_e32 v54, 0x49, v148
	global_store_short v[72:73], v0, off
	v_cvt_pk_bf16_f32 v0, v55, s0
	v_ashrrev_i32_e32 v55, 31, v54
	v_or_b32_e32 v74, 0x4a, v148
	v_lshlrev_b64 v[54:55], s93, v[54:55]
	v_ashrrev_i32_e32 v75, 31, v74
	v_lshl_add_u64 v[54:55], v[54:55], 1, v[66:67]
	v_lshlrev_b64 v[74:75], s93, v[74:75]
	global_store_short v[54:55], v0, off
	v_cvt_pk_bf16_f32 v0, v56, s0
	v_lshl_add_u64 v[74:75], v[74:75], 1, v[66:67]
	v_or_b32_e32 v56, 0x4b, v148
	global_store_short v[74:75], v0, off
	v_cvt_pk_bf16_f32 v0, v57, s0
	v_ashrrev_i32_e32 v57, 31, v56
	v_or_b32_e32 v76, 0x50, v148
	v_lshlrev_b64 v[56:57], s93, v[56:57]
	v_ashrrev_i32_e32 v77, 31, v76
	v_lshl_add_u64 v[56:57], v[56:57], 1, v[66:67]
	v_lshlrev_b64 v[76:77], s93, v[76:77]
	global_store_short v[56:57], v0, off
	v_cvt_pk_bf16_f32 v0, v58, s0
	v_lshl_add_u64 v[76:77], v[76:77], 1, v[66:67]
	v_or_b32_e32 v58, 0x51, v148
	global_store_short v[76:77], v0, off
	v_cvt_pk_bf16_f32 v0, v59, s0
	v_ashrrev_i32_e32 v59, 31, v58
	v_or_b32_e32 v78, 0x52, v148
	v_lshlrev_b64 v[58:59], s93, v[58:59]
	v_ashrrev_i32_e32 v79, 31, v78
	v_lshl_add_u64 v[58:59], v[58:59], 1, v[66:67]
	v_lshlrev_b64 v[78:79], s93, v[78:79]
	global_store_short v[58:59], v0, off
	v_cvt_pk_bf16_f32 v0, v60, s0
	v_lshl_add_u64 v[78:79], v[78:79], 1, v[66:67]
	v_or_b32_e32 v60, 0x53, v148
	global_store_short v[78:79], v0, off
	v_cvt_pk_bf16_f32 v0, v61, s0
	v_ashrrev_i32_e32 v61, 31, v60
	v_or_b32_e32 v80, 0x58, v148
	v_lshlrev_b64 v[60:61], s93, v[60:61]
	v_ashrrev_i32_e32 v81, 31, v80
	v_lshl_add_u64 v[60:61], v[60:61], 1, v[66:67]
	v_lshlrev_b64 v[80:81], s93, v[80:81]
	global_store_short v[60:61], v0, off
	v_cvt_pk_bf16_f32 v0, v62, s0
	v_lshl_add_u64 v[80:81], v[80:81], 1, v[66:67]
	v_or_b32_e32 v62, 0x59, v148
	global_store_short v[80:81], v0, off
	v_cvt_pk_bf16_f32 v0, v63, s0
	v_ashrrev_i32_e32 v63, 31, v62
	v_or_b32_e32 v82, 0x5a, v148
	v_lshlrev_b64 v[62:63], s93, v[62:63]
	v_ashrrev_i32_e32 v83, 31, v82
	v_lshl_add_u64 v[62:63], v[62:63], 1, v[66:67]
	v_lshlrev_b64 v[82:83], s93, v[82:83]
	global_store_short v[62:63], v0, off
	v_cvt_pk_bf16_f32 v0, v64, s0
	v_lshl_add_u64 v[82:83], v[82:83], 1, v[66:67]
	v_or_b32_e32 v64, 0x5b, v148
	global_store_short v[82:83], v0, off
	v_cvt_pk_bf16_f32 v0, v65, s0
	v_ashrrev_i32_e32 v65, 31, v64
	v_or_b32_e32 v84, 0x60, v148
	v_lshlrev_b64 v[64:65], s93, v[64:65]
	v_ashrrev_i32_e32 v85, 31, v84
	v_lshl_add_u64 v[64:65], v[64:65], 1, v[66:67]
	v_lshlrev_b64 v[84:85], s93, v[84:85]
	global_store_short v[64:65], v0, off
	v_cvt_pk_bf16_f32 v0, v34, s0
	v_lshl_add_u64 v[84:85], v[84:85], 1, v[66:67]
	v_or_b32_e32 v34, 0x61, v148
	global_store_short v[84:85], v0, off
	v_cvt_pk_bf16_f32 v0, v35, s0
	v_ashrrev_i32_e32 v35, 31, v34
	v_or_b32_e32 v86, 0x62, v148
	v_lshlrev_b64 v[34:35], s93, v[34:35]
	v_ashrrev_i32_e32 v87, 31, v86
	v_lshl_add_u64 v[34:35], v[34:35], 1, v[66:67]
	v_lshlrev_b64 v[86:87], s93, v[86:87]
	global_store_short v[34:35], v0, off
	v_cvt_pk_bf16_f32 v0, v36, s0
	v_lshl_add_u64 v[86:87], v[86:87], 1, v[66:67]
	v_or_b32_e32 v36, 0x63, v148
	global_store_short v[86:87], v0, off
	v_cvt_pk_bf16_f32 v0, v37, s0
	v_ashrrev_i32_e32 v37, 31, v36
	v_or_b32_e32 v88, 0x68, v148
	v_lshlrev_b64 v[36:37], s93, v[36:37]
	v_ashrrev_i32_e32 v89, 31, v88
	v_lshl_add_u64 v[36:37], v[36:37], 1, v[66:67]
	v_lshlrev_b64 v[88:89], s93, v[88:89]
	global_store_short v[36:37], v0, off
	v_cvt_pk_bf16_f32 v0, v38, s0
	v_lshl_add_u64 v[88:89], v[88:89], 1, v[66:67]
	v_or_b32_e32 v38, 0x69, v148
	global_store_short v[88:89], v0, off
	v_cvt_pk_bf16_f32 v0, v39, s0
	v_ashrrev_i32_e32 v39, 31, v38
	v_or_b32_e32 v90, 0x6a, v148
	v_lshlrev_b64 v[38:39], s93, v[38:39]
	v_ashrrev_i32_e32 v91, 31, v90
	v_lshl_add_u64 v[38:39], v[38:39], 1, v[66:67]
	v_lshlrev_b64 v[90:91], s93, v[90:91]
	global_store_short v[38:39], v0, off
	v_cvt_pk_bf16_f32 v0, v40, s0
	v_lshl_add_u64 v[90:91], v[90:91], 1, v[66:67]
	v_or_b32_e32 v40, 0x6b, v148
	global_store_short v[90:91], v0, off
	v_cvt_pk_bf16_f32 v0, v41, s0
	v_ashrrev_i32_e32 v41, 31, v40
	v_or_b32_e32 v92, 0x70, v148
	v_lshlrev_b64 v[40:41], s93, v[40:41]
	v_ashrrev_i32_e32 v93, 31, v92
	v_lshl_add_u64 v[40:41], v[40:41], 1, v[66:67]
	v_lshlrev_b64 v[92:93], s93, v[92:93]
	global_store_short v[40:41], v0, off
	v_cvt_pk_bf16_f32 v0, v42, s0
	v_lshl_add_u64 v[92:93], v[92:93], 1, v[66:67]
	v_or_b32_e32 v42, 0x71, v148
	global_store_short v[92:93], v0, off
	v_cvt_pk_bf16_f32 v0, v43, s0
	v_ashrrev_i32_e32 v43, 31, v42
	v_or_b32_e32 v94, 0x72, v148
	v_lshlrev_b64 v[42:43], s93, v[42:43]
	v_ashrrev_i32_e32 v95, 31, v94
	v_lshl_add_u64 v[42:43], v[42:43], 1, v[66:67]
	v_lshlrev_b64 v[94:95], s93, v[94:95]
	global_store_short v[42:43], v0, off
	v_cvt_pk_bf16_f32 v0, v44, s0
	v_lshl_add_u64 v[94:95], v[94:95], 1, v[66:67]
	v_or_b32_e32 v44, 0x73, v148
	global_store_short v[94:95], v0, off
	v_cvt_pk_bf16_f32 v0, v45, s0
	v_ashrrev_i32_e32 v45, 31, v44
	v_or_b32_e32 v96, 0x78, v148
	v_lshlrev_b64 v[44:45], s93, v[44:45]
	v_ashrrev_i32_e32 v97, 31, v96
	v_lshl_add_u64 v[44:45], v[44:45], 1, v[66:67]
	v_lshlrev_b64 v[96:97], s93, v[96:97]
	global_store_short v[44:45], v0, off
	v_cvt_pk_bf16_f32 v0, v46, s0
	v_lshl_add_u64 v[96:97], v[96:97], 1, v[66:67]
	v_or_b32_e32 v46, 0x79, v148
	global_store_short v[96:97], v0, off
	v_cvt_pk_bf16_f32 v0, v47, s0
	v_ashrrev_i32_e32 v47, 31, v46
	v_or_b32_e32 v98, 0x7a, v148
	v_lshlrev_b64 v[46:47], s93, v[46:47]
	v_ashrrev_i32_e32 v99, 31, v98
	v_lshl_add_u64 v[46:47], v[46:47], 1, v[66:67]
	v_lshlrev_b64 v[98:99], s93, v[98:99]
	global_store_short v[46:47], v0, off
	v_cvt_pk_bf16_f32 v0, v48, s0
	v_lshl_add_u64 v[98:99], v[98:99], 1, v[66:67]
	v_or_b32_e32 v48, 0x7b, v148
	global_store_short v[98:99], v0, off
	v_cvt_pk_bf16_f32 v0, v49, s0
	v_ashrrev_i32_e32 v49, 31, v48
	v_lshlrev_b64 v[48:49], s93, v[48:49]
	v_lshl_add_u64 v[48:49], v[48:49], 1, v[66:67]
	global_store_short v[48:49], v0, off
	v_cvt_pk_bf16_f32 v0, v18, s0
	global_store_short v[68:69], v0, off offset:64
	v_cvt_pk_bf16_f32 v0, v19, s0
	global_store_short v[50:51], v0, off offset:64
	v_cvt_pk_bf16_f32 v0, v20, s0
	global_store_short v[70:71], v0, off offset:64
	v_cvt_pk_bf16_f32 v0, v21, s0
	global_store_short v[52:53], v0, off offset:64
	v_cvt_pk_bf16_f32 v0, v22, s0
	global_store_short v[72:73], v0, off offset:64
	v_cvt_pk_bf16_f32 v0, v23, s0
	global_store_short v[54:55], v0, off offset:64
	v_cvt_pk_bf16_f32 v0, v24, s0
	global_store_short v[74:75], v0, off offset:64
	v_cvt_pk_bf16_f32 v0, v25, s0
	global_store_short v[56:57], v0, off offset:64
	v_cvt_pk_bf16_f32 v0, v26, s0
	global_store_short v[76:77], v0, off offset:64
	v_cvt_pk_bf16_f32 v0, v27, s0
	global_store_short v[58:59], v0, off offset:64
	v_cvt_pk_bf16_f32 v0, v28, s0
	global_store_short v[78:79], v0, off offset:64
	v_cvt_pk_bf16_f32 v0, v29, s0
	global_store_short v[60:61], v0, off offset:64
	v_cvt_pk_bf16_f32 v0, v30, s0
	global_store_short v[80:81], v0, off offset:64
	v_cvt_pk_bf16_f32 v0, v31, s0
	global_store_short v[62:63], v0, off offset:64
	v_cvt_pk_bf16_f32 v0, v32, s0
	global_store_short v[82:83], v0, off offset:64
	v_cvt_pk_bf16_f32 v0, v33, s0
	global_store_short v[64:65], v0, off offset:64
	v_cvt_pk_bf16_f32 v0, v2, s0
	global_store_short v[84:85], v0, off offset:64
	v_cvt_pk_bf16_f32 v0, v3, s0
	global_store_short v[34:35], v0, off offset:64
	v_cvt_pk_bf16_f32 v0, v4, s0
	global_store_short v[86:87], v0, off offset:64
	v_cvt_pk_bf16_f32 v0, v5, s0
	global_store_short v[36:37], v0, off offset:64
	v_cvt_pk_bf16_f32 v0, v6, s0
	global_store_short v[88:89], v0, off offset:64
	v_cvt_pk_bf16_f32 v0, v7, s0
	global_store_short v[38:39], v0, off offset:64
	v_cvt_pk_bf16_f32 v0, v8, s0
	global_store_short v[90:91], v0, off offset:64
	v_cvt_pk_bf16_f32 v0, v9, s0
	global_store_short v[40:41], v0, off offset:64
	v_cvt_pk_bf16_f32 v0, v10, s0
	global_store_short v[92:93], v0, off offset:64
	v_cvt_pk_bf16_f32 v0, v11, s0
	global_store_short v[42:43], v0, off offset:64
	v_cvt_pk_bf16_f32 v0, v12, s0
	global_store_short v[94:95], v0, off offset:64
	v_cvt_pk_bf16_f32 v0, v13, s0
	global_store_short v[44:45], v0, off offset:64
	v_cvt_pk_bf16_f32 v0, v14, s0
	global_store_short v[96:97], v0, off offset:64
	v_cvt_pk_bf16_f32 v0, v15, s0
	global_store_short v[46:47], v0, off offset:64
	v_cvt_pk_bf16_f32 v0, v16, s0
	global_store_short v[98:99], v0, off offset:64
	v_cvt_pk_bf16_f32 v0, v17, s0
	global_store_short v[48:49], v0, off offset:64

.LBB0_438:
	s_andn2_saveexec_b64 s[0:1], s[20:21]
	s_cbranch_execz .LBB0_442
	v_mov_b64_e32 v[70:71], 0xf400000
	v_mov_b64_e32 v[68:69], 0x100
	v_mov_b32_e32 v66, 0x3e000000
	s_and_saveexec_b64 s[6:7], s[4:5]
	v_cndmask_b32_e64 v0, v233, v234, s[22:23]
	v_cndmask_b32_e64 v66, v235, v236, s[22:23]
	v_add_u32_e32 v152, v66, v144
	v_cndmask_b32_e64 v68, v237, v238, s[22:23]
	v_mov_b32_e32 v66, 1.0
	v_mov_b64_e32 v[70:71], v[0:1]
	s_or_b64 exec, exec, s[6:7]
	v_lshl_add_u64 v[70:71], s[78:79], 0, v[70:71]
	v_lshlrev_b32_e32 v0, 1, v153
	v_pk_mul_f32 v[50:51], v[50:51], v[66:67] op_sel_hi:[1,0]
	v_pk_mul_f32 v[52:53], v[52:53], v[66:67] op_sel_hi:[1,0]
	v_pk_mul_f32 v[34:35], v[34:35], v[66:67] op_sel_hi:[1,0]
	v_pk_mul_f32 v[36:37], v[36:37], v[66:67] op_sel_hi:[1,0]
	v_lshl_add_u64 v[70:71], v[70:71], 0, v[0:1]
	v_mad_i64_i32 v[72:73], s[2:3], v68, v140, 0
	v_cvt_pk_bf16_f32 v50, v50, v51
	v_cvt_pk_bf16_f32 v51, v52, v53
	v_pk_mul_f32 v[52:53], v[54:55], v[66:67] op_sel_hi:[1,0]
	v_pk_mul_f32 v[54:55], v[56:57], v[66:67] op_sel_hi:[1,0]
	v_ashrrev_i32_e32 v153, 31, v152
	v_cvt_pk_bf16_f32 v34, v34, v35
	v_cvt_pk_bf16_f32 v35, v36, v37
	v_pk_mul_f32 v[36:37], v[38:39], v[66:67] op_sel_hi:[1,0]
	v_pk_mul_f32 v[38:39], v[40:41], v[66:67] op_sel_hi:[1,0]
	v_lshl_add_u64 v[72:73], v[72:73], 1, v[70:71]
	v_cvt_pk_bf16_f32 v52, v52, v53
	v_cvt_pk_bf16_f32 v53, v54, v55
	v_lshlrev_b64 v[54:55], 1, v[152:153]
	v_cvt_pk_bf16_f32 v36, v36, v37
	v_cvt_pk_bf16_f32 v37, v38, v39
	v_lshl_add_u64 v[56:57], v[72:73], 0, v[54:55]
	v_permlane32_swap_b32_e32 v34, v36
	v_permlane32_swap_b32_e32 v35, v37
	global_store_dwordx4 v[56:57], v[34:37], off offset:192
	v_pk_mul_f32 v[38:39], v[48:49], v[66:67] op_sel_hi:[1,0]
	v_permlane32_swap_b32_e32 v50, v52
	v_pk_mul_f32 v[34:35], v[42:43], v[66:67] op_sel_hi:[1,0]
	v_pk_mul_f32 v[36:37], v[44:45], v[66:67] op_sel_hi:[1,0]
	v_cvt_pk_bf16_f32 v34, v34, v35
	v_cvt_pk_bf16_f32 v35, v36, v37
	v_pk_mul_f32 v[36:37], v[46:47], v[66:67] op_sel_hi:[1,0]
	v_permlane32_swap_b32_e32 v51, v53
	v_cvt_pk_bf16_f32 v36, v36, v37
	v_cvt_pk_bf16_f32 v37, v38, v39
	global_store_dwordx4 v[56:57], v[50:53], off offset:128
	v_permlane32_swap_b32_e32 v34, v36
	s_nop 0
	v_pk_mul_f32 v[50:51], v[58:59], v[66:67] op_sel_hi:[1,0]
	v_pk_mul_f32 v[52:53], v[60:61], v[66:67] op_sel_hi:[1,0]
	v_permlane32_swap_b32_e32 v35, v37
	v_or_b32_e32 v0, 32, v140
	v_pk_mul_f32 v[18:19], v[18:19], v[66:67] op_sel_hi:[1,0]
	v_pk_mul_f32 v[20:21], v[20:21], v[66:67] op_sel_hi:[1,0]
	v_pk_mul_f32 v[2:3], v[2:3], v[66:67] op_sel_hi:[1,0]
	v_pk_mul_f32 v[4:5], v[4:5], v[66:67] op_sel_hi:[1,0]
	v_cvt_pk_bf16_f32 v50, v50, v51
	v_cvt_pk_bf16_f32 v51, v52, v53
	v_pk_mul_f32 v[52:53], v[62:63], v[66:67] op_sel_hi:[1,0]
	v_pk_mul_f32 v[58:59], v[64:65], v[66:67] op_sel_hi:[1,0]
	global_store_dwordx4 v[56:57], v[34:37], off offset:224
	v_cvt_pk_bf16_f32 v18, v18, v19
	v_cvt_pk_bf16_f32 v19, v20, v21
	v_mad_i64_i32 v[34:35], s[2:3], v68, v0, 0
	v_pk_mul_f32 v[20:21], v[22:23], v[66:67] op_sel_hi:[1,0]
	v_pk_mul_f32 v[22:23], v[24:25], v[66:67] op_sel_hi:[1,0]
	v_cvt_pk_bf16_f32 v2, v2, v3
	v_cvt_pk_bf16_f32 v3, v4, v5
	v_pk_mul_f32 v[4:5], v[6:7], v[66:67] op_sel_hi:[1,0]
	v_pk_mul_f32 v[6:7], v[8:9], v[66:67] op_sel_hi:[1,0]
	v_cvt_pk_bf16_f32 v52, v52, v53
	v_cvt_pk_bf16_f32 v53, v58, v59
	v_lshl_add_u64 v[34:35], v[34:35], 1, v[70:71]
	v_cvt_pk_bf16_f32 v20, v20, v21
	v_cvt_pk_bf16_f32 v21, v22, v23
	v_cvt_pk_bf16_f32 v4, v4, v5
	v_cvt_pk_bf16_f32 v5, v6, v7
	v_permlane32_swap_b32_e32 v50, v52
	v_permlane32_swap_b32_e32 v51, v53
	v_permlane32_swap_b32_e32 v18, v20
	v_permlane32_swap_b32_e32 v19, v21
	v_lshl_add_u64 v[22:23], v[34:35], 0, v[54:55]
	v_permlane32_swap_b32_e32 v2, v4
	v_permlane32_swap_b32_e32 v3, v5
	global_store_dwordx4 v[56:57], v[50:53], off offset:160
	global_store_dwordx4 v[22:23], v[18:21], off offset:128
	global_store_dwordx4 v[22:23], v[2:5], off offset:192
	v_pk_mul_f32 v[24:25], v[32:33], v[66:67] op_sel_hi:[1,0]
	v_pk_mul_f32 v[18:19], v[26:27], v[66:67] op_sel_hi:[1,0]
	v_pk_mul_f32 v[20:21], v[28:29], v[66:67] op_sel_hi:[1,0]
	v_pk_mul_f32 v[2:3], v[10:11], v[66:67] op_sel_hi:[1,0]
	v_pk_mul_f32 v[4:5], v[12:13], v[66:67] op_sel_hi:[1,0]
	v_cvt_pk_bf16_f32 v18, v18, v19
	v_cvt_pk_bf16_f32 v19, v20, v21
	v_pk_mul_f32 v[20:21], v[30:31], v[66:67] op_sel_hi:[1,0]
	v_cvt_pk_bf16_f32 v2, v2, v3
	v_cvt_pk_bf16_f32 v3, v4, v5
	v_pk_mul_f32 v[4:5], v[14:15], v[66:67] op_sel_hi:[1,0]
	v_pk_mul_f32 v[6:7], v[16:17], v[66:67] op_sel_hi:[1,0]
	v_cvt_pk_bf16_f32 v20, v20, v21
	v_cvt_pk_bf16_f32 v21, v24, v25
	v_cvt_pk_bf16_f32 v4, v4, v5
	v_cvt_pk_bf16_f32 v5, v6, v7
	v_permlane32_swap_b32_e32 v18, v20
	v_permlane32_swap_b32_e32 v19, v21
	v_permlane32_swap_b32_e32 v2, v4
	v_permlane32_swap_b32_e32 v3, v5
	global_store_dwordx4 v[22:23], v[18:21], off offset:160
	global_store_dwordx4 v[22:23], v[2:5], off offset:224

.LBB0_443:
	s_movk_i32 s3, 0x180
	v_and_or_b32 v100, v144, s3, v196
	s_ashr_i32 s2, s37, 1
	v_or_b32_e32 v0, 64, v100
	v_lshlrev_b32_e32 v0, s36, v0
	s_lshl_b32 s2, s2, s93
	s_ashr_i32 s3, s2, 31
	v_lshlrev_b32_e32 v0, 1, v0
	v_ashrrev_i32_e32 v147, 31, v146
	v_lshl_add_u64 v[66:67], s[40:41], 0, v[0:1]
	s_lshl_b64 s[4:5], s[2:3], 1
	v_or_b32_e32 v0, 0x41, v100
	v_lshl_add_u64 v[66:67], v[66:67], 0, s[4:5]
	v_lshlrev_b64 v[68:69], 1, v[146:147]
	v_lshlrev_b32_e32 v0, s36, v0
	v_cvt_pk_bf16_f32 v50, v50, s0
	v_lshl_add_u64 v[66:67], v[66:67], 0, v[68:69]
	v_lshlrev_b32_e32 v0, 1, v0
	global_store_short v[66:67], v50, off
	v_cvt_pk_bf16_f32 v70, v51, s0
	v_lshl_add_u64 v[50:51], s[40:41], 0, v[0:1]
	v_or_b32_e32 v0, 0x42, v100
	v_lshl_add_u64 v[50:51], v[50:51], 0, s[4:5]
	v_lshlrev_b32_e32 v0, s36, v0
	v_lshl_add_u64 v[50:51], v[50:51], 0, v[68:69]
	v_lshlrev_b32_e32 v0, 1, v0
	global_store_short v[50:51], v70, off
	v_lshl_add_u64 v[70:71], s[40:41], 0, v[0:1]
	v_or_b32_e32 v0, 0x43, v100
	v_lshl_add_u64 v[70:71], v[70:71], 0, s[4:5]
	v_lshlrev_b32_e32 v0, s36, v0
	v_cvt_pk_bf16_f32 v52, v52, s0
	v_lshl_add_u64 v[70:71], v[70:71], 0, v[68:69]
	v_lshlrev_b32_e32 v0, 1, v0
	global_store_short v[70:71], v52, off
	v_cvt_pk_bf16_f32 v72, v53, s0
	v_lshl_add_u64 v[52:53], s[40:41], 0, v[0:1]
	v_or_b32_e32 v0, 0x48, v100
	v_lshl_add_u64 v[52:53], v[52:53], 0, s[4:5]
	v_lshlrev_b32_e32 v0, s36, v0
	v_lshl_add_u64 v[52:53], v[52:53], 0, v[68:69]
	v_lshlrev_b32_e32 v0, 1, v0
	global_store_short v[52:53], v72, off
	v_lshl_add_u64 v[72:73], s[40:41], 0, v[0:1]
	v_or_b32_e32 v0, 0x49, v100
	v_lshl_add_u64 v[72:73], v[72:73], 0, s[4:5]
	v_lshlrev_b32_e32 v0, s36, v0
	v_cvt_pk_bf16_f32 v54, v54, s0
	v_lshl_add_u64 v[72:73], v[72:73], 0, v[68:69]
	v_lshlrev_b32_e32 v0, 1, v0
	global_store_short v[72:73], v54, off
	v_cvt_pk_bf16_f32 v74, v55, s0
	v_lshl_add_u64 v[54:55], s[40:41], 0, v[0:1]
	v_or_b32_e32 v0, 0x4a, v100
	v_lshl_add_u64 v[54:55], v[54:55], 0, s[4:5]
	v_lshlrev_b32_e32 v0, s36, v0
	v_lshl_add_u64 v[54:55], v[54:55], 0, v[68:69]
	v_lshlrev_b32_e32 v0, 1, v0
	global_store_short v[54:55], v74, off
	v_lshl_add_u64 v[74:75], s[40:41], 0, v[0:1]
	v_or_b32_e32 v0, 0x4b, v100
	v_lshl_add_u64 v[74:75], v[74:75], 0, s[4:5]
	v_lshlrev_b32_e32 v0, s36, v0
	v_cvt_pk_bf16_f32 v56, v56, s0
	v_lshl_add_u64 v[74:75], v[74:75], 0, v[68:69]
	v_lshlrev_b32_e32 v0, 1, v0
	global_store_short v[74:75], v56, off
	v_cvt_pk_bf16_f32 v76, v57, s0
	v_lshl_add_u64 v[56:57], s[40:41], 0, v[0:1]
	v_or_b32_e32 v0, 0x50, v100
	v_lshl_add_u64 v[56:57], v[56:57], 0, s[4:5]
	v_lshlrev_b32_e32 v0, s36, v0
	v_lshl_add_u64 v[56:57], v[56:57], 0, v[68:69]
	v_lshlrev_b32_e32 v0, 1, v0
	global_store_short v[56:57], v76, off
	v_lshl_add_u64 v[76:77], s[40:41], 0, v[0:1]
	v_or_b32_e32 v0, 0x51, v100
	v_lshl_add_u64 v[76:77], v[76:77], 0, s[4:5]
	v_lshlrev_b32_e32 v0, s36, v0
	v_cvt_pk_bf16_f32 v58, v58, s0
	v_lshl_add_u64 v[76:77], v[76:77], 0, v[68:69]
	v_lshlrev_b32_e32 v0, 1, v0
	global_store_short v[76:77], v58, off
	v_cvt_pk_bf16_f32 v78, v59, s0
	v_lshl_add_u64 v[58:59], s[40:41], 0, v[0:1]
	v_or_b32_e32 v0, 0x52, v100
	v_lshl_add_u64 v[58:59], v[58:59], 0, s[4:5]
	v_lshlrev_b32_e32 v0, s36, v0
	v_lshl_add_u64 v[58:59], v[58:59], 0, v[68:69]
	v_lshlrev_b32_e32 v0, 1, v0
	global_store_short v[58:59], v78, off
	v_lshl_add_u64 v[78:79], s[40:41], 0, v[0:1]
	v_or_b32_e32 v0, 0x53, v100
	v_lshl_add_u64 v[78:79], v[78:79], 0, s[4:5]
	v_lshlrev_b32_e32 v0, s36, v0
	v_cvt_pk_bf16_f32 v60, v60, s0
	v_lshl_add_u64 v[78:79], v[78:79], 0, v[68:69]
	v_lshlrev_b32_e32 v0, 1, v0
	global_store_short v[78:79], v60, off
	v_cvt_pk_bf16_f32 v80, v61, s0
	v_lshl_add_u64 v[60:61], s[40:41], 0, v[0:1]
	v_or_b32_e32 v0, 0x58, v100
	v_lshl_add_u64 v[60:61], v[60:61], 0, s[4:5]
	v_lshlrev_b32_e32 v0, s36, v0
	v_lshl_add_u64 v[60:61], v[60:61], 0, v[68:69]
	v_lshlrev_b32_e32 v0, 1, v0
	global_store_short v[60:61], v80, off
	v_lshl_add_u64 v[80:81], s[40:41], 0, v[0:1]
	v_or_b32_e32 v0, 0x59, v100
	v_lshl_add_u64 v[80:81], v[80:81], 0, s[4:5]
	v_lshlrev_b32_e32 v0, s36, v0
	v_cvt_pk_bf16_f32 v62, v62, s0
	v_lshl_add_u64 v[80:81], v[80:81], 0, v[68:69]
	v_lshlrev_b32_e32 v0, 1, v0
	global_store_short v[80:81], v62, off
	v_cvt_pk_bf16_f32 v82, v63, s0
	v_lshl_add_u64 v[62:63], s[40:41], 0, v[0:1]
	v_or_b32_e32 v0, 0x5a, v100
	v_lshl_add_u64 v[62:63], v[62:63], 0, s[4:5]
	v_lshlrev_b32_e32 v0, s36, v0
	v_lshl_add_u64 v[62:63], v[62:63], 0, v[68:69]
	v_lshlrev_b32_e32 v0, 1, v0
	global_store_short v[62:63], v82, off
	v_lshl_add_u64 v[82:83], s[40:41], 0, v[0:1]
	v_or_b32_e32 v0, 0x5b, v100
	v_lshl_add_u64 v[82:83], v[82:83], 0, s[4:5]
	v_lshlrev_b32_e32 v0, s36, v0
	v_cvt_pk_bf16_f32 v64, v64, s0
	v_lshl_add_u64 v[82:83], v[82:83], 0, v[68:69]
	v_lshlrev_b32_e32 v0, 1, v0
	v_or_b32_e32 v84, 0x60, v100
	global_store_short v[82:83], v64, off
	v_cvt_pk_bf16_f32 v85, v65, s0
	v_lshl_add_u64 v[64:65], s[40:41], 0, v[0:1]
	v_lshl_add_u64 v[64:65], v[64:65], 0, s[4:5]
	v_lshlrev_b32_e32 v0, s36, v84
	v_lshl_add_u64 v[64:65], v[64:65], 0, v[68:69]
	v_lshlrev_b32_e32 v0, 1, v0
	global_store_short v[64:65], v85, off
	v_lshl_add_u64 v[84:85], s[40:41], 0, v[0:1]
	v_or_b32_e32 v0, 0x61, v100
	v_lshl_add_u64 v[84:85], v[84:85], 0, s[4:5]
	v_lshlrev_b32_e32 v0, s36, v0
	v_cvt_pk_bf16_f32 v34, v34, s0
	v_lshl_add_u64 v[84:85], v[84:85], 0, v[68:69]
	v_lshlrev_b32_e32 v0, 1, v0
	global_store_short v[84:85], v34, off
	v_cvt_pk_bf16_f32 v86, v35, s0
	v_lshl_add_u64 v[34:35], s[40:41], 0, v[0:1]
	v_or_b32_e32 v0, 0x62, v100
	v_lshl_add_u64 v[34:35], v[34:35], 0, s[4:5]
	v_lshlrev_b32_e32 v0, s36, v0
	v_lshl_add_u64 v[34:35], v[34:35], 0, v[68:69]
	v_lshlrev_b32_e32 v0, 1, v0
	global_store_short v[34:35], v86, off
	v_lshl_add_u64 v[86:87], s[40:41], 0, v[0:1]
	v_or_b32_e32 v0, 0x63, v100
	v_lshl_add_u64 v[86:87], v[86:87], 0, s[4:5]
	v_lshlrev_b32_e32 v0, s36, v0
	v_cvt_pk_bf16_f32 v36, v36, s0
	v_lshl_add_u64 v[86:87], v[86:87], 0, v[68:69]
	v_lshlrev_b32_e32 v0, 1, v0
	global_store_short v[86:87], v36, off
	v_cvt_pk_bf16_f32 v88, v37, s0
	v_lshl_add_u64 v[36:37], s[40:41], 0, v[0:1]
	v_or_b32_e32 v0, 0x68, v100
	v_lshl_add_u64 v[36:37], v[36:37], 0, s[4:5]
	v_lshlrev_b32_e32 v0, s36, v0
	v_lshl_add_u64 v[36:37], v[36:37], 0, v[68:69]
	v_lshlrev_b32_e32 v0, 1, v0
	global_store_short v[36:37], v88, off
	v_lshl_add_u64 v[88:89], s[40:41], 0, v[0:1]
	v_or_b32_e32 v0, 0x69, v100
	v_lshl_add_u64 v[88:89], v[88:89], 0, s[4:5]
	v_lshlrev_b32_e32 v0, s36, v0
	v_cvt_pk_bf16_f32 v38, v38, s0
	v_lshl_add_u64 v[88:89], v[88:89], 0, v[68:69]
	v_lshlrev_b32_e32 v0, 1, v0
	global_store_short v[88:89], v38, off
	v_cvt_pk_bf16_f32 v90, v39, s0
	v_lshl_add_u64 v[38:39], s[40:41], 0, v[0:1]
	v_or_b32_e32 v0, 0x6a, v100
	v_lshl_add_u64 v[38:39], v[38:39], 0, s[4:5]
	v_lshlrev_b32_e32 v0, s36, v0
	v_lshl_add_u64 v[38:39], v[38:39], 0, v[68:69]
	v_lshlrev_b32_e32 v0, 1, v0
	global_store_short v[38:39], v90, off
	v_lshl_add_u64 v[90:91], s[40:41], 0, v[0:1]
	v_or_b32_e32 v0, 0x6b, v100
	v_lshl_add_u64 v[90:91], v[90:91], 0, s[4:5]
	v_lshlrev_b32_e32 v0, s36, v0
	v_cvt_pk_bf16_f32 v40, v40, s0
	v_lshl_add_u64 v[90:91], v[90:91], 0, v[68:69]
	v_lshlrev_b32_e32 v0, 1, v0
	global_store_short v[90:91], v40, off
	v_cvt_pk_bf16_f32 v92, v41, s0
	v_lshl_add_u64 v[40:41], s[40:41], 0, v[0:1]
	v_or_b32_e32 v0, 0x70, v100
	v_lshl_add_u64 v[40:41], v[40:41], 0, s[4:5]
	v_lshlrev_b32_e32 v0, s36, v0
	v_lshl_add_u64 v[40:41], v[40:41], 0, v[68:69]
	v_lshlrev_b32_e32 v0, 1, v0
	global_store_short v[40:41], v92, off
	v_lshl_add_u64 v[92:93], s[40:41], 0, v[0:1]
	v_or_b32_e32 v0, 0x71, v100
	v_lshl_add_u64 v[92:93], v[92:93], 0, s[4:5]
	v_lshlrev_b32_e32 v0, s36, v0
	v_cvt_pk_bf16_f32 v42, v42, s0
	v_lshl_add_u64 v[92:93], v[92:93], 0, v[68:69]
	v_lshlrev_b32_e32 v0, 1, v0
	global_store_short v[92:93], v42, off
	v_cvt_pk_bf16_f32 v94, v43, s0
	v_lshl_add_u64 v[42:43], s[40:41], 0, v[0:1]
	v_or_b32_e32 v0, 0x72, v100
	v_lshl_add_u64 v[42:43], v[42:43], 0, s[4:5]
	v_lshlrev_b32_e32 v0, s36, v0
	v_lshl_add_u64 v[42:43], v[42:43], 0, v[68:69]
	v_lshlrev_b32_e32 v0, 1, v0
	global_store_short v[42:43], v94, off
	v_lshl_add_u64 v[94:95], s[40:41], 0, v[0:1]
	v_or_b32_e32 v0, 0x73, v100
	v_lshl_add_u64 v[94:95], v[94:95], 0, s[4:5]
	v_lshlrev_b32_e32 v0, s36, v0
	v_cvt_pk_bf16_f32 v44, v44, s0
	v_lshl_add_u64 v[94:95], v[94:95], 0, v[68:69]
	v_lshlrev_b32_e32 v0, 1, v0
	global_store_short v[94:95], v44, off
	v_cvt_pk_bf16_f32 v96, v45, s0
	v_lshl_add_u64 v[44:45], s[40:41], 0, v[0:1]
	v_or_b32_e32 v0, 0x78, v100
	v_lshl_add_u64 v[44:45], v[44:45], 0, s[4:5]
	v_lshlrev_b32_e32 v0, s36, v0
	v_lshl_add_u64 v[44:45], v[44:45], 0, v[68:69]
	v_lshlrev_b32_e32 v0, 1, v0
	global_store_short v[44:45], v96, off
	v_lshl_add_u64 v[96:97], s[40:41], 0, v[0:1]
	v_or_b32_e32 v0, 0x79, v100
	v_lshl_add_u64 v[96:97], v[96:97], 0, s[4:5]
	v_lshlrev_b32_e32 v0, s36, v0
	v_cvt_pk_bf16_f32 v46, v46, s0
	v_lshl_add_u64 v[96:97], v[96:97], 0, v[68:69]
	v_lshlrev_b32_e32 v0, 1, v0
	global_store_short v[96:97], v46, off
	v_cvt_pk_bf16_f32 v98, v47, s0
	v_lshl_add_u64 v[46:47], s[40:41], 0, v[0:1]
	v_or_b32_e32 v0, 0x7a, v100
	v_lshl_add_u64 v[46:47], v[46:47], 0, s[4:5]
	v_lshlrev_b32_e32 v0, s36, v0
	v_lshl_add_u64 v[46:47], v[46:47], 0, v[68:69]
	v_lshlrev_b32_e32 v0, 1, v0
	global_store_short v[46:47], v98, off
	v_lshl_add_u64 v[98:99], s[40:41], 0, v[0:1]
	v_or_b32_e32 v0, 0x7b, v100
	v_lshl_add_u64 v[98:99], v[98:99], 0, s[4:5]
	v_lshlrev_b32_e32 v0, s36, v0
	v_cvt_pk_bf16_f32 v48, v48, s0
	v_lshl_add_u64 v[98:99], v[98:99], 0, v[68:69]
	v_lshlrev_b32_e32 v0, 1, v0
	global_store_short v[98:99], v48, off
	v_cvt_pk_bf16_f32 v100, v49, s0
	v_lshl_add_u64 v[48:49], s[40:41], 0, v[0:1]
	v_lshl_add_u64 v[48:49], v[48:49], 0, s[4:5]
	v_lshl_add_u64 v[48:49], v[48:49], 0, v[68:69]
	v_cvt_pk_bf16_f32 v0, v18, s0
	global_store_short v[48:49], v100, off
	global_store_short v[66:67], v0, off offset:64
	v_cvt_pk_bf16_f32 v0, v19, s0
	global_store_short v[50:51], v0, off offset:64
	v_cvt_pk_bf16_f32 v0, v20, s0
	global_store_short v[70:71], v0, off offset:64
	v_cvt_pk_bf16_f32 v0, v21, s0
	global_store_short v[52:53], v0, off offset:64
	v_cvt_pk_bf16_f32 v0, v22, s0
	global_store_short v[72:73], v0, off offset:64
	v_cvt_pk_bf16_f32 v0, v23, s0
	global_store_short v[54:55], v0, off offset:64
	v_cvt_pk_bf16_f32 v0, v24, s0
	global_store_short v[74:75], v0, off offset:64
	v_cvt_pk_bf16_f32 v0, v25, s0
	global_store_short v[56:57], v0, off offset:64
	v_cvt_pk_bf16_f32 v0, v26, s0
	global_store_short v[76:77], v0, off offset:64
	v_cvt_pk_bf16_f32 v0, v27, s0
	global_store_short v[58:59], v0, off offset:64
	v_cvt_pk_bf16_f32 v0, v28, s0
	global_store_short v[78:79], v0, off offset:64
	v_cvt_pk_bf16_f32 v0, v29, s0
	global_store_short v[60:61], v0, off offset:64
	v_cvt_pk_bf16_f32 v0, v30, s0
	global_store_short v[80:81], v0, off offset:64
	v_cvt_pk_bf16_f32 v0, v31, s0
	global_store_short v[62:63], v0, off offset:64
	v_cvt_pk_bf16_f32 v0, v32, s0
	global_store_short v[82:83], v0, off offset:64
	v_cvt_pk_bf16_f32 v0, v33, s0
	global_store_short v[64:65], v0, off offset:64
	v_cvt_pk_bf16_f32 v0, v2, s0
	global_store_short v[84:85], v0, off offset:64
	v_cvt_pk_bf16_f32 v0, v3, s0
	global_store_short v[34:35], v0, off offset:64
	v_cvt_pk_bf16_f32 v0, v4, s0
	global_store_short v[86:87], v0, off offset:64
	v_cvt_pk_bf16_f32 v0, v5, s0
	global_store_short v[36:37], v0, off offset:64
	v_cvt_pk_bf16_f32 v0, v6, s0
	global_store_short v[88:89], v0, off offset:64
	v_cvt_pk_bf16_f32 v0, v7, s0
	global_store_short v[38:39], v0, off offset:64
	v_cvt_pk_bf16_f32 v0, v8, s0
	global_store_short v[90:91], v0, off offset:64
	v_cvt_pk_bf16_f32 v0, v9, s0
	global_store_short v[40:41], v0, off offset:64
	v_cvt_pk_bf16_f32 v0, v10, s0
	global_store_short v[92:93], v0, off offset:64
	v_cvt_pk_bf16_f32 v0, v11, s0
	global_store_short v[42:43], v0, off offset:64
	v_cvt_pk_bf16_f32 v0, v12, s0
	global_store_short v[94:95], v0, off offset:64
	v_cvt_pk_bf16_f32 v0, v13, s0
	global_store_short v[44:45], v0, off offset:64
	v_cvt_pk_bf16_f32 v0, v14, s0
	global_store_short v[96:97], v0, off offset:64
	v_cvt_pk_bf16_f32 v0, v15, s0
	global_store_short v[46:47], v0, off offset:64
	v_cvt_pk_bf16_f32 v0, v16, s0
	global_store_short v[98:99], v0, off offset:64
	v_cvt_pk_bf16_f32 v0, v17, s0
	global_store_short v[48:49], v0, off offset:64
	s_branch .LBB0_340

.LBB0_454:
	v_lshl_add_u64 v[18:19], v[12:13], 0, s[4:5]
	v_add_co_u32_e32 v20, vcc, s89, v18
	global_load_dword v54, v[18:19], off
	s_nop 0
	v_addc_co_u32_e32 v21, vcc, 0, v19, vcc
	v_add_co_u32_e32 v22, vcc, s6, v18
	s_waitcnt vmcnt(0)
	v_mov_b32_e32 v50, s3
	v_addc_co_u32_e32 v23, vcc, 0, v19, vcc
	v_add_co_u32_e32 v18, vcc, s65, v18
	s_add_u32 s4, s4, 0x18000
	s_nop 0
	v_addc_co_u32_e32 v19, vcc, 0, v19, vcc
	global_load_dword v56, v[20:21], off
	global_load_dword v58, v[22:23], off
	global_load_dword v60, v[18:19], off
	ds_read_b128 v[18:21], v50
	ds_read_b128 v[22:25], v50 offset:256
	ds_read_b128 v[26:29], v50 offset:512
	ds_read_b128 v[30:33], v50 offset:768
	ds_read_b128 v[34:37], v50 offset:1024
	ds_read_b128 v[38:41], v50 offset:1280
	ds_read_b128 v[42:45], v50 offset:1536
	ds_read_b128 v[46:49], v50 offset:1792
	ds_read_b128 v[50:53], v50 offset:2048
	s_waitcnt lgkmcnt(8)
	v_mov_b32_e32 v62, v18
	s_waitcnt lgkmcnt(7)
	v_mov_b32_e32 v63, v22
	s_waitcnt lgkmcnt(6)
	v_mov_b32_e32 v64, v26
	s_waitcnt lgkmcnt(5)
	v_mov_b32_e32 v65, v30
	s_waitcnt lgkmcnt(4)
	v_mov_b32_e32 v66, v34
	s_waitcnt lgkmcnt(3)
	v_mov_b32_e32 v67, v38
	s_waitcnt lgkmcnt(2)
	v_mov_b32_e32 v68, v42
	s_waitcnt lgkmcnt(1)
	v_mov_b32_e32 v69, v46
	v_mov_b32_e32 v22, v19
	v_mov_b32_e32 v30, v27
	v_mov_b32_e32 v38, v35
	v_mov_b32_e32 v46, v43
	v_mov_b32_e32 v18, v20
	v_mov_b32_e32 v19, v24
	v_mov_b32_e32 v26, v28
	v_mov_b32_e32 v27, v32
	v_mov_b32_e32 v24, v21
	v_mov_b32_e32 v20, v36
	v_mov_b32_e32 v21, v40
	v_mov_b32_e32 v34, v44
	v_mov_b32_e32 v35, v48
	s_addc_u32 s5, s5, 0
	s_add_i32 s3, s3, 16
	v_mov_b32_e32 v32, v29
	v_mov_b32_e32 v40, v37
	v_mov_b32_e32 v48, v45
	s_cmp_eq_u32 s4, 0x180000
	v_pk_fma_f32 v[10:11], v[54:55], v[62:63], v[10:11] op_sel_hi:[0,1,1]
	v_pk_fma_f32 v[8:9], v[54:55], v[64:65], v[8:9] op_sel_hi:[0,1,1]
	v_pk_fma_f32 v[6:7], v[54:55], v[66:67], v[6:7] op_sel_hi:[0,1,1]
	v_pk_fma_f32 v[4:5], v[54:55], v[68:69], v[4:5] op_sel_hi:[0,1,1]
	s_waitcnt lgkmcnt(0)
	v_fmac_f32_e32 v17, v54, v50
	s_waitcnt vmcnt(2)
	v_pk_fma_f32 v[10:11], v[56:57], v[22:23], v[10:11] op_sel_hi:[0,1,1]
	v_pk_fma_f32 v[8:9], v[56:57], v[30:31], v[8:9] op_sel_hi:[0,1,1]
	v_pk_fma_f32 v[6:7], v[56:57], v[38:39], v[6:7] op_sel_hi:[0,1,1]
	v_pk_fma_f32 v[4:5], v[56:57], v[46:47], v[4:5] op_sel_hi:[0,1,1]
	v_fmac_f32_e32 v17, v56, v51
	s_waitcnt vmcnt(1)
	v_pk_fma_f32 v[10:11], v[58:59], v[18:19], v[10:11] op_sel_hi:[0,1,1]
	v_pk_fma_f32 v[8:9], v[58:59], v[26:27], v[8:9] op_sel_hi:[0,1,1]
	v_pk_fma_f32 v[6:7], v[58:59], v[20:21], v[6:7] op_sel_hi:[0,1,1]
	v_pk_fma_f32 v[4:5], v[58:59], v[34:35], v[4:5] op_sel_hi:[0,1,1]
	v_fmac_f32_e32 v17, v58, v52
	s_waitcnt vmcnt(0)
	v_pk_fma_f32 v[10:11], v[60:61], v[24:25], v[10:11] op_sel_hi:[0,1,1]
	v_pk_fma_f32 v[8:9], v[60:61], v[32:33], v[8:9] op_sel_hi:[0,1,1]
	v_pk_fma_f32 v[6:7], v[60:61], v[40:41], v[6:7] op_sel_hi:[0,1,1]
	v_pk_fma_f32 v[4:5], v[60:61], v[48:49], v[4:5] op_sel_hi:[0,1,1]
	v_fmac_f32_e32 v17, v60, v53
	s_cbranch_scc0 .LBB0_454
	s_sext_i32_i16 s3, s11
	s_lshl_b32 s3, s3, 2
	s_add_i32 s2, s3, s2
	s_mul_hi_i32 s3, s2, 0x36000
	s_mul_i32 s2, s2, 0x36000
	s_add_u32 s2, s9, s2
	s_addc_u32 s3, s10, s3
	v_lshl_add_u64 v[2:3], v[2:3], 2, s[2:3]
	v_add_co_u32_e32 v12, vcc, s89, v2
	global_store_dword v[2:3], v10, off
	s_nop 0
	v_addc_co_u32_e32 v13, vcc, 0, v3, vcc
	v_add_co_u32_e32 v10, vcc, s6, v2
	global_store_dword v[12:13], v11, off
	s_nop 0
	v_addc_co_u32_e32 v11, vcc, 0, v3, vcc
	global_store_dword v[10:11], v8, off
	v_add_co_u32_e32 v10, vcc, s65, v2
	s_mov_b32 s2, 0x18000
	s_nop 0
	v_addc_co_u32_e32 v11, vcc, 0, v3, vcc
	v_add_co_u32_e32 v8, vcc, s2, v2
	global_store_dword v[10:11], v9, off
	s_nop 0
	v_addc_co_u32_e32 v9, vcc, 0, v3, vcc
	s_mov_b32 s2, 0x1e000
	global_store_dword v[8:9], v6, off
	v_add_co_u32_e32 v8, vcc, s2, v2
	s_mov_b32 s2, 0x24000
	s_nop 0
	v_addc_co_u32_e32 v9, vcc, 0, v3, vcc
	v_add_co_u32_e32 v6, vcc, s2, v2
	global_store_dword v[8:9], v7, off
	s_nop 0
	v_addc_co_u32_e32 v7, vcc, 0, v3, vcc
	global_store_dword v[6:7], v4, off
	v_add_co_u32_e32 v6, vcc, 0x2a000, v2
	s_mov_b32 s2, s90
	s_nop 0
	v_addc_co_u32_e32 v7, vcc, 0, v3, vcc
	v_add_co_u32_e32 v2, vcc, 0x30000, v2
	global_store_dword v[6:7], v5, off
	s_nop 0
	v_addc_co_u32_e32 v3, vcc, 0, v3, vcc
	global_store_dword v[2:3], v17, off
	s_add_i32 s8, s2, s8
	s_cmpk_gt_i32 s8, 0x2ff
	s_cbranch_scc0 .LBB0_450

.LBB0_458:
	v_ashrrev_i32_e32 v6, 10, v4
	v_mul_lo_u32 v8, v3, v6
	v_ashrrev_i32_e32 v7, 31, v6
	v_and_b32_e32 v10, 0xff8, v8
	v_add_u32_e32 v11, v8, v6
	v_and_b32_e32 v5, 0x1ff8, v3
	v_lshlrev_b64 v[8:9], 14, v[6:7]
	v_cvt_f32_u32_e32 v7, v10
	v_and_b32_e32 v10, 0xfff, v11
	v_add_u32_e32 v11, v11, v6
	v_lshlrev_b32_e32 v0, 1, v5
	v_lshl_add_u64 v[8:9], s[4:5], 0, v[8:9]
	v_add_u32_e32 v15, v11, v6
	v_cvt_f32_u32_e32 v12, v10
	v_and_b32_e32 v13, 0xffe, v11
	v_lshl_add_u64 v[10:11], v[8:9], 0, v[0:1]
	v_and_b32_e32 v8, 0xfff, v15
	v_add_u32_e32 v9, v15, v6
	v_cvt_f32_u32_e32 v0, v13
	v_cvt_f32_u32_e32 v8, v8
	v_and_b32_e32 v13, 0xffc, v9
	v_add_u32_e32 v9, v9, v6
	v_add_u32_e32 v4, s0, v4
	s_mov_b32 s8, 0x1fffff
	v_and_b32_e32 v15, 0xfff, v9
	v_add_u32_e32 v9, v9, v6
	v_cmp_lt_i32_e32 vcc, s8, v4
	v_add_u32_e32 v6, v9, v6
	s_or_b64 s[6:7], vcc, s[6:7]
	v_mul_f32_e32 v7, 0x39800000, v7
	v_cvt_f32_u32_e32 v13, v13
	v_cmp_gt_u32_e32 vcc, s9, v5
	v_mul_f32_e32 v5, 0x39800000, v12
	v_cvt_f32_u32_e32 v12, v15
	v_and_b32_e32 v15, 0xffe, v9
	v_and_b32_e32 v6, 0xfff, v6
	v_cos_f32_e32 v16, v7
	v_sin_f32_e64 v7, -v7
	v_cos_f32_e32 v9, v5
	v_sin_f32_e64 v5, -v5
	v_mul_f32_e32 v0, 0x39800000, v0
	v_cvt_f32_u32_e32 v15, v15
	v_mul_f32_e32 v8, 0x39800000, v8
	v_cvt_f32_u32_e32 v6, v6
	v_cos_f32_e32 v17, v0
	v_sin_f32_e64 v0, -v0
	v_cos_f32_e32 v18, v8
	v_sin_f32_e64 v8, -v8
	v_mul_f32_e32 v13, 0x39800000, v13
	v_mul_f32_e32 v12, 0x39800000, v12
	v_cndmask_b32_e32 v7, v7, v16, vcc
	v_cos_f32_e32 v16, v13
	v_sin_f32_e64 v13, -v13
	v_cndmask_b32_e32 v5, v5, v9, vcc
	v_cos_f32_e32 v9, v12
	v_sin_f32_e64 v12, -v12
	v_mul_f32_e32 v15, 0x39800000, v15
	v_mul_f32_e32 v6, 0x39800000, v6
	v_cndmask_b32_e32 v0, v0, v17, vcc
	v_cos_f32_e32 v17, v15
	v_sin_f32_e64 v15, -v15
	v_cndmask_b32_e32 v8, v8, v18, vcc
	v_cos_f32_e32 v18, v6
	v_sin_f32_e64 v19, -v6
	v_mul_f32_e32 v7, 0x3c800000, v7
	v_mul_f32_e32 v5, 0x3c800000, v5
	v_mul_f32_e32 v0, 0x3c800000, v0
	v_cvt_pk_bf16_f32 v6, v7, v5
	v_mul_f32_e32 v5, 0x3c800000, v8
	v_cndmask_b32_e32 v7, v13, v16, vcc
	v_cndmask_b32_e32 v9, v12, v9, vcc
	v_mul_f32_e32 v8, 0x3c800000, v7
	v_cvt_pk_bf16_f32 v7, v0, v5
	v_mul_f32_e32 v0, 0x3c800000, v9
	v_cndmask_b32_e32 v5, v15, v17, vcc
	v_cndmask_b32_e32 v9, v19, v18, vcc
	v_mul_f32_e32 v5, 0x3c800000, v5
	v_cvt_pk_bf16_f32 v8, v8, v0
	v_mul_f32_e32 v0, 0x3c800000, v9
	v_add_u32_e32 v3, s1, v3
	v_cvt_pk_bf16_f32 v9, v5, v0
	global_store_dwordx4 v[10:11], v[6:9], off
	s_andn2_b64 exec, exec, s[6:7]
	s_cbranch_execnz .LBB0_458

.LBB0_461:
	v_lshrrev_b32_e32 v6, 9, v0
	v_mul_lo_u32 v6, v6, v0
	v_cvt_f32_ubyte0_e32 v6, v6
	v_mul_f32_e32 v6, 0x3b800000, v6
	v_cos_f32_e32 v8, v6
	v_sin_f32_e64 v6, -v6
	v_and_b32_e32 v7, 0x100, v0
	s_mov_b32 s1, 0x1ffff
	v_add_u32_e32 v0, s0, v0
	v_cmp_lt_i32_e32 vcc, s1, v0
	s_or_b64 s[6:7], vcc, s[6:7]
	v_cmp_eq_u32_e32 vcc, 0, v7
	s_nop 1
	v_cndmask_b32_e32 v6, v6, v8, vcc
	v_mul_f32_e32 v6, 0x3d800000, v6
	v_cvt_pk_bf16_f32 v6, v6, s0
	global_store_short v[4:5], v6, off
	v_lshl_add_u64 v[4:5], v[4:5], 0, s[4:5]
	s_andn2_b64 exec, exec, s[6:7]
	s_cbranch_execnz .LBB0_461

.LBB0_464:
	v_ashrrev_i32_e32 v7, 4, v6
	v_cvt_f32_i32_e32 v7, v7
	v_add_co_u32_e32 v8, vcc, -4, v4
	v_add_u32_e32 v6, s0, v6
	v_mul_f32_e32 v7, v0, v7
	v_cvt_f64_f32_e32 v[10:11], v7
	v_mul_f64 v[12:13], v[10:11], s[8:9]
	v_floor_f64_e32 v[12:13], v[12:13]
	v_fma_f64 v[10:11], v[10:11], s[8:9], -v[12:13]
	v_cvt_f32_f64_e32 v7, v[10:11]
	v_cos_f32_e32 v10, v7
	v_sin_f32_e32 v11, v7
	v_addc_co_u32_e32 v9, vcc, -1, v5, vcc
	s_movk_i32 s1, 0x3ff
	v_cmp_lt_i32_e32 vcc, s1, v6
	v_lshl_add_u64 v[4:5], v[4:5], 0, s[4:5]
	s_or_b64 s[6:7], vcc, s[6:7]
	global_store_dwordx2 v[8:9], v[10:11], off
	s_andn2_b64 exec, exec, s[6:7]
	s_cbranch_execnz .LBB0_464

.LBB0_467:
	v_lshl_add_u64 v[68:69], v[6:7], 0, s[2:3]
	global_load_dwordx4 v[8:11], v[68:69], off offset:512
	global_load_dwordx4 v[12:15], v[68:69], off
	global_load_dwordx4 v[16:19], v[68:69], off offset:768
	global_load_dwordx4 v[20:23], v[68:69], off offset:256
	global_load_dwordx4 v[24:27], v[68:69], off offset:528
	global_load_dwordx4 v[28:31], v[68:69], off offset:16
	global_load_dwordx4 v[32:35], v[68:69], off offset:784
	global_load_dwordx4 v[36:39], v[68:69], off offset:272
	global_load_dwordx4 v[40:43], v[68:69], off offset:544
	global_load_dwordx4 v[44:47], v[68:69], off offset:32
	global_load_dwordx4 v[48:51], v[68:69], off offset:800
	global_load_dwordx4 v[52:55], v[68:69], off offset:288
	global_load_dwordx4 v[56:59], v[68:69], off offset:560
	global_load_dwordx4 v[60:63], v[68:69], off offset:48
	global_load_dwordx4 v[64:67], v[68:69], off offset:816
	s_nop 0
	global_load_dwordx4 v[68:71], v[68:69], off offset:304
	s_add_u32 s2, s2, 64
	s_addc_u32 s3, s3, 0
	s_cmpk_eq_i32 s2, 0x100
	s_waitcnt vmcnt(0)
	v_mov_b32_e32 v72, v8
	v_mov_b32_e32 v73, v12
	v_mov_b32_e32 v74, v16
	v_mov_b32_e32 v75, v20
	v_mov_b32_e32 v12, v9
	v_mov_b32_e32 v20, v17
	v_pk_fma_f32 v[4:5], v[72:73], v[74:75], v[4:5]
	v_mov_b32_e32 v8, v10
	v_mov_b32_e32 v9, v14
	v_mov_b32_e32 v16, v18
	v_mov_b32_e32 v17, v22
	v_pk_fma_f32 v[4:5], v[12:13], v[20:21], v[4:5]
	v_mov_b32_e32 v14, v11
	v_mov_b32_e32 v22, v19
	v_pk_fma_f32 v[4:5], v[8:9], v[16:17], v[4:5]
	v_mov_b32_e32 v10, v24
	v_mov_b32_e32 v11, v28
	v_mov_b32_e32 v18, v32
	v_mov_b32_e32 v19, v36
	v_pk_fma_f32 v[4:5], v[14:15], v[22:23], v[4:5]
	v_mov_b32_e32 v28, v25
	v_mov_b32_e32 v36, v33
	v_pk_fma_f32 v[4:5], v[10:11], v[18:19], v[4:5]
	v_mov_b32_e32 v24, v26
	v_mov_b32_e32 v25, v30
	v_mov_b32_e32 v32, v34
	v_mov_b32_e32 v33, v38
	v_pk_fma_f32 v[4:5], v[28:29], v[36:37], v[4:5]
	v_mov_b32_e32 v30, v27
	v_mov_b32_e32 v38, v35
	v_pk_fma_f32 v[4:5], v[24:25], v[32:33], v[4:5]
	v_mov_b32_e32 v26, v40
	v_mov_b32_e32 v27, v44
	v_mov_b32_e32 v34, v48
	v_mov_b32_e32 v35, v52
	v_pk_fma_f32 v[4:5], v[30:31], v[38:39], v[4:5]
	v_mov_b32_e32 v44, v41
	v_mov_b32_e32 v52, v49
	v_pk_fma_f32 v[4:5], v[26:27], v[34:35], v[4:5]
	v_mov_b32_e32 v40, v42
	v_mov_b32_e32 v41, v46
	v_mov_b32_e32 v48, v50
	v_mov_b32_e32 v49, v54
	v_pk_fma_f32 v[4:5], v[44:45], v[52:53], v[4:5]
	v_mov_b32_e32 v46, v43
	v_mov_b32_e32 v54, v51
	v_pk_fma_f32 v[4:5], v[40:41], v[48:49], v[4:5]
	v_mov_b32_e32 v42, v56
	v_mov_b32_e32 v43, v60
	v_mov_b32_e32 v50, v64
	v_mov_b32_e32 v51, v68
	v_pk_fma_f32 v[4:5], v[46:47], v[54:55], v[4:5]
	v_mov_b32_e32 v60, v57
	v_mov_b32_e32 v68, v65
	v_pk_fma_f32 v[4:5], v[42:43], v[50:51], v[4:5]
	v_mov_b32_e32 v56, v58
	v_mov_b32_e32 v57, v62
	v_mov_b32_e32 v64, v66
	v_mov_b32_e32 v65, v70
	v_pk_fma_f32 v[4:5], v[60:61], v[68:69], v[4:5]
	v_mov_b32_e32 v62, v59
	v_mov_b32_e32 v70, v67
	v_pk_fma_f32 v[4:5], v[56:57], v[64:65], v[4:5]
	s_nop 0
	v_pk_fma_f32 v[4:5], v[62:63], v[70:71], v[4:5]
	s_cbranch_scc0 .LBB0_467
	v_mul_f32_e32 v0, 0x3fb8aa3b, v5
	v_rndne_f32_e32 v6, v0
	s_mov_b32 s2, 0x3fb8aa3b
	v_sub_f32_e32 v7, v0, v6
	v_fma_f32 v0, v5, s2, -v0
	v_fmac_f32_e32 v0, 0x32a5705f, v5
	v_add_f32_e32 v0, v7, v0
	v_cvt_i32_f32_e32 v6, v6
	v_exp_f32_e32 v0, v0
	s_mov_b32 s3, 0xc2ce8ed0
	v_cmp_ngt_f32_e32 vcc, s3, v5
	v_mov_b32_e32 v9, 0x7f800000
	v_ldexp_f32 v0, v0, v6
	v_mul_f32_e32 v6, 0x3fb8aa3b, v4
	v_rndne_f32_e32 v7, v6
	v_sub_f32_e32 v8, v6, v7
	v_fma_f32 v6, v4, s2, -v6
	v_fmac_f32_e32 v6, 0x32a5705f, v4
	v_add_f32_e32 v6, v8, v6
	v_cvt_f32_i32_e32 v8, v2
	v_exp_f32_e32 v6, v6
	v_cvt_i32_f32_e32 v7, v7
	s_mov_b32 s2, 0x42b17218
	v_cndmask_b32_e32 v0, 0, v0, vcc
	v_cmp_nlt_f32_e32 vcc, s2, v5
	v_mul_f32_e32 v5, 0xbe99999a, v8
	v_mul_f32_e32 v5, 0x3fb8aa3b, v5
	v_cndmask_b32_e32 v211, v9, v0, vcc
	v_ldexp_f32 v0, v6, v7
	v_exp_f32_e32 v6, v5
	v_cmp_ngt_f32_e32 vcc, s3, v4
	v_lshl_add_u64 v[2:3], v[2:3], 2, s[78:79]
	s_nop 0
	v_cndmask_b32_e32 v0, 0, v0, vcc
	v_cmp_nlt_f32_e32 vcc, s2, v4
	v_mul_f32_e32 v4, 0x3f19999a, v6
	s_nop 0
	v_cndmask_b32_e32 v5, v9, v0, vcc
	v_pk_add_f32 v[4:5], v[210:211], v[4:5] neg_lo:[0,1] neg_hi:[0,1]
	v_add_co_u32_e32 v2, vcc, 0x1f95a000, v2
	v_add_f32_e32 v0, v4, v5
	s_nop 0
	v_addc_co_u32_e32 v3, vcc, 0, v3, vcc
	global_store_dword v[2:3], v0, off

.LBB0_471:
	v_lshlrev_b32_e32 v5, 4, v5
	v_sub_u32_e32 v5, v9, v5
	s_waitcnt lgkmcnt(0)
	v_lshlrev_b32_e32 v28, 6, v5
	ds_read_b32 v5, v36
	ds_read_b32 v27, v36 offset:132
	ds_read_b32 v30, v36 offset:264
	ds_read_b32 v31, v36 offset:396
	ds_read_b32 v41, v36 offset:528
	ds_read_b32 v42, v36 offset:660
	ds_read_b32 v43, v36 offset:792
	ds_read_b32 v44, v36 offset:924
	v_add_u32_e32 v0, 0x400, v0
	v_ashrrev_i32_e32 v29, 31, v28
	v_lshl_add_u64 v[32:33], v[28:29], 1, v[10:11]
	s_waitcnt lgkmcnt(0)
	v_cvt_pk_bf16_f32 v29, v30, v31
	v_cvt_pk_bf16_f32 v30, v41, v42
	v_or_b32_e32 v42, v0, v35
	v_cvt_pk_bf16_f32 v31, v43, v44
	v_ashrrev_i32_e32 v43, 31, v42
	v_lshlrev_b64 v[42:43], 11, v[42:43]
	v_cvt_pk_bf16_f32 v28, v5, v27
	v_lshl_add_u64 v[42:43], v[32:33], 0, v[42:43]
	global_store_dwordx4 v[42:43], v[28:31], off
	ds_read_b32 v5, v36 offset:32
	ds_read_b32 v27, v36 offset:164
	ds_read_b32 v29, v36 offset:296
	ds_read_b32 v30, v36 offset:428
	ds_read_b32 v31, v36 offset:560
	ds_read_b32 v41, v36 offset:692
	ds_read_b32 v42, v36 offset:824
	ds_read_b32 v43, v36 offset:956
	s_waitcnt lgkmcnt(0)
	v_cvt_pk_bf16_f32 v29, v29, v30
	v_cvt_pk_bf16_f32 v28, v5, v27
	v_cvt_pk_bf16_f32 v30, v31, v41
	v_cvt_pk_bf16_f32 v31, v42, v43
	v_or_b32_e32 v42, v0, v37
	v_ashrrev_i32_e32 v43, 31, v42
	v_lshlrev_b64 v[42:43], 11, v[42:43]
	v_lshl_add_u64 v[42:43], v[32:33], 0, v[42:43]
	global_store_dwordx4 v[42:43], v[28:31], off
	ds_read_b32 v5, v36 offset:64
	ds_read_b32 v27, v36 offset:196
	ds_read_b32 v29, v36 offset:328
	ds_read_b32 v30, v36 offset:460
	ds_read_b32 v31, v36 offset:592
	ds_read_b32 v41, v36 offset:724
	ds_read_b32 v42, v36 offset:856
	ds_read_b32 v43, v36 offset:988
	s_waitcnt lgkmcnt(0)
	v_cvt_pk_bf16_f32 v29, v29, v30
	v_cvt_pk_bf16_f32 v28, v5, v27
	v_cvt_pk_bf16_f32 v30, v31, v41
	v_cvt_pk_bf16_f32 v31, v42, v43
	v_or_b32_e32 v42, v0, v38
	v_ashrrev_i32_e32 v43, 31, v42
	v_lshlrev_b64 v[42:43], 11, v[42:43]
	v_lshl_add_u64 v[42:43], v[32:33], 0, v[42:43]
	global_store_dwordx4 v[42:43], v[28:31], off
	ds_read_b32 v5, v36 offset:96
	ds_read_b32 v27, v36 offset:228
	ds_read_b32 v29, v36 offset:360
	ds_read_b32 v30, v36 offset:492
	ds_read_b32 v31, v36 offset:624
	ds_read_b32 v41, v36 offset:756
	ds_read_b32 v42, v36 offset:888
	ds_read_b32 v43, v36 offset:1020
	s_waitcnt lgkmcnt(0)
	v_cvt_pk_bf16_f32 v29, v29, v30
	v_cvt_pk_bf16_f32 v28, v5, v27
	v_cvt_pk_bf16_f32 v30, v31, v41
	v_cvt_pk_bf16_f32 v31, v42, v43
	v_or_b32_e32 v42, v0, v39
	v_ashrrev_i32_e32 v43, 31, v42
	v_lshlrev_b64 v[42:43], 11, v[42:43]
	v_lshl_add_u64 v[32:33], v[32:33], 0, v[42:43]
	global_store_dwordx4 v[32:33], v[28:31], off
	s_waitcnt lgkmcnt(0)

.LBB0_479:
	s_lshl_b32 s19, s15, 1
	s_lshl_b32 s20, s17, 1
	v_or_b32_e32 v41, s20, v4
	s_add_i32 s21, s19, 4
	s_add_i32 s22, s20, 4
	s_add_i32 s24, s20, 8
	v_add_u32_e32 v0, v41, v28
	v_or_b32_e32 v62, s21, v3
	v_or_b32_e32 v63, s22, v4
	v_mov_b32_e32 v43, v1
	v_or_b32_e32 v29, s19, v3
	s_add_i32 s26, s20, 12
	v_or_b32_e32 v65, s24, v4
	s_waitcnt vmcnt(0)
	v_lshlrev_b64 v[56:57], 12, v[0:1]
	v_add_u32_e32 v42, v62, v5
	v_add_u32_e32 v0, v63, v28
	v_mov_b32_e32 v33, v1
	s_add_i32 s23, s19, 8
	s_add_i32 s25, s19, 12
	s_add_i32 s28, s20, 16
	v_add_u32_e32 v32, v29, v5
	v_or_b32_e32 v67, s26, v4
	v_lshlrev_b64 v[42:43], 12, v[42:43]
	v_lshlrev_b64 v[58:59], 12, v[0:1]
	v_add_u32_e32 v0, v65, v28
	s_add_i32 s30, s20, 20
	v_or_b32_e32 v64, s23, v3
	v_or_b32_e32 v66, s25, v3
	v_or_b32_e32 v69, s28, v4
	v_lshlrev_b64 v[32:33], 12, v[32:33]
	v_lshl_add_u64 v[56:57], v[30:31], 0, v[56:57]
	v_lshl_add_u64 v[42:43], v[30:31], 0, v[42:43]
	v_lshlrev_b64 v[60:61], 12, v[0:1]
	v_add_u32_e32 v0, v67, v28
	v_mov_b32_e32 v45, v1
	v_mov_b32_e32 v47, v1
	s_add_i32 s27, s19, 16
	s_add_i32 s29, s19, 20
	s_add_i32 s34, s20, 24
	v_or_b32_e32 v71, s30, v4
	v_add_u32_e32 v44, v64, v5
	v_add_u32_e32 v46, v66, v5
	v_lshl_add_u64 v[32:33], v[30:31], 0, v[32:33]
	v_lshl_add_u64 v[58:59], v[30:31], 0, v[58:59]
	global_load_dword v76, v[56:57], off
	global_load_dword v77, v[32:33], off
	global_load_dword v78, v[58:59], off
	global_load_dword v79, v[42:43], off
	v_lshlrev_b64 v[42:43], 12, v[0:1]
	v_add_u32_e32 v0, v69, v28
	s_add_i32 s31, s19, 24
	s_add_i32 s19, s19, 28
	s_add_i32 s20, s20, 28
	v_or_b32_e32 v68, s27, v3
	v_or_b32_e32 v70, s29, v3
	v_or_b32_e32 v73, s34, v4
	v_lshlrev_b64 v[44:45], 12, v[44:45]
	v_lshlrev_b64 v[46:47], 12, v[46:47]
	v_lshl_add_u64 v[32:33], v[30:31], 0, v[60:61]
	v_lshl_add_u64 v[42:43], v[30:31], 0, v[42:43]
	v_lshlrev_b64 v[56:57], 12, v[0:1]
	v_add_u32_e32 v0, v71, v28
	v_mov_b32_e32 v49, v1
	v_mov_b32_e32 v51, v1
	v_or_b32_e32 v72, s31, v3
	v_or_b32_e32 v74, s19, v3
	v_or_b32_e32 v75, s20, v4
	v_add_u32_e32 v48, v68, v5
	v_add_u32_e32 v50, v70, v5
	v_lshl_add_u64 v[44:45], v[30:31], 0, v[44:45]
	v_lshl_add_u64 v[46:47], v[30:31], 0, v[46:47]
	global_load_dword v80, v[32:33], off
	global_load_dword v81, v[44:45], off
	global_load_dword v82, v[42:43], off
	global_load_dword v83, v[46:47], off
	v_lshlrev_b64 v[42:43], 12, v[0:1]
	v_add_u32_e32 v0, v73, v28
	v_mov_b32_e32 v53, v1
	v_mov_b32_e32 v55, v1
	v_add_u32_e32 v52, v72, v5
	v_add_u32_e32 v54, v74, v5
	v_lshlrev_b64 v[48:49], 12, v[48:49]
	v_lshlrev_b64 v[50:51], 12, v[50:51]
	v_lshl_add_u64 v[32:33], v[30:31], 0, v[56:57]
	v_lshl_add_u64 v[42:43], v[30:31], 0, v[42:43]
	v_lshlrev_b64 v[44:45], 12, v[0:1]
	v_add_u32_e32 v0, v75, v28
	v_lshlrev_b64 v[52:53], 12, v[52:53]
	v_lshlrev_b64 v[54:55], 12, v[54:55]
	v_lshl_add_u64 v[48:49], v[30:31], 0, v[48:49]
	v_lshl_add_u64 v[50:51], v[30:31], 0, v[50:51]
	global_load_dword v84, v[32:33], off
	global_load_dword v85, v[48:49], off
	global_load_dword v86, v[42:43], off
	global_load_dword v87, v[50:51], off
	v_lshl_add_u64 v[32:33], v[30:31], 0, v[44:45]
	v_lshlrev_b64 v[42:43], 12, v[0:1]
	v_lshl_add_u64 v[52:53], v[30:31], 0, v[52:53]
	v_lshl_add_u64 v[54:55], v[30:31], 0, v[54:55]
	v_lshl_add_u64 v[42:43], v[30:31], 0, v[42:43]
	global_load_dword v0, v[32:33], off
	global_load_dword v88, v[52:53], off
	global_load_dword v89, v[42:43], off
	global_load_dword v90, v[54:55], off
	s_add_i32 s17, s17, 16
	s_add_i32 s15, s15, 16
	s_add_i32 s18, s18, -16
	v_mad_u64_u32 v[32:33], s[20:21], v41, s86, v[8:9]
	s_cmp_lg_u32 s18, 0
	v_mad_u64_u32 v[42:43], s[20:21], v29, s86, v[8:9]
	v_mad_u64_u32 v[44:45], s[20:21], v63, s86, v[8:9]
	v_mad_u64_u32 v[46:47], s[20:21], v62, s86, v[8:9]
	v_mad_u64_u32 v[48:49], s[20:21], v65, s86, v[8:9]
	v_mad_u64_u32 v[50:51], s[20:21], v64, s86, v[8:9]
	v_mad_u64_u32 v[52:53], s[20:21], v67, s86, v[8:9]
	v_mad_u64_u32 v[54:55], s[20:21], v66, s86, v[8:9]
	v_mad_u64_u32 v[56:57], s[20:21], v69, s86, v[8:9]
	v_mad_u64_u32 v[58:59], s[20:21], v68, s86, v[8:9]
	v_mad_u64_u32 v[60:61], s[20:21], v71, s86, v[8:9]
	v_mad_u64_u32 v[62:63], s[20:21], v70, s86, v[8:9]
	v_mad_u64_u32 v[64:65], s[20:21], v73, s86, v[8:9]
	v_mad_u64_u32 v[66:67], s[20:21], v72, s86, v[8:9]
	v_mad_u64_u32 v[68:69], s[20:21], v75, s86, v[8:9]
	v_mad_u64_u32 v[70:71], s[20:21], v74, s86, v[8:9]
	s_waitcnt vmcnt(0)
	ds_write_b32 v32, v76
	s_waitcnt vmcnt(14)
	ds_write_b32 v42, v77
	s_waitcnt vmcnt(13)
	ds_write_b32 v44, v78
	s_waitcnt vmcnt(12)
	ds_write_b32 v46, v79
	s_waitcnt vmcnt(11)
	ds_write_b32 v48, v80
	s_waitcnt vmcnt(10)
	ds_write_b32 v50, v81
	s_waitcnt vmcnt(9)
	ds_write_b32 v52, v82
	s_waitcnt vmcnt(8)
	ds_write_b32 v54, v83
	s_waitcnt vmcnt(7)
	ds_write_b32 v56, v84
	s_waitcnt vmcnt(6)
	ds_write_b32 v58, v85
	s_waitcnt vmcnt(5)
	ds_write_b32 v60, v86
	s_waitcnt vmcnt(4)
	ds_write_b32 v62, v87
	s_waitcnt vmcnt(3)
	ds_write_b32 v64, v0
	s_waitcnt vmcnt(2)
	ds_write_b32 v66, v88
	s_waitcnt vmcnt(1)
	ds_write_b32 v68, v89
	s_waitcnt vmcnt(0)
	ds_write_b32 v70, v90
	s_cbranch_scc1 .LBB0_479
	s_waitcnt lgkmcnt(0)
	v_lshlrev_b32_e32 v0, 1, v28
	ds_read_b32 v5, v36
	ds_read_b32 v28, v36 offset:132
	ds_read_b32 v29, v36 offset:264
	ds_read_b32 v30, v36 offset:396
	ds_read_b32 v31, v36 offset:528
	ds_read_b32 v41, v36 offset:660
	ds_read_b32 v42, v36 offset:792
	ds_read_b32 v43, v36 offset:924
	v_lshl_add_u64 v[32:33], v[12:13], 0, v[0:1]
	v_or_b32_sdwa v0, v35, v27 dst_sel:DWORD dst_unused:UNUSED_PAD src0_sel:DWORD src1_sel:WORD_0
	v_mul_u32_u24_e32 v0, 0xb00, v0
	v_lshlrev_b32_e32 v0, 1, v0
	s_waitcnt lgkmcnt(6)
	v_cvt_pk_bf16_f32 v28, v5, v28
	s_waitcnt lgkmcnt(4)
	v_cvt_pk_bf16_f32 v29, v29, v30
	s_waitcnt lgkmcnt(2)
	v_cvt_pk_bf16_f32 v30, v31, v41
	s_waitcnt lgkmcnt(0)
	v_cvt_pk_bf16_f32 v31, v42, v43
	v_lshl_add_u64 v[42:43], v[32:33], 0, v[0:1]
	global_store_dwordx4 v[42:43], v[28:31], off
	ds_read_b32 v0, v36 offset:32
	ds_read_b32 v5, v36 offset:164
	ds_read_b32 v29, v36 offset:296
	ds_read_b32 v30, v36 offset:428
	ds_read_b32 v31, v36 offset:560
	ds_read_b32 v41, v36 offset:692
	ds_read_b32 v42, v36 offset:824
	ds_read_b32 v43, v36 offset:956
	s_waitcnt lgkmcnt(0)
	v_cvt_pk_bf16_f32 v28, v0, v5
	v_or_b32_sdwa v0, v37, v27 dst_sel:DWORD dst_unused:UNUSED_PAD src0_sel:DWORD src1_sel:WORD_0
	v_mul_u32_u24_e32 v0, 0xb00, v0
	v_lshlrev_b32_e32 v0, 1, v0
	v_cvt_pk_bf16_f32 v29, v29, v30
	v_cvt_pk_bf16_f32 v30, v31, v41
	v_cvt_pk_bf16_f32 v31, v42, v43
	v_lshl_add_u64 v[42:43], v[32:33], 0, v[0:1]
	global_store_dwordx4 v[42:43], v[28:31], off
	ds_read_b32 v0, v36 offset:64
	ds_read_b32 v5, v36 offset:196
	ds_read_b32 v29, v36 offset:328
	ds_read_b32 v30, v36 offset:460
	ds_read_b32 v31, v36 offset:592
	ds_read_b32 v41, v36 offset:724
	ds_read_b32 v42, v36 offset:856
	ds_read_b32 v43, v36 offset:988
	s_waitcnt lgkmcnt(0)
	v_cvt_pk_bf16_f32 v28, v0, v5
	v_or_b32_sdwa v0, v38, v27 dst_sel:DWORD dst_unused:UNUSED_PAD src0_sel:DWORD src1_sel:WORD_0
	v_mul_u32_u24_e32 v0, 0xb00, v0
	v_lshlrev_b32_e32 v0, 1, v0
	v_cvt_pk_bf16_f32 v29, v29, v30
	v_cvt_pk_bf16_f32 v30, v31, v41
	v_cvt_pk_bf16_f32 v31, v42, v43
	v_lshl_add_u64 v[42:43], v[32:33], 0, v[0:1]
	global_store_dwordx4 v[42:43], v[28:31], off
	ds_read_b32 v0, v36 offset:96
	ds_read_b32 v5, v36 offset:228
	ds_read_b32 v29, v36 offset:360
	ds_read_b32 v30, v36 offset:492
	ds_read_b32 v31, v36 offset:624
	ds_read_b32 v41, v36 offset:756
	ds_read_b32 v42, v36 offset:888
	ds_read_b32 v43, v36 offset:1020
	s_waitcnt lgkmcnt(0)
	v_cvt_pk_bf16_f32 v28, v0, v5
	v_or_b32_sdwa v0, v39, v27 dst_sel:DWORD dst_unused:UNUSED_PAD src0_sel:DWORD src1_sel:WORD_0
	v_mul_u32_u24_e32 v0, 0xb00, v0
	v_lshlrev_b32_e32 v0, 1, v0
	v_cvt_pk_bf16_f32 v29, v29, v30
	v_cvt_pk_bf16_f32 v30, v31, v41
	v_cvt_pk_bf16_f32 v31, v42, v43
	v_lshl_add_u64 v[32:33], v[32:33], 0, v[0:1]
	global_store_dwordx4 v[32:33], v[28:31], off
	s_waitcnt lgkmcnt(0)

.LBB0_483:
	s_lshl_b32 s19, s15, 1
	s_lshl_b32 s20, s18, 1
	v_or_b32_e32 v0, s19, v3
	v_or_b32_e32 v29, s20, v4
	s_add_i32 s21, s19, 4
	s_add_i32 s22, s20, 4
	s_add_i32 s23, s19, 8
	s_add_i32 s24, s20, 8
	s_add_i32 s25, s19, 12
	s_add_i32 s26, s20, 12
	s_add_i32 s27, s19, 16
	s_add_i32 s28, s20, 16
	s_add_i32 s29, s19, 20
	s_add_i32 s30, s20, 20
	s_add_i32 s31, s19, 24
	s_add_i32 s34, s20, 24
	s_add_i32 s19, s19, 28
	s_add_i32 s20, s20, 28
	v_add_u32_e32 v41, v0, v5
	v_add_u32_e32 v32, v29, v28
	s_waitcnt vmcnt(0)
	v_or_b32_e32 v72, s21, v3
	v_or_b32_e32 v73, s22, v4
	v_or_b32_e32 v74, s23, v3
	v_or_b32_e32 v75, s24, v4
	v_or_b32_e32 v76, s25, v3
	v_or_b32_e32 v77, s26, v4
	v_or_b32_e32 v78, s27, v3
	v_or_b32_e32 v79, s28, v4
	v_or_b32_e32 v80, s29, v3
	v_or_b32_e32 v81, s30, v4
	v_or_b32_e32 v82, s31, v3
	v_or_b32_e32 v83, s34, v4
	v_or_b32_e32 v84, s19, v3
	v_or_b32_e32 v85, s20, v4
	v_mad_u64_u32 v[32:33], s[20:21], v32, s35, v[30:31]
	v_mad_u64_u32 v[42:43], s[20:21], v41, s35, v[30:31]
	v_add_u32_e32 v41, v72, v5
	v_add_u32_e32 v44, v73, v28
	v_add_u32_e32 v50, v74, v5
	v_add_u32_e32 v48, v75, v28
	v_add_u32_e32 v54, v76, v5
	v_add_u32_e32 v52, v77, v28
	v_add_u32_e32 v58, v78, v5
	v_add_u32_e32 v56, v79, v28
	v_add_u32_e32 v62, v80, v5
	v_add_u32_e32 v60, v81, v28
	v_add_u32_e32 v66, v82, v5
	v_add_u32_e32 v64, v83, v28
	v_add_u32_e32 v70, v84, v5
	v_add_u32_e32 v68, v85, v28
	v_mad_u64_u32 v[44:45], s[20:21], v44, s35, v[30:31]
	v_mad_u64_u32 v[46:47], s[20:21], v41, s35, v[30:31]
	v_mad_u64_u32 v[48:49], s[20:21], v48, s35, v[30:31]
	v_mad_u64_u32 v[50:51], s[20:21], v50, s35, v[30:31]
	v_mad_u64_u32 v[52:53], s[20:21], v52, s35, v[30:31]
	v_mad_u64_u32 v[54:55], s[20:21], v54, s35, v[30:31]
	v_mad_u64_u32 v[56:57], s[20:21], v56, s35, v[30:31]
	v_mad_u64_u32 v[58:59], s[20:21], v58, s35, v[30:31]
	v_mad_u64_u32 v[60:61], s[20:21], v60, s35, v[30:31]
	v_mad_u64_u32 v[62:63], s[20:21], v62, s35, v[30:31]
	v_mad_u64_u32 v[64:65], s[20:21], v64, s35, v[30:31]
	v_mad_u64_u32 v[66:67], s[20:21], v66, s35, v[30:31]
	v_mad_u64_u32 v[68:69], s[20:21], v68, s35, v[30:31]
	v_mad_u64_u32 v[70:71], s[20:21], v70, s35, v[30:31]
	global_load_dword v41, v[32:33], off
	global_load_dword v86, v[42:43], off
	global_load_dword v87, v[44:45], off
	global_load_dword v88, v[46:47], off
	global_load_dword v89, v[48:49], off
	global_load_dword v90, v[50:51], off
	global_load_dword v91, v[52:53], off
	global_load_dword v92, v[54:55], off
	global_load_dword v93, v[56:57], off
	global_load_dword v94, v[58:59], off
	global_load_dword v95, v[60:61], off
	global_load_dword v96, v[62:63], off
	global_load_dword v97, v[64:65], off
	global_load_dword v98, v[66:67], off
	global_load_dword v99, v[68:69], off
	global_load_dword v100, v[70:71], off
	s_add_i32 s18, s18, 16
	s_add_i32 s15, s15, 16
	s_add_i32 s17, s17, -16
	v_mad_u64_u32 v[32:33], s[20:21], v29, s86, v[8:9]
	s_cmp_lg_u32 s17, 0
	v_mad_u64_u32 v[42:43], s[20:21], v0, s86, v[8:9]
	v_mad_u64_u32 v[44:45], s[20:21], v73, s86, v[8:9]
	v_mad_u64_u32 v[46:47], s[20:21], v72, s86, v[8:9]
	v_mad_u64_u32 v[48:49], s[20:21], v75, s86, v[8:9]
	v_mad_u64_u32 v[50:51], s[20:21], v74, s86, v[8:9]
	v_mad_u64_u32 v[52:53], s[20:21], v77, s86, v[8:9]
	v_mad_u64_u32 v[54:55], s[20:21], v76, s86, v[8:9]
	v_mad_u64_u32 v[56:57], s[20:21], v79, s86, v[8:9]
	v_mad_u64_u32 v[58:59], s[20:21], v78, s86, v[8:9]
	v_mad_u64_u32 v[60:61], s[20:21], v81, s86, v[8:9]
	v_mad_u64_u32 v[62:63], s[20:21], v80, s86, v[8:9]
	v_mad_u64_u32 v[64:65], s[20:21], v83, s86, v[8:9]
	v_mad_u64_u32 v[66:67], s[20:21], v82, s86, v[8:9]
	v_mad_u64_u32 v[68:69], s[20:21], v85, s86, v[8:9]
	v_mad_u64_u32 v[70:71], s[20:21], v84, s86, v[8:9]
	s_waitcnt vmcnt(0)
	ds_write_b32 v32, v41
	ds_write_b32 v42, v86
	ds_write_b32 v44, v87
	ds_write_b32 v46, v88
	ds_write_b32 v48, v89
	ds_write_b32 v50, v90
	ds_write_b32 v52, v91
	ds_write_b32 v54, v92
	ds_write_b32 v56, v93
	ds_write_b32 v58, v94
	ds_write_b32 v60, v95
	ds_write_b32 v62, v96
	ds_write_b32 v64, v97
	ds_write_b32 v66, v98
	ds_write_b32 v68, v99
	ds_write_b32 v70, v100
	s_cbranch_scc1 .LBB0_483
	s_waitcnt lgkmcnt(0)
	v_lshlrev_b32_e32 v0, 1, v28
	ds_read_b32 v5, v36
	ds_read_b32 v28, v36 offset:132
	ds_read_b32 v29, v36 offset:264
	ds_read_b32 v30, v36 offset:396
	ds_read_b32 v31, v36 offset:528
	ds_read_b32 v41, v36 offset:660
	ds_read_b32 v42, v36 offset:792
	ds_read_b32 v43, v36 offset:924
	v_lshl_add_u64 v[32:33], v[14:15], 0, v[0:1]
	v_or_b32_e32 v0, v27, v35
	s_waitcnt lgkmcnt(0)
	v_cvt_pk_bf16_f32 v29, v29, v30
	v_cvt_pk_bf16_f32 v30, v31, v41
	v_cvt_pk_bf16_f32 v31, v42, v43
	v_lshlrev_b64 v[42:43], 11, v[0:1]
	v_cvt_pk_bf16_f32 v28, v5, v28
	v_lshl_add_u64 v[42:43], v[32:33], 0, v[42:43]
	global_store_dwordx4 v[42:43], v[28:31], off
	ds_read_b32 v0, v36 offset:32
	ds_read_b32 v5, v36 offset:164
	ds_read_b32 v29, v36 offset:296
	ds_read_b32 v30, v36 offset:428
	ds_read_b32 v31, v36 offset:560
	ds_read_b32 v41, v36 offset:692
	ds_read_b32 v42, v36 offset:824
	ds_read_b32 v43, v36 offset:956
	s_waitcnt lgkmcnt(0)
	v_cvt_pk_bf16_f32 v28, v0, v5
	v_or_b32_e32 v0, v27, v37
	v_cvt_pk_bf16_f32 v29, v29, v30
	v_cvt_pk_bf16_f32 v30, v31, v41
	v_cvt_pk_bf16_f32 v31, v42, v43
	v_lshlrev_b64 v[42:43], 11, v[0:1]
	v_lshl_add_u64 v[42:43], v[32:33], 0, v[42:43]
	global_store_dwordx4 v[42:43], v[28:31], off
	ds_read_b32 v0, v36 offset:64
	ds_read_b32 v5, v36 offset:196
	ds_read_b32 v29, v36 offset:328
	ds_read_b32 v30, v36 offset:460
	ds_read_b32 v31, v36 offset:592
	ds_read_b32 v41, v36 offset:724
	ds_read_b32 v42, v36 offset:856
	ds_read_b32 v43, v36 offset:988
	s_waitcnt lgkmcnt(0)
	v_cvt_pk_bf16_f32 v28, v0, v5
	v_or_b32_e32 v0, v27, v38
	v_cvt_pk_bf16_f32 v29, v29, v30
	v_cvt_pk_bf16_f32 v30, v31, v41
	v_cvt_pk_bf16_f32 v31, v42, v43
	v_lshlrev_b64 v[42:43], 11, v[0:1]
	v_lshl_add_u64 v[42:43], v[32:33], 0, v[42:43]
	global_store_dwordx4 v[42:43], v[28:31], off
	ds_read_b32 v0, v36 offset:96
	ds_read_b32 v5, v36 offset:228
	ds_read_b32 v29, v36 offset:360
	ds_read_b32 v30, v36 offset:492
	ds_read_b32 v31, v36 offset:624
	ds_read_b32 v41, v36 offset:756
	ds_read_b32 v42, v36 offset:888
	ds_read_b32 v43, v36 offset:1020
	s_waitcnt lgkmcnt(0)
	v_cvt_pk_bf16_f32 v28, v0, v5
	v_or_b32_e32 v0, v27, v39
	v_cvt_pk_bf16_f32 v29, v29, v30
	v_cvt_pk_bf16_f32 v30, v31, v41
	v_cvt_pk_bf16_f32 v31, v42, v43
	v_lshlrev_b64 v[42:43], 11, v[0:1]
	v_lshl_add_u64 v[32:33], v[32:33], 0, v[42:43]
	global_store_dwordx4 v[32:33], v[28:31], off
	s_waitcnt lgkmcnt(0)

.LBB0_488:
	s_lshl_b32 s17, s12, 1
	s_lshl_b32 s18, s13, 1
	v_or_b32_e32 v29, s18, v4
	s_add_i32 s19, s17, 4
	s_add_i32 s20, s18, 4
	s_add_i32 s22, s18, 8
	v_add_u32_e32 v0, v29, v30
	v_or_b32_e32 v31, s19, v3
	v_or_b32_e32 v41, s20, v4
	v_mov_b32_e32 v45, v1
	v_or_b32_e32 v27, s17, v3
	s_add_i32 s24, s18, 12
	v_or_b32_e32 v65, s22, v4
	v_lshlrev_b64 v[58:59], 12, v[0:1]
	v_add_u32_e32 v44, v31, v5
	v_add_u32_e32 v0, v41, v30
	v_mov_b32_e32 v43, v1
	s_add_i32 s21, s17, 8
	s_add_i32 s23, s17, 12
	s_add_i32 s26, s18, 16
	v_add_u32_e32 v42, v27, v5
	v_or_b32_e32 v67, s24, v4
	v_lshlrev_b64 v[44:45], 12, v[44:45]
	v_lshlrev_b64 v[60:61], 12, v[0:1]
	v_add_u32_e32 v0, v65, v30
	s_add_i32 s28, s18, 20
	v_or_b32_e32 v64, s21, v3
	v_or_b32_e32 v66, s23, v3
	v_or_b32_e32 v69, s26, v4
	v_lshlrev_b64 v[42:43], 12, v[42:43]
	v_lshl_add_u64 v[58:59], v[32:33], 0, v[58:59]
	v_lshl_add_u64 v[44:45], v[32:33], 0, v[44:45]
	v_lshlrev_b64 v[62:63], 12, v[0:1]
	v_add_u32_e32 v0, v67, v30
	v_mov_b32_e32 v47, v1
	v_mov_b32_e32 v49, v1
	s_add_i32 s25, s17, 16
	s_add_i32 s27, s17, 20
	s_add_i32 s30, s18, 24
	s_waitcnt vmcnt(0)
	v_or_b32_e32 v71, s28, v4
	v_add_u32_e32 v46, v64, v5
	v_add_u32_e32 v48, v66, v5
	v_lshl_add_u64 v[42:43], v[32:33], 0, v[42:43]
	v_lshl_add_u64 v[60:61], v[32:33], 0, v[60:61]
	global_load_dword v76, v[58:59], off
	global_load_dword v77, v[42:43], off
	global_load_dword v78, v[60:61], off
	global_load_dword v79, v[44:45], off
	v_lshlrev_b64 v[44:45], 12, v[0:1]
	v_add_u32_e32 v0, v69, v30
	s_add_i32 s29, s17, 24
	s_add_i32 s17, s17, 28
	s_add_i32 s18, s18, 28
	v_or_b32_e32 v68, s25, v3
	v_or_b32_e32 v70, s27, v3
	v_or_b32_e32 v73, s30, v4
	v_lshlrev_b64 v[46:47], 12, v[46:47]
	v_lshlrev_b64 v[48:49], 12, v[48:49]
	v_lshl_add_u64 v[42:43], v[32:33], 0, v[62:63]
	v_lshl_add_u64 v[44:45], v[32:33], 0, v[44:45]
	v_lshlrev_b64 v[58:59], 12, v[0:1]
	v_add_u32_e32 v0, v71, v30
	v_mov_b32_e32 v51, v1
	v_mov_b32_e32 v53, v1
	v_or_b32_e32 v72, s29, v3
	v_or_b32_e32 v74, s17, v3
	v_or_b32_e32 v75, s18, v4
	v_add_u32_e32 v50, v68, v5
	v_add_u32_e32 v52, v70, v5
	v_lshl_add_u64 v[46:47], v[32:33], 0, v[46:47]
	v_lshl_add_u64 v[48:49], v[32:33], 0, v[48:49]
	global_load_dword v80, v[42:43], off
	global_load_dword v81, v[46:47], off
	global_load_dword v82, v[44:45], off
	global_load_dword v83, v[48:49], off
	v_lshlrev_b64 v[44:45], 12, v[0:1]
	v_add_u32_e32 v0, v73, v30
	v_mov_b32_e32 v55, v1
	v_mov_b32_e32 v57, v1
	v_add_u32_e32 v54, v72, v5
	v_add_u32_e32 v56, v74, v5
	v_lshlrev_b64 v[50:51], 12, v[50:51]
	v_lshlrev_b64 v[52:53], 12, v[52:53]
	v_lshl_add_u64 v[42:43], v[32:33], 0, v[58:59]
	v_lshl_add_u64 v[44:45], v[32:33], 0, v[44:45]
	v_lshlrev_b64 v[46:47], 12, v[0:1]
	v_add_u32_e32 v0, v75, v30
	v_lshlrev_b64 v[54:55], 12, v[54:55]
	v_lshlrev_b64 v[56:57], 12, v[56:57]
	v_lshl_add_u64 v[50:51], v[32:33], 0, v[50:51]
	v_lshl_add_u64 v[52:53], v[32:33], 0, v[52:53]
	global_load_dword v84, v[42:43], off
	global_load_dword v85, v[50:51], off
	global_load_dword v86, v[44:45], off
	global_load_dword v87, v[52:53], off
	v_lshl_add_u64 v[42:43], v[32:33], 0, v[46:47]
	v_lshlrev_b64 v[44:45], 12, v[0:1]
	v_lshl_add_u64 v[54:55], v[32:33], 0, v[54:55]
	v_lshl_add_u64 v[56:57], v[32:33], 0, v[56:57]
	v_lshl_add_u64 v[44:45], v[32:33], 0, v[44:45]
	global_load_dword v0, v[42:43], off
	global_load_dword v88, v[54:55], off
	global_load_dword v89, v[44:45], off
	global_load_dword v90, v[56:57], off
	s_add_i32 s13, s13, 16
	s_add_i32 s12, s12, 16
	s_add_i32 s15, s15, -16
	v_mad_u64_u32 v[42:43], s[18:19], v29, s86, v[8:9]
	s_cmp_lg_u32 s15, 0
	v_mad_u64_u32 v[44:45], s[18:19], v27, s86, v[8:9]
	v_mad_u64_u32 v[46:47], s[18:19], v41, s86, v[8:9]
	v_mad_u64_u32 v[48:49], s[18:19], v31, s86, v[8:9]
	v_mad_u64_u32 v[50:51], s[18:19], v65, s86, v[8:9]
	v_mad_u64_u32 v[52:53], s[18:19], v64, s86, v[8:9]
	v_mad_u64_u32 v[54:55], s[18:19], v67, s86, v[8:9]
	v_mad_u64_u32 v[56:57], s[18:19], v66, s86, v[8:9]
	v_mad_u64_u32 v[58:59], s[18:19], v69, s86, v[8:9]
	v_mad_u64_u32 v[60:61], s[18:19], v68, s86, v[8:9]
	v_mad_u64_u32 v[62:63], s[18:19], v71, s86, v[8:9]
	v_mad_u64_u32 v[64:65], s[18:19], v70, s86, v[8:9]
	v_mad_u64_u32 v[66:67], s[18:19], v73, s86, v[8:9]
	v_mad_u64_u32 v[68:69], s[18:19], v72, s86, v[8:9]
	v_mad_u64_u32 v[70:71], s[18:19], v75, s86, v[8:9]
	v_mad_u64_u32 v[72:73], s[18:19], v74, s86, v[8:9]
	s_waitcnt vmcnt(0)
	ds_write_b32 v42, v76
	ds_write_b32 v44, v77
	ds_write_b32 v46, v78
	ds_write_b32 v48, v79
	ds_write_b32 v50, v80
	ds_write_b32 v52, v81
	ds_write_b32 v54, v82
	ds_write_b32 v56, v83
	ds_write_b32 v58, v84
	ds_write_b32 v60, v85
	ds_write_b32 v62, v86
	ds_write_b32 v64, v87
	ds_write_b32 v66, v0
	ds_write_b32 v68, v88
	ds_write_b32 v70, v89
	ds_write_b32 v72, v90
	s_cbranch_scc1 .LBB0_488
	s_waitcnt lgkmcnt(0)
	ds_read_b32 v5, v36
	ds_read_b32 v27, v36 offset:132
	ds_read_b32 v29, v36 offset:264
	ds_read_b32 v31, v36 offset:396
	ds_read_b32 v32, v36 offset:528
	ds_read_b32 v33, v36 offset:660
	ds_read_b32 v41, v36 offset:792
	ds_read_b32 v44, v36 offset:924
	v_lshlrev_b32_e32 v0, 1, v30
	v_lshl_add_u64 v[42:43], v[16:17], 0, v[0:1]
	v_or_b32_e32 v0, v28, v35
	s_waitcnt lgkmcnt(0)
	v_cvt_pk_bf16_f32 v32, v32, v33
	v_cvt_pk_bf16_f32 v33, v41, v44
	v_lshlrev_b64 v[44:45], 11, v[0:1]
	v_cvt_pk_bf16_f32 v30, v5, v27
	v_cvt_pk_bf16_f32 v31, v29, v31
	v_lshl_add_u64 v[44:45], v[42:43], 0, v[44:45]
	global_store_dwordx4 v[44:45], v[30:33], off
	ds_read_b32 v0, v36 offset:32
	ds_read_b32 v5, v36 offset:164
	ds_read_b32 v27, v36 offset:296
	ds_read_b32 v29, v36 offset:428
	ds_read_b32 v32, v36 offset:560
	ds_read_b32 v33, v36 offset:692
	ds_read_b32 v41, v36 offset:824
	ds_read_b32 v44, v36 offset:956
	s_waitcnt lgkmcnt(0)
	v_cvt_pk_bf16_f32 v30, v0, v5
	v_or_b32_e32 v0, v28, v37
	v_cvt_pk_bf16_f32 v32, v32, v33
	v_cvt_pk_bf16_f32 v31, v27, v29
	v_cvt_pk_bf16_f32 v33, v41, v44
	v_lshlrev_b64 v[44:45], 11, v[0:1]
	v_lshl_add_u64 v[44:45], v[42:43], 0, v[44:45]
	global_store_dwordx4 v[44:45], v[30:33], off
	ds_read_b32 v0, v36 offset:64
	ds_read_b32 v5, v36 offset:196
	ds_read_b32 v27, v36 offset:328
	ds_read_b32 v29, v36 offset:460
	ds_read_b32 v32, v36 offset:592
	ds_read_b32 v33, v36 offset:724
	ds_read_b32 v41, v36 offset:856
	ds_read_b32 v44, v36 offset:988
	s_waitcnt lgkmcnt(0)
	v_cvt_pk_bf16_f32 v30, v0, v5
	v_or_b32_e32 v0, v28, v38
	v_cvt_pk_bf16_f32 v32, v32, v33
	v_cvt_pk_bf16_f32 v31, v27, v29
	v_cvt_pk_bf16_f32 v33, v41, v44
	v_lshlrev_b64 v[44:45], 11, v[0:1]
	v_lshl_add_u64 v[44:45], v[42:43], 0, v[44:45]
	global_store_dwordx4 v[44:45], v[30:33], off
	ds_read_b32 v0, v36 offset:96
	ds_read_b32 v5, v36 offset:228
	ds_read_b32 v27, v36 offset:360
	ds_read_b32 v29, v36 offset:492
	ds_read_b32 v32, v36 offset:624
	ds_read_b32 v33, v36 offset:756
	ds_read_b32 v41, v36 offset:888
	ds_read_b32 v44, v36 offset:1020
	s_waitcnt lgkmcnt(0)
	v_cvt_pk_bf16_f32 v30, v0, v5
	v_or_b32_e32 v0, v28, v39
	v_cvt_pk_bf16_f32 v31, v27, v29
	v_lshlrev_b64 v[28:29], 11, v[0:1]
	v_cvt_pk_bf16_f32 v32, v32, v33
	v_cvt_pk_bf16_f32 v33, v41, v44
	v_lshl_add_u64 v[28:29], v[42:43], 0, v[28:29]
	global_store_dwordx4 v[28:29], v[30:33], off
	s_waitcnt lgkmcnt(0)

.LBB0_493:
	s_lshl_b32 s17, s12, 1
	s_lshl_b32 s18, s13, 1
	v_or_b32_e32 v41, s18, v4
	s_add_i32 s19, s17, 4
	s_add_i32 s20, s18, 4
	s_add_i32 s22, s18, 8
	v_add_u32_e32 v0, v41, v28
	v_or_b32_e32 v62, s19, v3
	v_or_b32_e32 v63, s20, v4
	v_mov_b32_e32 v43, v1
	v_or_b32_e32 v27, s17, v3
	s_add_i32 s24, s18, 12
	v_or_b32_e32 v65, s22, v4
	s_waitcnt vmcnt(0)
	v_lshlrev_b64 v[56:57], 12, v[0:1]
	v_add_u32_e32 v42, v62, v5
	v_add_u32_e32 v0, v63, v28
	v_mov_b32_e32 v33, v1
	s_add_i32 s21, s17, 8
	s_add_i32 s23, s17, 12
	s_add_i32 s26, s18, 16
	v_add_u32_e32 v32, v27, v5
	v_or_b32_e32 v67, s24, v4
	v_lshlrev_b64 v[42:43], 12, v[42:43]
	v_lshlrev_b64 v[58:59], 12, v[0:1]
	v_add_u32_e32 v0, v65, v28
	s_add_i32 s28, s18, 20
	v_or_b32_e32 v64, s21, v3
	v_or_b32_e32 v66, s23, v3
	v_or_b32_e32 v69, s26, v4
	v_lshlrev_b64 v[32:33], 12, v[32:33]
	v_lshl_add_u64 v[56:57], v[30:31], 0, v[56:57]
	v_lshl_add_u64 v[42:43], v[30:31], 0, v[42:43]
	v_lshlrev_b64 v[60:61], 12, v[0:1]
	v_add_u32_e32 v0, v67, v28
	v_mov_b32_e32 v45, v1
	v_mov_b32_e32 v47, v1
	s_add_i32 s25, s17, 16
	s_add_i32 s27, s17, 20
	s_add_i32 s30, s18, 24
	v_or_b32_e32 v71, s28, v4
	v_add_u32_e32 v44, v64, v5
	v_add_u32_e32 v46, v66, v5
	v_lshl_add_u64 v[32:33], v[30:31], 0, v[32:33]
	v_lshl_add_u64 v[58:59], v[30:31], 0, v[58:59]
	global_load_dword v76, v[56:57], off
	global_load_dword v77, v[32:33], off
	global_load_dword v78, v[58:59], off
	global_load_dword v79, v[42:43], off
	v_lshlrev_b64 v[42:43], 12, v[0:1]
	v_add_u32_e32 v0, v69, v28
	s_add_i32 s29, s17, 24
	s_add_i32 s17, s17, 28
	s_add_i32 s18, s18, 28
	v_or_b32_e32 v68, s25, v3
	v_or_b32_e32 v70, s27, v3
	v_or_b32_e32 v73, s30, v4
	v_lshlrev_b64 v[44:45], 12, v[44:45]
	v_lshlrev_b64 v[46:47], 12, v[46:47]
	v_lshl_add_u64 v[32:33], v[30:31], 0, v[60:61]
	v_lshl_add_u64 v[42:43], v[30:31], 0, v[42:43]
	v_lshlrev_b64 v[56:57], 12, v[0:1]
	v_add_u32_e32 v0, v71, v28
	v_mov_b32_e32 v49, v1
	v_mov_b32_e32 v51, v1
	v_or_b32_e32 v72, s29, v3
	v_or_b32_e32 v74, s17, v3
	v_or_b32_e32 v75, s18, v4
	v_add_u32_e32 v48, v68, v5
	v_add_u32_e32 v50, v70, v5
	v_lshl_add_u64 v[44:45], v[30:31], 0, v[44:45]
	v_lshl_add_u64 v[46:47], v[30:31], 0, v[46:47]
	global_load_dword v80, v[32:33], off
	global_load_dword v81, v[44:45], off
	global_load_dword v82, v[42:43], off
	global_load_dword v83, v[46:47], off
	v_lshlrev_b64 v[42:43], 12, v[0:1]
	v_add_u32_e32 v0, v73, v28
	v_mov_b32_e32 v53, v1
	v_mov_b32_e32 v55, v1
	v_add_u32_e32 v52, v72, v5
	v_add_u32_e32 v54, v74, v5
	v_lshlrev_b64 v[48:49], 12, v[48:49]
	v_lshlrev_b64 v[50:51], 12, v[50:51]
	v_lshl_add_u64 v[32:33], v[30:31], 0, v[56:57]
	v_lshl_add_u64 v[42:43], v[30:31], 0, v[42:43]
	v_lshlrev_b64 v[44:45], 12, v[0:1]
	v_add_u32_e32 v0, v75, v28
	v_lshlrev_b64 v[52:53], 12, v[52:53]
	v_lshlrev_b64 v[54:55], 12, v[54:55]
	v_lshl_add_u64 v[48:49], v[30:31], 0, v[48:49]
	v_lshl_add_u64 v[50:51], v[30:31], 0, v[50:51]
	global_load_dword v84, v[32:33], off
	global_load_dword v85, v[48:49], off
	global_load_dword v86, v[42:43], off
	global_load_dword v87, v[50:51], off
	v_lshl_add_u64 v[32:33], v[30:31], 0, v[44:45]
	v_lshlrev_b64 v[42:43], 12, v[0:1]
	v_lshl_add_u64 v[52:53], v[30:31], 0, v[52:53]
	v_lshl_add_u64 v[54:55], v[30:31], 0, v[54:55]
	v_lshl_add_u64 v[42:43], v[30:31], 0, v[42:43]
	global_load_dword v0, v[32:33], off
	global_load_dword v88, v[52:53], off
	global_load_dword v89, v[42:43], off
	global_load_dword v90, v[54:55], off
	s_add_i32 s13, s13, 16
	s_add_i32 s12, s12, 16
	s_add_i32 s15, s15, -16
	v_mad_u64_u32 v[32:33], s[18:19], v41, s86, v[8:9]
	s_cmp_lg_u32 s15, 0
	v_mad_u64_u32 v[42:43], s[18:19], v27, s86, v[8:9]
	v_mad_u64_u32 v[44:45], s[18:19], v63, s86, v[8:9]
	v_mad_u64_u32 v[46:47], s[18:19], v62, s86, v[8:9]
	v_mad_u64_u32 v[48:49], s[18:19], v65, s86, v[8:9]
	v_mad_u64_u32 v[50:51], s[18:19], v64, s86, v[8:9]
	v_mad_u64_u32 v[52:53], s[18:19], v67, s86, v[8:9]
	v_mad_u64_u32 v[54:55], s[18:19], v66, s86, v[8:9]
	v_mad_u64_u32 v[56:57], s[18:19], v69, s86, v[8:9]
	v_mad_u64_u32 v[58:59], s[18:19], v68, s86, v[8:9]
	v_mad_u64_u32 v[60:61], s[18:19], v71, s86, v[8:9]
	v_mad_u64_u32 v[62:63], s[18:19], v70, s86, v[8:9]
	v_mad_u64_u32 v[64:65], s[18:19], v73, s86, v[8:9]
	v_mad_u64_u32 v[66:67], s[18:19], v72, s86, v[8:9]
	v_mad_u64_u32 v[68:69], s[18:19], v75, s86, v[8:9]
	v_mad_u64_u32 v[70:71], s[18:19], v74, s86, v[8:9]
	s_waitcnt vmcnt(0)
	ds_write_b32 v32, v76
	ds_write_b32 v42, v77
	ds_write_b32 v44, v78
	ds_write_b32 v46, v79
	ds_write_b32 v48, v80
	ds_write_b32 v50, v81
	ds_write_b32 v52, v82
	ds_write_b32 v54, v83
	ds_write_b32 v56, v84
	ds_write_b32 v58, v85
	ds_write_b32 v60, v86
	ds_write_b32 v62, v87
	ds_write_b32 v64, v0
	ds_write_b32 v66, v88
	ds_write_b32 v68, v89
	ds_write_b32 v70, v90
	s_cbranch_scc1 .LBB0_493
	v_mov_b32_e32 v0, 0x1040000
	v_mov_b32_e32 v5, 0xf40000
	v_cndmask_b32_e32 v0, v0, v5, vcc
	v_mov_b32_e32 v5, 0xe40000
	v_cndmask_b32_e64 v0, v0, v5, s[0:1]
	v_lshl_add_u64 v[30:31], s[78:79], 0, v[0:1]
	s_waitcnt lgkmcnt(0)
	v_lshlrev_b32_e32 v0, 1, v28
	v_lshl_add_u64 v[30:31], v[30:31], 0, v[0:1]
	ds_read_b32 v0, v36
	ds_read_b32 v5, v36 offset:132
	ds_read_b32 v28, v36 offset:264
	ds_read_b32 v32, v36 offset:396
	ds_read_b32 v33, v36 offset:528
	ds_read_b32 v41, v36 offset:660
	ds_read_b32 v44, v36 offset:792
	ds_read_b32 v45, v36 offset:924
	v_mov_b32_e32 v27, v1
	v_lshl_add_u64 v[42:43], v[30:31], 0, v[26:27]
	s_waitcnt lgkmcnt(0)
	v_cvt_pk_bf16_f32 v30, v0, v5
	v_or_b32_e32 v0, v29, v35
	v_lshlrev_b32_e32 v0, 10, v0
	v_cvt_pk_bf16_f32 v31, v28, v32
	v_cvt_pk_bf16_f32 v32, v33, v41
	v_cvt_pk_bf16_f32 v33, v44, v45
	v_lshl_add_u64 v[44:45], v[42:43], 0, v[0:1]
	global_store_dwordx4 v[44:45], v[30:33], off
	ds_read_b32 v0, v36 offset:32
	ds_read_b32 v5, v36 offset:164
	ds_read_b32 v27, v36 offset:296
	ds_read_b32 v28, v36 offset:428
	ds_read_b32 v32, v36 offset:560
	ds_read_b32 v33, v36 offset:692
	ds_read_b32 v41, v36 offset:824
	ds_read_b32 v44, v36 offset:956
	s_waitcnt lgkmcnt(0)
	v_cvt_pk_bf16_f32 v30, v0, v5
	v_or_b32_e32 v0, v29, v37
	v_lshlrev_b32_e32 v0, 10, v0
	v_cvt_pk_bf16_f32 v31, v27, v28
	v_cvt_pk_bf16_f32 v32, v32, v33
	v_cvt_pk_bf16_f32 v33, v41, v44
	v_lshl_add_u64 v[44:45], v[42:43], 0, v[0:1]
	global_store_dwordx4 v[44:45], v[30:33], off
	ds_read_b32 v0, v36 offset:64
	ds_read_b32 v5, v36 offset:196
	ds_read_b32 v27, v36 offset:328
	ds_read_b32 v28, v36 offset:460
	ds_read_b32 v32, v36 offset:592
	ds_read_b32 v33, v36 offset:724
	ds_read_b32 v41, v36 offset:856
	ds_read_b32 v44, v36 offset:988
	s_waitcnt lgkmcnt(0)
	v_cvt_pk_bf16_f32 v30, v0, v5
	v_or_b32_e32 v0, v29, v38
	v_lshlrev_b32_e32 v0, 10, v0
	v_cvt_pk_bf16_f32 v31, v27, v28
	v_cvt_pk_bf16_f32 v32, v32, v33
	v_cvt_pk_bf16_f32 v33, v41, v44
	v_lshl_add_u64 v[44:45], v[42:43], 0, v[0:1]
	global_store_dwordx4 v[44:45], v[30:33], off
	ds_read_b32 v0, v36 offset:96
	ds_read_b32 v5, v36 offset:228
	ds_read_b32 v27, v36 offset:360
	ds_read_b32 v28, v36 offset:492
	ds_read_b32 v32, v36 offset:624
	ds_read_b32 v33, v36 offset:756
	ds_read_b32 v41, v36 offset:888
	ds_read_b32 v44, v36 offset:1020
	s_waitcnt lgkmcnt(0)
	v_cvt_pk_bf16_f32 v30, v0, v5
	v_or_b32_e32 v0, v29, v39
	v_lshlrev_b32_e32 v0, 10, v0
	v_cvt_pk_bf16_f32 v31, v27, v28
	v_cvt_pk_bf16_f32 v32, v32, v33
	v_cvt_pk_bf16_f32 v33, v41, v44
	v_lshl_add_u64 v[28:29], v[42:43], 0, v[0:1]
	global_store_dwordx4 v[28:29], v[30:33], off
	s_waitcnt lgkmcnt(0)

.LBB0_498:
	s_lshl_b32 s11, s8, 1
	s_lshl_b32 s12, s9, 1
	v_or_b32_e32 v0, s11, v3
	v_or_b32_e32 v29, s12, v4
	s_add_i32 s13, s11, 4
	s_add_i32 s15, s12, 4
	s_add_i32 s17, s11, 8
	s_add_i32 s18, s12, 8
	s_add_i32 s19, s11, 12
	s_add_i32 s20, s12, 12
	s_add_i32 s21, s11, 16
	s_add_i32 s22, s12, 16
	s_add_i32 s23, s11, 20
	s_add_i32 s24, s12, 20
	s_add_i32 s25, s11, 24
	s_add_i32 s26, s12, 24
	s_add_i32 s11, s11, 28
	s_add_i32 s12, s12, 28
	v_add_u32_e32 v41, v0, v5
	v_add_u32_e32 v32, v29, v28
	s_waitcnt vmcnt(0)
	v_or_b32_e32 v72, s13, v3
	v_or_b32_e32 v73, s15, v4
	v_or_b32_e32 v74, s17, v3
	v_or_b32_e32 v75, s18, v4
	v_or_b32_e32 v76, s19, v3
	v_or_b32_e32 v77, s20, v4
	v_or_b32_e32 v78, s21, v3
	v_or_b32_e32 v79, s22, v4
	v_or_b32_e32 v80, s23, v3
	v_or_b32_e32 v81, s24, v4
	v_or_b32_e32 v82, s25, v3
	v_or_b32_e32 v83, s26, v4
	v_or_b32_e32 v84, s11, v3
	v_or_b32_e32 v85, s12, v4
	v_mad_u64_u32 v[32:33], s[12:13], v32, s92, v[30:31]
	v_mad_u64_u32 v[42:43], s[12:13], v41, s92, v[30:31]
	v_add_u32_e32 v41, v72, v5
	v_add_u32_e32 v44, v73, v28
	v_add_u32_e32 v50, v74, v5
	v_add_u32_e32 v48, v75, v28
	v_add_u32_e32 v54, v76, v5
	v_add_u32_e32 v52, v77, v28
	v_add_u32_e32 v58, v78, v5
	v_add_u32_e32 v56, v79, v28
	v_add_u32_e32 v62, v80, v5
	v_add_u32_e32 v60, v81, v28
	v_add_u32_e32 v66, v82, v5
	v_add_u32_e32 v64, v83, v28
	v_add_u32_e32 v70, v84, v5
	v_add_u32_e32 v68, v85, v28
	v_mad_u64_u32 v[44:45], s[12:13], v44, s92, v[30:31]
	v_mad_u64_u32 v[46:47], s[12:13], v41, s92, v[30:31]
	v_mad_u64_u32 v[48:49], s[12:13], v48, s92, v[30:31]
	v_mad_u64_u32 v[50:51], s[12:13], v50, s92, v[30:31]
	v_mad_u64_u32 v[52:53], s[12:13], v52, s92, v[30:31]
	v_mad_u64_u32 v[54:55], s[12:13], v54, s92, v[30:31]
	v_mad_u64_u32 v[56:57], s[12:13], v56, s92, v[30:31]
	v_mad_u64_u32 v[58:59], s[12:13], v58, s92, v[30:31]
	v_mad_u64_u32 v[60:61], s[12:13], v60, s92, v[30:31]
	v_mad_u64_u32 v[62:63], s[12:13], v62, s92, v[30:31]
	v_mad_u64_u32 v[64:65], s[12:13], v64, s92, v[30:31]
	v_mad_u64_u32 v[66:67], s[12:13], v66, s92, v[30:31]
	v_mad_u64_u32 v[68:69], s[12:13], v68, s92, v[30:31]
	v_mad_u64_u32 v[70:71], s[12:13], v70, s92, v[30:31]
	global_load_dword v41, v[32:33], off offset:1664
	global_load_dword v86, v[42:43], off offset:1664
	global_load_dword v87, v[44:45], off offset:1664
	global_load_dword v88, v[46:47], off offset:1664
	global_load_dword v89, v[48:49], off offset:1664
	global_load_dword v90, v[50:51], off offset:1664
	global_load_dword v91, v[52:53], off offset:1664
	global_load_dword v92, v[54:55], off offset:1664
	global_load_dword v93, v[56:57], off offset:1664
	global_load_dword v94, v[58:59], off offset:1664
	global_load_dword v95, v[60:61], off offset:1664
	global_load_dword v96, v[62:63], off offset:1664
	global_load_dword v97, v[64:65], off offset:1664
	global_load_dword v98, v[66:67], off offset:1664
	global_load_dword v99, v[68:69], off offset:1664
	global_load_dword v100, v[70:71], off offset:1664
	s_add_i32 s9, s9, 16
	s_add_i32 s8, s8, 16
	s_add_i32 s10, s10, -16
	v_mad_u64_u32 v[32:33], s[12:13], v29, s86, v[8:9]
	s_cmp_lg_u32 s10, 0
	v_mad_u64_u32 v[42:43], s[12:13], v0, s86, v[8:9]
	v_mad_u64_u32 v[44:45], s[12:13], v73, s86, v[8:9]
	v_mad_u64_u32 v[46:47], s[12:13], v72, s86, v[8:9]
	v_mad_u64_u32 v[48:49], s[12:13], v75, s86, v[8:9]
	v_mad_u64_u32 v[50:51], s[12:13], v74, s86, v[8:9]
	v_mad_u64_u32 v[52:53], s[12:13], v77, s86, v[8:9]
	v_mad_u64_u32 v[54:55], s[12:13], v76, s86, v[8:9]
	v_mad_u64_u32 v[56:57], s[12:13], v79, s86, v[8:9]
	v_mad_u64_u32 v[58:59], s[12:13], v78, s86, v[8:9]
	v_mad_u64_u32 v[60:61], s[12:13], v81, s86, v[8:9]
	v_mad_u64_u32 v[62:63], s[12:13], v80, s86, v[8:9]
	v_mad_u64_u32 v[64:65], s[12:13], v83, s86, v[8:9]
	v_mad_u64_u32 v[66:67], s[12:13], v82, s86, v[8:9]
	v_mad_u64_u32 v[68:69], s[12:13], v85, s86, v[8:9]
	v_mad_u64_u32 v[70:71], s[12:13], v84, s86, v[8:9]
	s_waitcnt vmcnt(0)
	ds_write_b32 v32, v41
	ds_write_b32 v42, v86
	ds_write_b32 v44, v87
	ds_write_b32 v46, v88
	ds_write_b32 v48, v89
	ds_write_b32 v50, v90
	ds_write_b32 v52, v91
	ds_write_b32 v54, v92
	ds_write_b32 v56, v93
	ds_write_b32 v58, v94
	ds_write_b32 v60, v95
	ds_write_b32 v62, v96
	ds_write_b32 v64, v97
	ds_write_b32 v66, v98
	ds_write_b32 v68, v99
	ds_write_b32 v70, v100
	s_cbranch_scc1 .LBB0_498
	s_waitcnt lgkmcnt(0)
	v_add_u32_e32 v5, 0xfffff380, v27
	v_lshlrev_b32_e32 v0, 1, v28
	ds_read_b32 v27, v36
	ds_read_b32 v28, v36 offset:132
	ds_read_b32 v29, v36 offset:264
	ds_read_b32 v30, v36 offset:396
	ds_read_b32 v31, v36 offset:528
	ds_read_b32 v41, v36 offset:660
	ds_read_b32 v42, v36 offset:792
	ds_read_b32 v43, v36 offset:924
	v_lshl_add_u64 v[32:33], v[18:19], 0, v[0:1]
	v_or_b32_e32 v0, v5, v35
	s_waitcnt lgkmcnt(0)
	v_cvt_pk_bf16_f32 v29, v29, v30
	v_cvt_pk_bf16_f32 v30, v31, v41
	v_cvt_pk_bf16_f32 v31, v42, v43
	v_lshlrev_b64 v[42:43], 11, v[0:1]
	v_cvt_pk_bf16_f32 v28, v27, v28
	v_lshl_add_u64 v[42:43], v[32:33], 0, v[42:43]
	global_store_dwordx4 v[42:43], v[28:31], off
	ds_read_b32 v0, v36 offset:32
	ds_read_b32 v27, v36 offset:164
	ds_read_b32 v29, v36 offset:296
	ds_read_b32 v30, v36 offset:428
	ds_read_b32 v31, v36 offset:560
	ds_read_b32 v41, v36 offset:692
	ds_read_b32 v42, v36 offset:824
	ds_read_b32 v43, v36 offset:956
	s_waitcnt lgkmcnt(0)
	v_cvt_pk_bf16_f32 v28, v0, v27
	v_or_b32_e32 v0, v5, v37
	v_cvt_pk_bf16_f32 v29, v29, v30
	v_cvt_pk_bf16_f32 v30, v31, v41
	v_cvt_pk_bf16_f32 v31, v42, v43
	v_lshlrev_b64 v[42:43], 11, v[0:1]
	v_lshl_add_u64 v[42:43], v[32:33], 0, v[42:43]
	global_store_dwordx4 v[42:43], v[28:31], off
	ds_read_b32 v0, v36 offset:64
	ds_read_b32 v27, v36 offset:196
	ds_read_b32 v29, v36 offset:328
	ds_read_b32 v30, v36 offset:460
	ds_read_b32 v31, v36 offset:592
	ds_read_b32 v41, v36 offset:724
	ds_read_b32 v42, v36 offset:856
	ds_read_b32 v43, v36 offset:988
	s_waitcnt lgkmcnt(0)
	v_cvt_pk_bf16_f32 v28, v0, v27
	v_or_b32_e32 v0, v5, v38
	v_cvt_pk_bf16_f32 v29, v29, v30
	v_cvt_pk_bf16_f32 v30, v31, v41
	v_cvt_pk_bf16_f32 v31, v42, v43
	v_lshlrev_b64 v[42:43], 11, v[0:1]
	v_lshl_add_u64 v[42:43], v[32:33], 0, v[42:43]
	global_store_dwordx4 v[42:43], v[28:31], off
	ds_read_b32 v0, v36 offset:96
	ds_read_b32 v27, v36 offset:228
	ds_read_b32 v29, v36 offset:360
	ds_read_b32 v30, v36 offset:492
	ds_read_b32 v31, v36 offset:624
	ds_read_b32 v41, v36 offset:756
	ds_read_b32 v42, v36 offset:888
	ds_read_b32 v43, v36 offset:1020
	s_waitcnt lgkmcnt(0)
	v_cvt_pk_bf16_f32 v28, v0, v27
	v_or_b32_e32 v0, v5, v39
	v_cvt_pk_bf16_f32 v29, v29, v30
	v_cvt_pk_bf16_f32 v30, v31, v41
	v_cvt_pk_bf16_f32 v31, v42, v43
	v_lshlrev_b64 v[42:43], 11, v[0:1]
	v_lshl_add_u64 v[32:33], v[32:33], 0, v[42:43]
	global_store_dwordx4 v[32:33], v[28:31], off
	s_waitcnt lgkmcnt(0)

.LBB0_536:
	v_add_u32_e32 v35, s10, v15
	v_and_b32_e32 v36, 0x78, v33
	v_add_u32_e32 v37, v25, v33
	v_add_u32_e32 v38, v11, v33
	v_add_u32_e32 v39, v26, v33
	v_add_u32_e32 v40, v27, v33
	v_add_u32_e32 v41, v28, v33
	v_add_u32_e32 v44, v29, v33
	v_add_u32_e32 v45, v30, v33
	v_lshl_add_u32 v46, v36, 2, v32
	v_and_b32_e32 v47, 0x7f, v37
	v_and_b32_e32 v48, 0x7e, v38
	v_and_b32_e32 v49, 0x7f, v39
	v_and_b32_e32 v50, 0x7c, v40
	v_and_b32_e32 v51, 0x7f, v41
	ds_read2_b32 v[36:37], v35 offset1:1
	ds_read2_b32 v[38:39], v35 offset0:2 offset1:3
	ds_read2_b32 v[40:41], v35 offset0:4 offset1:5
	ds_read2_b32 v[42:43], v35 offset0:6 offset1:7
	v_and_b32_e32 v35, 0x7e, v44
	v_and_b32_e32 v44, 0x7f, v45
	v_lshl_add_u32 v45, v47, 2, v32
	v_lshl_add_u32 v47, v48, 2, v32
	v_lshl_add_u32 v48, v49, 2, v32
	v_lshl_add_u32 v49, v50, 2, v32
	v_lshl_add_u32 v50, v51, 2, v32
	v_lshl_add_u32 v35, v35, 2, v32
	v_lshl_add_u32 v44, v44, 2, v32
	ds_read_b32 v46, v46 offset:33024
	ds_read_b32 v45, v45 offset:33024
	ds_read_b32 v47, v47 offset:33024
	ds_read_b32 v48, v48 offset:33024
	ds_read_b32 v49, v49 offset:33024
	ds_read_b32 v50, v50 offset:33024
	ds_read_b32 v35, v35 offset:33024
	ds_read_b32 v44, v44 offset:33024
	s_waitcnt lgkmcnt(0)
	v_fmac_f32_e32 v31, v36, v46
	s_waitcnt lgkmcnt(6)
	v_fmac_f32_e32 v31, v37, v45
	s_waitcnt lgkmcnt(5)
	v_fmac_f32_e32 v31, v38, v47
	s_waitcnt lgkmcnt(4)
	v_fmac_f32_e32 v31, v39, v48
	s_waitcnt lgkmcnt(3)
	v_fmac_f32_e32 v31, v40, v49
	s_waitcnt lgkmcnt(2)
	v_fmac_f32_e32 v31, v41, v50
	s_add_i32 s10, s10, 32
	s_waitcnt lgkmcnt(1)
	v_fmac_f32_e32 v31, v42, v35
	v_add_u32_e32 v33, v33, v10
	s_cmpk_eq_i32 s10, 0x200
	s_waitcnt lgkmcnt(0)
	v_fmac_f32_e32 v31, v43, v44
	s_cbranch_scc0 .LBB0_536
	v_lshlrev_b32_e32 v33, 2, v25
	v_and_b32_e32 v32, 0x7f, v25
	v_and_b32_e32 v33, 0xfffffe00, v33
	v_or3_b32 v32, v33, s14, v32
	v_ashrrev_i32_e32 v33, 31, v32
	v_lshlrev_b64 v[32:33], 11, v[32:33]
	v_cvt_pk_bf16_f32 v31, v31, s0
	v_lshl_add_u64 v[32:33], v[8:9], 0, v[32:33]
	global_store_short v[32:33], v31, off
	v_add_u32_e32 v31, 8, v25
	v_cmp_le_i32_e64 s[10:11], s15, v25
	v_add_u32_e32 v10, 64, v10
	v_add_u32_e32 v11, 16, v11
	v_add_u32_e32 v26, 24, v26
	v_add_u32_e32 v27, 32, v27
	v_add_u32_e32 v28, 40, v28
	v_add_u32_e32 v29, 48, v29
	v_add_u32_e32 v30, 56, v30
	s_or_b64 s[12:13], s[10:11], s[12:13]
	v_mov_b32_e32 v25, v31
	s_andn2_b64 exec, exec, s[12:13]
	s_cbranch_execnz .LBB0_535
	s_branch .LBB0_522

.LBB0_540:
	v_ashrrev_i32_e32 v0, 31, v4
	v_lshrrev_b32_e32 v6, 17, v0
	v_add_u32_e32 v6, v4, v6
	v_ashrrev_i32_e32 v10, 15, v6
	v_mul_i32_i24_e32 v6, 0x8000, v10
	v_sub_u32_e32 v8, v4, v6
	v_ashrrev_i32_e32 v11, 31, v10
	v_ashrrev_i32_e32 v12, 7, v8
	v_lshlrev_b64 v[6:7], 21, v[10:11]
	v_ashrrev_i32_e32 v13, 31, v12
	v_and_b32_e32 v5, 0x1fc, v3
	v_lshl_add_u64 v[6:7], s[50:51], 0, v[6:7]
	v_lshlrev_b64 v[8:9], 11, v[12:13]
	v_lshlrev_b32_e32 v0, 2, v5
	v_lshl_add_u64 v[6:7], v[6:7], 0, v[8:9]
	v_lshl_add_u64 v[6:7], v[6:7], 0, v[0:1]
	global_load_dwordx4 v[6:9], v[6:7], off
	v_mul_hi_i32_i24_e32 v11, 0x1100, v10
	v_mul_i32_i24_e32 v10, 0x1100, v10
	v_lshl_add_u64 v[10:11], v[10:11], 0, v[12:13]
	v_lshlrev_b64 v[10:11], 10, v[10:11]
	v_add_u32_e32 v4, s8, v4
	v_lshl_add_u64 v[10:11], s[2:3], 0, v[10:11]
	v_lshlrev_b32_e32 v0, 1, v5
	v_cmp_lt_i32_e32 vcc, s7, v4
	v_lshl_add_u64 v[10:11], v[10:11], 0, v[0:1]
	s_or_b64 s[4:5], vcc, s[4:5]
	v_add_co_u32_e32 v10, vcc, 0x400000, v10
	v_add_u32_e32 v3, s6, v3
	s_nop 0
	v_addc_co_u32_e32 v11, vcc, 0, v11, vcc
	s_waitcnt vmcnt(0)
	v_cvt_pk_bf16_f32 v6, v6, v7
	v_cvt_pk_bf16_f32 v7, v8, v9
	global_store_dwordx2 v[10:11], v[6:7], off
	s_andn2_b64 exec, exec, s[4:5]
	s_cbranch_execnz .LBB0_540

.LBB0_544:
	v_ashrrev_i32_e32 v0, 31, v4
	v_ashrrev_i32_e32 v3, 31, v5
	v_lshrrev_b32_e32 v0, 15, v0
	v_lshrrev_b32_e32 v3, 15, v3
	v_add_u32_e32 v0, v4, v0
	v_add_u32_e32 v3, v5, v3
	v_ashrrev_i32_e32 v12, 17, v0
	v_ashrrev_i32_e32 v14, 17, v3
	v_and_b32_e32 v0, 0xfffe0000, v0
	v_ashrrev_i32_e32 v13, 31, v12
	v_and_b32_e32 v3, 0xfffe0000, v3
	v_sub_u32_e32 v9, v4, v0
	v_ashrrev_i32_e32 v15, 31, v14
	v_lshlrev_b64 v[22:23], 21, v[12:13]
	v_sub_u32_e32 v3, v5, v3
	v_ashrrev_i32_e32 v16, 8, v9
	v_lshlrev_b64 v[20:21], 21, v[14:15]
	v_lshlrev_b32_sdwa v0, v244, v9 dst_sel:DWORD dst_unused:UNUSED_PAD src0_sel:DWORD src1_sel:BYTE_0
	v_lshl_add_u64 v[22:23], s[20:21], 0, v[22:23]
	v_mov_b32_e32 v11, v1
	v_ashrrev_i32_e32 v18, 8, v3
	v_lshlrev_b32_sdwa v10, v244, v3 dst_sel:DWORD dst_unused:UNUSED_PAD src0_sel:DWORD src1_sel:BYTE_0
	v_ashrrev_i32_e32 v17, 31, v16
	v_lshl_add_u64 v[20:21], s[20:21], 0, v[20:21]
	v_lshl_add_u64 v[22:23], v[22:23], 0, v[0:1]
	v_ashrrev_i32_e32 v19, 31, v18
	v_lshl_add_u64 v[10:11], v[20:21], 0, v[10:11]
	v_lshl_add_u64 v[20:21], v[16:17], 2, v[22:23]
	v_lshl_add_u64 v[10:11], v[18:19], 2, v[10:11]
	global_load_dword v15, v[20:21], off
	global_load_dword v17, v[10:11], off
	v_mov_b64_e32 v[10:11], s[2:3]
	v_lshl_add_u32 v0, v14, 9, v18
	v_lshl_add_u32 v12, v12, 9, v16
	v_add_u32_e32 v8, -2, v8
	v_mad_i64_i32 v[12:13], s[12:13], v12, s11, v[10:11]
	v_mad_i64_i32 v[10:11], s[12:13], v0, s11, v[10:11]
	v_lshlrev_b32_sdwa v0, v229, v9 dst_sel:DWORD dst_unused:UNUSED_PAD src0_sel:DWORD src1_sel:BYTE_0
	v_cmp_eq_u32_e32 vcc, 0, v8
	v_lshl_add_u64 v[12:13], v[12:13], 0, v[0:1]
	v_lshlrev_b32_sdwa v0, v229, v3 dst_sel:DWORD dst_unused:UNUSED_PAD src0_sel:DWORD src1_sel:BYTE_0
	s_or_b64 s[6:7], vcc, s[6:7]
	v_add_u32_e32 v5, s10, v5
	v_add_u32_e32 v4, s9, v4
	v_lshl_add_u64 v[10:11], v[10:11], 0, v[0:1]
	s_waitcnt vmcnt(0)
	v_cvt_pk_bf16_f32 v0, v15, v17
	global_store_short v[12:13], v0, off
	global_store_short_d16_hi v[10:11], v0, off
	s_andn2_b64 exec, exec, s[6:7]
	s_cbranch_execnz .LBB0_544
	s_or_b64 exec, exec, s[6:7]
	v_mad_u64_u32 v[2:3], s[6:7], v7, s8, v[2:3]
	v_cmp_ne_u32_e32 vcc, v6, v7
	s_orn2_b64 s[6:7], vcc, exec

.LBB0_548:
	v_ashrrev_i32_e32 v0, 31, v2
	v_lshrrev_b32_e32 v0, 15, v0
	v_add_u32_e32 v0, v2, v0
	v_ashrrev_i32_e32 v4, 17, v0
	v_mul_i32_i24_e32 v0, 0x20000, v4
	v_ashrrev_i32_e32 v5, 31, v4
	v_sub_u32_e32 v3, v2, v0
	v_lshlrev_b64 v[6:7], 21, v[4:5]
	v_ashrrev_i32_e32 v8, 8, v3
	v_lshlrev_b32_sdwa v0, v244, v3 dst_sel:DWORD dst_unused:UNUSED_PAD src0_sel:DWORD src1_sel:BYTE_0
	v_lshl_add_u64 v[6:7], s[20:21], 0, v[6:7]
	v_ashrrev_i32_e32 v9, 31, v8
	v_lshl_add_u64 v[6:7], v[6:7], 0, v[0:1]
	v_lshl_add_u64 v[6:7], v[8:9], 2, v[6:7]
	global_load_dword v10, v[6:7], off
	v_lshlrev_b64 v[4:5], 9, v[4:5]
	v_mov_b64_e32 v[6:7], s[2:3]
	v_lshl_add_u64 v[4:5], v[4:5], 0, v[8:9]
	v_add_u32_e32 v2, s8, v2
	v_mad_u64_u32 v[6:7], s[6:7], v4, s9, v[6:7]
	v_cmp_lt_i32_e32 vcc, s10, v2
	v_lshlrev_b32_sdwa v0, v229, v3 dst_sel:DWORD dst_unused:UNUSED_PAD src0_sel:DWORD src1_sel:BYTE_0
	v_mad_i32_i24 v7, v5, s9, v7
	s_or_b64 s[4:5], vcc, s[4:5]
	v_lshl_add_u64 v[4:5], v[6:7], 0, v[0:1]
	s_waitcnt vmcnt(0)
	v_cvt_pk_bf16_f32 v0, v10, s0
	global_store_short v[4:5], v0, off
	s_andn2_b64 exec, exec, s[4:5]
	s_cbranch_execnz .LBB0_548
	s_branch .LBB0_2

.LBB0_560:
	s_lshl_b32 s24, s3, 1
	s_lshl_b32 s25, s22, 1
	v_or_b32_e32 v41, s25, v4
	s_add_i32 s26, s24, 4
	s_add_i32 s27, s25, 4
	s_add_i32 s29, s25, 8
	v_add_u32_e32 v0, v41, v28
	v_or_b32_e32 v62, s26, v3
	v_or_b32_e32 v63, s27, v4
	v_mov_b32_e32 v43, v1
	v_or_b32_e32 v29, s24, v3
	s_add_i32 s31, s25, 12
	v_or_b32_e32 v65, s29, v4
	s_waitcnt vmcnt(0)
	v_lshlrev_b64 v[56:57], 12, v[0:1]
	v_add_u32_e32 v42, v62, v5
	v_add_u32_e32 v0, v63, v28
	v_mov_b32_e32 v33, v1
	s_add_i32 s28, s24, 8
	s_add_i32 s30, s24, 12
	s_add_i32 s35, s25, 16
	v_add_u32_e32 v32, v29, v5
	v_or_b32_e32 v67, s31, v4
	v_lshlrev_b64 v[42:43], 12, v[42:43]
	v_lshlrev_b64 v[58:59], 12, v[0:1]
	v_add_u32_e32 v0, v65, v28
	s_add_i32 s37, s25, 20
	v_or_b32_e32 v64, s28, v3
	v_or_b32_e32 v66, s30, v3
	v_or_b32_e32 v69, s35, v4
	v_lshlrev_b64 v[32:33], 12, v[32:33]
	v_lshl_add_u64 v[56:57], v[30:31], 0, v[56:57]
	v_lshl_add_u64 v[42:43], v[30:31], 0, v[42:43]
	v_lshlrev_b64 v[60:61], 12, v[0:1]
	v_add_u32_e32 v0, v67, v28
	v_mov_b32_e32 v45, v1
	v_mov_b32_e32 v47, v1
	s_add_i32 s34, s24, 16
	s_add_i32 s36, s24, 20
	s_add_i32 s39, s25, 24
	v_or_b32_e32 v71, s37, v4
	v_add_u32_e32 v44, v64, v5
	v_add_u32_e32 v46, v66, v5
	v_lshl_add_u64 v[32:33], v[30:31], 0, v[32:33]
	v_lshl_add_u64 v[58:59], v[30:31], 0, v[58:59]
	global_load_dword v76, v[56:57], off
	global_load_dword v77, v[32:33], off
	global_load_dword v78, v[58:59], off
	global_load_dword v79, v[42:43], off
	v_lshlrev_b64 v[42:43], 12, v[0:1]
	v_add_u32_e32 v0, v69, v28
	s_add_i32 s38, s24, 24
	s_add_i32 s24, s24, 28
	s_add_i32 s25, s25, 28
	v_or_b32_e32 v68, s34, v3
	v_or_b32_e32 v70, s36, v3
	v_or_b32_e32 v73, s39, v4
	v_lshlrev_b64 v[44:45], 12, v[44:45]
	v_lshlrev_b64 v[46:47], 12, v[46:47]
	v_lshl_add_u64 v[32:33], v[30:31], 0, v[60:61]
	v_lshl_add_u64 v[42:43], v[30:31], 0, v[42:43]
	v_lshlrev_b64 v[56:57], 12, v[0:1]
	v_add_u32_e32 v0, v71, v28
	v_mov_b32_e32 v49, v1
	v_mov_b32_e32 v51, v1
	v_or_b32_e32 v72, s38, v3
	v_or_b32_e32 v74, s24, v3
	v_or_b32_e32 v75, s25, v4
	v_add_u32_e32 v48, v68, v5
	v_add_u32_e32 v50, v70, v5
	v_lshl_add_u64 v[44:45], v[30:31], 0, v[44:45]
	v_lshl_add_u64 v[46:47], v[30:31], 0, v[46:47]
	global_load_dword v80, v[32:33], off
	global_load_dword v81, v[44:45], off
	global_load_dword v82, v[42:43], off
	global_load_dword v83, v[46:47], off
	v_lshlrev_b64 v[42:43], 12, v[0:1]
	v_add_u32_e32 v0, v73, v28
	v_mov_b32_e32 v53, v1
	v_mov_b32_e32 v55, v1
	v_add_u32_e32 v52, v72, v5
	v_add_u32_e32 v54, v74, v5
	v_lshlrev_b64 v[48:49], 12, v[48:49]
	v_lshlrev_b64 v[50:51], 12, v[50:51]
	v_lshl_add_u64 v[32:33], v[30:31], 0, v[56:57]
	v_lshl_add_u64 v[42:43], v[30:31], 0, v[42:43]
	v_lshlrev_b64 v[44:45], 12, v[0:1]
	v_add_u32_e32 v0, v75, v28
	v_lshlrev_b64 v[52:53], 12, v[52:53]
	v_lshlrev_b64 v[54:55], 12, v[54:55]
	v_lshl_add_u64 v[48:49], v[30:31], 0, v[48:49]
	v_lshl_add_u64 v[50:51], v[30:31], 0, v[50:51]
	global_load_dword v84, v[32:33], off
	global_load_dword v85, v[48:49], off
	global_load_dword v86, v[42:43], off
	global_load_dword v87, v[50:51], off
	v_lshl_add_u64 v[32:33], v[30:31], 0, v[44:45]
	v_lshlrev_b64 v[42:43], 12, v[0:1]
	v_lshl_add_u64 v[52:53], v[30:31], 0, v[52:53]
	v_lshl_add_u64 v[54:55], v[30:31], 0, v[54:55]
	v_lshl_add_u64 v[42:43], v[30:31], 0, v[42:43]
	global_load_dword v0, v[32:33], off
	global_load_dword v88, v[52:53], off
	global_load_dword v89, v[42:43], off
	global_load_dword v90, v[54:55], off
	s_add_i32 s22, s22, 16
	s_add_i32 s3, s3, 16
	s_add_i32 s23, s23, -16
	v_mad_u64_u32 v[32:33], s[24:25], v41, s86, v[8:9]
	s_cmp_lg_u32 s23, 0
	v_mad_u64_u32 v[42:43], s[24:25], v29, s86, v[8:9]
	v_mad_u64_u32 v[44:45], s[24:25], v63, s86, v[8:9]
	v_mad_u64_u32 v[46:47], s[24:25], v62, s86, v[8:9]
	v_mad_u64_u32 v[48:49], s[24:25], v65, s86, v[8:9]
	v_mad_u64_u32 v[50:51], s[24:25], v64, s86, v[8:9]
	v_mad_u64_u32 v[52:53], s[24:25], v67, s86, v[8:9]
	v_mad_u64_u32 v[54:55], s[24:25], v66, s86, v[8:9]
	v_mad_u64_u32 v[56:57], s[24:25], v69, s86, v[8:9]
	v_mad_u64_u32 v[58:59], s[24:25], v68, s86, v[8:9]
	v_mad_u64_u32 v[60:61], s[24:25], v71, s86, v[8:9]
	v_mad_u64_u32 v[62:63], s[24:25], v70, s86, v[8:9]
	v_mad_u64_u32 v[64:65], s[24:25], v73, s86, v[8:9]
	v_mad_u64_u32 v[66:67], s[24:25], v72, s86, v[8:9]
	v_mad_u64_u32 v[68:69], s[24:25], v75, s86, v[8:9]
	v_mad_u64_u32 v[70:71], s[24:25], v74, s86, v[8:9]
	s_waitcnt vmcnt(0)
	ds_write_b32 v32, v76
	s_waitcnt vmcnt(14)
	ds_write_b32 v42, v77
	s_waitcnt vmcnt(13)
	ds_write_b32 v44, v78
	s_waitcnt vmcnt(12)
	ds_write_b32 v46, v79
	s_waitcnt vmcnt(11)
	ds_write_b32 v48, v80
	s_waitcnt vmcnt(10)
	ds_write_b32 v50, v81
	s_waitcnt vmcnt(9)
	ds_write_b32 v52, v82
	s_waitcnt vmcnt(8)
	ds_write_b32 v54, v83
	s_waitcnt vmcnt(7)
	ds_write_b32 v56, v84
	s_waitcnt vmcnt(6)
	ds_write_b32 v58, v85
	s_waitcnt vmcnt(5)
	ds_write_b32 v60, v86
	s_waitcnt vmcnt(4)
	ds_write_b32 v62, v87
	s_waitcnt vmcnt(3)
	ds_write_b32 v64, v0
	s_waitcnt vmcnt(2)
	ds_write_b32 v66, v88
	s_waitcnt vmcnt(1)
	ds_write_b32 v68, v89
	s_waitcnt vmcnt(0)
	ds_write_b32 v70, v90
	s_cbranch_scc1 .LBB0_560
	s_waitcnt lgkmcnt(0)
	v_lshlrev_b32_e32 v0, 1, v28
	ds_read_b32 v5, v36
	ds_read_b32 v28, v36 offset:132
	ds_read_b32 v29, v36 offset:264
	ds_read_b32 v30, v36 offset:396
	ds_read_b32 v31, v36 offset:528
	ds_read_b32 v41, v36 offset:660
	ds_read_b32 v42, v36 offset:792
	ds_read_b32 v43, v36 offset:924
	v_lshl_add_u64 v[32:33], v[12:13], 0, v[0:1]
	v_or_b32_sdwa v0, v35, v27 dst_sel:DWORD dst_unused:UNUSED_PAD src0_sel:DWORD src1_sel:WORD_0
	v_mul_u32_u24_e32 v0, 0xb00, v0
	v_lshlrev_b32_e32 v0, 1, v0
	s_waitcnt lgkmcnt(6)
	v_cvt_pk_bf16_f32 v28, v5, v28
	s_waitcnt lgkmcnt(4)
	v_cvt_pk_bf16_f32 v29, v29, v30
	s_waitcnt lgkmcnt(2)
	v_cvt_pk_bf16_f32 v30, v31, v41
	s_waitcnt lgkmcnt(0)
	v_cvt_pk_bf16_f32 v31, v42, v43
	v_lshl_add_u64 v[42:43], v[32:33], 0, v[0:1]
	global_store_dwordx4 v[42:43], v[28:31], off
	ds_read_b32 v0, v36 offset:32
	ds_read_b32 v5, v36 offset:164
	ds_read_b32 v29, v36 offset:296
	ds_read_b32 v30, v36 offset:428
	ds_read_b32 v31, v36 offset:560
	ds_read_b32 v41, v36 offset:692
	ds_read_b32 v42, v36 offset:824
	ds_read_b32 v43, v36 offset:956
	s_waitcnt lgkmcnt(0)
	v_cvt_pk_bf16_f32 v28, v0, v5
	v_or_b32_sdwa v0, v37, v27 dst_sel:DWORD dst_unused:UNUSED_PAD src0_sel:DWORD src1_sel:WORD_0
	v_mul_u32_u24_e32 v0, 0xb00, v0
	v_lshlrev_b32_e32 v0, 1, v0
	v_cvt_pk_bf16_f32 v29, v29, v30
	v_cvt_pk_bf16_f32 v30, v31, v41
	v_cvt_pk_bf16_f32 v31, v42, v43
	v_lshl_add_u64 v[42:43], v[32:33], 0, v[0:1]
	global_store_dwordx4 v[42:43], v[28:31], off
	ds_read_b32 v0, v36 offset:64
	ds_read_b32 v5, v36 offset:196
	ds_read_b32 v29, v36 offset:328
	ds_read_b32 v30, v36 offset:460
	ds_read_b32 v31, v36 offset:592
	ds_read_b32 v41, v36 offset:724
	ds_read_b32 v42, v36 offset:856
	ds_read_b32 v43, v36 offset:988
	s_waitcnt lgkmcnt(0)
	v_cvt_pk_bf16_f32 v28, v0, v5
	v_or_b32_sdwa v0, v38, v27 dst_sel:DWORD dst_unused:UNUSED_PAD src0_sel:DWORD src1_sel:WORD_0
	v_mul_u32_u24_e32 v0, 0xb00, v0
	v_lshlrev_b32_e32 v0, 1, v0
	v_cvt_pk_bf16_f32 v29, v29, v30
	v_cvt_pk_bf16_f32 v30, v31, v41
	v_cvt_pk_bf16_f32 v31, v42, v43
	v_lshl_add_u64 v[42:43], v[32:33], 0, v[0:1]
	global_store_dwordx4 v[42:43], v[28:31], off
	ds_read_b32 v0, v36 offset:96
	ds_read_b32 v5, v36 offset:228
	ds_read_b32 v29, v36 offset:360
	ds_read_b32 v30, v36 offset:492
	ds_read_b32 v31, v36 offset:624
	ds_read_b32 v41, v36 offset:756
	ds_read_b32 v42, v36 offset:888
	ds_read_b32 v43, v36 offset:1020
	s_waitcnt lgkmcnt(0)
	v_cvt_pk_bf16_f32 v28, v0, v5
	v_or_b32_sdwa v0, v39, v27 dst_sel:DWORD dst_unused:UNUSED_PAD src0_sel:DWORD src1_sel:WORD_0
	v_mul_u32_u24_e32 v0, 0xb00, v0
	v_lshlrev_b32_e32 v0, 1, v0
	v_cvt_pk_bf16_f32 v29, v29, v30
	v_cvt_pk_bf16_f32 v30, v31, v41
	v_cvt_pk_bf16_f32 v31, v42, v43
	v_lshl_add_u64 v[32:33], v[32:33], 0, v[0:1]
	global_store_dwordx4 v[32:33], v[28:31], off
	s_waitcnt lgkmcnt(0)
	s_mov_b32 s39, s41

.LBB0_564:
	s_lshl_b32 s24, s3, 1
	s_lshl_b32 s25, s23, 1
	v_or_b32_e32 v0, s24, v3
	v_or_b32_e32 v29, s25, v4
	s_add_i32 s26, s24, 4
	s_add_i32 s27, s25, 4
	s_add_i32 s28, s24, 8
	s_add_i32 s29, s25, 8
	s_add_i32 s30, s24, 12
	s_add_i32 s31, s25, 12
	s_add_i32 s34, s24, 16
	s_add_i32 s35, s25, 16
	s_add_i32 s36, s24, 20
	s_add_i32 s37, s25, 20
	s_add_i32 s38, s24, 24
	s_add_i32 s39, s25, 24
	s_add_i32 s24, s24, 28
	s_add_i32 s25, s25, 28
	v_add_u32_e32 v41, v0, v5
	v_add_u32_e32 v32, v29, v28
	s_waitcnt vmcnt(0)
	v_or_b32_e32 v72, s26, v3
	v_or_b32_e32 v73, s27, v4
	v_or_b32_e32 v74, s28, v3
	v_or_b32_e32 v75, s29, v4
	v_or_b32_e32 v76, s30, v3
	v_or_b32_e32 v77, s31, v4
	v_or_b32_e32 v78, s34, v3
	v_or_b32_e32 v79, s35, v4
	v_or_b32_e32 v80, s36, v3
	v_or_b32_e32 v81, s37, v4
	v_or_b32_e32 v82, s38, v3
	v_or_b32_e32 v83, s39, v4
	v_or_b32_e32 v84, s24, v3
	v_or_b32_e32 v85, s25, v4
	v_mad_u64_u32 v[32:33], s[24:25], v32, s40, v[30:31]
	v_mad_u64_u32 v[42:43], s[24:25], v41, s40, v[30:31]
	v_add_u32_e32 v41, v72, v5
	v_add_u32_e32 v44, v73, v28
	v_add_u32_e32 v50, v74, v5
	v_add_u32_e32 v48, v75, v28
	v_add_u32_e32 v54, v76, v5
	v_add_u32_e32 v52, v77, v28
	v_add_u32_e32 v58, v78, v5
	v_add_u32_e32 v56, v79, v28
	v_add_u32_e32 v62, v80, v5
	v_add_u32_e32 v60, v81, v28
	v_add_u32_e32 v66, v82, v5
	v_add_u32_e32 v64, v83, v28
	v_add_u32_e32 v70, v84, v5
	v_add_u32_e32 v68, v85, v28
	v_mad_u64_u32 v[44:45], s[24:25], v44, s40, v[30:31]
	v_mad_u64_u32 v[46:47], s[24:25], v41, s40, v[30:31]
	v_mad_u64_u32 v[48:49], s[24:25], v48, s40, v[30:31]
	v_mad_u64_u32 v[50:51], s[24:25], v50, s40, v[30:31]
	v_mad_u64_u32 v[52:53], s[24:25], v52, s40, v[30:31]
	v_mad_u64_u32 v[54:55], s[24:25], v54, s40, v[30:31]
	v_mad_u64_u32 v[56:57], s[24:25], v56, s40, v[30:31]
	v_mad_u64_u32 v[58:59], s[24:25], v58, s40, v[30:31]
	v_mad_u64_u32 v[60:61], s[24:25], v60, s40, v[30:31]
	v_mad_u64_u32 v[62:63], s[24:25], v62, s40, v[30:31]
	v_mad_u64_u32 v[64:65], s[24:25], v64, s40, v[30:31]
	v_mad_u64_u32 v[66:67], s[24:25], v66, s40, v[30:31]
	v_mad_u64_u32 v[68:69], s[24:25], v68, s40, v[30:31]
	v_mad_u64_u32 v[70:71], s[24:25], v70, s40, v[30:31]
	global_load_dword v41, v[32:33], off
	global_load_dword v86, v[42:43], off
	global_load_dword v87, v[44:45], off
	global_load_dword v88, v[46:47], off
	global_load_dword v89, v[48:49], off
	global_load_dword v90, v[50:51], off
	global_load_dword v91, v[52:53], off
	global_load_dword v92, v[54:55], off
	global_load_dword v93, v[56:57], off
	global_load_dword v94, v[58:59], off
	global_load_dword v95, v[60:61], off
	global_load_dword v96, v[62:63], off
	global_load_dword v97, v[64:65], off
	global_load_dword v98, v[66:67], off
	global_load_dword v99, v[68:69], off
	global_load_dword v100, v[70:71], off
	s_add_i32 s23, s23, 16
	s_add_i32 s3, s3, 16
	s_add_i32 s22, s22, -16
	v_mad_u64_u32 v[32:33], s[24:25], v29, s86, v[8:9]
	s_cmp_lg_u32 s22, 0
	v_mad_u64_u32 v[42:43], s[24:25], v0, s86, v[8:9]
	v_mad_u64_u32 v[44:45], s[24:25], v73, s86, v[8:9]
	v_mad_u64_u32 v[46:47], s[24:25], v72, s86, v[8:9]
	v_mad_u64_u32 v[48:49], s[24:25], v75, s86, v[8:9]
	v_mad_u64_u32 v[50:51], s[24:25], v74, s86, v[8:9]
	v_mad_u64_u32 v[52:53], s[24:25], v77, s86, v[8:9]
	v_mad_u64_u32 v[54:55], s[24:25], v76, s86, v[8:9]
	v_mad_u64_u32 v[56:57], s[24:25], v79, s86, v[8:9]
	v_mad_u64_u32 v[58:59], s[24:25], v78, s86, v[8:9]
	v_mad_u64_u32 v[60:61], s[24:25], v81, s86, v[8:9]
	v_mad_u64_u32 v[62:63], s[24:25], v80, s86, v[8:9]
	v_mad_u64_u32 v[64:65], s[24:25], v83, s86, v[8:9]
	v_mad_u64_u32 v[66:67], s[24:25], v82, s86, v[8:9]
	v_mad_u64_u32 v[68:69], s[24:25], v85, s86, v[8:9]
	v_mad_u64_u32 v[70:71], s[24:25], v84, s86, v[8:9]
	s_waitcnt vmcnt(0)
	ds_write_b32 v32, v41
	ds_write_b32 v42, v86
	ds_write_b32 v44, v87
	ds_write_b32 v46, v88
	ds_write_b32 v48, v89
	ds_write_b32 v50, v90
	ds_write_b32 v52, v91
	ds_write_b32 v54, v92
	ds_write_b32 v56, v93
	ds_write_b32 v58, v94
	ds_write_b32 v60, v95
	ds_write_b32 v62, v96
	ds_write_b32 v64, v97
	ds_write_b32 v66, v98
	ds_write_b32 v68, v99
	ds_write_b32 v70, v100
	s_cbranch_scc1 .LBB0_564
	s_waitcnt lgkmcnt(0)
	v_lshlrev_b32_e32 v0, 1, v28
	ds_read_b32 v5, v36
	ds_read_b32 v28, v36 offset:132
	ds_read_b32 v29, v36 offset:264
	ds_read_b32 v30, v36 offset:396
	ds_read_b32 v31, v36 offset:528
	ds_read_b32 v41, v36 offset:660
	ds_read_b32 v42, v36 offset:792
	ds_read_b32 v43, v36 offset:924
	v_lshl_add_u64 v[32:33], v[14:15], 0, v[0:1]
	v_or_b32_e32 v0, v27, v35
	s_waitcnt lgkmcnt(0)
	v_cvt_pk_bf16_f32 v29, v29, v30
	v_cvt_pk_bf16_f32 v30, v31, v41
	v_cvt_pk_bf16_f32 v31, v42, v43
	v_lshlrev_b64 v[42:43], 11, v[0:1]
	v_cvt_pk_bf16_f32 v28, v5, v28
	v_lshl_add_u64 v[42:43], v[32:33], 0, v[42:43]
	global_store_dwordx4 v[42:43], v[28:31], off
	ds_read_b32 v0, v36 offset:32
	ds_read_b32 v5, v36 offset:164
	ds_read_b32 v29, v36 offset:296
	ds_read_b32 v30, v36 offset:428
	ds_read_b32 v31, v36 offset:560
	ds_read_b32 v41, v36 offset:692
	ds_read_b32 v42, v36 offset:824
	ds_read_b32 v43, v36 offset:956
	s_waitcnt lgkmcnt(0)
	v_cvt_pk_bf16_f32 v28, v0, v5
	v_or_b32_e32 v0, v27, v37
	v_cvt_pk_bf16_f32 v29, v29, v30
	v_cvt_pk_bf16_f32 v30, v31, v41
	v_cvt_pk_bf16_f32 v31, v42, v43
	v_lshlrev_b64 v[42:43], 11, v[0:1]
	v_lshl_add_u64 v[42:43], v[32:33], 0, v[42:43]
	global_store_dwordx4 v[42:43], v[28:31], off
	ds_read_b32 v0, v36 offset:64
	ds_read_b32 v5, v36 offset:196
	ds_read_b32 v29, v36 offset:328
	ds_read_b32 v30, v36 offset:460
	ds_read_b32 v31, v36 offset:592
	ds_read_b32 v41, v36 offset:724
	ds_read_b32 v42, v36 offset:856
	ds_read_b32 v43, v36 offset:988
	s_waitcnt lgkmcnt(0)
	v_cvt_pk_bf16_f32 v28, v0, v5
	v_or_b32_e32 v0, v27, v38
	v_cvt_pk_bf16_f32 v29, v29, v30
	v_cvt_pk_bf16_f32 v30, v31, v41
	v_cvt_pk_bf16_f32 v31, v42, v43
	v_lshlrev_b64 v[42:43], 11, v[0:1]
	v_lshl_add_u64 v[42:43], v[32:33], 0, v[42:43]
	global_store_dwordx4 v[42:43], v[28:31], off
	ds_read_b32 v0, v36 offset:96
	ds_read_b32 v5, v36 offset:228
	ds_read_b32 v29, v36 offset:360
	ds_read_b32 v30, v36 offset:492
	ds_read_b32 v31, v36 offset:624
	ds_read_b32 v41, v36 offset:756
	ds_read_b32 v42, v36 offset:888
	ds_read_b32 v43, v36 offset:1020
	s_waitcnt lgkmcnt(0)
	v_cvt_pk_bf16_f32 v28, v0, v5
	v_or_b32_e32 v0, v27, v39
	v_cvt_pk_bf16_f32 v29, v29, v30
	v_cvt_pk_bf16_f32 v30, v31, v41
	v_cvt_pk_bf16_f32 v31, v42, v43
	v_lshlrev_b64 v[42:43], 11, v[0:1]
	v_lshl_add_u64 v[32:33], v[32:33], 0, v[42:43]
	global_store_dwordx4 v[32:33], v[28:31], off
	s_waitcnt lgkmcnt(0)
	s_mov_b32 s39, s41

.LBB0_569:
	s_lshl_b32 s22, s3, 1
	s_lshl_b32 s23, s20, 1
	v_or_b32_e32 v29, s23, v4
	s_add_i32 s24, s22, 4
	s_add_i32 s25, s23, 4
	s_add_i32 s27, s23, 8
	v_add_u32_e32 v0, v29, v30
	v_or_b32_e32 v31, s24, v3
	v_or_b32_e32 v41, s25, v4
	v_mov_b32_e32 v45, v1
	v_or_b32_e32 v27, s22, v3
	s_add_i32 s29, s23, 12
	v_or_b32_e32 v65, s27, v4
	v_lshlrev_b64 v[58:59], 12, v[0:1]
	v_add_u32_e32 v44, v31, v5
	v_add_u32_e32 v0, v41, v30
	v_mov_b32_e32 v43, v1
	s_add_i32 s26, s22, 8
	s_add_i32 s28, s22, 12
	s_add_i32 s31, s23, 16
	v_add_u32_e32 v42, v27, v5
	v_or_b32_e32 v67, s29, v4
	v_lshlrev_b64 v[44:45], 12, v[44:45]
	v_lshlrev_b64 v[60:61], 12, v[0:1]
	v_add_u32_e32 v0, v65, v30
	s_add_i32 s35, s23, 20
	v_or_b32_e32 v64, s26, v3
	v_or_b32_e32 v66, s28, v3
	v_or_b32_e32 v69, s31, v4
	v_lshlrev_b64 v[42:43], 12, v[42:43]
	v_lshl_add_u64 v[58:59], v[32:33], 0, v[58:59]
	v_lshl_add_u64 v[44:45], v[32:33], 0, v[44:45]
	v_lshlrev_b64 v[62:63], 12, v[0:1]
	v_add_u32_e32 v0, v67, v30
	v_mov_b32_e32 v47, v1
	v_mov_b32_e32 v49, v1
	s_add_i32 s30, s22, 16
	s_add_i32 s34, s22, 20
	s_add_i32 s37, s23, 24
	s_waitcnt vmcnt(0)
	v_or_b32_e32 v71, s35, v4
	v_add_u32_e32 v46, v64, v5
	v_add_u32_e32 v48, v66, v5
	v_lshl_add_u64 v[42:43], v[32:33], 0, v[42:43]
	v_lshl_add_u64 v[60:61], v[32:33], 0, v[60:61]
	global_load_dword v76, v[58:59], off
	global_load_dword v77, v[42:43], off
	global_load_dword v78, v[60:61], off
	global_load_dword v79, v[44:45], off
	v_lshlrev_b64 v[44:45], 12, v[0:1]
	v_add_u32_e32 v0, v69, v30
	s_add_i32 s36, s22, 24
	s_add_i32 s22, s22, 28
	s_add_i32 s23, s23, 28
	v_or_b32_e32 v68, s30, v3
	v_or_b32_e32 v70, s34, v3
	v_or_b32_e32 v73, s37, v4
	v_lshlrev_b64 v[46:47], 12, v[46:47]
	v_lshlrev_b64 v[48:49], 12, v[48:49]
	v_lshl_add_u64 v[42:43], v[32:33], 0, v[62:63]
	v_lshl_add_u64 v[44:45], v[32:33], 0, v[44:45]
	v_lshlrev_b64 v[58:59], 12, v[0:1]
	v_add_u32_e32 v0, v71, v30
	v_mov_b32_e32 v51, v1
	v_mov_b32_e32 v53, v1
	v_or_b32_e32 v72, s36, v3
	v_or_b32_e32 v74, s22, v3
	v_or_b32_e32 v75, s23, v4
	v_add_u32_e32 v50, v68, v5
	v_add_u32_e32 v52, v70, v5
	v_lshl_add_u64 v[46:47], v[32:33], 0, v[46:47]
	v_lshl_add_u64 v[48:49], v[32:33], 0, v[48:49]
	global_load_dword v80, v[42:43], off
	global_load_dword v81, v[46:47], off
	global_load_dword v82, v[44:45], off
	global_load_dword v83, v[48:49], off
	v_lshlrev_b64 v[44:45], 12, v[0:1]
	v_add_u32_e32 v0, v73, v30
	v_mov_b32_e32 v55, v1
	v_mov_b32_e32 v57, v1
	v_add_u32_e32 v54, v72, v5
	v_add_u32_e32 v56, v74, v5
	v_lshlrev_b64 v[50:51], 12, v[50:51]
	v_lshlrev_b64 v[52:53], 12, v[52:53]
	v_lshl_add_u64 v[42:43], v[32:33], 0, v[58:59]
	v_lshl_add_u64 v[44:45], v[32:33], 0, v[44:45]
	v_lshlrev_b64 v[46:47], 12, v[0:1]
	v_add_u32_e32 v0, v75, v30
	v_lshlrev_b64 v[54:55], 12, v[54:55]
	v_lshlrev_b64 v[56:57], 12, v[56:57]
	v_lshl_add_u64 v[50:51], v[32:33], 0, v[50:51]
	v_lshl_add_u64 v[52:53], v[32:33], 0, v[52:53]
	global_load_dword v84, v[42:43], off
	global_load_dword v85, v[50:51], off
	global_load_dword v86, v[44:45], off
	global_load_dword v87, v[52:53], off
	v_lshl_add_u64 v[42:43], v[32:33], 0, v[46:47]
	v_lshlrev_b64 v[44:45], 12, v[0:1]
	v_lshl_add_u64 v[54:55], v[32:33], 0, v[54:55]
	v_lshl_add_u64 v[56:57], v[32:33], 0, v[56:57]
	v_lshl_add_u64 v[44:45], v[32:33], 0, v[44:45]
	global_load_dword v0, v[42:43], off
	global_load_dword v88, v[54:55], off
	global_load_dword v89, v[44:45], off
	global_load_dword v90, v[56:57], off
	s_add_i32 s20, s20, 16
	s_add_i32 s3, s3, 16
	s_add_i32 s21, s21, -16
	v_mad_u64_u32 v[42:43], s[22:23], v29, s86, v[8:9]
	s_cmp_lg_u32 s21, 0
	v_mad_u64_u32 v[44:45], s[22:23], v27, s86, v[8:9]
	v_mad_u64_u32 v[46:47], s[22:23], v41, s86, v[8:9]
	v_mad_u64_u32 v[48:49], s[22:23], v31, s86, v[8:9]
	v_mad_u64_u32 v[50:51], s[22:23], v65, s86, v[8:9]
	v_mad_u64_u32 v[52:53], s[22:23], v64, s86, v[8:9]
	v_mad_u64_u32 v[54:55], s[22:23], v67, s86, v[8:9]
	v_mad_u64_u32 v[56:57], s[22:23], v66, s86, v[8:9]
	v_mad_u64_u32 v[58:59], s[22:23], v69, s86, v[8:9]
	v_mad_u64_u32 v[60:61], s[22:23], v68, s86, v[8:9]
	v_mad_u64_u32 v[62:63], s[22:23], v71, s86, v[8:9]
	v_mad_u64_u32 v[64:65], s[22:23], v70, s86, v[8:9]
	v_mad_u64_u32 v[66:67], s[22:23], v73, s86, v[8:9]
	v_mad_u64_u32 v[68:69], s[22:23], v72, s86, v[8:9]
	v_mad_u64_u32 v[70:71], s[22:23], v75, s86, v[8:9]
	v_mad_u64_u32 v[72:73], s[22:23], v74, s86, v[8:9]
	s_waitcnt vmcnt(0)
	ds_write_b32 v42, v76
	ds_write_b32 v44, v77
	ds_write_b32 v46, v78
	ds_write_b32 v48, v79
	ds_write_b32 v50, v80
	ds_write_b32 v52, v81
	ds_write_b32 v54, v82
	ds_write_b32 v56, v83
	ds_write_b32 v58, v84
	ds_write_b32 v60, v85
	ds_write_b32 v62, v86
	ds_write_b32 v64, v87
	ds_write_b32 v66, v0
	ds_write_b32 v68, v88
	ds_write_b32 v70, v89
	ds_write_b32 v72, v90
	s_cbranch_scc1 .LBB0_569
	s_waitcnt lgkmcnt(0)
	ds_read_b32 v5, v36
	ds_read_b32 v27, v36 offset:132
	ds_read_b32 v29, v36 offset:264
	ds_read_b32 v31, v36 offset:396
	ds_read_b32 v32, v36 offset:528
	ds_read_b32 v33, v36 offset:660
	ds_read_b32 v41, v36 offset:792
	ds_read_b32 v44, v36 offset:924
	v_lshlrev_b32_e32 v0, 1, v30
	v_lshl_add_u64 v[42:43], v[16:17], 0, v[0:1]
	v_or_b32_e32 v0, v28, v35
	s_waitcnt lgkmcnt(0)
	v_cvt_pk_bf16_f32 v32, v32, v33
	v_cvt_pk_bf16_f32 v33, v41, v44
	v_lshlrev_b64 v[44:45], 11, v[0:1]
	v_cvt_pk_bf16_f32 v30, v5, v27
	v_cvt_pk_bf16_f32 v31, v29, v31
	v_lshl_add_u64 v[44:45], v[42:43], 0, v[44:45]
	global_store_dwordx4 v[44:45], v[30:33], off
	ds_read_b32 v0, v36 offset:32
	ds_read_b32 v5, v36 offset:164
	ds_read_b32 v27, v36 offset:296
	ds_read_b32 v29, v36 offset:428
	ds_read_b32 v32, v36 offset:560
	ds_read_b32 v33, v36 offset:692
	ds_read_b32 v41, v36 offset:824
	ds_read_b32 v44, v36 offset:956
	s_waitcnt lgkmcnt(0)
	v_cvt_pk_bf16_f32 v30, v0, v5
	v_or_b32_e32 v0, v28, v37
	v_cvt_pk_bf16_f32 v32, v32, v33
	v_cvt_pk_bf16_f32 v31, v27, v29
	v_cvt_pk_bf16_f32 v33, v41, v44
	v_lshlrev_b64 v[44:45], 11, v[0:1]
	v_lshl_add_u64 v[44:45], v[42:43], 0, v[44:45]
	global_store_dwordx4 v[44:45], v[30:33], off
	ds_read_b32 v0, v36 offset:64
	ds_read_b32 v5, v36 offset:196
	ds_read_b32 v27, v36 offset:328
	ds_read_b32 v29, v36 offset:460
	ds_read_b32 v32, v36 offset:592
	ds_read_b32 v33, v36 offset:724
	ds_read_b32 v41, v36 offset:856
	ds_read_b32 v44, v36 offset:988
	s_waitcnt lgkmcnt(0)
	v_cvt_pk_bf16_f32 v30, v0, v5
	v_or_b32_e32 v0, v28, v38
	v_cvt_pk_bf16_f32 v32, v32, v33
	v_cvt_pk_bf16_f32 v31, v27, v29
	v_cvt_pk_bf16_f32 v33, v41, v44
	v_lshlrev_b64 v[44:45], 11, v[0:1]
	v_lshl_add_u64 v[44:45], v[42:43], 0, v[44:45]
	global_store_dwordx4 v[44:45], v[30:33], off
	ds_read_b32 v0, v36 offset:96
	ds_read_b32 v5, v36 offset:228
	ds_read_b32 v27, v36 offset:360
	ds_read_b32 v29, v36 offset:492
	ds_read_b32 v32, v36 offset:624
	ds_read_b32 v33, v36 offset:756
	ds_read_b32 v41, v36 offset:888
	ds_read_b32 v44, v36 offset:1020
	s_waitcnt lgkmcnt(0)
	v_cvt_pk_bf16_f32 v30, v0, v5
	v_or_b32_e32 v0, v28, v39
	v_cvt_pk_bf16_f32 v31, v27, v29
	v_lshlrev_b64 v[28:29], 11, v[0:1]
	v_cvt_pk_bf16_f32 v32, v32, v33
	v_cvt_pk_bf16_f32 v33, v41, v44
	v_lshl_add_u64 v[28:29], v[42:43], 0, v[28:29]
	global_store_dwordx4 v[28:29], v[30:33], off
	s_waitcnt lgkmcnt(0)

.LBB0_574:
	s_lshl_b32 s22, s3, 1
	s_lshl_b32 s23, s20, 1
	v_or_b32_e32 v41, s23, v4
	s_add_i32 s24, s22, 4
	s_add_i32 s25, s23, 4
	s_add_i32 s27, s23, 8
	v_add_u32_e32 v0, v41, v28
	v_or_b32_e32 v62, s24, v3
	v_or_b32_e32 v63, s25, v4
	v_mov_b32_e32 v43, v1
	v_or_b32_e32 v27, s22, v3
	s_add_i32 s29, s23, 12
	v_or_b32_e32 v65, s27, v4
	s_waitcnt vmcnt(0)
	v_lshlrev_b64 v[56:57], 12, v[0:1]
	v_add_u32_e32 v42, v62, v5
	v_add_u32_e32 v0, v63, v28
	v_mov_b32_e32 v33, v1
	s_add_i32 s26, s22, 8
	s_add_i32 s28, s22, 12
	s_add_i32 s31, s23, 16
	v_add_u32_e32 v32, v27, v5
	v_or_b32_e32 v67, s29, v4
	v_lshlrev_b64 v[42:43], 12, v[42:43]
	v_lshlrev_b64 v[58:59], 12, v[0:1]
	v_add_u32_e32 v0, v65, v28
	s_add_i32 s35, s23, 20
	v_or_b32_e32 v64, s26, v3
	v_or_b32_e32 v66, s28, v3
	v_or_b32_e32 v69, s31, v4
	v_lshlrev_b64 v[32:33], 12, v[32:33]
	v_lshl_add_u64 v[56:57], v[30:31], 0, v[56:57]
	v_lshl_add_u64 v[42:43], v[30:31], 0, v[42:43]
	v_lshlrev_b64 v[60:61], 12, v[0:1]
	v_add_u32_e32 v0, v67, v28
	v_mov_b32_e32 v45, v1
	v_mov_b32_e32 v47, v1
	s_add_i32 s30, s22, 16
	s_add_i32 s34, s22, 20
	s_add_i32 s37, s23, 24
	v_or_b32_e32 v71, s35, v4
	v_add_u32_e32 v44, v64, v5
	v_add_u32_e32 v46, v66, v5
	v_lshl_add_u64 v[32:33], v[30:31], 0, v[32:33]
	v_lshl_add_u64 v[58:59], v[30:31], 0, v[58:59]
	global_load_dword v76, v[56:57], off
	global_load_dword v77, v[32:33], off
	global_load_dword v78, v[58:59], off
	global_load_dword v79, v[42:43], off
	v_lshlrev_b64 v[42:43], 12, v[0:1]
	v_add_u32_e32 v0, v69, v28
	s_add_i32 s36, s22, 24
	s_add_i32 s22, s22, 28
	s_add_i32 s23, s23, 28
	v_or_b32_e32 v68, s30, v3
	v_or_b32_e32 v70, s34, v3
	v_or_b32_e32 v73, s37, v4
	v_lshlrev_b64 v[44:45], 12, v[44:45]
	v_lshlrev_b64 v[46:47], 12, v[46:47]
	v_lshl_add_u64 v[32:33], v[30:31], 0, v[60:61]
	v_lshl_add_u64 v[42:43], v[30:31], 0, v[42:43]
	v_lshlrev_b64 v[56:57], 12, v[0:1]
	v_add_u32_e32 v0, v71, v28
	v_mov_b32_e32 v49, v1
	v_mov_b32_e32 v51, v1
	v_or_b32_e32 v72, s36, v3
	v_or_b32_e32 v74, s22, v3
	v_or_b32_e32 v75, s23, v4
	v_add_u32_e32 v48, v68, v5
	v_add_u32_e32 v50, v70, v5
	v_lshl_add_u64 v[44:45], v[30:31], 0, v[44:45]
	v_lshl_add_u64 v[46:47], v[30:31], 0, v[46:47]
	global_load_dword v80, v[32:33], off
	global_load_dword v81, v[44:45], off
	global_load_dword v82, v[42:43], off
	global_load_dword v83, v[46:47], off
	v_lshlrev_b64 v[42:43], 12, v[0:1]
	v_add_u32_e32 v0, v73, v28
	v_mov_b32_e32 v53, v1
	v_mov_b32_e32 v55, v1
	v_add_u32_e32 v52, v72, v5
	v_add_u32_e32 v54, v74, v5
	v_lshlrev_b64 v[48:49], 12, v[48:49]
	v_lshlrev_b64 v[50:51], 12, v[50:51]
	v_lshl_add_u64 v[32:33], v[30:31], 0, v[56:57]
	v_lshl_add_u64 v[42:43], v[30:31], 0, v[42:43]
	v_lshlrev_b64 v[44:45], 12, v[0:1]
	v_add_u32_e32 v0, v75, v28
	v_lshlrev_b64 v[52:53], 12, v[52:53]
	v_lshlrev_b64 v[54:55], 12, v[54:55]
	v_lshl_add_u64 v[48:49], v[30:31], 0, v[48:49]
	v_lshl_add_u64 v[50:51], v[30:31], 0, v[50:51]
	global_load_dword v84, v[32:33], off
	global_load_dword v85, v[48:49], off
	global_load_dword v86, v[42:43], off
	global_load_dword v87, v[50:51], off
	v_lshl_add_u64 v[32:33], v[30:31], 0, v[44:45]
	v_lshlrev_b64 v[42:43], 12, v[0:1]
	v_lshl_add_u64 v[52:53], v[30:31], 0, v[52:53]
	v_lshl_add_u64 v[54:55], v[30:31], 0, v[54:55]
	v_lshl_add_u64 v[42:43], v[30:31], 0, v[42:43]
	global_load_dword v0, v[32:33], off
	global_load_dword v88, v[52:53], off
	global_load_dword v89, v[42:43], off
	global_load_dword v90, v[54:55], off
	s_add_i32 s20, s20, 16
	s_add_i32 s3, s3, 16
	s_add_i32 s21, s21, -16
	v_mad_u64_u32 v[32:33], s[22:23], v41, s86, v[8:9]
	s_cmp_lg_u32 s21, 0
	v_mad_u64_u32 v[42:43], s[22:23], v27, s86, v[8:9]
	v_mad_u64_u32 v[44:45], s[22:23], v63, s86, v[8:9]
	v_mad_u64_u32 v[46:47], s[22:23], v62, s86, v[8:9]
	v_mad_u64_u32 v[48:49], s[22:23], v65, s86, v[8:9]
	v_mad_u64_u32 v[50:51], s[22:23], v64, s86, v[8:9]
	v_mad_u64_u32 v[52:53], s[22:23], v67, s86, v[8:9]
	v_mad_u64_u32 v[54:55], s[22:23], v66, s86, v[8:9]
	v_mad_u64_u32 v[56:57], s[22:23], v69, s86, v[8:9]
	v_mad_u64_u32 v[58:59], s[22:23], v68, s86, v[8:9]
	v_mad_u64_u32 v[60:61], s[22:23], v71, s86, v[8:9]
	v_mad_u64_u32 v[62:63], s[22:23], v70, s86, v[8:9]
	v_mad_u64_u32 v[64:65], s[22:23], v73, s86, v[8:9]
	v_mad_u64_u32 v[66:67], s[22:23], v72, s86, v[8:9]
	v_mad_u64_u32 v[68:69], s[22:23], v75, s86, v[8:9]
	v_mad_u64_u32 v[70:71], s[22:23], v74, s86, v[8:9]
	s_waitcnt vmcnt(0)
	ds_write_b32 v32, v76
	ds_write_b32 v42, v77
	ds_write_b32 v44, v78
	ds_write_b32 v46, v79
	ds_write_b32 v48, v80
	ds_write_b32 v50, v81
	ds_write_b32 v52, v82
	ds_write_b32 v54, v83
	ds_write_b32 v56, v84
	ds_write_b32 v58, v85
	ds_write_b32 v60, v86
	ds_write_b32 v62, v87
	ds_write_b32 v64, v0
	ds_write_b32 v66, v88
	ds_write_b32 v68, v89
	ds_write_b32 v70, v90
	s_cbranch_scc1 .LBB0_574
	v_mov_b32_e32 v0, 0x1040000
	v_mov_b32_e32 v5, 0xf40000
	v_cndmask_b32_e32 v0, v0, v5, vcc
	v_mov_b32_e32 v5, 0xe40000
	v_cndmask_b32_e64 v0, v0, v5, s[0:1]
	v_lshl_add_u64 v[30:31], s[78:79], 0, v[0:1]
	s_waitcnt lgkmcnt(0)
	v_lshlrev_b32_e32 v0, 1, v28
	v_lshl_add_u64 v[30:31], v[30:31], 0, v[0:1]
	ds_read_b32 v0, v36
	ds_read_b32 v5, v36 offset:132
	ds_read_b32 v28, v36 offset:264
	ds_read_b32 v32, v36 offset:396
	ds_read_b32 v33, v36 offset:528
	ds_read_b32 v41, v36 offset:660
	ds_read_b32 v44, v36 offset:792
	ds_read_b32 v45, v36 offset:924
	v_mov_b32_e32 v27, v1
	v_lshl_add_u64 v[42:43], v[30:31], 0, v[26:27]
	s_waitcnt lgkmcnt(0)
	v_cvt_pk_bf16_f32 v30, v0, v5
	v_or_b32_e32 v0, v29, v35
	v_lshlrev_b32_e32 v0, 10, v0
	v_cvt_pk_bf16_f32 v31, v28, v32
	v_cvt_pk_bf16_f32 v32, v33, v41
	v_cvt_pk_bf16_f32 v33, v44, v45
	v_lshl_add_u64 v[44:45], v[42:43], 0, v[0:1]
	global_store_dwordx4 v[44:45], v[30:33], off
	ds_read_b32 v0, v36 offset:32
	ds_read_b32 v5, v36 offset:164
	ds_read_b32 v27, v36 offset:296
	ds_read_b32 v28, v36 offset:428
	ds_read_b32 v32, v36 offset:560
	ds_read_b32 v33, v36 offset:692
	ds_read_b32 v41, v36 offset:824
	ds_read_b32 v44, v36 offset:956
	s_waitcnt lgkmcnt(0)
	v_cvt_pk_bf16_f32 v30, v0, v5
	v_or_b32_e32 v0, v29, v37
	v_lshlrev_b32_e32 v0, 10, v0
	v_cvt_pk_bf16_f32 v31, v27, v28
	v_cvt_pk_bf16_f32 v32, v32, v33
	v_cvt_pk_bf16_f32 v33, v41, v44
	v_lshl_add_u64 v[44:45], v[42:43], 0, v[0:1]
	global_store_dwordx4 v[44:45], v[30:33], off
	ds_read_b32 v0, v36 offset:64
	ds_read_b32 v5, v36 offset:196
	ds_read_b32 v27, v36 offset:328
	ds_read_b32 v28, v36 offset:460
	ds_read_b32 v32, v36 offset:592
	ds_read_b32 v33, v36 offset:724
	ds_read_b32 v41, v36 offset:856
	ds_read_b32 v44, v36 offset:988
	s_waitcnt lgkmcnt(0)
	v_cvt_pk_bf16_f32 v30, v0, v5
	v_or_b32_e32 v0, v29, v38
	v_lshlrev_b32_e32 v0, 10, v0
	v_cvt_pk_bf16_f32 v31, v27, v28
	v_cvt_pk_bf16_f32 v32, v32, v33
	v_cvt_pk_bf16_f32 v33, v41, v44
	v_lshl_add_u64 v[44:45], v[42:43], 0, v[0:1]
	global_store_dwordx4 v[44:45], v[30:33], off
	ds_read_b32 v0, v36 offset:96
	ds_read_b32 v5, v36 offset:228
	ds_read_b32 v27, v36 offset:360
	ds_read_b32 v28, v36 offset:492
	ds_read_b32 v32, v36 offset:624
	ds_read_b32 v33, v36 offset:756
	ds_read_b32 v41, v36 offset:888
	ds_read_b32 v44, v36 offset:1020
	s_waitcnt lgkmcnt(0)
	v_cvt_pk_bf16_f32 v30, v0, v5
	v_or_b32_e32 v0, v29, v39
	v_lshlrev_b32_e32 v0, 10, v0
	v_cvt_pk_bf16_f32 v31, v27, v28
	v_cvt_pk_bf16_f32 v32, v32, v33
	v_cvt_pk_bf16_f32 v33, v41, v44
	v_lshl_add_u64 v[28:29], v[42:43], 0, v[0:1]
	global_store_dwordx4 v[28:29], v[30:33], off
	s_waitcnt lgkmcnt(0)

.LBB0_579:
	s_lshl_b32 s18, s3, 1
	s_lshl_b32 s19, s16, 1
	v_or_b32_e32 v0, s18, v3
	v_or_b32_e32 v29, s19, v4
	s_add_i32 s20, s18, 4
	s_add_i32 s21, s19, 4
	s_add_i32 s22, s18, 8
	s_add_i32 s23, s19, 8
	s_add_i32 s24, s18, 12
	s_add_i32 s25, s19, 12
	s_add_i32 s26, s18, 16
	s_add_i32 s27, s19, 16
	s_add_i32 s28, s18, 20
	s_add_i32 s29, s19, 20
	s_add_i32 s30, s18, 24
	s_add_i32 s31, s19, 24
	s_add_i32 s18, s18, 28
	s_add_i32 s19, s19, 28
	v_add_u32_e32 v41, v0, v5
	v_add_u32_e32 v32, v29, v28
	s_waitcnt vmcnt(0)
	v_or_b32_e32 v72, s20, v3
	v_or_b32_e32 v73, s21, v4
	v_or_b32_e32 v74, s22, v3
	v_or_b32_e32 v75, s23, v4
	v_or_b32_e32 v76, s24, v3
	v_or_b32_e32 v77, s25, v4
	v_or_b32_e32 v78, s26, v3
	v_or_b32_e32 v79, s27, v4
	v_or_b32_e32 v80, s28, v3
	v_or_b32_e32 v81, s29, v4
	v_or_b32_e32 v82, s30, v3
	v_or_b32_e32 v83, s31, v4
	v_or_b32_e32 v84, s18, v3
	v_or_b32_e32 v85, s19, v4
	v_mad_u64_u32 v[32:33], s[18:19], v32, s92, v[30:31]
	v_mad_u64_u32 v[42:43], s[18:19], v41, s92, v[30:31]
	v_add_u32_e32 v41, v72, v5
	v_add_u32_e32 v44, v73, v28
	v_add_u32_e32 v50, v74, v5
	v_add_u32_e32 v48, v75, v28
	v_add_u32_e32 v54, v76, v5
	v_add_u32_e32 v52, v77, v28
	v_add_u32_e32 v58, v78, v5
	v_add_u32_e32 v56, v79, v28
	v_add_u32_e32 v62, v80, v5
	v_add_u32_e32 v60, v81, v28
	v_add_u32_e32 v66, v82, v5
	v_add_u32_e32 v64, v83, v28
	v_add_u32_e32 v70, v84, v5
	v_add_u32_e32 v68, v85, v28
	v_mad_u64_u32 v[44:45], s[18:19], v44, s92, v[30:31]
	v_mad_u64_u32 v[46:47], s[18:19], v41, s92, v[30:31]
	v_mad_u64_u32 v[48:49], s[18:19], v48, s92, v[30:31]
	v_mad_u64_u32 v[50:51], s[18:19], v50, s92, v[30:31]
	v_mad_u64_u32 v[52:53], s[18:19], v52, s92, v[30:31]
	v_mad_u64_u32 v[54:55], s[18:19], v54, s92, v[30:31]
	v_mad_u64_u32 v[56:57], s[18:19], v56, s92, v[30:31]
	v_mad_u64_u32 v[58:59], s[18:19], v58, s92, v[30:31]
	v_mad_u64_u32 v[60:61], s[18:19], v60, s92, v[30:31]
	v_mad_u64_u32 v[62:63], s[18:19], v62, s92, v[30:31]
	v_mad_u64_u32 v[64:65], s[18:19], v64, s92, v[30:31]
	v_mad_u64_u32 v[66:67], s[18:19], v66, s92, v[30:31]
	v_mad_u64_u32 v[68:69], s[18:19], v68, s92, v[30:31]
	v_mad_u64_u32 v[70:71], s[18:19], v70, s92, v[30:31]
	global_load_dword v41, v[32:33], off offset:1664
	global_load_dword v86, v[42:43], off offset:1664
	global_load_dword v87, v[44:45], off offset:1664
	global_load_dword v88, v[46:47], off offset:1664
	global_load_dword v89, v[48:49], off offset:1664
	global_load_dword v90, v[50:51], off offset:1664
	global_load_dword v91, v[52:53], off offset:1664
	global_load_dword v92, v[54:55], off offset:1664
	global_load_dword v93, v[56:57], off offset:1664
	global_load_dword v94, v[58:59], off offset:1664
	global_load_dword v95, v[60:61], off offset:1664
	global_load_dword v96, v[62:63], off offset:1664
	global_load_dword v97, v[64:65], off offset:1664
	global_load_dword v98, v[66:67], off offset:1664
	global_load_dword v99, v[68:69], off offset:1664
	global_load_dword v100, v[70:71], off offset:1664
	s_add_i32 s16, s16, 16
	s_add_i32 s3, s3, 16
	s_add_i32 s17, s17, -16
	v_mad_u64_u32 v[32:33], s[18:19], v29, s86, v[8:9]
	s_cmp_lg_u32 s17, 0
	v_mad_u64_u32 v[42:43], s[18:19], v0, s86, v[8:9]
	v_mad_u64_u32 v[44:45], s[18:19], v73, s86, v[8:9]
	v_mad_u64_u32 v[46:47], s[18:19], v72, s86, v[8:9]
	v_mad_u64_u32 v[48:49], s[18:19], v75, s86, v[8:9]
	v_mad_u64_u32 v[50:51], s[18:19], v74, s86, v[8:9]
	v_mad_u64_u32 v[52:53], s[18:19], v77, s86, v[8:9]
	v_mad_u64_u32 v[54:55], s[18:19], v76, s86, v[8:9]
	v_mad_u64_u32 v[56:57], s[18:19], v79, s86, v[8:9]
	v_mad_u64_u32 v[58:59], s[18:19], v78, s86, v[8:9]
	v_mad_u64_u32 v[60:61], s[18:19], v81, s86, v[8:9]
	v_mad_u64_u32 v[62:63], s[18:19], v80, s86, v[8:9]
	v_mad_u64_u32 v[64:65], s[18:19], v83, s86, v[8:9]
	v_mad_u64_u32 v[66:67], s[18:19], v82, s86, v[8:9]
	v_mad_u64_u32 v[68:69], s[18:19], v85, s86, v[8:9]
	v_mad_u64_u32 v[70:71], s[18:19], v84, s86, v[8:9]
	s_waitcnt vmcnt(0)
	ds_write_b32 v32, v41
	ds_write_b32 v42, v86
	ds_write_b32 v44, v87
	ds_write_b32 v46, v88
	ds_write_b32 v48, v89
	ds_write_b32 v50, v90
	ds_write_b32 v52, v91
	ds_write_b32 v54, v92
	ds_write_b32 v56, v93
	ds_write_b32 v58, v94
	ds_write_b32 v60, v95
	ds_write_b32 v62, v96
	ds_write_b32 v64, v97
	ds_write_b32 v66, v98
	ds_write_b32 v68, v99
	ds_write_b32 v70, v100
	s_cbranch_scc1 .LBB0_579
	s_waitcnt lgkmcnt(0)
	v_add_u32_e32 v5, 0xfffff380, v27
	v_lshlrev_b32_e32 v0, 1, v28
	ds_read_b32 v27, v36
	ds_read_b32 v28, v36 offset:132
	ds_read_b32 v29, v36 offset:264
	ds_read_b32 v30, v36 offset:396
	ds_read_b32 v31, v36 offset:528
	ds_read_b32 v41, v36 offset:660
	ds_read_b32 v42, v36 offset:792
	ds_read_b32 v43, v36 offset:924
	v_lshl_add_u64 v[32:33], v[18:19], 0, v[0:1]
	v_or_b32_e32 v0, v5, v35
	s_waitcnt lgkmcnt(0)
	v_cvt_pk_bf16_f32 v29, v29, v30
	v_cvt_pk_bf16_f32 v30, v31, v41
	v_cvt_pk_bf16_f32 v31, v42, v43
	v_lshlrev_b64 v[42:43], 11, v[0:1]
	v_cvt_pk_bf16_f32 v28, v27, v28
	v_lshl_add_u64 v[42:43], v[32:33], 0, v[42:43]
	global_store_dwordx4 v[42:43], v[28:31], off
	ds_read_b32 v0, v36 offset:32
	ds_read_b32 v27, v36 offset:164
	ds_read_b32 v29, v36 offset:296
	ds_read_b32 v30, v36 offset:428
	ds_read_b32 v31, v36 offset:560
	ds_read_b32 v41, v36 offset:692
	ds_read_b32 v42, v36 offset:824
	ds_read_b32 v43, v36 offset:956
	s_waitcnt lgkmcnt(0)
	v_cvt_pk_bf16_f32 v28, v0, v27
	v_or_b32_e32 v0, v5, v37
	v_cvt_pk_bf16_f32 v29, v29, v30
	v_cvt_pk_bf16_f32 v30, v31, v41
	v_cvt_pk_bf16_f32 v31, v42, v43
	v_lshlrev_b64 v[42:43], 11, v[0:1]
	v_lshl_add_u64 v[42:43], v[32:33], 0, v[42:43]
	global_store_dwordx4 v[42:43], v[28:31], off
	ds_read_b32 v0, v36 offset:64
	ds_read_b32 v27, v36 offset:196
	ds_read_b32 v29, v36 offset:328
	ds_read_b32 v30, v36 offset:460
	ds_read_b32 v31, v36 offset:592
	ds_read_b32 v41, v36 offset:724
	ds_read_b32 v42, v36 offset:856
	ds_read_b32 v43, v36 offset:988
	s_waitcnt lgkmcnt(0)
	v_cvt_pk_bf16_f32 v28, v0, v27
	v_or_b32_e32 v0, v5, v38
	v_cvt_pk_bf16_f32 v29, v29, v30
	v_cvt_pk_bf16_f32 v30, v31, v41
	v_cvt_pk_bf16_f32 v31, v42, v43
	v_lshlrev_b64 v[42:43], 11, v[0:1]
	v_lshl_add_u64 v[42:43], v[32:33], 0, v[42:43]
	global_store_dwordx4 v[42:43], v[28:31], off
	ds_read_b32 v0, v36 offset:96
	ds_read_b32 v27, v36 offset:228
	ds_read_b32 v29, v36 offset:360
	ds_read_b32 v30, v36 offset:492
	ds_read_b32 v31, v36 offset:624
	ds_read_b32 v41, v36 offset:756
	ds_read_b32 v42, v36 offset:888
	ds_read_b32 v43, v36 offset:1020
	s_waitcnt lgkmcnt(0)
	v_cvt_pk_bf16_f32 v28, v0, v27
	v_or_b32_e32 v0, v5, v39
	v_cvt_pk_bf16_f32 v29, v29, v30
	v_cvt_pk_bf16_f32 v30, v31, v41
	v_cvt_pk_bf16_f32 v31, v42, v43
	v_lshlrev_b64 v[42:43], 11, v[0:1]
	v_lshl_add_u64 v[32:33], v[32:33], 0, v[42:43]
	global_store_dwordx4 v[32:33], v[28:31], off
	s_waitcnt lgkmcnt(0)

.LBB0_617:
	v_add_u32_e32 v35, s10, v15
	v_and_b32_e32 v36, 0x78, v33
	v_add_u32_e32 v37, v25, v33
	v_add_u32_e32 v38, v11, v33
	v_add_u32_e32 v39, v26, v33
	v_add_u32_e32 v40, v27, v33
	v_add_u32_e32 v41, v28, v33
	v_add_u32_e32 v44, v29, v33
	v_add_u32_e32 v45, v30, v33
	v_lshl_add_u32 v46, v36, 2, v32
	v_and_b32_e32 v47, 0x7f, v37
	v_and_b32_e32 v48, 0x7e, v38
	v_and_b32_e32 v49, 0x7f, v39
	v_and_b32_e32 v50, 0x7c, v40
	v_and_b32_e32 v51, 0x7f, v41
	ds_read2_b32 v[36:37], v35 offset1:1
	ds_read2_b32 v[38:39], v35 offset0:2 offset1:3
	ds_read2_b32 v[40:41], v35 offset0:4 offset1:5
	ds_read2_b32 v[42:43], v35 offset0:6 offset1:7
	v_and_b32_e32 v35, 0x7e, v44
	v_and_b32_e32 v44, 0x7f, v45
	v_lshl_add_u32 v45, v47, 2, v32
	v_lshl_add_u32 v47, v48, 2, v32
	v_lshl_add_u32 v48, v49, 2, v32
	v_lshl_add_u32 v49, v50, 2, v32
	v_lshl_add_u32 v50, v51, 2, v32
	v_lshl_add_u32 v35, v35, 2, v32
	v_lshl_add_u32 v44, v44, 2, v32
	ds_read_b32 v46, v46 offset:33024
	ds_read_b32 v45, v45 offset:33024
	ds_read_b32 v47, v47 offset:33024
	ds_read_b32 v48, v48 offset:33024
	ds_read_b32 v49, v49 offset:33024
	ds_read_b32 v50, v50 offset:33024
	ds_read_b32 v35, v35 offset:33024
	ds_read_b32 v44, v44 offset:33024
	s_waitcnt lgkmcnt(0)
	v_fmac_f32_e32 v31, v36, v46
	s_waitcnt lgkmcnt(6)
	v_fmac_f32_e32 v31, v37, v45
	s_waitcnt lgkmcnt(5)
	v_fmac_f32_e32 v31, v38, v47
	s_waitcnt lgkmcnt(4)
	v_fmac_f32_e32 v31, v39, v48
	s_waitcnt lgkmcnt(3)
	v_fmac_f32_e32 v31, v40, v49
	s_waitcnt lgkmcnt(2)
	v_fmac_f32_e32 v31, v41, v50
	s_add_i32 s10, s10, 32
	s_waitcnt lgkmcnt(1)
	v_fmac_f32_e32 v31, v42, v35
	v_add_u32_e32 v33, v33, v10
	s_cmpk_eq_i32 s10, 0x200
	s_waitcnt lgkmcnt(0)
	v_fmac_f32_e32 v31, v43, v44
	s_cbranch_scc0 .LBB0_617
	v_lshlrev_b32_e32 v33, 2, v25
	v_and_b32_e32 v32, 0x7f, v25
	v_and_b32_e32 v33, 0xfffffe00, v33
	v_or3_b32 v32, v33, s3, v32
	v_ashrrev_i32_e32 v33, 31, v32
	v_lshlrev_b64 v[32:33], 11, v[32:33]
	v_cvt_pk_bf16_f32 v31, v31, s0
	v_lshl_add_u64 v[32:33], v[8:9], 0, v[32:33]
	global_store_short v[32:33], v31, off
	v_add_u32_e32 v31, 8, v25
	v_cmp_le_i32_e64 s[10:11], s16, v25
	v_add_u32_e32 v10, 64, v10
	v_add_u32_e32 v11, 16, v11
	v_add_u32_e32 v26, 24, v26
	v_add_u32_e32 v27, 32, v27
	v_add_u32_e32 v28, 40, v28
	v_add_u32_e32 v29, 48, v29
	v_add_u32_e32 v30, 56, v30
	s_or_b64 s[14:15], s[10:11], s[14:15]
	v_mov_b32_e32 v25, v31
	s_andn2_b64 exec, exec, s[14:15]
	s_cbranch_execnz .LBB0_616
	s_branch .LBB0_603

.LBB0_621:
	v_ashrrev_i32_e32 v0, 31, v4
	v_lshrrev_b32_e32 v6, 17, v0
	v_add_u32_e32 v6, v4, v6
	v_ashrrev_i32_e32 v10, 15, v6
	v_mul_i32_i24_e32 v6, 0x8000, v10
	v_ashrrev_i32_e32 v11, 31, v10
	v_sub_u32_e32 v8, v4, v6
	v_lshlrev_b64 v[6:7], 10, v[10:11]
	v_ashrrev_i32_e32 v12, 7, v8
	v_lshl_add_u64 v[6:7], v[6:7], 0, s[6:7]
	v_ashrrev_i32_e32 v13, 31, v12
	v_lshl_add_u64 v[6:7], v[6:7], 0, v[12:13]
	v_and_b32_e32 v5, 0x1fc, v3
	v_lshlrev_b64 v[6:7], 11, v[6:7]
	v_lshlrev_b32_e32 v0, 2, v5
	v_lshl_add_u64 v[6:7], s[18:19], 0, v[6:7]
	v_lshl_add_u64 v[6:7], v[6:7], 0, v[0:1]
	global_load_dwordx4 v[6:9], v[6:7], off
	v_mul_hi_i32_i24_e32 v11, 0x1100, v10
	v_mul_i32_i24_e32 v10, 0x1100, v10
	v_lshl_add_u64 v[10:11], v[10:11], 0, v[12:13]
	v_lshlrev_b64 v[10:11], 10, v[10:11]
	v_add_u32_e32 v4, s2, v4
	v_lshl_add_u64 v[10:11], s[4:5], 0, v[10:11]
	v_lshlrev_b32_e32 v0, 1, v5
	v_cmp_lt_i32_e32 vcc, s11, v4
	v_lshl_add_u64 v[10:11], v[10:11], 0, v[0:1]
	s_or_b64 s[8:9], vcc, s[8:9]
	v_add_co_u32_e32 v10, vcc, 0x400000, v10
	v_add_u32_e32 v3, s10, v3
	s_nop 0
	v_addc_co_u32_e32 v11, vcc, 0, v11, vcc
	s_waitcnt vmcnt(0)
	v_cvt_pk_bf16_f32 v6, v6, v7
	v_cvt_pk_bf16_f32 v7, v8, v9
	global_store_dwordx2 v[10:11], v[6:7], off
	s_andn2_b64 exec, exec, s[8:9]
	s_cbranch_execnz .LBB0_621

.LBB0_625:
	v_ashrrev_i32_e32 v0, 31, v4
	v_ashrrev_i32_e32 v3, 31, v5
	v_lshrrev_b32_e32 v0, 15, v0
	v_lshrrev_b32_e32 v3, 15, v3
	v_add_u32_e32 v0, v4, v0
	v_add_u32_e32 v3, v5, v3
	v_ashrrev_i32_e32 v10, 17, v0
	v_ashrrev_i32_e32 v12, 17, v3
	v_ashrrev_i32_e32 v11, 31, v10
	v_and_b32_e32 v0, 0xfffe0000, v0
	v_ashrrev_i32_e32 v13, 31, v12
	v_lshlrev_b64 v[18:19], 10, v[10:11]
	v_and_b32_e32 v3, 0xfffe0000, v3
	v_sub_u32_e32 v0, v4, v0
	v_lshlrev_b64 v[20:21], 10, v[12:13]
	v_lshl_add_u64 v[18:19], v[18:19], 0, s[4:5]
	v_sub_u32_e32 v3, v5, v3
	v_lshl_add_u64 v[20:21], v[20:21], 0, s[10:11]
	v_or_b32_sdwa v18, v18, v0 dst_sel:DWORD dst_unused:UNUSED_PAD src0_sel:DWORD src1_sel:BYTE_0
	v_ashrrev_i32_e32 v14, 8, v0
	v_or_b32_sdwa v20, v20, v3 dst_sel:DWORD dst_unused:UNUSED_PAD src0_sel:DWORD src1_sel:BYTE_0
	v_lshlrev_b64 v[18:19], 11, v[18:19]
	v_ashrrev_i32_e32 v16, 8, v3
	v_ashrrev_i32_e32 v15, 31, v14
	v_lshlrev_b64 v[20:21], 11, v[20:21]
	v_lshl_add_u64 v[18:19], s[24:25], 0, v[18:19]
	v_ashrrev_i32_e32 v17, 31, v16
	v_lshl_add_u64 v[20:21], s[24:25], 0, v[20:21]
	v_lshl_add_u64 v[18:19], v[14:15], 2, v[18:19]
	v_lshl_add_u64 v[20:21], v[16:17], 2, v[20:21]
	global_load_dword v9, v[18:19], off
	global_load_dword v15, v[20:21], off
	v_mov_b64_e32 v[18:19], s[6:7]
	v_lshl_add_u32 v10, v10, 9, v14
	v_add_u32_e32 v8, -2, v8
	v_lshlrev_b32_sdwa v0, v229, v0 dst_sel:DWORD dst_unused:UNUSED_PAD src0_sel:DWORD src1_sel:BYTE_0
	v_lshl_add_u32 v12, v12, 9, v16
	v_mad_i64_i32 v[10:11], s[16:17], v10, s15, v[18:19]
	v_cmp_eq_u32_e32 vcc, 0, v8
	v_mad_i64_i32 v[12:13], s[16:17], v12, s15, v[18:19]
	v_lshl_add_u64 v[10:11], v[10:11], 0, v[0:1]
	v_lshlrev_b32_sdwa v0, v229, v3 dst_sel:DWORD dst_unused:UNUSED_PAD src0_sel:DWORD src1_sel:BYTE_0
	s_or_b64 s[12:13], vcc, s[12:13]
	v_add_u32_e32 v5, s14, v5
	v_add_u32_e32 v4, s3, v4
	v_lshl_add_u64 v[12:13], v[12:13], 0, v[0:1]
	s_waitcnt vmcnt(0)
	v_cvt_pk_bf16_f32 v0, v9, v15
	global_store_short v[10:11], v0, off
	global_store_short_d16_hi v[12:13], v0, off
	s_andn2_b64 exec, exec, s[12:13]
	s_cbranch_execnz .LBB0_625
	s_or_b64 exec, exec, s[12:13]
	v_mad_u64_u32 v[2:3], s[10:11], v7, s2, v[2:3]
	v_cmp_ne_u32_e32 vcc, v6, v7
	s_orn2_b64 s[10:11], vcc, exec

.LBB0_629:
	v_ashrrev_i32_e32 v0, 31, v2
	v_lshrrev_b32_e32 v0, 15, v0
	v_add_u32_e32 v0, v2, v0
	v_ashrrev_i32_e32 v4, 17, v0
	v_ashrrev_i32_e32 v5, 31, v4
	v_mul_i32_i24_e32 v0, 0x20000, v4
	v_lshlrev_b64 v[6:7], 10, v[4:5]
	v_sub_u32_e32 v0, v2, v0
	v_lshl_add_u64 v[6:7], v[6:7], 0, s[4:5]
	v_or_b32_sdwa v6, v6, v0 dst_sel:DWORD dst_unused:UNUSED_PAD src0_sel:DWORD src1_sel:BYTE_0
	v_ashrrev_i32_e32 v8, 8, v0
	v_lshlrev_b64 v[6:7], 11, v[6:7]
	v_ashrrev_i32_e32 v9, 31, v8
	v_lshl_add_u64 v[6:7], s[24:25], 0, v[6:7]
	v_lshl_add_u64 v[6:7], v[8:9], 2, v[6:7]
	global_load_dword v3, v[6:7], off
	v_lshlrev_b64 v[4:5], 9, v[4:5]
	v_mov_b64_e32 v[6:7], s[6:7]
	v_lshl_add_u64 v[4:5], v[4:5], 0, v[8:9]
	v_add_u32_e32 v2, s2, v2
	v_mad_u64_u32 v[6:7], s[10:11], v4, s3, v[6:7]
	v_lshlrev_b32_sdwa v0, v229, v0 dst_sel:DWORD dst_unused:UNUSED_PAD src0_sel:DWORD src1_sel:BYTE_0
	v_cmp_lt_i32_e32 vcc, s12, v2
	v_mad_i32_i24 v7, v5, s3, v7
	s_or_b64 s[8:9], vcc, s[8:9]
	v_lshl_add_u64 v[4:5], v[6:7], 0, v[0:1]
	s_waitcnt vmcnt(0)
	v_cvt_pk_bf16_f32 v0, v3, s0
	global_store_short v[4:5], v0, off
	s_andn2_b64 exec, exec, s[8:9]
	s_cbranch_execnz .LBB0_629

.LBB0_633:
	s_or_b64 exec, exec, s[14:15]
	v_add_u32_e32 v41, 0xfffff000, v46
	v_lshrrev_b32_e32 v41, 12, v41
	s_movk_i32 s4, 0xfff
	v_add_u32_e32 v41, 1, v41
	v_cmp_lt_i32_e64 s[4:5], s4, v46
	v_mov_b64_e32 v[54:55], s[10:11]
	v_pk_mul_f32 v[82:83], v[14:15], v[14:15]
	v_cndmask_b32_e64 v41, 0, v41, s[4:5]
	v_mad_u64_u32 v[54:55], s[4:5], v41, s89, v[54:55]
	s_mov_b64 s[4:5], 0x1000
	s_nop 0
	v_lshl_add_u64 v[66:67], v[54:55], 0, s[4:5]
	v_lshl_add_u64 v[62:63], v[66:67], 0, v[0:1]
	v_lshl_add_u64 v[68:69], v[54:55], 0, v[0:1]
	global_load_dwordx4 v[54:57], v[36:37], off
	global_load_dwordx4 v[58:61], v[68:69], off
	s_nop 0
	global_load_dwordx4 v[62:65], v[62:63], off
	v_pk_mul_f32 v[84:85], v[10:11], v[10:11]
	v_pk_mul_f32 v[78:79], v[16:17], v[16:17]
	v_pk_mul_f32 v[80:81], v[12:13], v[12:13]
	v_mov_b32_e32 v86, v82
	v_mov_b32_e32 v87, v84
	v_mov_b32_e32 v84, v83
	v_pk_add_f32 v[82:83], v[86:87], v[84:85]
	v_mov_b32_e32 v84, v78
	v_mov_b32_e32 v85, v80
	v_pk_mul_f32 v[74:75], v[2:3], v[2:3]
	v_pk_mul_f32 v[76:77], v[6:7], v[6:7]
	v_pk_add_f32 v[82:83], v[84:85], v[82:83]
	v_mov_b32_e32 v80, v79
	v_pk_mul_f32 v[70:71], v[4:5], v[4:5]
	v_pk_mul_f32 v[72:73], v[8:9], v[8:9]
	v_pk_add_f32 v[78:79], v[80:81], v[82:83]
	v_mov_b32_e32 v80, v74
	v_mov_b32_e32 v81, v76
	v_mov_b32_e32 v76, v75
	v_pk_add_f32 v[74:75], v[80:81], v[76:77]
	v_mov_b32_e32 v76, v70
	v_mov_b32_e32 v77, v72
	v_pk_add_f32 v[74:75], v[76:77], v[74:75]
	v_mov_b32_e32 v72, v71
	v_pk_add_f32 v[70:71], v[72:73], v[74:75]
	v_add_f32_e32 v0, v78, v79
	v_add_f32_e32 v0, v71, v0
	v_add_f32_e32 v0, v70, v0
	ds_bpermute_b32 v41, v35, v0
	v_mov_b32_e32 v43, v1
	v_mov_b32_e32 v45, v1
	s_and_b64 s[0:1], exec, s[0:1]
	s_or_b64 s[12:13], s[0:1], s[12:13]
	s_waitcnt lgkmcnt(0)
	v_add_f32_e32 v0, v0, v41
	ds_bpermute_b32 v41, v48, v0
	v_mov_b32_e32 v46, v47
	s_waitcnt lgkmcnt(0)
	v_add_f32_e32 v0, v0, v41
	ds_bpermute_b32 v41, v49, v0
	s_waitcnt lgkmcnt(0)
	v_add_f32_e32 v0, v0, v41
	ds_bpermute_b32 v41, v50, v0
	s_waitcnt lgkmcnt(0)
	v_add_f32_e32 v0, v0, v41
	ds_bpermute_b32 v41, v51, v0
	s_waitcnt lgkmcnt(0)
	v_add_f32_e32 v0, v0, v41
	ds_bpermute_b32 v41, v52, v0
	s_waitcnt lgkmcnt(0)
	v_add_f32_e32 v0, v0, v41
	v_fmamk_f32 v0, v0, 0x3a800000, v230
	v_mul_f32_e32 v41, 0x4b800000, v0
	v_cmp_gt_f32_e64 s[4:5], s95, v0
	s_nop 1
	v_cndmask_b32_e64 v0, v0, v41, s[4:5]
	v_rsq_f32_e32 v0, v0
	v_mov_b32_e32 v41, v1
	v_lshl_add_u64 v[70:71], v[66:67], 0, v[40:41]
	v_mul_f32_e32 v41, 0x45800000, v0
	v_cndmask_b32_e64 v0, v0, v41, s[4:5]
	v_pk_mul_f32 v[14:15], v[14:15], v[0:1] op_sel_hi:[1,0]
	v_pk_mul_f32 v[16:17], v[16:17], v[0:1] op_sel_hi:[1,0]
	s_waitcnt vmcnt(0)
	v_pk_mul_f32 v[14:15], v[54:55], v[14:15]
	v_pk_mul_f32 v[16:17], v[56:57], v[16:17]
	v_pk_add_f32 v[54:55], v[62:63], 1.0 op_sel_hi:[1,0]
	v_pk_add_f32 v[56:57], v[64:65], 1.0 op_sel_hi:[1,0]
	v_pk_fma_f32 v[14:15], v[54:55], v[14:15], v[58:59]
	v_pk_fma_f32 v[16:17], v[16:17], v[56:57], v[60:61]
	v_cvt_pk_bf16_f32 v14, v14, v15
	v_cvt_pk_bf16_f32 v15, v16, v17
	global_store_dwordx2 v[38:39], v[14:15], off
	global_load_dwordx4 v[14:17], v[36:37], off offset:1024
	s_nop 0
	global_load_dwordx4 v[54:57], v[70:71], off
	global_load_dwordx4 v[58:61], v[68:69], off offset:1024
	v_pk_mul_f32 v[10:11], v[10:11], v[0:1] op_sel_hi:[1,0]
	v_pk_mul_f32 v[12:13], v[12:13], v[0:1] op_sel_hi:[1,0]
	v_lshl_add_u64 v[62:63], v[66:67], 0, v[42:43]
	v_pk_mul_f32 v[6:7], v[6:7], v[0:1] op_sel_hi:[1,0]
	v_pk_mul_f32 v[8:9], v[8:9], v[0:1] op_sel_hi:[1,0]
	s_waitcnt vmcnt(0)
	v_pk_mul_f32 v[10:11], v[10:11], v[14:15]
	s_waitcnt lgkmcnt(0)
	v_pk_add_f32 v[14:15], v[54:55], 1.0 op_sel_hi:[1,0]
	v_pk_mul_f32 v[12:13], v[12:13], v[16:17]
	v_pk_add_f32 v[16:17], v[56:57], 1.0 op_sel_hi:[1,0]
	v_pk_fma_f32 v[10:11], v[10:11], v[14:15], v[58:59]
	v_pk_fma_f32 v[12:13], v[12:13], v[16:17], v[60:61]
	v_cvt_pk_bf16_f32 v10, v10, v11
	v_cvt_pk_bf16_f32 v11, v12, v13
	global_store_dwordx2 v[38:39], v[10:11], off offset:512
	global_load_dwordx4 v[10:13], v[36:37], off offset:2048
	s_nop 0
	global_load_dwordx4 v[14:17], v[62:63], off
	global_load_dwordx4 v[54:57], v[68:69], off offset:2048
	v_lshl_add_u64 v[58:59], v[66:67], 0, v[44:45]
	v_pk_mul_f32 v[66:67], v[2:3], v[0:1] op_sel_hi:[1,0]
	v_mov_b32_e32 v2, v18
	v_mov_b32_e32 v3, v19
	s_waitcnt vmcnt(0)
	v_pk_mul_f32 v[6:7], v[6:7], v[10:11]
	s_waitcnt lgkmcnt(0)
	v_pk_add_f32 v[10:11], v[14:15], 1.0 op_sel_hi:[1,0]
	v_pk_mul_f32 v[8:9], v[8:9], v[12:13]
	v_pk_add_f32 v[12:13], v[16:17], 1.0 op_sel_hi:[1,0]
	v_pk_fma_f32 v[6:7], v[6:7], v[10:11], v[54:55]
	v_pk_fma_f32 v[8:9], v[8:9], v[12:13], v[56:57]
	v_cvt_pk_bf16_f32 v6, v6, v7
	v_cvt_pk_bf16_f32 v7, v8, v9
	global_store_dwordx2 v[38:39], v[6:7], off offset:1024
	global_load_dwordx4 v[54:57], v[36:37], off offset:3072
	s_nop 0
	global_load_dwordx4 v[58:61], v[58:59], off
	s_nop 0
	global_load_dwordx4 v[62:65], v[68:69], off offset:3072
	v_pk_mul_f32 v[68:69], v[4:5], v[0:1] op_sel_hi:[1,0]
	v_mov_b32_e32 v14, v22
	v_mov_b32_e32 v15, v23
	v_mov_b32_e32 v16, v24
	v_mov_b32_e32 v17, v25
	v_mov_b32_e32 v10, v26
	v_mov_b32_e32 v11, v27
	v_mov_b32_e32 v12, v28
	v_mov_b32_e32 v13, v29
	v_mov_b32_e32 v6, v30
	v_mov_b32_e32 v7, v31
	v_mov_b32_e32 v8, v32
	v_mov_b32_e32 v9, v33
	v_mov_b32_e32 v4, v20
	v_mov_b32_e32 v5, v21
	s_waitcnt vmcnt(0)
	v_pk_mul_f32 v[18:19], v[66:67], v[54:55]
	s_waitcnt lgkmcnt(0)
	v_pk_add_f32 v[22:23], v[58:59], 1.0 op_sel_hi:[1,0]
	v_pk_mul_f32 v[24:25], v[68:69], v[56:57]
	v_pk_add_f32 v[26:27], v[60:61], 1.0 op_sel_hi:[1,0]
	v_pk_fma_f32 v[18:19], v[18:19], v[22:23], v[62:63]
	v_pk_fma_f32 v[22:23], v[24:25], v[26:27], v[64:65]
	v_cvt_pk_bf16_f32 v18, v18, v19
	v_cvt_pk_bf16_f32 v19, v22, v23
	global_store_dwordx2 v[38:39], v[18:19], off offset:1536
	v_lshl_add_u64 v[38:39], v[38:39], 0, s[2:3]
	s_andn2_b64 exec, exec, s[12:13]
	s_cbranch_execz .LBB0_636
